# strategy 1 waitcnt placement: merged the back-to-back vmcnt(8) and lgkmcnt(0) waits closing each K-loop load segment into one s_waitcnt; on top of v46
# baseline (speedup 1.0000x reference)
; #define PG8_STAGE(bufoff, gbase, voff) do { _Pragma("unroll") for (int _i = 0; _i < 2; ++_i) \
;         __builtin_amdgcn_global_load_lds((const unsigned*)((const char*)(gbase) + (voff)[_i]), (PG8_LAS unsigned*)(lds + (bufoff) + ldsw + _i * 8192), 16, 0, 0); } while (0)
; #define PG8_LDA(dst, b, h) do { _Pragma("unroll") for (int m = 0; m < 4; ++m) _Pragma("unroll") for (int k = 0; k < 2; ++k) dst[m][k] = *(const PG8_LAS bf16x8*)(lds + PG8_SA(b, h) + aoff + m * 2048 + k * 1024); } while (0)
; #define PG8_LDB(dst, b, h) do { _Pragma("unroll") for (int n = 0; n < 2; ++n) _Pragma("unroll") for (int k = 0; k < 2; ++k) dst[n][k] = *(const PG8_LAS bf16x8*)(lds + PG8_SB(b, h) + boff + n * 2048 + k * 1024); } while (0)
; #define PG8_SCHED __builtin_amdgcn_sched_barrier(0)
; template <class Epi, class Sched, bool ALIGN_EPI = false, bool SP2 = false>
; __device__ __forceinline__ void gemm_phase(PG8_LAS unsigned char* lds, const Gemm g, const Sched& S, const Epi& E) {
;     ...
;             const char* a2 = last ? nA : cA + (size_t)(t + 2) * kstep; const char* b2 = last ? nB : cB + (size_t)(t + 2) * kstep;
;     ...
;             PG8_LDB(B0, 0, 0); PG8_LDB(B1, 0, 1); PG8_SCHED; PG8_LDA(At, 0, 0); PG8_STAGE(PG8_SA(1, 1), a1 + hstep, voffA);
.LBB0_66:
	ds_read_b128 v[152:155], v149
	ds_read_b128 v[156:159], v149 offset:1024
	ds_read_b128 v[160:163], v149 offset:2048
	ds_read_b128 v[164:167], v149 offset:3072
	ds_read_b128 v[168:171], v150
	ds_read_b128 v[172:175], v150 offset:1024
	ds_read_b128 v[176:179], v150 offset:2048
	ds_read_b128 v[180:183], v150 offset:3072
	s_add_u32 s42, s40, 0xfff80080
	s_addc_u32 s43, s41, -1
	s_cmp_eq_u32 s68, 28
	s_cselect_b32 s45, s35, s43
	s_cselect_b32 s44, s63, s42
	s_cselect_b32 s43, s31, s67
	s_cselect_b32 s42, s64, s65

; #define PG8_STAGE(bufoff, gbase, voff) do { _Pragma("unroll") for (int _i = 0; _i < 2; ++_i) \
;         __builtin_amdgcn_global_load_lds((const unsigned*)((const char*)(gbase) + (voff)[_i]), (PG8_LAS unsigned*)(lds + (bufoff) + ldsw + _i * 8192), 16, 0, 0); } while (0)
; #define PG8_LDA(dst, b, h) do { _Pragma("unroll") for (int m = 0; m < 4; ++m) _Pragma("unroll") for (int k = 0; k < 2; ++k) dst[m][k] = *(const PG8_LAS bf16x8*)(lds + PG8_SA(b, h) + aoff + m * 2048 + k * 1024); } while (0)
; #define PG8_LDB(dst, b, h) do { _Pragma("unroll") for (int n = 0; n < 2; ++n) _Pragma("unroll") for (int k = 0; k < 2; ++k) dst[n][k] = *(const PG8_LAS bf16x8*)(lds + PG8_SB(b, h) + boff + n * 2048 + k * 1024); } while (0)
; #define PG8_SCHED __builtin_amdgcn_sched_barrier(0)
; template <class Epi, class Sched, bool ALIGN_EPI = false, bool SP2 = false>
; __device__ __forceinline__ void gemm_phase(PG8_LAS unsigned char* lds, const Gemm g, const Sched& S, const Epi& E) {
;     ...
;             PG8_LDB(B0, 0, 0); PG8_LDB(B1, 0, 1); PG8_SCHED; PG8_LDA(At, 0, 0); PG8_STAGE(PG8_SA(1, 1), a1 + hstep, voffA);
	s_add_i32 m0, s29, 0xc000
	ds_read_b128 v[184:187], v151
	ds_read_b128 v[188:191], v151 offset:1024
	ds_read_b128 v[192:195], v151 offset:2048
	ds_read_b128 v[196:199], v151 offset:3072
	ds_read_b128 v[200:203], v151 offset:4096
	ds_read_b128 v[204:207], v151 offset:5120
	ds_read_b128 v[208:211], v151 offset:6144
	ds_read_b128 v[212:215], v151 offset:7168
	global_load_lds_dwordx4 v136, s[40:41]

; #define PG8_STAGE(bufoff, gbase, voff) do { _Pragma("unroll") for (int _i = 0; _i < 2; ++_i) \
;         __builtin_amdgcn_global_load_lds((const unsigned*)((const char*)(gbase) + (voff)[_i]), (PG8_LAS unsigned*)(lds + (bufoff) + ldsw + _i * 8192), 16, 0, 0); } while (0)
; #define PG8_LDA(dst, b, h) do { _Pragma("unroll") for (int m = 0; m < 4; ++m) _Pragma("unroll") for (int k = 0; k < 2; ++k) dst[m][k] = *(const PG8_LAS bf16x8*)(lds + PG8_SA(b, h) + aoff + m * 2048 + k * 1024); } while (0)
; #define PG8_LDB(dst, b, h) do { _Pragma("unroll") for (int n = 0; n < 2; ++n) _Pragma("unroll") for (int k = 0; k < 2; ++k) dst[n][k] = *(const PG8_LAS bf16x8*)(lds + PG8_SB(b, h) + boff + n * 2048 + k * 1024); } while (0)
; #define PG8_MMA(ai, bj, At, Bt) do { __builtin_amdgcn_s_setprio(1); _Pragma("unroll") for (int m = 0; m < 4; ++m) _Pragma("unroll") for (int n = 0; n < 2; ++n) _Pragma("unroll") for (int k = 0; k < 2; ++k) \
;         acc[ai][bj][m][n] = __builtin_amdgcn_mfma_f32_16x16x32_bf16(Bt[n][k], At[m][k], acc[ai][bj][m][n], 0, 0, 0); __builtin_amdgcn_s_setprio(0); } while (0)
; #define PG8_WAIT_V(n) asm volatile("s_waitcnt vmcnt(" #n ")" ::: "memory")
; #define PG8_WAIT_L(n) asm volatile("s_waitcnt lgkmcnt(" #n ")" ::: "memory")
; #define PG8_BAR __builtin_amdgcn_s_barrier()
; #define PG8_SCHED __builtin_amdgcn_sched_barrier(0)
; template <class Epi, class Sched, bool ALIGN_EPI = false, bool SP2 = false>
; __device__ __forceinline__ void gemm_phase(PG8_LAS unsigned char* lds, const Gemm g, const Sched& S, const Epi& E) {
;     ...
;             PG8_LDB(B0, 0, 0); PG8_LDB(B1, 0, 1); PG8_SCHED; PG8_LDA(At, 0, 0); PG8_STAGE(PG8_SA(1, 1), a1 + hstep, voffA);
;             PG8_WAIT_V(8); PG8_WAIT_L(0); PG8_BAR; PG8_MMA(0, 0, At, B0); PG8_MMA(0, 1, At, B1); PG8_BAR; PG8_SCHED;
	s_add_i32 m0, s29, 0xe000
	s_nop 0
	global_load_lds_dwordx4 v138, s[40:41]
	s_waitcnt vmcnt(8) lgkmcnt(0)


; #define PG8_MMA(ai, bj, At, Bt) do { __builtin_amdgcn_s_setprio(1); _Pragma("unroll") for (int m = 0; m < 4; ++m) _Pragma("unroll") for (int n = 0; n < 2; ++n) _Pragma("unroll") for (int k = 0; k < 2; ++k) \
;         acc[ai][bj][m][n] = __builtin_amdgcn_mfma_f32_16x16x32_bf16(Bt[n][k], At[m][k], acc[ai][bj][m][n], 0, 0, 0); __builtin_amdgcn_s_setprio(0); } while (0)
; #define PG8_WAIT_V(n) asm volatile("s_waitcnt vmcnt(" #n ")" ::: "memory")
; #define PG8_WAIT_L(n) asm volatile("s_waitcnt lgkmcnt(" #n ")" ::: "memory")
; #define PG8_BAR __builtin_amdgcn_s_barrier()
; #define PG8_SCHED __builtin_amdgcn_sched_barrier(0)
; template <class Epi, class Sched, bool ALIGN_EPI = false, bool SP2 = false>
; __device__ __forceinline__ void gemm_phase(PG8_LAS unsigned char* lds, const Gemm g, const Sched& S, const Epi& E) {
;     ...
;             PG8_WAIT_V(8); PG8_WAIT_L(0); PG8_BAR; PG8_MMA(0, 0, At, B0); PG8_MMA(0, 1, At, B1); PG8_BAR; PG8_SCHED;
	s_barrier

; #define PG8_MMA(ai, bj, At, Bt) do { __builtin_amdgcn_s_setprio(1); _Pragma("unroll") for (int m = 0; m < 4; ++m) _Pragma("unroll") for (int n = 0; n < 2; ++n) _Pragma("unroll") for (int k = 0; k < 2; ++k) \
;         acc[ai][bj][m][n] = __builtin_amdgcn_mfma_f32_16x16x32_bf16(Bt[n][k], At[m][k], acc[ai][bj][m][n], 0, 0, 0); __builtin_amdgcn_s_setprio(0); } while (0)
; #define PG8_WAIT_V(n) asm volatile("s_waitcnt vmcnt(" #n ")" ::: "memory")
; #define PG8_WAIT_L(n) asm volatile("s_waitcnt lgkmcnt(" #n ")" ::: "memory")
; #define PG8_BAR __builtin_amdgcn_s_barrier()
; #define PG8_SCHED __builtin_amdgcn_sched_barrier(0)
; template <class Epi, class Sched, bool ALIGN_EPI = false, bool SP2 = false>
; __device__ __forceinline__ void gemm_phase(PG8_LAS unsigned char* lds, const Gemm g, const Sched& S, const Epi& E) {
;     ...
;             PG8_WAIT_V(8); PG8_WAIT_L(0); PG8_BAR; PG8_MMA(0, 0, At, B0); PG8_MMA(0, 1, At, B1); PG8_BAR; PG8_SCHED;
	v_mfma_f32_16x16x32_bf16 v[124:127], v[152:155], v[184:187], v[124:127]
	v_mfma_f32_16x16x32_bf16 v[120:123], v[160:163], v[184:187], v[120:123]
	v_mfma_f32_16x16x32_bf16 v[116:119], v[152:155], v[192:195], v[116:119]
	v_mfma_f32_16x16x32_bf16 v[112:115], v[160:163], v[192:195], v[112:115]
	v_mfma_f32_16x16x32_bf16 v[100:103], v[152:155], v[200:203], v[100:103]
	v_mfma_f32_16x16x32_bf16 v[96:99], v[160:163], v[200:203], v[96:99]
	v_mfma_f32_16x16x32_bf16 v[84:87], v[152:155], v[208:211], v[84:87]
	v_mfma_f32_16x16x32_bf16 v[80:83], v[160:163], v[208:211], v[80:83]
	v_mfma_f32_16x16x32_bf16 v[124:127], v[156:159], v[188:191], v[124:127]
	v_mfma_f32_16x16x32_bf16 v[120:123], v[164:167], v[188:191], v[120:123]
	v_mfma_f32_16x16x32_bf16 v[116:119], v[156:159], v[196:199], v[116:119]
	v_mfma_f32_16x16x32_bf16 v[112:115], v[164:167], v[196:199], v[112:115]
	v_mfma_f32_16x16x32_bf16 v[100:103], v[156:159], v[204:207], v[100:103]
	v_mfma_f32_16x16x32_bf16 v[96:99], v[164:167], v[204:207], v[96:99]
	v_mfma_f32_16x16x32_bf16 v[84:87], v[156:159], v[212:215], v[84:87]
	v_mfma_f32_16x16x32_bf16 v[80:83], v[164:167], v[212:215], v[80:83]


; #define PG8_MMA(ai, bj, At, Bt) do { __builtin_amdgcn_s_setprio(1); _Pragma("unroll") for (int m = 0; m < 4; ++m) _Pragma("unroll") for (int n = 0; n < 2; ++n) _Pragma("unroll") for (int k = 0; k < 2; ++k) \
;         acc[ai][bj][m][n] = __builtin_amdgcn_mfma_f32_16x16x32_bf16(Bt[n][k], At[m][k], acc[ai][bj][m][n], 0, 0, 0); __builtin_amdgcn_s_setprio(0); } while (0)
; #define PG8_WAIT_V(n) asm volatile("s_waitcnt vmcnt(" #n ")" ::: "memory")
; #define PG8_WAIT_L(n) asm volatile("s_waitcnt lgkmcnt(" #n ")" ::: "memory")
; #define PG8_BAR __builtin_amdgcn_s_barrier()
; #define PG8_SCHED __builtin_amdgcn_sched_barrier(0)
; template <class Epi, class Sched, bool ALIGN_EPI = false, bool SP2 = false>
; __device__ __forceinline__ void gemm_phase(PG8_LAS unsigned char* lds, const Gemm g, const Sched& S, const Epi& E) {
;     ...
;             PG8_WAIT_V(8); PG8_WAIT_L(0); PG8_BAR; PG8_MMA(0, 0, At, B0); PG8_MMA(0, 1, At, B1); PG8_BAR; PG8_SCHED;
	v_mfma_f32_16x16x32_bf16 v[108:111], v[168:171], v[184:187], v[108:111]
	v_mfma_f32_16x16x32_bf16 v[104:107], v[176:179], v[184:187], v[104:107]
	v_mfma_f32_16x16x32_bf16 v[92:95], v[168:171], v[192:195], v[92:95]
	v_mfma_f32_16x16x32_bf16 v[88:91], v[176:179], v[192:195], v[88:91]
	v_mfma_f32_16x16x32_bf16 v[76:79], v[168:171], v[200:203], v[76:79]
	v_mfma_f32_16x16x32_bf16 v[72:75], v[176:179], v[200:203], v[72:75]
	v_mfma_f32_16x16x32_bf16 v[68:71], v[168:171], v[208:211], v[68:71]
	v_mfma_f32_16x16x32_bf16 v[64:67], v[176:179], v[208:211], v[64:67]
	v_mfma_f32_16x16x32_bf16 v[108:111], v[172:175], v[188:191], v[108:111]
	v_mfma_f32_16x16x32_bf16 v[104:107], v[180:183], v[188:191], v[104:107]
	v_mfma_f32_16x16x32_bf16 v[92:95], v[172:175], v[196:199], v[92:95]
	v_mfma_f32_16x16x32_bf16 v[88:91], v[180:183], v[196:199], v[88:91]
	v_mfma_f32_16x16x32_bf16 v[76:79], v[172:175], v[204:207], v[76:79]
	v_mfma_f32_16x16x32_bf16 v[72:75], v[180:183], v[204:207], v[72:75]
	v_mfma_f32_16x16x32_bf16 v[68:71], v[172:175], v[212:215], v[68:71]
	v_mfma_f32_16x16x32_bf16 v[64:67], v[180:183], v[212:215], v[64:67]

; #define PG8_STAGE(bufoff, gbase, voff) do { _Pragma("unroll") for (int _i = 0; _i < 2; ++_i) \
;         __builtin_amdgcn_global_load_lds((const unsigned*)((const char*)(gbase) + (voff)[_i]), (PG8_LAS unsigned*)(lds + (bufoff) + ldsw + _i * 8192), 16, 0, 0); } while (0)
; #define PG8_LDA(dst, b, h) do { _Pragma("unroll") for (int m = 0; m < 4; ++m) _Pragma("unroll") for (int k = 0; k < 2; ++k) dst[m][k] = *(const PG8_LAS bf16x8*)(lds + PG8_SA(b, h) + aoff + m * 2048 + k * 1024); } while (0)
; #define PG8_MMA(ai, bj, At, Bt) do { __builtin_amdgcn_s_setprio(1); _Pragma("unroll") for (int m = 0; m < 4; ++m) _Pragma("unroll") for (int n = 0; n < 2; ++n) _Pragma("unroll") for (int k = 0; k < 2; ++k) \
;         acc[ai][bj][m][n] = __builtin_amdgcn_mfma_f32_16x16x32_bf16(Bt[n][k], At[m][k], acc[ai][bj][m][n], 0, 0, 0); __builtin_amdgcn_s_setprio(0); } while (0)
; #define PG8_WAIT_V(n) asm volatile("s_waitcnt vmcnt(" #n ")" ::: "memory")
; #define PG8_WAIT_L(n) asm volatile("s_waitcnt lgkmcnt(" #n ")" ::: "memory")
; #define PG8_BAR __builtin_amdgcn_s_barrier()
; #define PG8_SCHED __builtin_amdgcn_sched_barrier(0)
; template <class Epi, class Sched, bool ALIGN_EPI = false, bool SP2 = false>
; __device__ __forceinline__ void gemm_phase(PG8_LAS unsigned char* lds, const Gemm g, const Sched& S, const Epi& E) {
;     ...
;             PG8_WAIT_V(8); PG8_WAIT_L(0); PG8_BAR; PG8_MMA(0, 0, At, B0); PG8_MMA(0, 1, At, B1); PG8_BAR; PG8_SCHED;
;             PG8_LDA(At, 0, 1); PG8_STAGE(PG8_SB(0, 0), b2, voffB); PG8_STAGE(PG8_SB(0, 1), b2 + hstep, voffB); PG8_STAGE(PG8_SA(0, 0), a2, voffA);
	s_barrier
	s_add_i32 s69, s59, s48
	s_mov_b64 s[96:97], s[42:43]

; #define PG8_STAGE(bufoff, gbase, voff) do { _Pragma("unroll") for (int _i = 0; _i < 2; ++_i) \
;         __builtin_amdgcn_global_load_lds((const unsigned*)((const char*)(gbase) + (voff)[_i]), (PG8_LAS unsigned*)(lds + (bufoff) + ldsw + _i * 8192), 16, 0, 0); } while (0)
; #define PG8_LDA(dst, b, h) do { _Pragma("unroll") for (int m = 0; m < 4; ++m) _Pragma("unroll") for (int k = 0; k < 2; ++k) dst[m][k] = *(const PG8_LAS bf16x8*)(lds + PG8_SA(b, h) + aoff + m * 2048 + k * 1024); } while (0)
; template <class Epi, class Sched, bool ALIGN_EPI = false, bool SP2 = false>
; __device__ __forceinline__ void gemm_phase(PG8_LAS unsigned char* lds, const Gemm g, const Sched& S, const Epi& E) {
;     ...
;             PG8_LDA(At, 0, 1); PG8_STAGE(PG8_SB(0, 0), b2, voffB); PG8_STAGE(PG8_SB(0, 1), b2 + hstep, voffB); PG8_STAGE(PG8_SA(0, 0), a2, voffA);
	s_mov_b32 m0, s69
	ds_read_b128 v[184:187], v151 offset:16384
	ds_read_b128 v[188:191], v151 offset:17408
	ds_read_b128 v[192:195], v151 offset:18432
	ds_read_b128 v[196:199], v151 offset:19456
	ds_read_b128 v[200:203], v151 offset:20480
	ds_read_b128 v[204:207], v151 offset:21504
	ds_read_b128 v[208:211], v151 offset:22528
	ds_read_b128 v[212:215], v151 offset:23552
	global_load_lds_dwordx4 v132, s[42:43]
	s_add_i32 m0, s69, 0x2000
	s_add_u32 s70, s42, 0x80000

; #define PG8_STAGE(bufoff, gbase, voff) do { _Pragma("unroll") for (int _i = 0; _i < 2; ++_i) \
;         __builtin_amdgcn_global_load_lds((const unsigned*)((const char*)(gbase) + (voff)[_i]), (PG8_LAS unsigned*)(lds + (bufoff) + ldsw + _i * 8192), 16, 0, 0); } while (0)
; #define PG8_LDA(dst, b, h) do { _Pragma("unroll") for (int m = 0; m < 4; ++m) _Pragma("unroll") for (int k = 0; k < 2; ++k) dst[m][k] = *(const PG8_LAS bf16x8*)(lds + PG8_SA(b, h) + aoff + m * 2048 + k * 1024); } while (0)
; template <class Epi, class Sched, bool ALIGN_EPI = false, bool SP2 = false>
; __device__ __forceinline__ void gemm_phase(PG8_LAS unsigned char* lds, const Gemm g, const Sched& S, const Epi& E) {
;     ...
;             PG8_LDA(At, 0, 1); PG8_STAGE(PG8_SB(0, 0), b2, voffB); PG8_STAGE(PG8_SB(0, 1), b2 + hstep, voffB); PG8_STAGE(PG8_SA(0, 0), a2, voffA);
	s_addc_u32 s71, s43, 0
	s_add_i32 s69, s60, s48
	global_load_lds_dwordx4 v128, s[42:43]

; #define PG8_STAGE(bufoff, gbase, voff) do { _Pragma("unroll") for (int _i = 0; _i < 2; ++_i) \
;         __builtin_amdgcn_global_load_lds((const unsigned*)((const char*)(gbase) + (voff)[_i]), (PG8_LAS unsigned*)(lds + (bufoff) + ldsw + _i * 8192), 16, 0, 0); } while (0)
; #define PG8_LDA(dst, b, h) do { _Pragma("unroll") for (int m = 0; m < 4; ++m) _Pragma("unroll") for (int k = 0; k < 2; ++k) dst[m][k] = *(const PG8_LAS bf16x8*)(lds + PG8_SA(b, h) + aoff + m * 2048 + k * 1024); } while (0)
; template <class Epi, class Sched, bool ALIGN_EPI = false, bool SP2 = false>
; __device__ __forceinline__ void gemm_phase(PG8_LAS unsigned char* lds, const Gemm g, const Sched& S, const Epi& E) {
;     ...
;             PG8_LDA(At, 0, 1); PG8_STAGE(PG8_SB(0, 0), b2, voffB); PG8_STAGE(PG8_SB(0, 1), b2 + hstep, voffB); PG8_STAGE(PG8_SA(0, 0), a2, voffA);
	s_mov_b32 m0, s69
	s_nop 0
	global_load_lds_dwordx4 v132, s[70:71]

; #define PG8_STAGE(bufoff, gbase, voff) do { _Pragma("unroll") for (int _i = 0; _i < 2; ++_i) \
;         __builtin_amdgcn_global_load_lds((const unsigned*)((const char*)(gbase) + (voff)[_i]), (PG8_LAS unsigned*)(lds + (bufoff) + ldsw + _i * 8192), 16, 0, 0); } while (0)
; #define PG8_LDA(dst, b, h) do { _Pragma("unroll") for (int m = 0; m < 4; ++m) _Pragma("unroll") for (int k = 0; k < 2; ++k) dst[m][k] = *(const PG8_LAS bf16x8*)(lds + PG8_SA(b, h) + aoff + m * 2048 + k * 1024); } while (0)
; template <class Epi, class Sched, bool ALIGN_EPI = false, bool SP2 = false>
; __device__ __forceinline__ void gemm_phase(PG8_LAS unsigned char* lds, const Gemm g, const Sched& S, const Epi& E) {
;     ...
;             PG8_LDA(At, 0, 1); PG8_STAGE(PG8_SB(0, 0), b2, voffB); PG8_STAGE(PG8_SB(0, 1), b2 + hstep, voffB); PG8_STAGE(PG8_SA(0, 0), a2, voffA);
	s_add_i32 m0, s69, 0x2000
	s_nop 0
	global_load_lds_dwordx4 v128, s[70:71]
	s_mov_b64 s[98:99], s[44:45]

; #define PG8_STAGE(bufoff, gbase, voff) do { _Pragma("unroll") for (int _i = 0; _i < 2; ++_i) \
;         __builtin_amdgcn_global_load_lds((const unsigned*)((const char*)(gbase) + (voff)[_i]), (PG8_LAS unsigned*)(lds + (bufoff) + ldsw + _i * 8192), 16, 0, 0); } while (0)
; #define PG8_LDA(dst, b, h) do { _Pragma("unroll") for (int m = 0; m < 4; ++m) _Pragma("unroll") for (int k = 0; k < 2; ++k) dst[m][k] = *(const PG8_LAS bf16x8*)(lds + PG8_SA(b, h) + aoff + m * 2048 + k * 1024); } while (0)
; #define PG8_MMA(ai, bj, At, Bt) do { __builtin_amdgcn_s_setprio(1); _Pragma("unroll") for (int m = 0; m < 4; ++m) _Pragma("unroll") for (int n = 0; n < 2; ++n) _Pragma("unroll") for (int k = 0; k < 2; ++k) \
;         acc[ai][bj][m][n] = __builtin_amdgcn_mfma_f32_16x16x32_bf16(Bt[n][k], At[m][k], acc[ai][bj][m][n], 0, 0, 0); __builtin_amdgcn_s_setprio(0); } while (0)
; #define PG8_WAIT_V(n) asm volatile("s_waitcnt vmcnt(" #n ")" ::: "memory")
; #define PG8_WAIT_L(n) asm volatile("s_waitcnt lgkmcnt(" #n ")" ::: "memory")
; #define PG8_BAR __builtin_amdgcn_s_barrier()
; #define PG8_SCHED __builtin_amdgcn_sched_barrier(0)
; template <class Epi, class Sched, bool ALIGN_EPI = false, bool SP2 = false>
; __device__ __forceinline__ void gemm_phase(PG8_LAS unsigned char* lds, const Gemm g, const Sched& S, const Epi& E) {
;     ...
;             PG8_LDA(At, 0, 1); PG8_STAGE(PG8_SB(0, 0), b2, voffB); PG8_STAGE(PG8_SB(0, 1), b2 + hstep, voffB); PG8_STAGE(PG8_SA(0, 0), a2, voffA);
;             PG8_WAIT_V(8); PG8_WAIT_L(0); PG8_BAR; PG8_MMA(1, 0, At, B0); PG8_MMA(1, 1, At, B1); PG8_BAR; PG8_SCHED;
	s_mov_b32 m0, s29
	s_nop 0
	global_load_lds_dwordx4 v134, s[44:45]
	s_mov_b32 m0, s51
	s_nop 0
	global_load_lds_dwordx4 v130, s[44:45]
	s_waitcnt vmcnt(8) lgkmcnt(0)


; #define PG8_MMA(ai, bj, At, Bt) do { __builtin_amdgcn_s_setprio(1); _Pragma("unroll") for (int m = 0; m < 4; ++m) _Pragma("unroll") for (int n = 0; n < 2; ++n) _Pragma("unroll") for (int k = 0; k < 2; ++k) \
;         acc[ai][bj][m][n] = __builtin_amdgcn_mfma_f32_16x16x32_bf16(Bt[n][k], At[m][k], acc[ai][bj][m][n], 0, 0, 0); __builtin_amdgcn_s_setprio(0); } while (0)
; #define PG8_WAIT_V(n) asm volatile("s_waitcnt vmcnt(" #n ")" ::: "memory")
; #define PG8_WAIT_L(n) asm volatile("s_waitcnt lgkmcnt(" #n ")" ::: "memory")
; #define PG8_BAR __builtin_amdgcn_s_barrier()
; #define PG8_SCHED __builtin_amdgcn_sched_barrier(0)
; template <class Epi, class Sched, bool ALIGN_EPI = false, bool SP2 = false>
; __device__ __forceinline__ void gemm_phase(PG8_LAS unsigned char* lds, const Gemm g, const Sched& S, const Epi& E) {
;     ...
;             PG8_WAIT_V(8); PG8_WAIT_L(0); PG8_BAR; PG8_MMA(1, 0, At, B0); PG8_MMA(1, 1, At, B1); PG8_BAR; PG8_SCHED;
	s_barrier

; #define PG8_MMA(ai, bj, At, Bt) do { __builtin_amdgcn_s_setprio(1); _Pragma("unroll") for (int m = 0; m < 4; ++m) _Pragma("unroll") for (int n = 0; n < 2; ++n) _Pragma("unroll") for (int k = 0; k < 2; ++k) \
;         acc[ai][bj][m][n] = __builtin_amdgcn_mfma_f32_16x16x32_bf16(Bt[n][k], At[m][k], acc[ai][bj][m][n], 0, 0, 0); __builtin_amdgcn_s_setprio(0); } while (0)
; #define PG8_WAIT_V(n) asm volatile("s_waitcnt vmcnt(" #n ")" ::: "memory")
; #define PG8_WAIT_L(n) asm volatile("s_waitcnt lgkmcnt(" #n ")" ::: "memory")
; #define PG8_BAR __builtin_amdgcn_s_barrier()
; #define PG8_SCHED __builtin_amdgcn_sched_barrier(0)
; template <class Epi, class Sched, bool ALIGN_EPI = false, bool SP2 = false>
; __device__ __forceinline__ void gemm_phase(PG8_LAS unsigned char* lds, const Gemm g, const Sched& S, const Epi& E) {
;     ...
;             PG8_WAIT_V(8); PG8_WAIT_L(0); PG8_BAR; PG8_MMA(1, 0, At, B0); PG8_MMA(1, 1, At, B1); PG8_BAR; PG8_SCHED;
	v_mfma_f32_16x16x32_bf16 v[60:63], v[152:155], v[184:187], v[60:63]
	v_mfma_f32_16x16x32_bf16 v[56:59], v[160:163], v[184:187], v[56:59]
	v_mfma_f32_16x16x32_bf16 v[52:55], v[152:155], v[192:195], v[52:55]
	v_mfma_f32_16x16x32_bf16 v[48:51], v[160:163], v[192:195], v[48:51]
	v_mfma_f32_16x16x32_bf16 v[36:39], v[152:155], v[200:203], v[36:39]
	v_mfma_f32_16x16x32_bf16 v[32:35], v[160:163], v[200:203], v[32:35]
	v_mfma_f32_16x16x32_bf16 v[20:23], v[152:155], v[208:211], v[20:23]
	v_mfma_f32_16x16x32_bf16 v[16:19], v[160:163], v[208:211], v[16:19]
	v_mfma_f32_16x16x32_bf16 v[60:63], v[156:159], v[188:191], v[60:63]
	v_mfma_f32_16x16x32_bf16 v[56:59], v[164:167], v[188:191], v[56:59]
	v_mfma_f32_16x16x32_bf16 v[52:55], v[156:159], v[196:199], v[52:55]
	v_mfma_f32_16x16x32_bf16 v[48:51], v[164:167], v[196:199], v[48:51]
	v_mfma_f32_16x16x32_bf16 v[36:39], v[156:159], v[204:207], v[36:39]
	v_mfma_f32_16x16x32_bf16 v[32:35], v[164:167], v[204:207], v[32:35]
	v_mfma_f32_16x16x32_bf16 v[20:23], v[156:159], v[212:215], v[20:23]
	v_mfma_f32_16x16x32_bf16 v[16:19], v[164:167], v[212:215], v[16:19]


; #define PG8_MMA(ai, bj, At, Bt) do { __builtin_amdgcn_s_setprio(1); _Pragma("unroll") for (int m = 0; m < 4; ++m) _Pragma("unroll") for (int n = 0; n < 2; ++n) _Pragma("unroll") for (int k = 0; k < 2; ++k) \
;         acc[ai][bj][m][n] = __builtin_amdgcn_mfma_f32_16x16x32_bf16(Bt[n][k], At[m][k], acc[ai][bj][m][n], 0, 0, 0); __builtin_amdgcn_s_setprio(0); } while (0)
; #define PG8_WAIT_V(n) asm volatile("s_waitcnt vmcnt(" #n ")" ::: "memory")
; #define PG8_WAIT_L(n) asm volatile("s_waitcnt lgkmcnt(" #n ")" ::: "memory")
; #define PG8_BAR __builtin_amdgcn_s_barrier()
; #define PG8_SCHED __builtin_amdgcn_sched_barrier(0)
; template <class Epi, class Sched, bool ALIGN_EPI = false, bool SP2 = false>
; __device__ __forceinline__ void gemm_phase(PG8_LAS unsigned char* lds, const Gemm g, const Sched& S, const Epi& E) {
;     ...
;             PG8_WAIT_V(8); PG8_WAIT_L(0); PG8_BAR; PG8_MMA(1, 0, At, B0); PG8_MMA(1, 1, At, B1); PG8_BAR; PG8_SCHED;
	v_mfma_f32_16x16x32_bf16 v[44:47], v[168:171], v[184:187], v[44:47]
	v_mfma_f32_16x16x32_bf16 v[40:43], v[176:179], v[184:187], v[40:43]
	v_mfma_f32_16x16x32_bf16 v[28:31], v[168:171], v[192:195], v[28:31]
	v_mfma_f32_16x16x32_bf16 v[24:27], v[176:179], v[192:195], v[24:27]
	v_mfma_f32_16x16x32_bf16 v[12:15], v[168:171], v[200:203], v[12:15]
	v_mfma_f32_16x16x32_bf16 v[8:11], v[176:179], v[200:203], v[8:11]
	v_mfma_f32_16x16x32_bf16 v[4:7], v[168:171], v[208:211], v[4:7]
	v_mfma_f32_16x16x32_bf16 v[0:3], v[176:179], v[208:211], v[0:3]
	v_mfma_f32_16x16x32_bf16 v[44:47], v[172:175], v[188:191], v[44:47]
	v_mfma_f32_16x16x32_bf16 v[40:43], v[180:183], v[188:191], v[40:43]
	v_mfma_f32_16x16x32_bf16 v[28:31], v[172:175], v[196:199], v[28:31]
	v_mfma_f32_16x16x32_bf16 v[24:27], v[180:183], v[196:199], v[24:27]
	v_mfma_f32_16x16x32_bf16 v[12:15], v[172:175], v[204:207], v[12:15]
	v_mfma_f32_16x16x32_bf16 v[8:11], v[180:183], v[204:207], v[8:11]
	v_mfma_f32_16x16x32_bf16 v[4:7], v[172:175], v[212:215], v[4:7]
	v_mfma_f32_16x16x32_bf16 v[0:3], v[180:183], v[212:215], v[0:3]

; #define PG8_STAGE(bufoff, gbase, voff) do { _Pragma("unroll") for (int _i = 0; _i < 2; ++_i) \
;         __builtin_amdgcn_global_load_lds((const unsigned*)((const char*)(gbase) + (voff)[_i]), (PG8_LAS unsigned*)(lds + (bufoff) + ldsw + _i * 8192), 16, 0, 0); } while (0)
; #define PG8_LDA(dst, b, h) do { _Pragma("unroll") for (int m = 0; m < 4; ++m) _Pragma("unroll") for (int k = 0; k < 2; ++k) dst[m][k] = *(const PG8_LAS bf16x8*)(lds + PG8_SA(b, h) + aoff + m * 2048 + k * 1024); } while (0)
; #define PG8_LDB(dst, b, h) do { _Pragma("unroll") for (int n = 0; n < 2; ++n) _Pragma("unroll") for (int k = 0; k < 2; ++k) dst[n][k] = *(const PG8_LAS bf16x8*)(lds + PG8_SB(b, h) + boff + n * 2048 + k * 1024); } while (0)
; #define PG8_MMA(ai, bj, At, Bt) do { __builtin_amdgcn_s_setprio(1); _Pragma("unroll") for (int m = 0; m < 4; ++m) _Pragma("unroll") for (int n = 0; n < 2; ++n) _Pragma("unroll") for (int k = 0; k < 2; ++k) \
;         acc[ai][bj][m][n] = __builtin_amdgcn_mfma_f32_16x16x32_bf16(Bt[n][k], At[m][k], acc[ai][bj][m][n], 0, 0, 0); __builtin_amdgcn_s_setprio(0); } while (0)
; #define PG8_WAIT_V(n) asm volatile("s_waitcnt vmcnt(" #n ")" ::: "memory")
; #define PG8_WAIT_L(n) asm volatile("s_waitcnt lgkmcnt(" #n ")" ::: "memory")
; #define PG8_BAR __builtin_amdgcn_s_barrier()
; #define PG8_SCHED __builtin_amdgcn_sched_barrier(0)
; template <class Epi, class Sched, bool ALIGN_EPI = false, bool SP2 = false>
; __device__ __forceinline__ void gemm_phase(PG8_LAS unsigned char* lds, const Gemm g, const Sched& S, const Epi& E) {
;     ...
;             PG8_WAIT_V(8); PG8_WAIT_L(0); PG8_BAR; PG8_MMA(1, 0, At, B0); PG8_MMA(1, 1, At, B1); PG8_BAR; PG8_SCHED;
;             PG8_LDB(B0, 1, 0); PG8_LDB(B1, 1, 1); PG8_SCHED; PG8_LDA(At, 1, 0); PG8_STAGE(PG8_SA(0, 1), a2 + hstep, voffA);
	s_barrier
	s_add_i32 s69, 0, 0x18000
	s_add_i32 s70, 0, 0x1c000


; #define PG8_STAGE(bufoff, gbase, voff) do { _Pragma("unroll") for (int _i = 0; _i < 2; ++_i) \
;         __builtin_amdgcn_global_load_lds((const unsigned*)((const char*)(gbase) + (voff)[_i]), (PG8_LAS unsigned*)(lds + (bufoff) + ldsw + _i * 8192), 16, 0, 0); } while (0)
; #define PG8_LDA(dst, b, h) do { _Pragma("unroll") for (int m = 0; m < 4; ++m) _Pragma("unroll") for (int k = 0; k < 2; ++k) dst[m][k] = *(const PG8_LAS bf16x8*)(lds + PG8_SA(b, h) + aoff + m * 2048 + k * 1024); } while (0)
; #define PG8_LDB(dst, b, h) do { _Pragma("unroll") for (int n = 0; n < 2; ++n) _Pragma("unroll") for (int k = 0; k < 2; ++k) dst[n][k] = *(const PG8_LAS bf16x8*)(lds + PG8_SB(b, h) + boff + n * 2048 + k * 1024); } while (0)
; #define PG8_SCHED __builtin_amdgcn_sched_barrier(0)
; template <class Epi, class Sched, bool ALIGN_EPI = false, bool SP2 = false>
; __device__ __forceinline__ void gemm_phase(PG8_LAS unsigned char* lds, const Gemm g, const Sched& S, const Epi& E) {
;     ...
;             PG8_LDB(B0, 1, 0); PG8_LDB(B1, 1, 1); PG8_SCHED; PG8_LDA(At, 1, 0); PG8_STAGE(PG8_SA(0, 1), a2 + hstep, voffA);
	ds_read_b128 v[152:155], v254
	ds_read_b128 v[156:159], v254 offset:1024
	ds_read_b128 v[160:163], v254 offset:2048
	ds_read_b128 v[164:167], v254 offset:3072
	ds_read_b128 v[168:171], v255
	ds_read_b128 v[172:175], v255 offset:1024
	ds_read_b128 v[176:179], v255 offset:2048
	ds_read_b128 v[180:183], v255 offset:3072
	s_add_u32 s44, s44, 0x80000
	s_addc_u32 s45, s45, 0
	s_mov_b32 m0, s52

; #define PG8_STAGE(bufoff, gbase, voff) do { _Pragma("unroll") for (int _i = 0; _i < 2; ++_i) \
;         __builtin_amdgcn_global_load_lds((const unsigned*)((const char*)(gbase) + (voff)[_i]), (PG8_LAS unsigned*)(lds + (bufoff) + ldsw + _i * 8192), 16, 0, 0); } while (0)
; #define PG8_LDA(dst, b, h) do { _Pragma("unroll") for (int m = 0; m < 4; ++m) _Pragma("unroll") for (int k = 0; k < 2; ++k) dst[m][k] = *(const PG8_LAS bf16x8*)(lds + PG8_SA(b, h) + aoff + m * 2048 + k * 1024); } while (0)
; #define PG8_LDB(dst, b, h) do { _Pragma("unroll") for (int n = 0; n < 2; ++n) _Pragma("unroll") for (int k = 0; k < 2; ++k) dst[n][k] = *(const PG8_LAS bf16x8*)(lds + PG8_SB(b, h) + boff + n * 2048 + k * 1024); } while (0)
; #define PG8_SCHED __builtin_amdgcn_sched_barrier(0)
; template <class Epi, class Sched, bool ALIGN_EPI = false, bool SP2 = false>
; __device__ __forceinline__ void gemm_phase(PG8_LAS unsigned char* lds, const Gemm g, const Sched& S, const Epi& E) {
;     ...
;             PG8_LDB(B0, 1, 0); PG8_LDB(B1, 1, 1); PG8_SCHED; PG8_LDA(At, 1, 0); PG8_STAGE(PG8_SA(0, 1), a2 + hstep, voffA);
	ds_read_b128 v[184:187], v151 offset:32768
	ds_read_b128 v[188:191], v151 offset:33792
	ds_read_b128 v[192:195], v151 offset:34816
	ds_read_b128 v[196:199], v151 offset:35840
	ds_read_b128 v[200:203], v151 offset:36864
	ds_read_b128 v[204:207], v151 offset:37888
	ds_read_b128 v[208:211], v151 offset:38912
	ds_read_b128 v[212:215], v151 offset:39936
	global_load_lds_dwordx4 v134, s[44:45]

; #define PG8_STAGE(bufoff, gbase, voff) do { _Pragma("unroll") for (int _i = 0; _i < 2; ++_i) \
;         __builtin_amdgcn_global_load_lds((const unsigned*)((const char*)(gbase) + (voff)[_i]), (PG8_LAS unsigned*)(lds + (bufoff) + ldsw + _i * 8192), 16, 0, 0); } while (0)
; #define PG8_LDA(dst, b, h) do { _Pragma("unroll") for (int m = 0; m < 4; ++m) _Pragma("unroll") for (int k = 0; k < 2; ++k) dst[m][k] = *(const PG8_LAS bf16x8*)(lds + PG8_SA(b, h) + aoff + m * 2048 + k * 1024); } while (0)
; #define PG8_LDB(dst, b, h) do { _Pragma("unroll") for (int n = 0; n < 2; ++n) _Pragma("unroll") for (int k = 0; k < 2; ++k) dst[n][k] = *(const PG8_LAS bf16x8*)(lds + PG8_SB(b, h) + boff + n * 2048 + k * 1024); } while (0)
; #define PG8_MMA(ai, bj, At, Bt) do { __builtin_amdgcn_s_setprio(1); _Pragma("unroll") for (int m = 0; m < 4; ++m) _Pragma("unroll") for (int n = 0; n < 2; ++n) _Pragma("unroll") for (int k = 0; k < 2; ++k) \
;         acc[ai][bj][m][n] = __builtin_amdgcn_mfma_f32_16x16x32_bf16(Bt[n][k], At[m][k], acc[ai][bj][m][n], 0, 0, 0); __builtin_amdgcn_s_setprio(0); } while (0)
; #define PG8_WAIT_V(n) asm volatile("s_waitcnt vmcnt(" #n ")" ::: "memory")
; #define PG8_WAIT_L(n) asm volatile("s_waitcnt lgkmcnt(" #n ")" ::: "memory")
; #define PG8_BAR __builtin_amdgcn_s_barrier()
; #define PG8_SCHED __builtin_amdgcn_sched_barrier(0)
; template <class Epi, class Sched, bool ALIGN_EPI = false, bool SP2 = false>
; __device__ __forceinline__ void gemm_phase(PG8_LAS unsigned char* lds, const Gemm g, const Sched& S, const Epi& E) {
;     ...
;             PG8_LDB(B0, 1, 0); PG8_LDB(B1, 1, 1); PG8_SCHED; PG8_LDA(At, 1, 0); PG8_STAGE(PG8_SA(0, 1), a2 + hstep, voffA);
;             PG8_WAIT_V(8); PG8_WAIT_L(0); PG8_BAR; PG8_MMA(0, 0, At, B0); PG8_MMA(0, 1, At, B1); PG8_BAR; PG8_SCHED;
	s_mov_b32 m0, s53
	s_nop 0
	global_load_lds_dwordx4 v130, s[44:45]
	s_waitcnt vmcnt(8) lgkmcnt(0)


; #define PG8_MMA(ai, bj, At, Bt) do { __builtin_amdgcn_s_setprio(1); _Pragma("unroll") for (int m = 0; m < 4; ++m) _Pragma("unroll") for (int n = 0; n < 2; ++n) _Pragma("unroll") for (int k = 0; k < 2; ++k) \
;         acc[ai][bj][m][n] = __builtin_amdgcn_mfma_f32_16x16x32_bf16(Bt[n][k], At[m][k], acc[ai][bj][m][n], 0, 0, 0); __builtin_amdgcn_s_setprio(0); } while (0)
; #define PG8_WAIT_V(n) asm volatile("s_waitcnt vmcnt(" #n ")" ::: "memory")
; #define PG8_WAIT_L(n) asm volatile("s_waitcnt lgkmcnt(" #n ")" ::: "memory")
; #define PG8_BAR __builtin_amdgcn_s_barrier()
; #define PG8_SCHED __builtin_amdgcn_sched_barrier(0)
; template <class Epi, class Sched, bool ALIGN_EPI = false, bool SP2 = false>
; __device__ __forceinline__ void gemm_phase(PG8_LAS unsigned char* lds, const Gemm g, const Sched& S, const Epi& E) {
;     ...
;             PG8_WAIT_V(8); PG8_WAIT_L(0); PG8_BAR; PG8_MMA(0, 0, At, B0); PG8_MMA(0, 1, At, B1); PG8_BAR; PG8_SCHED;
	s_barrier

; #define PG8_MMA(ai, bj, At, Bt) do { __builtin_amdgcn_s_setprio(1); _Pragma("unroll") for (int m = 0; m < 4; ++m) _Pragma("unroll") for (int n = 0; n < 2; ++n) _Pragma("unroll") for (int k = 0; k < 2; ++k) \
;         acc[ai][bj][m][n] = __builtin_amdgcn_mfma_f32_16x16x32_bf16(Bt[n][k], At[m][k], acc[ai][bj][m][n], 0, 0, 0); __builtin_amdgcn_s_setprio(0); } while (0)
; #define PG8_WAIT_V(n) asm volatile("s_waitcnt vmcnt(" #n ")" ::: "memory")
; #define PG8_WAIT_L(n) asm volatile("s_waitcnt lgkmcnt(" #n ")" ::: "memory")
; #define PG8_BAR __builtin_amdgcn_s_barrier()
; #define PG8_SCHED __builtin_amdgcn_sched_barrier(0)
; template <class Epi, class Sched, bool ALIGN_EPI = false, bool SP2 = false>
; __device__ __forceinline__ void gemm_phase(PG8_LAS unsigned char* lds, const Gemm g, const Sched& S, const Epi& E) {
;     ...
;             PG8_WAIT_V(8); PG8_WAIT_L(0); PG8_BAR; PG8_MMA(0, 0, At, B0); PG8_MMA(0, 1, At, B1); PG8_BAR; PG8_SCHED;
	v_mfma_f32_16x16x32_bf16 v[124:127], v[152:155], v[184:187], v[124:127]
	v_mfma_f32_16x16x32_bf16 v[120:123], v[160:163], v[184:187], v[120:123]
	v_mfma_f32_16x16x32_bf16 v[116:119], v[152:155], v[192:195], v[116:119]
	v_mfma_f32_16x16x32_bf16 v[112:115], v[160:163], v[192:195], v[112:115]
	v_mfma_f32_16x16x32_bf16 v[100:103], v[152:155], v[200:203], v[100:103]
	v_mfma_f32_16x16x32_bf16 v[96:99], v[160:163], v[200:203], v[96:99]
	v_mfma_f32_16x16x32_bf16 v[84:87], v[152:155], v[208:211], v[84:87]
	v_mfma_f32_16x16x32_bf16 v[80:83], v[160:163], v[208:211], v[80:83]
	v_mfma_f32_16x16x32_bf16 v[124:127], v[156:159], v[188:191], v[124:127]
	v_mfma_f32_16x16x32_bf16 v[120:123], v[164:167], v[188:191], v[120:123]
	v_mfma_f32_16x16x32_bf16 v[116:119], v[156:159], v[196:199], v[116:119]
	v_mfma_f32_16x16x32_bf16 v[112:115], v[164:167], v[196:199], v[112:115]
	v_mfma_f32_16x16x32_bf16 v[100:103], v[156:159], v[204:207], v[100:103]
	v_mfma_f32_16x16x32_bf16 v[96:99], v[164:167], v[204:207], v[96:99]
	v_mfma_f32_16x16x32_bf16 v[84:87], v[156:159], v[212:215], v[84:87]
	v_mfma_f32_16x16x32_bf16 v[80:83], v[164:167], v[212:215], v[80:83]


; #define PG8_MMA(ai, bj, At, Bt) do { __builtin_amdgcn_s_setprio(1); _Pragma("unroll") for (int m = 0; m < 4; ++m) _Pragma("unroll") for (int n = 0; n < 2; ++n) _Pragma("unroll") for (int k = 0; k < 2; ++k) \
;         acc[ai][bj][m][n] = __builtin_amdgcn_mfma_f32_16x16x32_bf16(Bt[n][k], At[m][k], acc[ai][bj][m][n], 0, 0, 0); __builtin_amdgcn_s_setprio(0); } while (0)
; #define PG8_WAIT_V(n) asm volatile("s_waitcnt vmcnt(" #n ")" ::: "memory")
; #define PG8_WAIT_L(n) asm volatile("s_waitcnt lgkmcnt(" #n ")" ::: "memory")
; #define PG8_BAR __builtin_amdgcn_s_barrier()
; #define PG8_SCHED __builtin_amdgcn_sched_barrier(0)
; template <class Epi, class Sched, bool ALIGN_EPI = false, bool SP2 = false>
; __device__ __forceinline__ void gemm_phase(PG8_LAS unsigned char* lds, const Gemm g, const Sched& S, const Epi& E) {
;     ...
;             PG8_WAIT_V(8); PG8_WAIT_L(0); PG8_BAR; PG8_MMA(0, 0, At, B0); PG8_MMA(0, 1, At, B1); PG8_BAR; PG8_SCHED;
	v_mfma_f32_16x16x32_bf16 v[108:111], v[168:171], v[184:187], v[108:111]
	v_mfma_f32_16x16x32_bf16 v[104:107], v[176:179], v[184:187], v[104:107]
	v_mfma_f32_16x16x32_bf16 v[92:95], v[168:171], v[192:195], v[92:95]
	v_mfma_f32_16x16x32_bf16 v[88:91], v[176:179], v[192:195], v[88:91]
	v_mfma_f32_16x16x32_bf16 v[76:79], v[168:171], v[200:203], v[76:79]
	v_mfma_f32_16x16x32_bf16 v[72:75], v[176:179], v[200:203], v[72:75]
	v_mfma_f32_16x16x32_bf16 v[68:71], v[168:171], v[208:211], v[68:71]
	v_mfma_f32_16x16x32_bf16 v[64:67], v[176:179], v[208:211], v[64:67]
	v_mfma_f32_16x16x32_bf16 v[108:111], v[172:175], v[188:191], v[108:111]
	v_mfma_f32_16x16x32_bf16 v[104:107], v[180:183], v[188:191], v[104:107]
	v_mfma_f32_16x16x32_bf16 v[92:95], v[172:175], v[196:199], v[92:95]
	v_mfma_f32_16x16x32_bf16 v[88:91], v[180:183], v[196:199], v[88:91]
	v_mfma_f32_16x16x32_bf16 v[76:79], v[172:175], v[204:207], v[76:79]
	v_mfma_f32_16x16x32_bf16 v[72:75], v[180:183], v[204:207], v[72:75]
	v_mfma_f32_16x16x32_bf16 v[68:71], v[172:175], v[212:215], v[68:71]
	v_mfma_f32_16x16x32_bf16 v[64:67], v[180:183], v[212:215], v[64:67]

; #define PG8_STAGE(bufoff, gbase, voff) do { _Pragma("unroll") for (int _i = 0; _i < 2; ++_i) \
;         __builtin_amdgcn_global_load_lds((const unsigned*)((const char*)(gbase) + (voff)[_i]), (PG8_LAS unsigned*)(lds + (bufoff) + ldsw + _i * 8192), 16, 0, 0); } while (0)
; #define PG8_LDA(dst, b, h) do { _Pragma("unroll") for (int m = 0; m < 4; ++m) _Pragma("unroll") for (int k = 0; k < 2; ++k) dst[m][k] = *(const PG8_LAS bf16x8*)(lds + PG8_SA(b, h) + aoff + m * 2048 + k * 1024); } while (0)
; #define PG8_MMA(ai, bj, At, Bt) do { __builtin_amdgcn_s_setprio(1); _Pragma("unroll") for (int m = 0; m < 4; ++m) _Pragma("unroll") for (int n = 0; n < 2; ++n) _Pragma("unroll") for (int k = 0; k < 2; ++k) \
;         acc[ai][bj][m][n] = __builtin_amdgcn_mfma_f32_16x16x32_bf16(Bt[n][k], At[m][k], acc[ai][bj][m][n], 0, 0, 0); __builtin_amdgcn_s_setprio(0); } while (0)
; #define PG8_WAIT_V(n) asm volatile("s_waitcnt vmcnt(" #n ")" ::: "memory")
; #define PG8_WAIT_L(n) asm volatile("s_waitcnt lgkmcnt(" #n ")" ::: "memory")
; #define PG8_BAR __builtin_amdgcn_s_barrier()
; #define PG8_SCHED __builtin_amdgcn_sched_barrier(0)
; template <class Epi, class Sched, bool ALIGN_EPI = false, bool SP2 = false>
; __device__ __forceinline__ void gemm_phase(PG8_LAS unsigned char* lds, const Gemm g, const Sched& S, const Epi& E) {
;     ...
;             PG8_WAIT_V(8); PG8_WAIT_L(0); PG8_BAR; PG8_MMA(0, 0, At, B0); PG8_MMA(0, 1, At, B1); PG8_BAR; PG8_SCHED;
;             PG8_LDA(At, 1, 1); PG8_STAGE(PG8_SB(1, 0), b3, voffB); PG8_STAGE(PG8_SB(1, 1), b3 + hstep, voffB); PG8_STAGE(PG8_SA(1, 0), a3, voffA);
	s_barrier
	s_add_i32 s44, s69, s48

; #define PG8_STAGE(bufoff, gbase, voff) do { _Pragma("unroll") for (int _i = 0; _i < 2; ++_i) \
;         __builtin_amdgcn_global_load_lds((const unsigned*)((const char*)(gbase) + (voff)[_i]), (PG8_LAS unsigned*)(lds + (bufoff) + ldsw + _i * 8192), 16, 0, 0); } while (0)
; #define PG8_LDA(dst, b, h) do { _Pragma("unroll") for (int m = 0; m < 4; ++m) _Pragma("unroll") for (int k = 0; k < 2; ++k) dst[m][k] = *(const PG8_LAS bf16x8*)(lds + PG8_SA(b, h) + aoff + m * 2048 + k * 1024); } while (0)
; template <class Epi, class Sched, bool ALIGN_EPI = false, bool SP2 = false>
; __device__ __forceinline__ void gemm_phase(PG8_LAS unsigned char* lds, const Gemm g, const Sched& S, const Epi& E) {
;     ...
;             PG8_LDA(At, 1, 1); PG8_STAGE(PG8_SB(1, 0), b3, voffB); PG8_STAGE(PG8_SB(1, 1), b3 + hstep, voffB); PG8_STAGE(PG8_SA(1, 0), a3, voffA);
	s_mov_b32 m0, s44
	ds_read_b128 v[184:187], v151 offset:49152
	ds_read_b128 v[188:191], v151 offset:50176
	ds_read_b128 v[192:195], v151 offset:51200
	ds_read_b128 v[196:199], v151 offset:52224
	ds_read_b128 v[200:203], v151 offset:53248
	ds_read_b128 v[204:207], v151 offset:54272
	ds_read_b128 v[208:211], v151 offset:55296
	ds_read_b128 v[212:215], v151 offset:56320
	global_load_lds_dwordx4 v250, s[96:97]
	s_add_i32 m0, s44, 0x2000
	s_add_u32 s42, s42, 0x80080

; #define PG8_STAGE(bufoff, gbase, voff) do { _Pragma("unroll") for (int _i = 0; _i < 2; ++_i) \
;         __builtin_amdgcn_global_load_lds((const unsigned*)((const char*)(gbase) + (voff)[_i]), (PG8_LAS unsigned*)(lds + (bufoff) + ldsw + _i * 8192), 16, 0, 0); } while (0)
; #define PG8_LDA(dst, b, h) do { _Pragma("unroll") for (int m = 0; m < 4; ++m) _Pragma("unroll") for (int k = 0; k < 2; ++k) dst[m][k] = *(const PG8_LAS bf16x8*)(lds + PG8_SA(b, h) + aoff + m * 2048 + k * 1024); } while (0)
; template <class Epi, class Sched, bool ALIGN_EPI = false, bool SP2 = false>
; __device__ __forceinline__ void gemm_phase(PG8_LAS unsigned char* lds, const Gemm g, const Sched& S, const Epi& E) {
;     ...
;             PG8_LDA(At, 1, 1); PG8_STAGE(PG8_SB(1, 0), b3, voffB); PG8_STAGE(PG8_SB(1, 1), b3 + hstep, voffB); PG8_STAGE(PG8_SA(1, 0), a3, voffA);
	s_addc_u32 s43, s43, 0
	s_add_i32 s44, s70, s48
	global_load_lds_dwordx4 v251, s[96:97]

; #define PG8_STAGE(bufoff, gbase, voff) do { _Pragma("unroll") for (int _i = 0; _i < 2; ++_i) \
;         __builtin_amdgcn_global_load_lds((const unsigned*)((const char*)(gbase) + (voff)[_i]), (PG8_LAS unsigned*)(lds + (bufoff) + ldsw + _i * 8192), 16, 0, 0); } while (0)
; #define PG8_LDA(dst, b, h) do { _Pragma("unroll") for (int m = 0; m < 4; ++m) _Pragma("unroll") for (int k = 0; k < 2; ++k) dst[m][k] = *(const PG8_LAS bf16x8*)(lds + PG8_SA(b, h) + aoff + m * 2048 + k * 1024); } while (0)
; template <class Epi, class Sched, bool ALIGN_EPI = false, bool SP2 = false>
; __device__ __forceinline__ void gemm_phase(PG8_LAS unsigned char* lds, const Gemm g, const Sched& S, const Epi& E) {
;     ...
;             PG8_LDA(At, 1, 1); PG8_STAGE(PG8_SB(1, 0), b3, voffB); PG8_STAGE(PG8_SB(1, 1), b3 + hstep, voffB); PG8_STAGE(PG8_SA(1, 0), a3, voffA);
	s_mov_b32 m0, s44
	s_nop 0
	global_load_lds_dwordx4 v132, s[42:43]

; #define PG8_STAGE(bufoff, gbase, voff) do { _Pragma("unroll") for (int _i = 0; _i < 2; ++_i) \
;         __builtin_amdgcn_global_load_lds((const unsigned*)((const char*)(gbase) + (voff)[_i]), (PG8_LAS unsigned*)(lds + (bufoff) + ldsw + _i * 8192), 16, 0, 0); } while (0)
; #define PG8_LDA(dst, b, h) do { _Pragma("unroll") for (int m = 0; m < 4; ++m) _Pragma("unroll") for (int k = 0; k < 2; ++k) dst[m][k] = *(const PG8_LAS bf16x8*)(lds + PG8_SA(b, h) + aoff + m * 2048 + k * 1024); } while (0)
; template <class Epi, class Sched, bool ALIGN_EPI = false, bool SP2 = false>
; __device__ __forceinline__ void gemm_phase(PG8_LAS unsigned char* lds, const Gemm g, const Sched& S, const Epi& E) {
;     ...
;             PG8_LDA(At, 1, 1); PG8_STAGE(PG8_SB(1, 0), b3, voffB); PG8_STAGE(PG8_SB(1, 1), b3 + hstep, voffB); PG8_STAGE(PG8_SA(1, 0), a3, voffA);
	s_add_i32 m0, s44, 0x2000
	s_nop 0
	global_load_lds_dwordx4 v128, s[42:43]

; #define PG8_STAGE(bufoff, gbase, voff) do { _Pragma("unroll") for (int _i = 0; _i < 2; ++_i) \
;         __builtin_amdgcn_global_load_lds((const unsigned*)((const char*)(gbase) + (voff)[_i]), (PG8_LAS unsigned*)(lds + (bufoff) + ldsw + _i * 8192), 16, 0, 0); } while (0)
; #define PG8_LDA(dst, b, h) do { _Pragma("unroll") for (int m = 0; m < 4; ++m) _Pragma("unroll") for (int k = 0; k < 2; ++k) dst[m][k] = *(const PG8_LAS bf16x8*)(lds + PG8_SA(b, h) + aoff + m * 2048 + k * 1024); } while (0)
; template <class Epi, class Sched, bool ALIGN_EPI = false, bool SP2 = false>
; __device__ __forceinline__ void gemm_phase(PG8_LAS unsigned char* lds, const Gemm g, const Sched& S, const Epi& E) {
;     ...
;             PG8_LDA(At, 1, 1); PG8_STAGE(PG8_SB(1, 0), b3, voffB); PG8_STAGE(PG8_SB(1, 1), b3 + hstep, voffB); PG8_STAGE(PG8_SA(1, 0), a3, voffA);
	s_mov_b32 m0, s55
	s_nop 0
	global_load_lds_dwordx4 v252, s[98:99]

; #define PG8_STAGE(bufoff, gbase, voff) do { _Pragma("unroll") for (int _i = 0; _i < 2; ++_i) \
;         __builtin_amdgcn_global_load_lds((const unsigned*)((const char*)(gbase) + (voff)[_i]), (PG8_LAS unsigned*)(lds + (bufoff) + ldsw + _i * 8192), 16, 0, 0); } while (0)
; #define PG8_LDA(dst, b, h) do { _Pragma("unroll") for (int m = 0; m < 4; ++m) _Pragma("unroll") for (int k = 0; k < 2; ++k) dst[m][k] = *(const PG8_LAS bf16x8*)(lds + PG8_SA(b, h) + aoff + m * 2048 + k * 1024); } while (0)
; #define PG8_MMA(ai, bj, At, Bt) do { __builtin_amdgcn_s_setprio(1); _Pragma("unroll") for (int m = 0; m < 4; ++m) _Pragma("unroll") for (int n = 0; n < 2; ++n) _Pragma("unroll") for (int k = 0; k < 2; ++k) \
;         acc[ai][bj][m][n] = __builtin_amdgcn_mfma_f32_16x16x32_bf16(Bt[n][k], At[m][k], acc[ai][bj][m][n], 0, 0, 0); __builtin_amdgcn_s_setprio(0); } while (0)
; #define PG8_WAIT_V(n) asm volatile("s_waitcnt vmcnt(" #n ")" ::: "memory")
; #define PG8_WAIT_L(n) asm volatile("s_waitcnt lgkmcnt(" #n ")" ::: "memory")
; #define PG8_BAR __builtin_amdgcn_s_barrier()
; #define PG8_SCHED __builtin_amdgcn_sched_barrier(0)
; template <class Epi, class Sched, bool ALIGN_EPI = false, bool SP2 = false>
; __device__ __forceinline__ void gemm_phase(PG8_LAS unsigned char* lds, const Gemm g, const Sched& S, const Epi& E) {
;     ...
;             PG8_LDA(At, 1, 1); PG8_STAGE(PG8_SB(1, 0), b3, voffB); PG8_STAGE(PG8_SB(1, 1), b3 + hstep, voffB); PG8_STAGE(PG8_SA(1, 0), a3, voffA);
;             PG8_WAIT_V(8); PG8_WAIT_L(0); PG8_BAR; PG8_MMA(1, 0, At, B0); PG8_MMA(1, 1, At, B1); PG8_BAR; PG8_SCHED;
	s_mov_b32 m0, s56
	s_nop 0
	global_load_lds_dwordx4 v253, s[98:99]
	s_waitcnt vmcnt(8) lgkmcnt(0)


; #define PG8_MMA(ai, bj, At, Bt) do { __builtin_amdgcn_s_setprio(1); _Pragma("unroll") for (int m = 0; m < 4; ++m) _Pragma("unroll") for (int n = 0; n < 2; ++n) _Pragma("unroll") for (int k = 0; k < 2; ++k) \
;         acc[ai][bj][m][n] = __builtin_amdgcn_mfma_f32_16x16x32_bf16(Bt[n][k], At[m][k], acc[ai][bj][m][n], 0, 0, 0); __builtin_amdgcn_s_setprio(0); } while (0)
; #define PG8_WAIT_V(n) asm volatile("s_waitcnt vmcnt(" #n ")" ::: "memory")
; #define PG8_WAIT_L(n) asm volatile("s_waitcnt lgkmcnt(" #n ")" ::: "memory")
; #define PG8_BAR __builtin_amdgcn_s_barrier()
; #define PG8_SCHED __builtin_amdgcn_sched_barrier(0)
; template <class Epi, class Sched, bool ALIGN_EPI = false, bool SP2 = false>
; __device__ __forceinline__ void gemm_phase(PG8_LAS unsigned char* lds, const Gemm g, const Sched& S, const Epi& E) {
;     ...
;             PG8_WAIT_V(8); PG8_WAIT_L(0); PG8_BAR; PG8_MMA(1, 0, At, B0); PG8_MMA(1, 1, At, B1); PG8_BAR; PG8_SCHED;
	s_barrier

; #define PG8_MMA(ai, bj, At, Bt) do { __builtin_amdgcn_s_setprio(1); _Pragma("unroll") for (int m = 0; m < 4; ++m) _Pragma("unroll") for (int n = 0; n < 2; ++n) _Pragma("unroll") for (int k = 0; k < 2; ++k) \
;         acc[ai][bj][m][n] = __builtin_amdgcn_mfma_f32_16x16x32_bf16(Bt[n][k], At[m][k], acc[ai][bj][m][n], 0, 0, 0); __builtin_amdgcn_s_setprio(0); } while (0)
; #define PG8_WAIT_V(n) asm volatile("s_waitcnt vmcnt(" #n ")" ::: "memory")
; #define PG8_WAIT_L(n) asm volatile("s_waitcnt lgkmcnt(" #n ")" ::: "memory")
; #define PG8_BAR __builtin_amdgcn_s_barrier()
; #define PG8_SCHED __builtin_amdgcn_sched_barrier(0)
; template <class Epi, class Sched, bool ALIGN_EPI = false, bool SP2 = false>
; __device__ __forceinline__ void gemm_phase(PG8_LAS unsigned char* lds, const Gemm g, const Sched& S, const Epi& E) {
;     ...
;             PG8_WAIT_V(8); PG8_WAIT_L(0); PG8_BAR; PG8_MMA(1, 0, At, B0); PG8_MMA(1, 1, At, B1); PG8_BAR; PG8_SCHED;
	v_mfma_f32_16x16x32_bf16 v[60:63], v[152:155], v[184:187], v[60:63]
	v_mfma_f32_16x16x32_bf16 v[56:59], v[160:163], v[184:187], v[56:59]
	v_mfma_f32_16x16x32_bf16 v[52:55], v[152:155], v[192:195], v[52:55]
	v_mfma_f32_16x16x32_bf16 v[48:51], v[160:163], v[192:195], v[48:51]
	v_mfma_f32_16x16x32_bf16 v[36:39], v[152:155], v[200:203], v[36:39]
	v_mfma_f32_16x16x32_bf16 v[32:35], v[160:163], v[200:203], v[32:35]
	v_mfma_f32_16x16x32_bf16 v[20:23], v[152:155], v[208:211], v[20:23]
	v_mfma_f32_16x16x32_bf16 v[16:19], v[160:163], v[208:211], v[16:19]
	v_mfma_f32_16x16x32_bf16 v[60:63], v[156:159], v[188:191], v[60:63]
	v_mfma_f32_16x16x32_bf16 v[56:59], v[164:167], v[188:191], v[56:59]
	v_mfma_f32_16x16x32_bf16 v[52:55], v[156:159], v[196:199], v[52:55]
	v_mfma_f32_16x16x32_bf16 v[48:51], v[164:167], v[196:199], v[48:51]
	v_mfma_f32_16x16x32_bf16 v[36:39], v[156:159], v[204:207], v[36:39]
	v_mfma_f32_16x16x32_bf16 v[32:35], v[164:167], v[204:207], v[32:35]
	v_mfma_f32_16x16x32_bf16 v[20:23], v[156:159], v[212:215], v[20:23]
	v_mfma_f32_16x16x32_bf16 v[16:19], v[164:167], v[212:215], v[16:19]


; #define PG8_MMA(ai, bj, At, Bt) do { __builtin_amdgcn_s_setprio(1); _Pragma("unroll") for (int m = 0; m < 4; ++m) _Pragma("unroll") for (int n = 0; n < 2; ++n) _Pragma("unroll") for (int k = 0; k < 2; ++k) \
;         acc[ai][bj][m][n] = __builtin_amdgcn_mfma_f32_16x16x32_bf16(Bt[n][k], At[m][k], acc[ai][bj][m][n], 0, 0, 0); __builtin_amdgcn_s_setprio(0); } while (0)
; #define PG8_WAIT_V(n) asm volatile("s_waitcnt vmcnt(" #n ")" ::: "memory")
; #define PG8_WAIT_L(n) asm volatile("s_waitcnt lgkmcnt(" #n ")" ::: "memory")
; #define PG8_BAR __builtin_amdgcn_s_barrier()
; #define PG8_SCHED __builtin_amdgcn_sched_barrier(0)
; template <class Epi, class Sched, bool ALIGN_EPI = false, bool SP2 = false>
; __device__ __forceinline__ void gemm_phase(PG8_LAS unsigned char* lds, const Gemm g, const Sched& S, const Epi& E) {
;     ...
;             PG8_WAIT_V(8); PG8_WAIT_L(0); PG8_BAR; PG8_MMA(1, 0, At, B0); PG8_MMA(1, 1, At, B1); PG8_BAR; PG8_SCHED;
	v_mfma_f32_16x16x32_bf16 v[44:47], v[168:171], v[184:187], v[44:47]
	v_mfma_f32_16x16x32_bf16 v[40:43], v[176:179], v[184:187], v[40:43]
	v_mfma_f32_16x16x32_bf16 v[28:31], v[168:171], v[192:195], v[28:31]
	v_mfma_f32_16x16x32_bf16 v[24:27], v[176:179], v[192:195], v[24:27]
	v_mfma_f32_16x16x32_bf16 v[12:15], v[168:171], v[200:203], v[12:15]
	v_mfma_f32_16x16x32_bf16 v[8:11], v[176:179], v[200:203], v[8:11]
	v_mfma_f32_16x16x32_bf16 v[4:7], v[168:171], v[208:211], v[4:7]
	v_mfma_f32_16x16x32_bf16 v[0:3], v[176:179], v[208:211], v[0:3]
	v_mfma_f32_16x16x32_bf16 v[44:47], v[172:175], v[188:191], v[44:47]
	v_mfma_f32_16x16x32_bf16 v[40:43], v[180:183], v[188:191], v[40:43]
	v_mfma_f32_16x16x32_bf16 v[28:31], v[172:175], v[196:199], v[28:31]
	v_mfma_f32_16x16x32_bf16 v[24:27], v[180:183], v[196:199], v[24:27]
	v_mfma_f32_16x16x32_bf16 v[12:15], v[172:175], v[204:207], v[12:15]
	v_mfma_f32_16x16x32_bf16 v[8:11], v[180:183], v[204:207], v[8:11]
	v_mfma_f32_16x16x32_bf16 v[4:7], v[172:175], v[212:215], v[4:7]
	v_mfma_f32_16x16x32_bf16 v[0:3], v[180:183], v[212:215], v[0:3]

; #define PG8_MMA(ai, bj, At, Bt) do { __builtin_amdgcn_s_setprio(1); _Pragma("unroll") for (int m = 0; m < 4; ++m) _Pragma("unroll") for (int n = 0; n < 2; ++n) _Pragma("unroll") for (int k = 0; k < 2; ++k) \
;         acc[ai][bj][m][n] = __builtin_amdgcn_mfma_f32_16x16x32_bf16(Bt[n][k], At[m][k], acc[ai][bj][m][n], 0, 0, 0); __builtin_amdgcn_s_setprio(0); } while (0)
; #define PG8_WAIT_V(n) asm volatile("s_waitcnt vmcnt(" #n ")" ::: "memory")
; #define PG8_WAIT_L(n) asm volatile("s_waitcnt lgkmcnt(" #n ")" ::: "memory")
; #define PG8_BAR __builtin_amdgcn_s_barrier()
; #define PG8_SCHED __builtin_amdgcn_sched_barrier(0)
; template <class Epi, class Sched, bool ALIGN_EPI = false, bool SP2 = false>
; __device__ __forceinline__ void gemm_phase(PG8_LAS unsigned char* lds, const Gemm g, const Sched& S, const Epi& E) {
;     ...
;             PG8_WAIT_V(8); PG8_WAIT_L(0); PG8_BAR; PG8_MMA(1, 0, At, B0); PG8_MMA(1, 1, At, B1); PG8_BAR; PG8_SCHED;
;     ...
;         if constexpr (ALIGN_EPI) { if (wr == 0) PG8_BAR; }
	s_barrier
	s_add_i32 s68, s68, 2
	s_add_u32 s40, s40, 0x100
	s_addc_u32 s41, s41, 0
	s_add_u32 s65, s65, 0x100
	s_addc_u32 s67, s67, 0
	s_cmp_gt_u32 s68, 29
	s_cbranch_scc0 .LBB0_66
	s_and_b64 vcc, exec, s[26:27]
	s_cbranch_vccz .LBB0_69
	s_barrier

; #define PG8_STAGE(bufoff, gbase, voff) do { _Pragma("unroll") for (int _i = 0; _i < 2; ++_i) \
;         __builtin_amdgcn_global_load_lds((const unsigned*)((const char*)(gbase) + (voff)[_i]), (PG8_LAS unsigned*)(lds + (bufoff) + ldsw + _i * 8192), 16, 0, 0); } while (0)
; #define PG8_LDA(dst, b, h) do { _Pragma("unroll") for (int m = 0; m < 4; ++m) _Pragma("unroll") for (int k = 0; k < 2; ++k) dst[m][k] = *(const PG8_LAS bf16x8*)(lds + PG8_SA(b, h) + aoff + m * 2048 + k * 1024); } while (0)
; #define PG8_LDB(dst, b, h) do { _Pragma("unroll") for (int n = 0; n < 2; ++n) _Pragma("unroll") for (int k = 0; k < 2; ++k) dst[n][k] = *(const PG8_LAS bf16x8*)(lds + PG8_SB(b, h) + boff + n * 2048 + k * 1024); } while (0)
; #define PG8_SCHED __builtin_amdgcn_sched_barrier(0)
; template <class Epi, class Sched, bool ALIGN_EPI = false, bool SP2 = false>
; __device__ __forceinline__ void gemm_phase(PG8_LAS unsigned char* lds, const Gemm g, const Sched& S, const Epi& E) {
;     ...
;             const char* a2 = last ? nA : cA + (size_t)(t + 2) * kstep; const char* b2 = last ? nB : cB + (size_t)(t + 2) * kstep;
;     ...
;             PG8_LDB(B0, 0, 0); PG8_LDB(B1, 0, 1); PG8_SCHED; PG8_LDA(At, 0, 0); PG8_STAGE(PG8_SA(1, 1), a1 + hstep, voffA);
.LBB0_333:
	ds_read_b128 v[64:67], v211
	ds_read_b128 v[68:71], v211 offset:1024
	ds_read_b128 v[72:75], v211 offset:2048
	ds_read_b128 v[76:79], v211 offset:3072
	ds_read_b128 v[144:147], v212
	ds_read_b128 v[148:151], v212 offset:1024
	ds_read_b128 v[152:155], v212 offset:2048
	ds_read_b128 v[156:159], v212 offset:3072
	s_add_u32 s60, s58, 0xfff80080
	s_addc_u32 s61, s59, -1
	s_cmp_eq_u32 s81, 28
	s_cselect_b32 s63, s11, s61
	s_cselect_b32 s62, s51, s60
	s_cselect_b32 s61, s49, s80
	s_cselect_b32 s60, s78, s79

; #define PG8_STAGE(bufoff, gbase, voff) do { _Pragma("unroll") for (int _i = 0; _i < 2; ++_i) \
;         __builtin_amdgcn_global_load_lds((const unsigned*)((const char*)(gbase) + (voff)[_i]), (PG8_LAS unsigned*)(lds + (bufoff) + ldsw + _i * 8192), 16, 0, 0); } while (0)
; #define PG8_LDA(dst, b, h) do { _Pragma("unroll") for (int m = 0; m < 4; ++m) _Pragma("unroll") for (int k = 0; k < 2; ++k) dst[m][k] = *(const PG8_LAS bf16x8*)(lds + PG8_SA(b, h) + aoff + m * 2048 + k * 1024); } while (0)
; #define PG8_LDB(dst, b, h) do { _Pragma("unroll") for (int n = 0; n < 2; ++n) _Pragma("unroll") for (int k = 0; k < 2; ++k) dst[n][k] = *(const PG8_LAS bf16x8*)(lds + PG8_SB(b, h) + boff + n * 2048 + k * 1024); } while (0)
; #define PG8_SCHED __builtin_amdgcn_sched_barrier(0)
; template <class Epi, class Sched, bool ALIGN_EPI = false, bool SP2 = false>
; __device__ __forceinline__ void gemm_phase(PG8_LAS unsigned char* lds, const Gemm g, const Sched& S, const Epi& E) {
;     ...
;             PG8_LDB(B0, 0, 0); PG8_LDB(B1, 0, 1); PG8_SCHED; PG8_LDA(At, 0, 0); PG8_STAGE(PG8_SA(1, 1), a1 + hstep, voffA);
	s_add_i32 m0, s57, 0xc000
	ds_read_b128 v[176:179], v213
	ds_read_b128 v[180:183], v213 offset:1024
	ds_read_b128 v[184:187], v213 offset:2048
	ds_read_b128 v[188:191], v213 offset:3072
	ds_read_b128 v[192:195], v213 offset:4096
	ds_read_b128 v[196:199], v213 offset:5120
	ds_read_b128 v[200:203], v213 offset:6144
	ds_read_b128 v[204:207], v213 offset:7168
	global_load_lds_dwordx4 v168, s[58:59]

; #define PG8_STAGE(bufoff, gbase, voff) do { _Pragma("unroll") for (int _i = 0; _i < 2; ++_i) \
;         __builtin_amdgcn_global_load_lds((const unsigned*)((const char*)(gbase) + (voff)[_i]), (PG8_LAS unsigned*)(lds + (bufoff) + ldsw + _i * 8192), 16, 0, 0); } while (0)
; #define PG8_LDA(dst, b, h) do { _Pragma("unroll") for (int m = 0; m < 4; ++m) _Pragma("unroll") for (int k = 0; k < 2; ++k) dst[m][k] = *(const PG8_LAS bf16x8*)(lds + PG8_SA(b, h) + aoff + m * 2048 + k * 1024); } while (0)
; #define PG8_LDB(dst, b, h) do { _Pragma("unroll") for (int n = 0; n < 2; ++n) _Pragma("unroll") for (int k = 0; k < 2; ++k) dst[n][k] = *(const PG8_LAS bf16x8*)(lds + PG8_SB(b, h) + boff + n * 2048 + k * 1024); } while (0)
; #define PG8_MMA(ai, bj, At, Bt) do { __builtin_amdgcn_s_setprio(1); _Pragma("unroll") for (int m = 0; m < 4; ++m) _Pragma("unroll") for (int n = 0; n < 2; ++n) _Pragma("unroll") for (int k = 0; k < 2; ++k) \
;         acc[ai][bj][m][n] = __builtin_amdgcn_mfma_f32_16x16x32_bf16(Bt[n][k], At[m][k], acc[ai][bj][m][n], 0, 0, 0); __builtin_amdgcn_s_setprio(0); } while (0)
; #define PG8_WAIT_V(n) asm volatile("s_waitcnt vmcnt(" #n ")" ::: "memory")
; #define PG8_WAIT_L(n) asm volatile("s_waitcnt lgkmcnt(" #n ")" ::: "memory")
; #define PG8_BAR __builtin_amdgcn_s_barrier()
; #define PG8_SCHED __builtin_amdgcn_sched_barrier(0)
; template <class Epi, class Sched, bool ALIGN_EPI = false, bool SP2 = false>
; __device__ __forceinline__ void gemm_phase(PG8_LAS unsigned char* lds, const Gemm g, const Sched& S, const Epi& E) {
;     ...
;             PG8_LDB(B0, 0, 0); PG8_LDB(B1, 0, 1); PG8_SCHED; PG8_LDA(At, 0, 0); PG8_STAGE(PG8_SA(1, 1), a1 + hstep, voffA);
;             PG8_WAIT_V(8); PG8_WAIT_L(0); PG8_BAR; PG8_MMA(0, 0, At, B0); PG8_MMA(0, 1, At, B1); PG8_BAR; PG8_SCHED;
	s_add_i32 m0, s57, 0xe000
	s_nop 0
	global_load_lds_dwordx4 v170, s[58:59]
	s_waitcnt vmcnt(8) lgkmcnt(0)


; #define PG8_MMA(ai, bj, At, Bt) do { __builtin_amdgcn_s_setprio(1); _Pragma("unroll") for (int m = 0; m < 4; ++m) _Pragma("unroll") for (int n = 0; n < 2; ++n) _Pragma("unroll") for (int k = 0; k < 2; ++k) \
;         acc[ai][bj][m][n] = __builtin_amdgcn_mfma_f32_16x16x32_bf16(Bt[n][k], At[m][k], acc[ai][bj][m][n], 0, 0, 0); __builtin_amdgcn_s_setprio(0); } while (0)
; #define PG8_WAIT_V(n) asm volatile("s_waitcnt vmcnt(" #n ")" ::: "memory")
; #define PG8_WAIT_L(n) asm volatile("s_waitcnt lgkmcnt(" #n ")" ::: "memory")
; #define PG8_BAR __builtin_amdgcn_s_barrier()
; #define PG8_SCHED __builtin_amdgcn_sched_barrier(0)
; template <class Epi, class Sched, bool ALIGN_EPI = false, bool SP2 = false>
; __device__ __forceinline__ void gemm_phase(PG8_LAS unsigned char* lds, const Gemm g, const Sched& S, const Epi& E) {
;     ...
;             PG8_WAIT_V(8); PG8_WAIT_L(0); PG8_BAR; PG8_MMA(0, 0, At, B0); PG8_MMA(0, 1, At, B1); PG8_BAR; PG8_SCHED;
	s_barrier

; #define PG8_MMA(ai, bj, At, Bt) do { __builtin_amdgcn_s_setprio(1); _Pragma("unroll") for (int m = 0; m < 4; ++m) _Pragma("unroll") for (int n = 0; n < 2; ++n) _Pragma("unroll") for (int k = 0; k < 2; ++k) \
;         acc[ai][bj][m][n] = __builtin_amdgcn_mfma_f32_16x16x32_bf16(Bt[n][k], At[m][k], acc[ai][bj][m][n], 0, 0, 0); __builtin_amdgcn_s_setprio(0); } while (0)
; #define PG8_WAIT_V(n) asm volatile("s_waitcnt vmcnt(" #n ")" ::: "memory")
; #define PG8_WAIT_L(n) asm volatile("s_waitcnt lgkmcnt(" #n ")" ::: "memory")
; #define PG8_BAR __builtin_amdgcn_s_barrier()
; #define PG8_SCHED __builtin_amdgcn_sched_barrier(0)
; template <class Epi, class Sched, bool ALIGN_EPI = false, bool SP2 = false>
; __device__ __forceinline__ void gemm_phase(PG8_LAS unsigned char* lds, const Gemm g, const Sched& S, const Epi& E) {
;     ...
;             PG8_WAIT_V(8); PG8_WAIT_L(0); PG8_BAR; PG8_MMA(0, 0, At, B0); PG8_MMA(0, 1, At, B1); PG8_BAR; PG8_SCHED;
	v_mfma_f32_16x16x32_bf16 v[140:143], v[64:67], v[176:179], v[140:143]
	v_mfma_f32_16x16x32_bf16 v[136:139], v[72:75], v[176:179], v[136:139]
	v_mfma_f32_16x16x32_bf16 v[124:127], v[64:67], v[184:187], v[124:127]
	v_mfma_f32_16x16x32_bf16 v[120:123], v[72:75], v[184:187], v[120:123]
	v_mfma_f32_16x16x32_bf16 v[108:111], v[64:67], v[192:195], v[108:111]
	v_mfma_f32_16x16x32_bf16 v[104:107], v[72:75], v[192:195], v[104:107]
	v_mfma_f32_16x16x32_bf16 v[92:95], v[64:67], v[200:203], v[92:95]
	v_mfma_f32_16x16x32_bf16 v[88:91], v[72:75], v[200:203], v[88:91]
	v_mfma_f32_16x16x32_bf16 v[140:143], v[68:71], v[180:183], v[140:143]
	v_mfma_f32_16x16x32_bf16 v[136:139], v[76:79], v[180:183], v[136:139]
	v_mfma_f32_16x16x32_bf16 v[124:127], v[68:71], v[188:191], v[124:127]
	v_mfma_f32_16x16x32_bf16 v[120:123], v[76:79], v[188:191], v[120:123]
	v_mfma_f32_16x16x32_bf16 v[108:111], v[68:71], v[196:199], v[108:111]
	v_mfma_f32_16x16x32_bf16 v[104:107], v[76:79], v[196:199], v[104:107]
	v_mfma_f32_16x16x32_bf16 v[92:95], v[68:71], v[204:207], v[92:95]
	v_mfma_f32_16x16x32_bf16 v[88:91], v[76:79], v[204:207], v[88:91]


; #define PG8_MMA(ai, bj, At, Bt) do { __builtin_amdgcn_s_setprio(1); _Pragma("unroll") for (int m = 0; m < 4; ++m) _Pragma("unroll") for (int n = 0; n < 2; ++n) _Pragma("unroll") for (int k = 0; k < 2; ++k) \
;         acc[ai][bj][m][n] = __builtin_amdgcn_mfma_f32_16x16x32_bf16(Bt[n][k], At[m][k], acc[ai][bj][m][n], 0, 0, 0); __builtin_amdgcn_s_setprio(0); } while (0)
; #define PG8_WAIT_V(n) asm volatile("s_waitcnt vmcnt(" #n ")" ::: "memory")
; #define PG8_WAIT_L(n) asm volatile("s_waitcnt lgkmcnt(" #n ")" ::: "memory")
; #define PG8_BAR __builtin_amdgcn_s_barrier()
; #define PG8_SCHED __builtin_amdgcn_sched_barrier(0)
; template <class Epi, class Sched, bool ALIGN_EPI = false, bool SP2 = false>
; __device__ __forceinline__ void gemm_phase(PG8_LAS unsigned char* lds, const Gemm g, const Sched& S, const Epi& E) {
;     ...
;             PG8_WAIT_V(8); PG8_WAIT_L(0); PG8_BAR; PG8_MMA(0, 0, At, B0); PG8_MMA(0, 1, At, B1); PG8_BAR; PG8_SCHED;
	v_mfma_f32_16x16x32_bf16 v[132:135], v[144:147], v[176:179], v[132:135]
	v_mfma_f32_16x16x32_bf16 v[128:131], v[152:155], v[176:179], v[128:131]
	v_mfma_f32_16x16x32_bf16 v[116:119], v[144:147], v[184:187], v[116:119]
	v_mfma_f32_16x16x32_bf16 v[112:115], v[152:155], v[184:187], v[112:115]
	v_mfma_f32_16x16x32_bf16 v[100:103], v[144:147], v[192:195], v[100:103]
	v_mfma_f32_16x16x32_bf16 v[96:99], v[152:155], v[192:195], v[96:99]
	v_mfma_f32_16x16x32_bf16 v[84:87], v[144:147], v[200:203], v[84:87]
	v_mfma_f32_16x16x32_bf16 v[80:83], v[152:155], v[200:203], v[80:83]
	v_mfma_f32_16x16x32_bf16 v[132:135], v[148:151], v[180:183], v[132:135]
	v_mfma_f32_16x16x32_bf16 v[128:131], v[156:159], v[180:183], v[128:131]
	v_mfma_f32_16x16x32_bf16 v[116:119], v[148:151], v[188:191], v[116:119]
	v_mfma_f32_16x16x32_bf16 v[112:115], v[156:159], v[188:191], v[112:115]
	v_mfma_f32_16x16x32_bf16 v[100:103], v[148:151], v[196:199], v[100:103]
	v_mfma_f32_16x16x32_bf16 v[96:99], v[156:159], v[196:199], v[96:99]
	v_mfma_f32_16x16x32_bf16 v[84:87], v[148:151], v[204:207], v[84:87]
	v_mfma_f32_16x16x32_bf16 v[80:83], v[156:159], v[204:207], v[80:83]

; #define PG8_STAGE(bufoff, gbase, voff) do { _Pragma("unroll") for (int _i = 0; _i < 2; ++_i) \
;         __builtin_amdgcn_global_load_lds((const unsigned*)((const char*)(gbase) + (voff)[_i]), (PG8_LAS unsigned*)(lds + (bufoff) + ldsw + _i * 8192), 16, 0, 0); } while (0)
; #define PG8_LDA(dst, b, h) do { _Pragma("unroll") for (int m = 0; m < 4; ++m) _Pragma("unroll") for (int k = 0; k < 2; ++k) dst[m][k] = *(const PG8_LAS bf16x8*)(lds + PG8_SA(b, h) + aoff + m * 2048 + k * 1024); } while (0)
; #define PG8_MMA(ai, bj, At, Bt) do { __builtin_amdgcn_s_setprio(1); _Pragma("unroll") for (int m = 0; m < 4; ++m) _Pragma("unroll") for (int n = 0; n < 2; ++n) _Pragma("unroll") for (int k = 0; k < 2; ++k) \
;         acc[ai][bj][m][n] = __builtin_amdgcn_mfma_f32_16x16x32_bf16(Bt[n][k], At[m][k], acc[ai][bj][m][n], 0, 0, 0); __builtin_amdgcn_s_setprio(0); } while (0)
; #define PG8_WAIT_V(n) asm volatile("s_waitcnt vmcnt(" #n ")" ::: "memory")
; #define PG8_WAIT_L(n) asm volatile("s_waitcnt lgkmcnt(" #n ")" ::: "memory")
; #define PG8_BAR __builtin_amdgcn_s_barrier()
; #define PG8_SCHED __builtin_amdgcn_sched_barrier(0)
; template <class Epi, class Sched, bool ALIGN_EPI = false, bool SP2 = false>
; __device__ __forceinline__ void gemm_phase(PG8_LAS unsigned char* lds, const Gemm g, const Sched& S, const Epi& E) {
;     ...
;             PG8_WAIT_V(8); PG8_WAIT_L(0); PG8_BAR; PG8_MMA(0, 0, At, B0); PG8_MMA(0, 1, At, B1); PG8_BAR; PG8_SCHED;
;             PG8_LDA(At, 0, 1); PG8_STAGE(PG8_SB(0, 0), b2, voffB); PG8_STAGE(PG8_SB(0, 1), b2 + hstep, voffB); PG8_STAGE(PG8_SA(0, 0), a2, voffA);
	s_barrier
	s_add_i32 s82, s75, s64
	s_mov_b64 s[96:97], s[60:61]

; #define PG8_STAGE(bufoff, gbase, voff) do { _Pragma("unroll") for (int _i = 0; _i < 2; ++_i) \
;         __builtin_amdgcn_global_load_lds((const unsigned*)((const char*)(gbase) + (voff)[_i]), (PG8_LAS unsigned*)(lds + (bufoff) + ldsw + _i * 8192), 16, 0, 0); } while (0)
; #define PG8_LDA(dst, b, h) do { _Pragma("unroll") for (int m = 0; m < 4; ++m) _Pragma("unroll") for (int k = 0; k < 2; ++k) dst[m][k] = *(const PG8_LAS bf16x8*)(lds + PG8_SA(b, h) + aoff + m * 2048 + k * 1024); } while (0)
; template <class Epi, class Sched, bool ALIGN_EPI = false, bool SP2 = false>
; __device__ __forceinline__ void gemm_phase(PG8_LAS unsigned char* lds, const Gemm g, const Sched& S, const Epi& E) {
;     ...
;             PG8_LDA(At, 0, 1); PG8_STAGE(PG8_SB(0, 0), b2, voffB); PG8_STAGE(PG8_SB(0, 1), b2 + hstep, voffB); PG8_STAGE(PG8_SA(0, 0), a2, voffA);
	s_mov_b32 m0, s82
	ds_read_b128 v[176:179], v213 offset:16384
	ds_read_b128 v[180:183], v213 offset:17408
	ds_read_b128 v[184:187], v213 offset:18432
	ds_read_b128 v[188:191], v213 offset:19456
	ds_read_b128 v[192:195], v213 offset:20480
	ds_read_b128 v[196:199], v213 offset:21504
	ds_read_b128 v[200:203], v213 offset:22528
	ds_read_b128 v[204:207], v213 offset:23552
	global_load_lds_dwordx4 v162, s[60:61]
	s_add_i32 m0, s82, 0x2000
	s_add_u32 s82, s60, 0x80000

; #define PG8_STAGE(bufoff, gbase, voff) do { _Pragma("unroll") for (int _i = 0; _i < 2; ++_i) \
;         __builtin_amdgcn_global_load_lds((const unsigned*)((const char*)(gbase) + (voff)[_i]), (PG8_LAS unsigned*)(lds + (bufoff) + ldsw + _i * 8192), 16, 0, 0); } while (0)
; #define PG8_LDA(dst, b, h) do { _Pragma("unroll") for (int m = 0; m < 4; ++m) _Pragma("unroll") for (int k = 0; k < 2; ++k) dst[m][k] = *(const PG8_LAS bf16x8*)(lds + PG8_SA(b, h) + aoff + m * 2048 + k * 1024); } while (0)
; template <class Epi, class Sched, bool ALIGN_EPI = false, bool SP2 = false>
; __device__ __forceinline__ void gemm_phase(PG8_LAS unsigned char* lds, const Gemm g, const Sched& S, const Epi& E) {
;     ...
;             PG8_LDA(At, 0, 1); PG8_STAGE(PG8_SB(0, 0), b2, voffB); PG8_STAGE(PG8_SB(0, 1), b2 + hstep, voffB); PG8_STAGE(PG8_SA(0, 0), a2, voffA);
	s_addc_u32 s83, s61, 0
	s_add_i32 s84, s76, s64
	global_load_lds_dwordx4 v166, s[60:61]

; #define PG8_STAGE(bufoff, gbase, voff) do { _Pragma("unroll") for (int _i = 0; _i < 2; ++_i) \
;         __builtin_amdgcn_global_load_lds((const unsigned*)((const char*)(gbase) + (voff)[_i]), (PG8_LAS unsigned*)(lds + (bufoff) + ldsw + _i * 8192), 16, 0, 0); } while (0)
; #define PG8_LDA(dst, b, h) do { _Pragma("unroll") for (int m = 0; m < 4; ++m) _Pragma("unroll") for (int k = 0; k < 2; ++k) dst[m][k] = *(const PG8_LAS bf16x8*)(lds + PG8_SA(b, h) + aoff + m * 2048 + k * 1024); } while (0)
; template <class Epi, class Sched, bool ALIGN_EPI = false, bool SP2 = false>
; __device__ __forceinline__ void gemm_phase(PG8_LAS unsigned char* lds, const Gemm g, const Sched& S, const Epi& E) {
;     ...
;             PG8_LDA(At, 0, 1); PG8_STAGE(PG8_SB(0, 0), b2, voffB); PG8_STAGE(PG8_SB(0, 1), b2 + hstep, voffB); PG8_STAGE(PG8_SA(0, 0), a2, voffA);
	s_mov_b32 m0, s84
	s_nop 0
	global_load_lds_dwordx4 v162, s[82:83]

; #define PG8_STAGE(bufoff, gbase, voff) do { _Pragma("unroll") for (int _i = 0; _i < 2; ++_i) \
;         __builtin_amdgcn_global_load_lds((const unsigned*)((const char*)(gbase) + (voff)[_i]), (PG8_LAS unsigned*)(lds + (bufoff) + ldsw + _i * 8192), 16, 0, 0); } while (0)
; #define PG8_LDA(dst, b, h) do { _Pragma("unroll") for (int m = 0; m < 4; ++m) _Pragma("unroll") for (int k = 0; k < 2; ++k) dst[m][k] = *(const PG8_LAS bf16x8*)(lds + PG8_SA(b, h) + aoff + m * 2048 + k * 1024); } while (0)
; template <class Epi, class Sched, bool ALIGN_EPI = false, bool SP2 = false>
; __device__ __forceinline__ void gemm_phase(PG8_LAS unsigned char* lds, const Gemm g, const Sched& S, const Epi& E) {
;     ...
;             PG8_LDA(At, 0, 1); PG8_STAGE(PG8_SB(0, 0), b2, voffB); PG8_STAGE(PG8_SB(0, 1), b2 + hstep, voffB); PG8_STAGE(PG8_SA(0, 0), a2, voffA);
	s_add_i32 m0, s84, 0x2000
	s_nop 0
	global_load_lds_dwordx4 v166, s[82:83]
	s_mov_b64 s[98:99], s[62:63]

; #define PG8_STAGE(bufoff, gbase, voff) do { _Pragma("unroll") for (int _i = 0; _i < 2; ++_i) \
;         __builtin_amdgcn_global_load_lds((const unsigned*)((const char*)(gbase) + (voff)[_i]), (PG8_LAS unsigned*)(lds + (bufoff) + ldsw + _i * 8192), 16, 0, 0); } while (0)
; #define PG8_LDA(dst, b, h) do { _Pragma("unroll") for (int m = 0; m < 4; ++m) _Pragma("unroll") for (int k = 0; k < 2; ++k) dst[m][k] = *(const PG8_LAS bf16x8*)(lds + PG8_SA(b, h) + aoff + m * 2048 + k * 1024); } while (0)
; #define PG8_MMA(ai, bj, At, Bt) do { __builtin_amdgcn_s_setprio(1); _Pragma("unroll") for (int m = 0; m < 4; ++m) _Pragma("unroll") for (int n = 0; n < 2; ++n) _Pragma("unroll") for (int k = 0; k < 2; ++k) \
;         acc[ai][bj][m][n] = __builtin_amdgcn_mfma_f32_16x16x32_bf16(Bt[n][k], At[m][k], acc[ai][bj][m][n], 0, 0, 0); __builtin_amdgcn_s_setprio(0); } while (0)
; #define PG8_WAIT_V(n) asm volatile("s_waitcnt vmcnt(" #n ")" ::: "memory")
; #define PG8_WAIT_L(n) asm volatile("s_waitcnt lgkmcnt(" #n ")" ::: "memory")
; #define PG8_BAR __builtin_amdgcn_s_barrier()
; #define PG8_SCHED __builtin_amdgcn_sched_barrier(0)
; template <class Epi, class Sched, bool ALIGN_EPI = false, bool SP2 = false>
; __device__ __forceinline__ void gemm_phase(PG8_LAS unsigned char* lds, const Gemm g, const Sched& S, const Epi& E) {
;     ...
;             PG8_LDA(At, 0, 1); PG8_STAGE(PG8_SB(0, 0), b2, voffB); PG8_STAGE(PG8_SB(0, 1), b2 + hstep, voffB); PG8_STAGE(PG8_SA(0, 0), a2, voffA);
;             PG8_WAIT_V(8); PG8_WAIT_L(0); PG8_BAR; PG8_MMA(1, 0, At, B0); PG8_MMA(1, 1, At, B1); PG8_BAR; PG8_SCHED;
	s_mov_b32 m0, s57
	s_nop 0
	global_load_lds_dwordx4 v160, s[62:63]
	s_mov_b32 m0, s65
	s_nop 0
	global_load_lds_dwordx4 v164, s[62:63]
	s_waitcnt vmcnt(8) lgkmcnt(0)


; #define PG8_MMA(ai, bj, At, Bt) do { __builtin_amdgcn_s_setprio(1); _Pragma("unroll") for (int m = 0; m < 4; ++m) _Pragma("unroll") for (int n = 0; n < 2; ++n) _Pragma("unroll") for (int k = 0; k < 2; ++k) \
;         acc[ai][bj][m][n] = __builtin_amdgcn_mfma_f32_16x16x32_bf16(Bt[n][k], At[m][k], acc[ai][bj][m][n], 0, 0, 0); __builtin_amdgcn_s_setprio(0); } while (0)
; #define PG8_WAIT_V(n) asm volatile("s_waitcnt vmcnt(" #n ")" ::: "memory")
; #define PG8_WAIT_L(n) asm volatile("s_waitcnt lgkmcnt(" #n ")" ::: "memory")
; #define PG8_BAR __builtin_amdgcn_s_barrier()
; #define PG8_SCHED __builtin_amdgcn_sched_barrier(0)
; template <class Epi, class Sched, bool ALIGN_EPI = false, bool SP2 = false>
; __device__ __forceinline__ void gemm_phase(PG8_LAS unsigned char* lds, const Gemm g, const Sched& S, const Epi& E) {
;     ...
;             PG8_WAIT_V(8); PG8_WAIT_L(0); PG8_BAR; PG8_MMA(1, 0, At, B0); PG8_MMA(1, 1, At, B1); PG8_BAR; PG8_SCHED;
	s_barrier

; #define PG8_MMA(ai, bj, At, Bt) do { __builtin_amdgcn_s_setprio(1); _Pragma("unroll") for (int m = 0; m < 4; ++m) _Pragma("unroll") for (int n = 0; n < 2; ++n) _Pragma("unroll") for (int k = 0; k < 2; ++k) \
;         acc[ai][bj][m][n] = __builtin_amdgcn_mfma_f32_16x16x32_bf16(Bt[n][k], At[m][k], acc[ai][bj][m][n], 0, 0, 0); __builtin_amdgcn_s_setprio(0); } while (0)
; #define PG8_WAIT_V(n) asm volatile("s_waitcnt vmcnt(" #n ")" ::: "memory")
; #define PG8_WAIT_L(n) asm volatile("s_waitcnt lgkmcnt(" #n ")" ::: "memory")
; #define PG8_BAR __builtin_amdgcn_s_barrier()
; #define PG8_SCHED __builtin_amdgcn_sched_barrier(0)
; template <class Epi, class Sched, bool ALIGN_EPI = false, bool SP2 = false>
; __device__ __forceinline__ void gemm_phase(PG8_LAS unsigned char* lds, const Gemm g, const Sched& S, const Epi& E) {
;     ...
;             PG8_WAIT_V(8); PG8_WAIT_L(0); PG8_BAR; PG8_MMA(1, 0, At, B0); PG8_MMA(1, 1, At, B1); PG8_BAR; PG8_SCHED;
	v_mfma_f32_16x16x32_bf16 v[60:63], v[64:67], v[176:179], v[60:63]
	v_mfma_f32_16x16x32_bf16 v[56:59], v[72:75], v[176:179], v[56:59]
	v_mfma_f32_16x16x32_bf16 v[44:47], v[64:67], v[184:187], v[44:47]
	v_mfma_f32_16x16x32_bf16 v[40:43], v[72:75], v[184:187], v[40:43]
	v_mfma_f32_16x16x32_bf16 v[28:31], v[64:67], v[192:195], v[28:31]
	v_mfma_f32_16x16x32_bf16 v[24:27], v[72:75], v[192:195], v[24:27]
	v_mfma_f32_16x16x32_bf16 v[12:15], v[64:67], v[200:203], v[12:15]
	v_mfma_f32_16x16x32_bf16 v[8:11], v[72:75], v[200:203], v[8:11]
	v_mfma_f32_16x16x32_bf16 v[60:63], v[68:71], v[180:183], v[60:63]
	v_mfma_f32_16x16x32_bf16 v[56:59], v[76:79], v[180:183], v[56:59]
	v_mfma_f32_16x16x32_bf16 v[44:47], v[68:71], v[188:191], v[44:47]
	v_mfma_f32_16x16x32_bf16 v[40:43], v[76:79], v[188:191], v[40:43]
	v_mfma_f32_16x16x32_bf16 v[28:31], v[68:71], v[196:199], v[28:31]
	v_mfma_f32_16x16x32_bf16 v[24:27], v[76:79], v[196:199], v[24:27]
	v_mfma_f32_16x16x32_bf16 v[12:15], v[68:71], v[204:207], v[12:15]
	v_mfma_f32_16x16x32_bf16 v[8:11], v[76:79], v[204:207], v[8:11]


; #define PG8_MMA(ai, bj, At, Bt) do { __builtin_amdgcn_s_setprio(1); _Pragma("unroll") for (int m = 0; m < 4; ++m) _Pragma("unroll") for (int n = 0; n < 2; ++n) _Pragma("unroll") for (int k = 0; k < 2; ++k) \
;         acc[ai][bj][m][n] = __builtin_amdgcn_mfma_f32_16x16x32_bf16(Bt[n][k], At[m][k], acc[ai][bj][m][n], 0, 0, 0); __builtin_amdgcn_s_setprio(0); } while (0)
; #define PG8_WAIT_V(n) asm volatile("s_waitcnt vmcnt(" #n ")" ::: "memory")
; #define PG8_WAIT_L(n) asm volatile("s_waitcnt lgkmcnt(" #n ")" ::: "memory")
; #define PG8_BAR __builtin_amdgcn_s_barrier()
; #define PG8_SCHED __builtin_amdgcn_sched_barrier(0)
; template <class Epi, class Sched, bool ALIGN_EPI = false, bool SP2 = false>
; __device__ __forceinline__ void gemm_phase(PG8_LAS unsigned char* lds, const Gemm g, const Sched& S, const Epi& E) {
;     ...
;             PG8_WAIT_V(8); PG8_WAIT_L(0); PG8_BAR; PG8_MMA(1, 0, At, B0); PG8_MMA(1, 1, At, B1); PG8_BAR; PG8_SCHED;
	v_mfma_f32_16x16x32_bf16 v[52:55], v[144:147], v[176:179], v[52:55]
	v_mfma_f32_16x16x32_bf16 v[48:51], v[152:155], v[176:179], v[48:51]
	v_mfma_f32_16x16x32_bf16 v[36:39], v[144:147], v[184:187], v[36:39]
	v_mfma_f32_16x16x32_bf16 v[32:35], v[152:155], v[184:187], v[32:35]
	v_mfma_f32_16x16x32_bf16 v[20:23], v[144:147], v[192:195], v[20:23]
	v_mfma_f32_16x16x32_bf16 v[16:19], v[152:155], v[192:195], v[16:19]
	v_mfma_f32_16x16x32_bf16 v[4:7], v[144:147], v[200:203], v[4:7]
	v_mfma_f32_16x16x32_bf16 v[0:3], v[152:155], v[200:203], v[0:3]
	v_mfma_f32_16x16x32_bf16 v[52:55], v[148:151], v[180:183], v[52:55]
	v_mfma_f32_16x16x32_bf16 v[48:51], v[156:159], v[180:183], v[48:51]
	v_mfma_f32_16x16x32_bf16 v[36:39], v[148:151], v[188:191], v[36:39]
	v_mfma_f32_16x16x32_bf16 v[32:35], v[156:159], v[188:191], v[32:35]
	v_mfma_f32_16x16x32_bf16 v[20:23], v[148:151], v[196:199], v[20:23]
	v_mfma_f32_16x16x32_bf16 v[16:19], v[156:159], v[196:199], v[16:19]
	v_mfma_f32_16x16x32_bf16 v[4:7], v[148:151], v[204:207], v[4:7]
	v_mfma_f32_16x16x32_bf16 v[0:3], v[156:159], v[204:207], v[0:3]

; #define PG8_STAGE(bufoff, gbase, voff) do { _Pragma("unroll") for (int _i = 0; _i < 2; ++_i) \
;         __builtin_amdgcn_global_load_lds((const unsigned*)((const char*)(gbase) + (voff)[_i]), (PG8_LAS unsigned*)(lds + (bufoff) + ldsw + _i * 8192), 16, 0, 0); } while (0)
; #define PG8_LDA(dst, b, h) do { _Pragma("unroll") for (int m = 0; m < 4; ++m) _Pragma("unroll") for (int k = 0; k < 2; ++k) dst[m][k] = *(const PG8_LAS bf16x8*)(lds + PG8_SA(b, h) + aoff + m * 2048 + k * 1024); } while (0)
; #define PG8_MMA(ai, bj, At, Bt) do { __builtin_amdgcn_s_setprio(1); _Pragma("unroll") for (int m = 0; m < 4; ++m) _Pragma("unroll") for (int n = 0; n < 2; ++n) _Pragma("unroll") for (int k = 0; k < 2; ++k) \
;         acc[ai][bj][m][n] = __builtin_amdgcn_mfma_f32_16x16x32_bf16(Bt[n][k], At[m][k], acc[ai][bj][m][n], 0, 0, 0); __builtin_amdgcn_s_setprio(0); } while (0)
; #define PG8_WAIT_V(n) asm volatile("s_waitcnt vmcnt(" #n ")" ::: "memory")
; #define PG8_WAIT_L(n) asm volatile("s_waitcnt lgkmcnt(" #n ")" ::: "memory")
; #define PG8_BAR __builtin_amdgcn_s_barrier()
; #define PG8_SCHED __builtin_amdgcn_sched_barrier(0)
; template <class Epi, class Sched, bool ALIGN_EPI = false, bool SP2 = false>
; __device__ __forceinline__ void gemm_phase(PG8_LAS unsigned char* lds, const Gemm g, const Sched& S, const Epi& E) {
;     ...
;             PG8_WAIT_V(8); PG8_WAIT_L(0); PG8_BAR; PG8_MMA(1, 0, At, B0); PG8_MMA(1, 1, At, B1); PG8_BAR; PG8_SCHED;
;     ...
;             PG8_LDA(At, 1, 1); PG8_STAGE(PG8_SB(1, 0), b3, voffB); PG8_STAGE(PG8_SB(1, 1), b3 + hstep, voffB); PG8_STAGE(PG8_SA(1, 0), a3, voffA);
	s_barrier
	s_add_i32 s82, 0, 0x18000
	s_add_i32 s83, 0, 0x1c000


; #define PG8_STAGE(bufoff, gbase, voff) do { _Pragma("unroll") for (int _i = 0; _i < 2; ++_i) \
;         __builtin_amdgcn_global_load_lds((const unsigned*)((const char*)(gbase) + (voff)[_i]), (PG8_LAS unsigned*)(lds + (bufoff) + ldsw + _i * 8192), 16, 0, 0); } while (0)
; #define PG8_LDA(dst, b, h) do { _Pragma("unroll") for (int m = 0; m < 4; ++m) _Pragma("unroll") for (int k = 0; k < 2; ++k) dst[m][k] = *(const PG8_LAS bf16x8*)(lds + PG8_SA(b, h) + aoff + m * 2048 + k * 1024); } while (0)
; #define PG8_LDB(dst, b, h) do { _Pragma("unroll") for (int n = 0; n < 2; ++n) _Pragma("unroll") for (int k = 0; k < 2; ++k) dst[n][k] = *(const PG8_LAS bf16x8*)(lds + PG8_SB(b, h) + boff + n * 2048 + k * 1024); } while (0)
; #define PG8_SCHED __builtin_amdgcn_sched_barrier(0)
; template <class Epi, class Sched, bool ALIGN_EPI = false, bool SP2 = false>
; __device__ __forceinline__ void gemm_phase(PG8_LAS unsigned char* lds, const Gemm g, const Sched& S, const Epi& E) {
;     ...
;             PG8_LDB(B0, 1, 0); PG8_LDB(B1, 1, 1); PG8_SCHED; PG8_LDA(At, 1, 0); PG8_STAGE(PG8_SA(0, 1), a2 + hstep, voffA);
	ds_read_b128 v[64:67], v254
	ds_read_b128 v[68:71], v254 offset:1024
	ds_read_b128 v[72:75], v254 offset:2048
	ds_read_b128 v[76:79], v254 offset:3072
	ds_read_b128 v[144:147], v255
	ds_read_b128 v[148:151], v255 offset:1024
	ds_read_b128 v[152:155], v255 offset:2048
	ds_read_b128 v[156:159], v255 offset:3072
	s_add_u32 s62, s62, 0x80000
	s_addc_u32 s63, s63, 0
	s_mov_b32 m0, s67

; #define PG8_STAGE(bufoff, gbase, voff) do { _Pragma("unroll") for (int _i = 0; _i < 2; ++_i) \
;         __builtin_amdgcn_global_load_lds((const unsigned*)((const char*)(gbase) + (voff)[_i]), (PG8_LAS unsigned*)(lds + (bufoff) + ldsw + _i * 8192), 16, 0, 0); } while (0)
; #define PG8_LDA(dst, b, h) do { _Pragma("unroll") for (int m = 0; m < 4; ++m) _Pragma("unroll") for (int k = 0; k < 2; ++k) dst[m][k] = *(const PG8_LAS bf16x8*)(lds + PG8_SA(b, h) + aoff + m * 2048 + k * 1024); } while (0)
; #define PG8_LDB(dst, b, h) do { _Pragma("unroll") for (int n = 0; n < 2; ++n) _Pragma("unroll") for (int k = 0; k < 2; ++k) dst[n][k] = *(const PG8_LAS bf16x8*)(lds + PG8_SB(b, h) + boff + n * 2048 + k * 1024); } while (0)
; #define PG8_SCHED __builtin_amdgcn_sched_barrier(0)
; template <class Epi, class Sched, bool ALIGN_EPI = false, bool SP2 = false>
; __device__ __forceinline__ void gemm_phase(PG8_LAS unsigned char* lds, const Gemm g, const Sched& S, const Epi& E) {
;     ...
;             PG8_LDB(B0, 1, 0); PG8_LDB(B1, 1, 1); PG8_SCHED; PG8_LDA(At, 1, 0); PG8_STAGE(PG8_SA(0, 1), a2 + hstep, voffA);
	ds_read_b128 v[176:179], v213 offset:32768
	ds_read_b128 v[180:183], v213 offset:33792
	ds_read_b128 v[184:187], v213 offset:34816
	ds_read_b128 v[188:191], v213 offset:35840
	ds_read_b128 v[192:195], v213 offset:36864
	ds_read_b128 v[196:199], v213 offset:37888
	ds_read_b128 v[200:203], v213 offset:38912
	ds_read_b128 v[204:207], v213 offset:39936
	global_load_lds_dwordx4 v160, s[62:63]

; #define PG8_STAGE(bufoff, gbase, voff) do { _Pragma("unroll") for (int _i = 0; _i < 2; ++_i) \
;         __builtin_amdgcn_global_load_lds((const unsigned*)((const char*)(gbase) + (voff)[_i]), (PG8_LAS unsigned*)(lds + (bufoff) + ldsw + _i * 8192), 16, 0, 0); } while (0)
; #define PG8_LDA(dst, b, h) do { _Pragma("unroll") for (int m = 0; m < 4; ++m) _Pragma("unroll") for (int k = 0; k < 2; ++k) dst[m][k] = *(const PG8_LAS bf16x8*)(lds + PG8_SA(b, h) + aoff + m * 2048 + k * 1024); } while (0)
; #define PG8_LDB(dst, b, h) do { _Pragma("unroll") for (int n = 0; n < 2; ++n) _Pragma("unroll") for (int k = 0; k < 2; ++k) dst[n][k] = *(const PG8_LAS bf16x8*)(lds + PG8_SB(b, h) + boff + n * 2048 + k * 1024); } while (0)
; #define PG8_MMA(ai, bj, At, Bt) do { __builtin_amdgcn_s_setprio(1); _Pragma("unroll") for (int m = 0; m < 4; ++m) _Pragma("unroll") for (int n = 0; n < 2; ++n) _Pragma("unroll") for (int k = 0; k < 2; ++k) \
;         acc[ai][bj][m][n] = __builtin_amdgcn_mfma_f32_16x16x32_bf16(Bt[n][k], At[m][k], acc[ai][bj][m][n], 0, 0, 0); __builtin_amdgcn_s_setprio(0); } while (0)
; #define PG8_WAIT_V(n) asm volatile("s_waitcnt vmcnt(" #n ")" ::: "memory")
; #define PG8_WAIT_L(n) asm volatile("s_waitcnt lgkmcnt(" #n ")" ::: "memory")
; #define PG8_BAR __builtin_amdgcn_s_barrier()
; #define PG8_SCHED __builtin_amdgcn_sched_barrier(0)
; template <class Epi, class Sched, bool ALIGN_EPI = false, bool SP2 = false>
; __device__ __forceinline__ void gemm_phase(PG8_LAS unsigned char* lds, const Gemm g, const Sched& S, const Epi& E) {
;     ...
;             PG8_LDB(B0, 1, 0); PG8_LDB(B1, 1, 1); PG8_SCHED; PG8_LDA(At, 1, 0); PG8_STAGE(PG8_SA(0, 1), a2 + hstep, voffA);
;             PG8_WAIT_V(8); PG8_WAIT_L(0); PG8_BAR; PG8_MMA(0, 0, At, B0); PG8_MMA(0, 1, At, B1); PG8_BAR; PG8_SCHED;
	s_mov_b32 m0, s68
	s_nop 0
	global_load_lds_dwordx4 v164, s[62:63]
	s_waitcnt vmcnt(8) lgkmcnt(0)


; #define PG8_MMA(ai, bj, At, Bt) do { __builtin_amdgcn_s_setprio(1); _Pragma("unroll") for (int m = 0; m < 4; ++m) _Pragma("unroll") for (int n = 0; n < 2; ++n) _Pragma("unroll") for (int k = 0; k < 2; ++k) \
;         acc[ai][bj][m][n] = __builtin_amdgcn_mfma_f32_16x16x32_bf16(Bt[n][k], At[m][k], acc[ai][bj][m][n], 0, 0, 0); __builtin_amdgcn_s_setprio(0); } while (0)
; #define PG8_WAIT_V(n) asm volatile("s_waitcnt vmcnt(" #n ")" ::: "memory")
; #define PG8_WAIT_L(n) asm volatile("s_waitcnt lgkmcnt(" #n ")" ::: "memory")
; #define PG8_BAR __builtin_amdgcn_s_barrier()
; #define PG8_SCHED __builtin_amdgcn_sched_barrier(0)
; template <class Epi, class Sched, bool ALIGN_EPI = false, bool SP2 = false>
; __device__ __forceinline__ void gemm_phase(PG8_LAS unsigned char* lds, const Gemm g, const Sched& S, const Epi& E) {
;     ...
;             PG8_WAIT_V(8); PG8_WAIT_L(0); PG8_BAR; PG8_MMA(0, 0, At, B0); PG8_MMA(0, 1, At, B1); PG8_BAR; PG8_SCHED;
	s_barrier

; #define PG8_MMA(ai, bj, At, Bt) do { __builtin_amdgcn_s_setprio(1); _Pragma("unroll") for (int m = 0; m < 4; ++m) _Pragma("unroll") for (int n = 0; n < 2; ++n) _Pragma("unroll") for (int k = 0; k < 2; ++k) \
;         acc[ai][bj][m][n] = __builtin_amdgcn_mfma_f32_16x16x32_bf16(Bt[n][k], At[m][k], acc[ai][bj][m][n], 0, 0, 0); __builtin_amdgcn_s_setprio(0); } while (0)
; #define PG8_WAIT_V(n) asm volatile("s_waitcnt vmcnt(" #n ")" ::: "memory")
; #define PG8_WAIT_L(n) asm volatile("s_waitcnt lgkmcnt(" #n ")" ::: "memory")
; #define PG8_BAR __builtin_amdgcn_s_barrier()
; #define PG8_SCHED __builtin_amdgcn_sched_barrier(0)
; template <class Epi, class Sched, bool ALIGN_EPI = false, bool SP2 = false>
; __device__ __forceinline__ void gemm_phase(PG8_LAS unsigned char* lds, const Gemm g, const Sched& S, const Epi& E) {
;     ...
;             PG8_WAIT_V(8); PG8_WAIT_L(0); PG8_BAR; PG8_MMA(0, 0, At, B0); PG8_MMA(0, 1, At, B1); PG8_BAR; PG8_SCHED;
	v_mfma_f32_16x16x32_bf16 v[140:143], v[64:67], v[176:179], v[140:143]
	v_mfma_f32_16x16x32_bf16 v[136:139], v[72:75], v[176:179], v[136:139]
	v_mfma_f32_16x16x32_bf16 v[124:127], v[64:67], v[184:187], v[124:127]
	v_mfma_f32_16x16x32_bf16 v[120:123], v[72:75], v[184:187], v[120:123]
	v_mfma_f32_16x16x32_bf16 v[108:111], v[64:67], v[192:195], v[108:111]
	v_mfma_f32_16x16x32_bf16 v[104:107], v[72:75], v[192:195], v[104:107]
	v_mfma_f32_16x16x32_bf16 v[92:95], v[64:67], v[200:203], v[92:95]
	v_mfma_f32_16x16x32_bf16 v[88:91], v[72:75], v[200:203], v[88:91]
	v_mfma_f32_16x16x32_bf16 v[140:143], v[68:71], v[180:183], v[140:143]
	v_mfma_f32_16x16x32_bf16 v[136:139], v[76:79], v[180:183], v[136:139]
	v_mfma_f32_16x16x32_bf16 v[124:127], v[68:71], v[188:191], v[124:127]
	v_mfma_f32_16x16x32_bf16 v[120:123], v[76:79], v[188:191], v[120:123]
	v_mfma_f32_16x16x32_bf16 v[108:111], v[68:71], v[196:199], v[108:111]
	v_mfma_f32_16x16x32_bf16 v[104:107], v[76:79], v[196:199], v[104:107]
	v_mfma_f32_16x16x32_bf16 v[92:95], v[68:71], v[204:207], v[92:95]
	v_mfma_f32_16x16x32_bf16 v[88:91], v[76:79], v[204:207], v[88:91]


; #define PG8_MMA(ai, bj, At, Bt) do { __builtin_amdgcn_s_setprio(1); _Pragma("unroll") for (int m = 0; m < 4; ++m) _Pragma("unroll") for (int n = 0; n < 2; ++n) _Pragma("unroll") for (int k = 0; k < 2; ++k) \
;         acc[ai][bj][m][n] = __builtin_amdgcn_mfma_f32_16x16x32_bf16(Bt[n][k], At[m][k], acc[ai][bj][m][n], 0, 0, 0); __builtin_amdgcn_s_setprio(0); } while (0)
; #define PG8_WAIT_V(n) asm volatile("s_waitcnt vmcnt(" #n ")" ::: "memory")
; #define PG8_WAIT_L(n) asm volatile("s_waitcnt lgkmcnt(" #n ")" ::: "memory")
; #define PG8_BAR __builtin_amdgcn_s_barrier()
; #define PG8_SCHED __builtin_amdgcn_sched_barrier(0)
; template <class Epi, class Sched, bool ALIGN_EPI = false, bool SP2 = false>
; __device__ __forceinline__ void gemm_phase(PG8_LAS unsigned char* lds, const Gemm g, const Sched& S, const Epi& E) {
;     ...
;             PG8_WAIT_V(8); PG8_WAIT_L(0); PG8_BAR; PG8_MMA(0, 0, At, B0); PG8_MMA(0, 1, At, B1); PG8_BAR; PG8_SCHED;
	v_mfma_f32_16x16x32_bf16 v[132:135], v[144:147], v[176:179], v[132:135]
	v_mfma_f32_16x16x32_bf16 v[128:131], v[152:155], v[176:179], v[128:131]
	v_mfma_f32_16x16x32_bf16 v[116:119], v[144:147], v[184:187], v[116:119]
	v_mfma_f32_16x16x32_bf16 v[112:115], v[152:155], v[184:187], v[112:115]
	v_mfma_f32_16x16x32_bf16 v[100:103], v[144:147], v[192:195], v[100:103]
	v_mfma_f32_16x16x32_bf16 v[96:99], v[152:155], v[192:195], v[96:99]
	v_mfma_f32_16x16x32_bf16 v[84:87], v[144:147], v[200:203], v[84:87]
	v_mfma_f32_16x16x32_bf16 v[80:83], v[152:155], v[200:203], v[80:83]
	v_mfma_f32_16x16x32_bf16 v[132:135], v[148:151], v[180:183], v[132:135]
	v_mfma_f32_16x16x32_bf16 v[128:131], v[156:159], v[180:183], v[128:131]
	v_mfma_f32_16x16x32_bf16 v[116:119], v[148:151], v[188:191], v[116:119]
	v_mfma_f32_16x16x32_bf16 v[112:115], v[156:159], v[188:191], v[112:115]
	v_mfma_f32_16x16x32_bf16 v[100:103], v[148:151], v[196:199], v[100:103]
	v_mfma_f32_16x16x32_bf16 v[96:99], v[156:159], v[196:199], v[96:99]
	v_mfma_f32_16x16x32_bf16 v[84:87], v[148:151], v[204:207], v[84:87]
	v_mfma_f32_16x16x32_bf16 v[80:83], v[156:159], v[204:207], v[80:83]

; #define PG8_STAGE(bufoff, gbase, voff) do { _Pragma("unroll") for (int _i = 0; _i < 2; ++_i) \
;         __builtin_amdgcn_global_load_lds((const unsigned*)((const char*)(gbase) + (voff)[_i]), (PG8_LAS unsigned*)(lds + (bufoff) + ldsw + _i * 8192), 16, 0, 0); } while (0)
; #define PG8_LDA(dst, b, h) do { _Pragma("unroll") for (int m = 0; m < 4; ++m) _Pragma("unroll") for (int k = 0; k < 2; ++k) dst[m][k] = *(const PG8_LAS bf16x8*)(lds + PG8_SA(b, h) + aoff + m * 2048 + k * 1024); } while (0)
; #define PG8_MMA(ai, bj, At, Bt) do { __builtin_amdgcn_s_setprio(1); _Pragma("unroll") for (int m = 0; m < 4; ++m) _Pragma("unroll") for (int n = 0; n < 2; ++n) _Pragma("unroll") for (int k = 0; k < 2; ++k) \
;         acc[ai][bj][m][n] = __builtin_amdgcn_mfma_f32_16x16x32_bf16(Bt[n][k], At[m][k], acc[ai][bj][m][n], 0, 0, 0); __builtin_amdgcn_s_setprio(0); } while (0)
; #define PG8_WAIT_V(n) asm volatile("s_waitcnt vmcnt(" #n ")" ::: "memory")
; #define PG8_WAIT_L(n) asm volatile("s_waitcnt lgkmcnt(" #n ")" ::: "memory")
; #define PG8_BAR __builtin_amdgcn_s_barrier()
; #define PG8_SCHED __builtin_amdgcn_sched_barrier(0)
; template <class Epi, class Sched, bool ALIGN_EPI = false, bool SP2 = false>
; __device__ __forceinline__ void gemm_phase(PG8_LAS unsigned char* lds, const Gemm g, const Sched& S, const Epi& E) {
;     ...
;             PG8_WAIT_V(8); PG8_WAIT_L(0); PG8_BAR; PG8_MMA(0, 0, At, B0); PG8_MMA(0, 1, At, B1); PG8_BAR; PG8_SCHED;
;             PG8_LDA(At, 1, 1); PG8_STAGE(PG8_SB(1, 0), b3, voffB); PG8_STAGE(PG8_SB(1, 1), b3 + hstep, voffB); PG8_STAGE(PG8_SA(1, 0), a3, voffA);
	s_barrier
	s_add_i32 s62, s82, s64

; #define PG8_STAGE(bufoff, gbase, voff) do { _Pragma("unroll") for (int _i = 0; _i < 2; ++_i) \
;         __builtin_amdgcn_global_load_lds((const unsigned*)((const char*)(gbase) + (voff)[_i]), (PG8_LAS unsigned*)(lds + (bufoff) + ldsw + _i * 8192), 16, 0, 0); } while (0)
; #define PG8_LDA(dst, b, h) do { _Pragma("unroll") for (int m = 0; m < 4; ++m) _Pragma("unroll") for (int k = 0; k < 2; ++k) dst[m][k] = *(const PG8_LAS bf16x8*)(lds + PG8_SA(b, h) + aoff + m * 2048 + k * 1024); } while (0)
; template <class Epi, class Sched, bool ALIGN_EPI = false, bool SP2 = false>
; __device__ __forceinline__ void gemm_phase(PG8_LAS unsigned char* lds, const Gemm g, const Sched& S, const Epi& E) {
;     ...
;             PG8_LDA(At, 1, 1); PG8_STAGE(PG8_SB(1, 0), b3, voffB); PG8_STAGE(PG8_SB(1, 1), b3 + hstep, voffB); PG8_STAGE(PG8_SA(1, 0), a3, voffA);
	s_mov_b32 m0, s62
	ds_read_b128 v[176:179], v213 offset:49152
	ds_read_b128 v[180:183], v213 offset:50176
	ds_read_b128 v[184:187], v213 offset:51200
	ds_read_b128 v[188:191], v213 offset:52224
	ds_read_b128 v[192:195], v213 offset:53248
	ds_read_b128 v[196:199], v213 offset:54272
	ds_read_b128 v[200:203], v213 offset:55296
	ds_read_b128 v[204:207], v213 offset:56320
	global_load_lds_dwordx4 v250, s[96:97]
	s_add_i32 m0, s62, 0x2000
	s_add_u32 s60, s60, 0x80080

; #define PG8_STAGE(bufoff, gbase, voff) do { _Pragma("unroll") for (int _i = 0; _i < 2; ++_i) \
;         __builtin_amdgcn_global_load_lds((const unsigned*)((const char*)(gbase) + (voff)[_i]), (PG8_LAS unsigned*)(lds + (bufoff) + ldsw + _i * 8192), 16, 0, 0); } while (0)
; #define PG8_LDA(dst, b, h) do { _Pragma("unroll") for (int m = 0; m < 4; ++m) _Pragma("unroll") for (int k = 0; k < 2; ++k) dst[m][k] = *(const PG8_LAS bf16x8*)(lds + PG8_SA(b, h) + aoff + m * 2048 + k * 1024); } while (0)
; template <class Epi, class Sched, bool ALIGN_EPI = false, bool SP2 = false>
; __device__ __forceinline__ void gemm_phase(PG8_LAS unsigned char* lds, const Gemm g, const Sched& S, const Epi& E) {
;     ...
;             PG8_LDA(At, 1, 1); PG8_STAGE(PG8_SB(1, 0), b3, voffB); PG8_STAGE(PG8_SB(1, 1), b3 + hstep, voffB); PG8_STAGE(PG8_SA(1, 0), a3, voffA);
	s_addc_u32 s61, s61, 0
	s_add_i32 s62, s83, s64
	global_load_lds_dwordx4 v251, s[96:97]

; #define PG8_STAGE(bufoff, gbase, voff) do { _Pragma("unroll") for (int _i = 0; _i < 2; ++_i) \
;         __builtin_amdgcn_global_load_lds((const unsigned*)((const char*)(gbase) + (voff)[_i]), (PG8_LAS unsigned*)(lds + (bufoff) + ldsw + _i * 8192), 16, 0, 0); } while (0)
; #define PG8_LDA(dst, b, h) do { _Pragma("unroll") for (int m = 0; m < 4; ++m) _Pragma("unroll") for (int k = 0; k < 2; ++k) dst[m][k] = *(const PG8_LAS bf16x8*)(lds + PG8_SA(b, h) + aoff + m * 2048 + k * 1024); } while (0)
; template <class Epi, class Sched, bool ALIGN_EPI = false, bool SP2 = false>
; __device__ __forceinline__ void gemm_phase(PG8_LAS unsigned char* lds, const Gemm g, const Sched& S, const Epi& E) {
;     ...
;             PG8_LDA(At, 1, 1); PG8_STAGE(PG8_SB(1, 0), b3, voffB); PG8_STAGE(PG8_SB(1, 1), b3 + hstep, voffB); PG8_STAGE(PG8_SA(1, 0), a3, voffA);
	s_mov_b32 m0, s62
	s_nop 0
	global_load_lds_dwordx4 v162, s[60:61]

; #define PG8_STAGE(bufoff, gbase, voff) do { _Pragma("unroll") for (int _i = 0; _i < 2; ++_i) \
;         __builtin_amdgcn_global_load_lds((const unsigned*)((const char*)(gbase) + (voff)[_i]), (PG8_LAS unsigned*)(lds + (bufoff) + ldsw + _i * 8192), 16, 0, 0); } while (0)
; #define PG8_LDA(dst, b, h) do { _Pragma("unroll") for (int m = 0; m < 4; ++m) _Pragma("unroll") for (int k = 0; k < 2; ++k) dst[m][k] = *(const PG8_LAS bf16x8*)(lds + PG8_SA(b, h) + aoff + m * 2048 + k * 1024); } while (0)
; template <class Epi, class Sched, bool ALIGN_EPI = false, bool SP2 = false>
; __device__ __forceinline__ void gemm_phase(PG8_LAS unsigned char* lds, const Gemm g, const Sched& S, const Epi& E) {
;     ...
;             PG8_LDA(At, 1, 1); PG8_STAGE(PG8_SB(1, 0), b3, voffB); PG8_STAGE(PG8_SB(1, 1), b3 + hstep, voffB); PG8_STAGE(PG8_SA(1, 0), a3, voffA);
	s_add_i32 m0, s62, 0x2000
	s_nop 0
	global_load_lds_dwordx4 v166, s[60:61]

; #define PG8_STAGE(bufoff, gbase, voff) do { _Pragma("unroll") for (int _i = 0; _i < 2; ++_i) \
;         __builtin_amdgcn_global_load_lds((const unsigned*)((const char*)(gbase) + (voff)[_i]), (PG8_LAS unsigned*)(lds + (bufoff) + ldsw + _i * 8192), 16, 0, 0); } while (0)
; #define PG8_LDA(dst, b, h) do { _Pragma("unroll") for (int m = 0; m < 4; ++m) _Pragma("unroll") for (int k = 0; k < 2; ++k) dst[m][k] = *(const PG8_LAS bf16x8*)(lds + PG8_SA(b, h) + aoff + m * 2048 + k * 1024); } while (0)
; template <class Epi, class Sched, bool ALIGN_EPI = false, bool SP2 = false>
; __device__ __forceinline__ void gemm_phase(PG8_LAS unsigned char* lds, const Gemm g, const Sched& S, const Epi& E) {
;     ...
;             PG8_LDA(At, 1, 1); PG8_STAGE(PG8_SB(1, 0), b3, voffB); PG8_STAGE(PG8_SB(1, 1), b3 + hstep, voffB); PG8_STAGE(PG8_SA(1, 0), a3, voffA);
	s_mov_b32 m0, s70
	s_nop 0
	global_load_lds_dwordx4 v252, s[98:99]

; #define PG8_STAGE(bufoff, gbase, voff) do { _Pragma("unroll") for (int _i = 0; _i < 2; ++_i) \
;         __builtin_amdgcn_global_load_lds((const unsigned*)((const char*)(gbase) + (voff)[_i]), (PG8_LAS unsigned*)(lds + (bufoff) + ldsw + _i * 8192), 16, 0, 0); } while (0)
; #define PG8_LDA(dst, b, h) do { _Pragma("unroll") for (int m = 0; m < 4; ++m) _Pragma("unroll") for (int k = 0; k < 2; ++k) dst[m][k] = *(const PG8_LAS bf16x8*)(lds + PG8_SA(b, h) + aoff + m * 2048 + k * 1024); } while (0)
; #define PG8_MMA(ai, bj, At, Bt) do { __builtin_amdgcn_s_setprio(1); _Pragma("unroll") for (int m = 0; m < 4; ++m) _Pragma("unroll") for (int n = 0; n < 2; ++n) _Pragma("unroll") for (int k = 0; k < 2; ++k) \
;         acc[ai][bj][m][n] = __builtin_amdgcn_mfma_f32_16x16x32_bf16(Bt[n][k], At[m][k], acc[ai][bj][m][n], 0, 0, 0); __builtin_amdgcn_s_setprio(0); } while (0)
; #define PG8_WAIT_V(n) asm volatile("s_waitcnt vmcnt(" #n ")" ::: "memory")
; #define PG8_WAIT_L(n) asm volatile("s_waitcnt lgkmcnt(" #n ")" ::: "memory")
; #define PG8_BAR __builtin_amdgcn_s_barrier()
; #define PG8_SCHED __builtin_amdgcn_sched_barrier(0)
; template <class Epi, class Sched, bool ALIGN_EPI = false, bool SP2 = false>
; __device__ __forceinline__ void gemm_phase(PG8_LAS unsigned char* lds, const Gemm g, const Sched& S, const Epi& E) {
;     ...
;             PG8_LDA(At, 1, 1); PG8_STAGE(PG8_SB(1, 0), b3, voffB); PG8_STAGE(PG8_SB(1, 1), b3 + hstep, voffB); PG8_STAGE(PG8_SA(1, 0), a3, voffA);
;             PG8_WAIT_V(8); PG8_WAIT_L(0); PG8_BAR; PG8_MMA(1, 0, At, B0); PG8_MMA(1, 1, At, B1); PG8_BAR; PG8_SCHED;
	s_mov_b32 m0, s71
	s_nop 0
	global_load_lds_dwordx4 v253, s[98:99]
	s_waitcnt vmcnt(8) lgkmcnt(0)


; #define PG8_MMA(ai, bj, At, Bt) do { __builtin_amdgcn_s_setprio(1); _Pragma("unroll") for (int m = 0; m < 4; ++m) _Pragma("unroll") for (int n = 0; n < 2; ++n) _Pragma("unroll") for (int k = 0; k < 2; ++k) \
;         acc[ai][bj][m][n] = __builtin_amdgcn_mfma_f32_16x16x32_bf16(Bt[n][k], At[m][k], acc[ai][bj][m][n], 0, 0, 0); __builtin_amdgcn_s_setprio(0); } while (0)
; #define PG8_WAIT_V(n) asm volatile("s_waitcnt vmcnt(" #n ")" ::: "memory")
; #define PG8_WAIT_L(n) asm volatile("s_waitcnt lgkmcnt(" #n ")" ::: "memory")
; #define PG8_BAR __builtin_amdgcn_s_barrier()
; #define PG8_SCHED __builtin_amdgcn_sched_barrier(0)
; template <class Epi, class Sched, bool ALIGN_EPI = false, bool SP2 = false>
; __device__ __forceinline__ void gemm_phase(PG8_LAS unsigned char* lds, const Gemm g, const Sched& S, const Epi& E) {
;     ...
;             PG8_WAIT_V(8); PG8_WAIT_L(0); PG8_BAR; PG8_MMA(1, 0, At, B0); PG8_MMA(1, 1, At, B1); PG8_BAR; PG8_SCHED;
	s_barrier

; #define PG8_MMA(ai, bj, At, Bt) do { __builtin_amdgcn_s_setprio(1); _Pragma("unroll") for (int m = 0; m < 4; ++m) _Pragma("unroll") for (int n = 0; n < 2; ++n) _Pragma("unroll") for (int k = 0; k < 2; ++k) \
;         acc[ai][bj][m][n] = __builtin_amdgcn_mfma_f32_16x16x32_bf16(Bt[n][k], At[m][k], acc[ai][bj][m][n], 0, 0, 0); __builtin_amdgcn_s_setprio(0); } while (0)
; #define PG8_WAIT_V(n) asm volatile("s_waitcnt vmcnt(" #n ")" ::: "memory")
; #define PG8_WAIT_L(n) asm volatile("s_waitcnt lgkmcnt(" #n ")" ::: "memory")
; #define PG8_BAR __builtin_amdgcn_s_barrier()
; #define PG8_SCHED __builtin_amdgcn_sched_barrier(0)
; template <class Epi, class Sched, bool ALIGN_EPI = false, bool SP2 = false>
; __device__ __forceinline__ void gemm_phase(PG8_LAS unsigned char* lds, const Gemm g, const Sched& S, const Epi& E) {
;     ...
;             PG8_WAIT_V(8); PG8_WAIT_L(0); PG8_BAR; PG8_MMA(1, 0, At, B0); PG8_MMA(1, 1, At, B1); PG8_BAR; PG8_SCHED;
	v_mfma_f32_16x16x32_bf16 v[60:63], v[64:67], v[176:179], v[60:63]
	v_mfma_f32_16x16x32_bf16 v[56:59], v[72:75], v[176:179], v[56:59]
	v_mfma_f32_16x16x32_bf16 v[44:47], v[64:67], v[184:187], v[44:47]
	v_mfma_f32_16x16x32_bf16 v[40:43], v[72:75], v[184:187], v[40:43]
	v_mfma_f32_16x16x32_bf16 v[28:31], v[64:67], v[192:195], v[28:31]
	v_mfma_f32_16x16x32_bf16 v[24:27], v[72:75], v[192:195], v[24:27]
	v_mfma_f32_16x16x32_bf16 v[12:15], v[64:67], v[200:203], v[12:15]
	v_mfma_f32_16x16x32_bf16 v[8:11], v[72:75], v[200:203], v[8:11]
	v_mfma_f32_16x16x32_bf16 v[60:63], v[68:71], v[180:183], v[60:63]
	v_mfma_f32_16x16x32_bf16 v[56:59], v[76:79], v[180:183], v[56:59]
	v_mfma_f32_16x16x32_bf16 v[44:47], v[68:71], v[188:191], v[44:47]
	v_mfma_f32_16x16x32_bf16 v[40:43], v[76:79], v[188:191], v[40:43]
	v_mfma_f32_16x16x32_bf16 v[28:31], v[68:71], v[196:199], v[28:31]
	v_mfma_f32_16x16x32_bf16 v[24:27], v[76:79], v[196:199], v[24:27]
	v_mfma_f32_16x16x32_bf16 v[12:15], v[68:71], v[204:207], v[12:15]
	v_mfma_f32_16x16x32_bf16 v[8:11], v[76:79], v[204:207], v[8:11]


; #define PG8_MMA(ai, bj, At, Bt) do { __builtin_amdgcn_s_setprio(1); _Pragma("unroll") for (int m = 0; m < 4; ++m) _Pragma("unroll") for (int n = 0; n < 2; ++n) _Pragma("unroll") for (int k = 0; k < 2; ++k) \
;         acc[ai][bj][m][n] = __builtin_amdgcn_mfma_f32_16x16x32_bf16(Bt[n][k], At[m][k], acc[ai][bj][m][n], 0, 0, 0); __builtin_amdgcn_s_setprio(0); } while (0)
; #define PG8_WAIT_V(n) asm volatile("s_waitcnt vmcnt(" #n ")" ::: "memory")
; #define PG8_WAIT_L(n) asm volatile("s_waitcnt lgkmcnt(" #n ")" ::: "memory")
; #define PG8_BAR __builtin_amdgcn_s_barrier()
; #define PG8_SCHED __builtin_amdgcn_sched_barrier(0)
; template <class Epi, class Sched, bool ALIGN_EPI = false, bool SP2 = false>
; __device__ __forceinline__ void gemm_phase(PG8_LAS unsigned char* lds, const Gemm g, const Sched& S, const Epi& E) {
;     ...
;             PG8_WAIT_V(8); PG8_WAIT_L(0); PG8_BAR; PG8_MMA(1, 0, At, B0); PG8_MMA(1, 1, At, B1); PG8_BAR; PG8_SCHED;
	v_mfma_f32_16x16x32_bf16 v[52:55], v[144:147], v[176:179], v[52:55]
	v_mfma_f32_16x16x32_bf16 v[48:51], v[152:155], v[176:179], v[48:51]
	v_mfma_f32_16x16x32_bf16 v[36:39], v[144:147], v[184:187], v[36:39]
	v_mfma_f32_16x16x32_bf16 v[32:35], v[152:155], v[184:187], v[32:35]
	v_mfma_f32_16x16x32_bf16 v[20:23], v[144:147], v[192:195], v[20:23]
	v_mfma_f32_16x16x32_bf16 v[16:19], v[152:155], v[192:195], v[16:19]
	v_mfma_f32_16x16x32_bf16 v[4:7], v[144:147], v[200:203], v[4:7]
	v_mfma_f32_16x16x32_bf16 v[0:3], v[152:155], v[200:203], v[0:3]
	v_mfma_f32_16x16x32_bf16 v[52:55], v[148:151], v[180:183], v[52:55]
	v_mfma_f32_16x16x32_bf16 v[48:51], v[156:159], v[180:183], v[48:51]
	v_mfma_f32_16x16x32_bf16 v[36:39], v[148:151], v[188:191], v[36:39]
	v_mfma_f32_16x16x32_bf16 v[32:35], v[156:159], v[188:191], v[32:35]
	v_mfma_f32_16x16x32_bf16 v[20:23], v[148:151], v[196:199], v[20:23]
	v_mfma_f32_16x16x32_bf16 v[16:19], v[156:159], v[196:199], v[16:19]
	v_mfma_f32_16x16x32_bf16 v[4:7], v[148:151], v[204:207], v[4:7]
	v_mfma_f32_16x16x32_bf16 v[0:3], v[156:159], v[204:207], v[0:3]

; #define PG8_STAGE(bufoff, gbase, voff) do { _Pragma("unroll") for (int _i = 0; _i < 2; ++_i) \
;         __builtin_amdgcn_global_load_lds((const unsigned*)((const char*)(gbase) + (voff)[_i]), (PG8_LAS unsigned*)(lds + (bufoff) + ldsw + _i * 8192), 16, 0, 0); } while (0)
; #define PG8_LDA(dst, b, h) do { _Pragma("unroll") for (int m = 0; m < 4; ++m) _Pragma("unroll") for (int k = 0; k < 2; ++k) dst[m][k] = *(const PG8_LAS bf16x8*)(lds + PG8_SA(b, h) + aoff + m * 2048 + k * 1024); } while (0)
; #define PG8_WAIT_V(n) asm volatile("s_waitcnt vmcnt(" #n ")" ::: "memory")
; #define PG8_WAIT_L(n) asm volatile("s_waitcnt lgkmcnt(" #n ")" ::: "memory")
; template <class Epi, class Sched, bool ALIGN_EPI = false, bool SP2 = false>
; __device__ __forceinline__ void gemm_phase(PG8_LAS unsigned char* lds, const Gemm g, const Sched& S, const Epi& E) {
;     ...
;         for (int t = 0; t < nt; t += 2) {
;             const bool last = (t == nt - 2);
;             const char* a1 = cA + (size_t)(t + 1) * kstep;
;             const char* a2 = last ? nA : cA + (size_t)(t + 2) * kstep; const char* b2 = last ? nB : cB + (size_t)(t + 2) * kstep;
;             const char* a3 = a2 + kstep; const char* b3 = b2 + kstep;
;             if (last && has_next) S.a_ready(nxt);
;             if constexpr (SP2) {
;             PG8_LDB(B0, 0, 0); PG8_LDB(B1, 0, 1); PG8_SCHED; PG8_LDA(At, 0, 0); PG8_STAGE(PG8_SA(1, 1), a1 + hstep, voffA);
;             PG8_WAIT_V(8); PG8_WAIT_L(0); PG8_BAR; PG8_MMA(0, 0, At, B0); PG8_MMA(0, 1, At, B1); PG8_BAR; PG8_SCHED;
;             PG8_LDA(At, 0, 1); PG8_STAGE(PG8_SB(0, 0), b2, voffB); PG8_STAGE(PG8_SB(0, 1), b2 + hstep, voffB); PG8_STAGE(PG8_SA(0, 0), a2, voffA);
;             PG8_WAIT_V(8); PG8_WAIT_L(0); PG8_BAR; PG8_MMA(1, 0, At, B0); PG8_MMA(1, 1, At, B1); PG8_BAR; PG8_SCHED;
;             PG8_LDB(B0, 1, 0); PG8_LDB(B1, 1, 1); PG8_SCHED; PG8_LDA(At, 1, 0); PG8_STAGE(PG8_SA(0, 1), a2 + hstep, voffA);
;             PG8_WAIT_V(8); PG8_WAIT_L(0); PG8_BAR; PG8_MMA(0, 0, At, B0); PG8_MMA(0, 1, At, B1); PG8_BAR; PG8_SCHED;
;             PG8_LDA(At, 1, 1); PG8_STAGE(PG8_SB(1, 0), b3, voffB); PG8_STAGE(PG8_SB(1, 1), b3 + hstep, voffB); PG8_STAGE(PG8_SA(1, 0), a3, voffA);
;             PG8_WAIT_V(8); PG8_WAIT_L(0); PG8_BAR; PG8_MMA(1, 0, At, B0); PG8_MMA(1, 1, At, B1); PG8_BAR; PG8_SCHED;
;     ...
;         if constexpr (ALIGN_EPI) { if (wr == 0) PG8_BAR; }
	s_barrier
	s_add_i32 s81, s81, 2
	s_add_u32 s58, s58, 0x100
	s_addc_u32 s59, s59, 0
	s_add_u32 s79, s79, 0x100
	s_addc_u32 s80, s80, 0
	s_cmp_gt_u32 s81, 29
	s_cbranch_scc0 .LBB0_333
	s_and_b64 vcc, exec, s[42:43]
	s_cbranch_vccz .LBB0_336
	s_barrier

; #define PG8_STAGE(bufoff, gbase, voff) do { _Pragma("unroll") for (int _i = 0; _i < 2; ++_i) \
;         __builtin_amdgcn_global_load_lds((const unsigned*)((const char*)(gbase) + (voff)[_i]), (PG8_LAS unsigned*)(lds + (bufoff) + ldsw + _i * 8192), 16, 0, 0); } while (0)
; #define PG8_LDA(dst, b, h) do { _Pragma("unroll") for (int m = 0; m < 4; ++m) _Pragma("unroll") for (int k = 0; k < 2; ++k) dst[m][k] = *(const PG8_LAS bf16x8*)(lds + PG8_SA(b, h) + aoff + m * 2048 + k * 1024); } while (0)
; #define PG8_LDB(dst, b, h) do { _Pragma("unroll") for (int n = 0; n < 2; ++n) _Pragma("unroll") for (int k = 0; k < 2; ++k) dst[n][k] = *(const PG8_LAS bf16x8*)(lds + PG8_SB(b, h) + boff + n * 2048 + k * 1024); } while (0)
; #define PG8_SCHED __builtin_amdgcn_sched_barrier(0)
; template <class Epi, class Sched, bool ALIGN_EPI = false, bool SP2 = false>
; __device__ __forceinline__ void gemm_phase(PG8_LAS unsigned char* lds, const Gemm g, const Sched& S, const Epi& E) {
;     ...
;             const char* a1 = cA + (size_t)(t + 1) * kstep;
;             const char* a2 = last ? nA : cA + (size_t)(t + 2) * kstep; const char* b2 = last ? nB : cB + (size_t)(t + 2) * kstep;
;             const char* a3 = a2 + kstep; const char* b3 = b2 + kstep;
;             if (last && has_next) S.a_ready(nxt);
;             if constexpr (SP2) {
;             PG8_LDB(B0, 0, 0); PG8_LDB(B1, 0, 1); PG8_SCHED; PG8_LDA(At, 0, 0); PG8_STAGE(PG8_SA(1, 1), a1 + hstep, voffA);
.LBB0_428:
	ds_read_b128 v[128:131], v201
	ds_read_b128 v[132:135], v201 offset:1024
	ds_read_b128 v[136:139], v201 offset:2048
	ds_read_b128 v[140:143], v201 offset:3072
	ds_read_b128 v[144:147], v205
	ds_read_b128 v[148:151], v205 offset:1024
	ds_read_b128 v[152:155], v205 offset:2048
	ds_read_b128 v[156:159], v205 offset:3072
	s_add_u32 s12, s10, 0xfff80080
	s_addc_u32 s13, s11, -1
	s_cmp_eq_u32 s85, 28
	s_cselect_b32 s61, s55, s13
	s_cselect_b32 s60, s81, s12
	s_cselect_b32 s13, s53, s84
	s_cselect_b32 s12, s82, s83

; #define PG8_STAGE(bufoff, gbase, voff) do { _Pragma("unroll") for (int _i = 0; _i < 2; ++_i) \
;         __builtin_amdgcn_global_load_lds((const unsigned*)((const char*)(gbase) + (voff)[_i]), (PG8_LAS unsigned*)(lds + (bufoff) + ldsw + _i * 8192), 16, 0, 0); } while (0)
; #define PG8_LDA(dst, b, h) do { _Pragma("unroll") for (int m = 0; m < 4; ++m) _Pragma("unroll") for (int k = 0; k < 2; ++k) dst[m][k] = *(const PG8_LAS bf16x8*)(lds + PG8_SA(b, h) + aoff + m * 2048 + k * 1024); } while (0)
; #define PG8_LDB(dst, b, h) do { _Pragma("unroll") for (int n = 0; n < 2; ++n) _Pragma("unroll") for (int k = 0; k < 2; ++k) dst[n][k] = *(const PG8_LAS bf16x8*)(lds + PG8_SB(b, h) + boff + n * 2048 + k * 1024); } while (0)
; #define PG8_SCHED __builtin_amdgcn_sched_barrier(0)
; template <class Epi, class Sched, bool ALIGN_EPI = false, bool SP2 = false>
; __device__ __forceinline__ void gemm_phase(PG8_LAS unsigned char* lds, const Gemm g, const Sched& S, const Epi& E) {
;     ...
;             PG8_LDB(B0, 0, 0); PG8_LDB(B1, 0, 1); PG8_SCHED; PG8_LDA(At, 0, 0); PG8_STAGE(PG8_SA(1, 1), a1 + hstep, voffA);
	s_add_i32 m0, s65, 0xc000
	ds_read_b128 v[176:179], v207
	ds_read_b128 v[184:187], v207 offset:1024
	ds_read_b128 v[190:193], v207 offset:2048
	ds_read_b128 v[210:213], v207 offset:3072
	ds_read_b128 v[214:217], v207 offset:4096
	ds_read_b128 v[218:221], v207 offset:5120
	ds_read_b128 v[222:225], v207 offset:6144
	ds_read_b128 v[226:229], v207 offset:7168
	global_load_lds_dwordx4 v168, s[10:11]

; #define PG8_STAGE(bufoff, gbase, voff) do { _Pragma("unroll") for (int _i = 0; _i < 2; ++_i) \
;         __builtin_amdgcn_global_load_lds((const unsigned*)((const char*)(gbase) + (voff)[_i]), (PG8_LAS unsigned*)(lds + (bufoff) + ldsw + _i * 8192), 16, 0, 0); } while (0)
; #define PG8_LDA(dst, b, h) do { _Pragma("unroll") for (int m = 0; m < 4; ++m) _Pragma("unroll") for (int k = 0; k < 2; ++k) dst[m][k] = *(const PG8_LAS bf16x8*)(lds + PG8_SA(b, h) + aoff + m * 2048 + k * 1024); } while (0)
; #define PG8_LDB(dst, b, h) do { _Pragma("unroll") for (int n = 0; n < 2; ++n) _Pragma("unroll") for (int k = 0; k < 2; ++k) dst[n][k] = *(const PG8_LAS bf16x8*)(lds + PG8_SB(b, h) + boff + n * 2048 + k * 1024); } while (0)
; #define PG8_MMA(ai, bj, At, Bt) do { __builtin_amdgcn_s_setprio(1); _Pragma("unroll") for (int m = 0; m < 4; ++m) _Pragma("unroll") for (int n = 0; n < 2; ++n) _Pragma("unroll") for (int k = 0; k < 2; ++k) \
;         acc[ai][bj][m][n] = __builtin_amdgcn_mfma_f32_16x16x32_bf16(Bt[n][k], At[m][k], acc[ai][bj][m][n], 0, 0, 0); __builtin_amdgcn_s_setprio(0); } while (0)
; #define PG8_WAIT_V(n) asm volatile("s_waitcnt vmcnt(" #n ")" ::: "memory")
; #define PG8_WAIT_L(n) asm volatile("s_waitcnt lgkmcnt(" #n ")" ::: "memory")
; #define PG8_BAR __builtin_amdgcn_s_barrier()
; #define PG8_SCHED __builtin_amdgcn_sched_barrier(0)
; template <class Epi, class Sched, bool ALIGN_EPI = false, bool SP2 = false>
; __device__ __forceinline__ void gemm_phase(PG8_LAS unsigned char* lds, const Gemm g, const Sched& S, const Epi& E) {
;     ...
;             PG8_LDB(B0, 0, 0); PG8_LDB(B1, 0, 1); PG8_SCHED; PG8_LDA(At, 0, 0); PG8_STAGE(PG8_SA(1, 1), a1 + hstep, voffA);
;             PG8_WAIT_V(8); PG8_WAIT_L(0); PG8_BAR; PG8_MMA(0, 0, At, B0); PG8_MMA(0, 1, At, B1); PG8_BAR; PG8_SCHED;
	s_add_i32 m0, s65, 0xe000
	s_nop 0
	global_load_lds_dwordx4 v170, s[10:11]
	s_waitcnt vmcnt(8) lgkmcnt(0)


; #define PG8_MMA(ai, bj, At, Bt) do { __builtin_amdgcn_s_setprio(1); _Pragma("unroll") for (int m = 0; m < 4; ++m) _Pragma("unroll") for (int n = 0; n < 2; ++n) _Pragma("unroll") for (int k = 0; k < 2; ++k) \
;         acc[ai][bj][m][n] = __builtin_amdgcn_mfma_f32_16x16x32_bf16(Bt[n][k], At[m][k], acc[ai][bj][m][n], 0, 0, 0); __builtin_amdgcn_s_setprio(0); } while (0)
; #define PG8_WAIT_V(n) asm volatile("s_waitcnt vmcnt(" #n ")" ::: "memory")
; #define PG8_WAIT_L(n) asm volatile("s_waitcnt lgkmcnt(" #n ")" ::: "memory")
; #define PG8_BAR __builtin_amdgcn_s_barrier()
; #define PG8_SCHED __builtin_amdgcn_sched_barrier(0)
; template <class Epi, class Sched, bool ALIGN_EPI = false, bool SP2 = false>
; __device__ __forceinline__ void gemm_phase(PG8_LAS unsigned char* lds, const Gemm g, const Sched& S, const Epi& E) {
;     ...
;             PG8_WAIT_V(8); PG8_WAIT_L(0); PG8_BAR; PG8_MMA(0, 0, At, B0); PG8_MMA(0, 1, At, B1); PG8_BAR; PG8_SCHED;
	s_barrier

; #define PG8_MMA(ai, bj, At, Bt) do { __builtin_amdgcn_s_setprio(1); _Pragma("unroll") for (int m = 0; m < 4; ++m) _Pragma("unroll") for (int n = 0; n < 2; ++n) _Pragma("unroll") for (int k = 0; k < 2; ++k) \
;         acc[ai][bj][m][n] = __builtin_amdgcn_mfma_f32_16x16x32_bf16(Bt[n][k], At[m][k], acc[ai][bj][m][n], 0, 0, 0); __builtin_amdgcn_s_setprio(0); } while (0)
; #define PG8_WAIT_V(n) asm volatile("s_waitcnt vmcnt(" #n ")" ::: "memory")
; #define PG8_WAIT_L(n) asm volatile("s_waitcnt lgkmcnt(" #n ")" ::: "memory")
; #define PG8_BAR __builtin_amdgcn_s_barrier()
; #define PG8_SCHED __builtin_amdgcn_sched_barrier(0)
; template <class Epi, class Sched, bool ALIGN_EPI = false, bool SP2 = false>
; __device__ __forceinline__ void gemm_phase(PG8_LAS unsigned char* lds, const Gemm g, const Sched& S, const Epi& E) {
;     ...
;             PG8_WAIT_V(8); PG8_WAIT_L(0); PG8_BAR; PG8_MMA(0, 0, At, B0); PG8_MMA(0, 1, At, B1); PG8_BAR; PG8_SCHED;
	v_mfma_f32_16x16x32_bf16 v[124:127], v[128:131], v[176:179], v[124:127]
	v_mfma_f32_16x16x32_bf16 v[120:123], v[136:139], v[176:179], v[120:123]
	v_mfma_f32_16x16x32_bf16 v[108:111], v[128:131], v[190:193], v[108:111]
	v_mfma_f32_16x16x32_bf16 v[104:107], v[136:139], v[190:193], v[104:107]
	v_mfma_f32_16x16x32_bf16 v[92:95], v[128:131], v[214:217], v[92:95]
	v_mfma_f32_16x16x32_bf16 v[88:91], v[136:139], v[214:217], v[88:91]
	v_mfma_f32_16x16x32_bf16 v[76:79], v[128:131], v[222:225], v[76:79]
	v_mfma_f32_16x16x32_bf16 v[72:75], v[136:139], v[222:225], v[72:75]
	v_mfma_f32_16x16x32_bf16 v[124:127], v[132:135], v[184:187], v[124:127]
	v_mfma_f32_16x16x32_bf16 v[120:123], v[140:143], v[184:187], v[120:123]
	v_mfma_f32_16x16x32_bf16 v[108:111], v[132:135], v[210:213], v[108:111]
	v_mfma_f32_16x16x32_bf16 v[104:107], v[140:143], v[210:213], v[104:107]
	v_mfma_f32_16x16x32_bf16 v[92:95], v[132:135], v[218:221], v[92:95]
	v_mfma_f32_16x16x32_bf16 v[88:91], v[140:143], v[218:221], v[88:91]
	v_mfma_f32_16x16x32_bf16 v[76:79], v[132:135], v[226:229], v[76:79]
	v_mfma_f32_16x16x32_bf16 v[72:75], v[140:143], v[226:229], v[72:75]


; #define PG8_MMA(ai, bj, At, Bt) do { __builtin_amdgcn_s_setprio(1); _Pragma("unroll") for (int m = 0; m < 4; ++m) _Pragma("unroll") for (int n = 0; n < 2; ++n) _Pragma("unroll") for (int k = 0; k < 2; ++k) \
;         acc[ai][bj][m][n] = __builtin_amdgcn_mfma_f32_16x16x32_bf16(Bt[n][k], At[m][k], acc[ai][bj][m][n], 0, 0, 0); __builtin_amdgcn_s_setprio(0); } while (0)
; #define PG8_WAIT_V(n) asm volatile("s_waitcnt vmcnt(" #n ")" ::: "memory")
; #define PG8_WAIT_L(n) asm volatile("s_waitcnt lgkmcnt(" #n ")" ::: "memory")
; #define PG8_BAR __builtin_amdgcn_s_barrier()
; #define PG8_SCHED __builtin_amdgcn_sched_barrier(0)
; template <class Epi, class Sched, bool ALIGN_EPI = false, bool SP2 = false>
; __device__ __forceinline__ void gemm_phase(PG8_LAS unsigned char* lds, const Gemm g, const Sched& S, const Epi& E) {
;     ...
;             PG8_WAIT_V(8); PG8_WAIT_L(0); PG8_BAR; PG8_MMA(0, 0, At, B0); PG8_MMA(0, 1, At, B1); PG8_BAR; PG8_SCHED;
	v_mfma_f32_16x16x32_bf16 v[116:119], v[144:147], v[176:179], v[116:119]
	v_mfma_f32_16x16x32_bf16 v[112:115], v[152:155], v[176:179], v[112:115]
	v_mfma_f32_16x16x32_bf16 v[100:103], v[144:147], v[190:193], v[100:103]
	v_mfma_f32_16x16x32_bf16 v[96:99], v[152:155], v[190:193], v[96:99]
	v_mfma_f32_16x16x32_bf16 v[84:87], v[144:147], v[214:217], v[84:87]
	v_mfma_f32_16x16x32_bf16 v[80:83], v[152:155], v[214:217], v[80:83]
	v_mfma_f32_16x16x32_bf16 v[68:71], v[144:147], v[222:225], v[68:71]
	v_mfma_f32_16x16x32_bf16 v[64:67], v[152:155], v[222:225], v[64:67]
	v_mfma_f32_16x16x32_bf16 v[116:119], v[148:151], v[184:187], v[116:119]
	v_mfma_f32_16x16x32_bf16 v[112:115], v[156:159], v[184:187], v[112:115]
	v_mfma_f32_16x16x32_bf16 v[100:103], v[148:151], v[210:213], v[100:103]
	v_mfma_f32_16x16x32_bf16 v[96:99], v[156:159], v[210:213], v[96:99]
	v_mfma_f32_16x16x32_bf16 v[84:87], v[148:151], v[218:221], v[84:87]
	v_mfma_f32_16x16x32_bf16 v[80:83], v[156:159], v[218:221], v[80:83]
	v_mfma_f32_16x16x32_bf16 v[68:71], v[148:151], v[226:229], v[68:71]
	v_mfma_f32_16x16x32_bf16 v[64:67], v[156:159], v[226:229], v[64:67]

; #define PG8_STAGE(bufoff, gbase, voff) do { _Pragma("unroll") for (int _i = 0; _i < 2; ++_i) \
;         __builtin_amdgcn_global_load_lds((const unsigned*)((const char*)(gbase) + (voff)[_i]), (PG8_LAS unsigned*)(lds + (bufoff) + ldsw + _i * 8192), 16, 0, 0); } while (0)
; #define PG8_LDA(dst, b, h) do { _Pragma("unroll") for (int m = 0; m < 4; ++m) _Pragma("unroll") for (int k = 0; k < 2; ++k) dst[m][k] = *(const PG8_LAS bf16x8*)(lds + PG8_SA(b, h) + aoff + m * 2048 + k * 1024); } while (0)
; #define PG8_MMA(ai, bj, At, Bt) do { __builtin_amdgcn_s_setprio(1); _Pragma("unroll") for (int m = 0; m < 4; ++m) _Pragma("unroll") for (int n = 0; n < 2; ++n) _Pragma("unroll") for (int k = 0; k < 2; ++k) \
;         acc[ai][bj][m][n] = __builtin_amdgcn_mfma_f32_16x16x32_bf16(Bt[n][k], At[m][k], acc[ai][bj][m][n], 0, 0, 0); __builtin_amdgcn_s_setprio(0); } while (0)
; #define PG8_WAIT_V(n) asm volatile("s_waitcnt vmcnt(" #n ")" ::: "memory")
; #define PG8_WAIT_L(n) asm volatile("s_waitcnt lgkmcnt(" #n ")" ::: "memory")
; #define PG8_BAR __builtin_amdgcn_s_barrier()
; #define PG8_SCHED __builtin_amdgcn_sched_barrier(0)
; template <class Epi, class Sched, bool ALIGN_EPI = false, bool SP2 = false>
; __device__ __forceinline__ void gemm_phase(PG8_LAS unsigned char* lds, const Gemm g, const Sched& S, const Epi& E) {
;     ...
;             PG8_WAIT_V(8); PG8_WAIT_L(0); PG8_BAR; PG8_MMA(0, 0, At, B0); PG8_MMA(0, 1, At, B1); PG8_BAR; PG8_SCHED;
;             PG8_LDA(At, 0, 1); PG8_STAGE(PG8_SB(0, 0), b2, voffB); PG8_STAGE(PG8_SB(0, 1), b2 + hstep, voffB); PG8_STAGE(PG8_SA(0, 0), a2, voffA);
	s_barrier
	s_add_i32 s86, s75, s64
	s_mov_b64 s[96:97], s[12:13]

; #define PG8_STAGE(bufoff, gbase, voff) do { _Pragma("unroll") for (int _i = 0; _i < 2; ++_i) \
;         __builtin_amdgcn_global_load_lds((const unsigned*)((const char*)(gbase) + (voff)[_i]), (PG8_LAS unsigned*)(lds + (bufoff) + ldsw + _i * 8192), 16, 0, 0); } while (0)
; #define PG8_LDA(dst, b, h) do { _Pragma("unroll") for (int m = 0; m < 4; ++m) _Pragma("unroll") for (int k = 0; k < 2; ++k) dst[m][k] = *(const PG8_LAS bf16x8*)(lds + PG8_SA(b, h) + aoff + m * 2048 + k * 1024); } while (0)
; template <class Epi, class Sched, bool ALIGN_EPI = false, bool SP2 = false>
; __device__ __forceinline__ void gemm_phase(PG8_LAS unsigned char* lds, const Gemm g, const Sched& S, const Epi& E) {
;     ...
;             PG8_LDA(At, 0, 1); PG8_STAGE(PG8_SB(0, 0), b2, voffB); PG8_STAGE(PG8_SB(0, 1), b2 + hstep, voffB); PG8_STAGE(PG8_SA(0, 0), a2, voffA);
	s_mov_b32 m0, s86
	ds_read_b128 v[176:179], v207 offset:16384
	ds_read_b128 v[184:187], v207 offset:17408
	ds_read_b128 v[190:193], v207 offset:18432
	ds_read_b128 v[210:213], v207 offset:19456
	ds_read_b128 v[214:217], v207 offset:20480
	ds_read_b128 v[218:221], v207 offset:21504
	ds_read_b128 v[222:225], v207 offset:22528
	ds_read_b128 v[226:229], v207 offset:23552
	global_load_lds_dwordx4 v162, s[12:13]
	s_add_i32 m0, s86, 0x2000
	s_add_u32 s86, s12, 0x80000

; #define PG8_STAGE(bufoff, gbase, voff) do { _Pragma("unroll") for (int _i = 0; _i < 2; ++_i) \
;         __builtin_amdgcn_global_load_lds((const unsigned*)((const char*)(gbase) + (voff)[_i]), (PG8_LAS unsigned*)(lds + (bufoff) + ldsw + _i * 8192), 16, 0, 0); } while (0)
; #define PG8_LDA(dst, b, h) do { _Pragma("unroll") for (int m = 0; m < 4; ++m) _Pragma("unroll") for (int k = 0; k < 2; ++k) dst[m][k] = *(const PG8_LAS bf16x8*)(lds + PG8_SA(b, h) + aoff + m * 2048 + k * 1024); } while (0)
; template <class Epi, class Sched, bool ALIGN_EPI = false, bool SP2 = false>
; __device__ __forceinline__ void gemm_phase(PG8_LAS unsigned char* lds, const Gemm g, const Sched& S, const Epi& E) {
;     ...
;             PG8_LDA(At, 0, 1); PG8_STAGE(PG8_SB(0, 0), b2, voffB); PG8_STAGE(PG8_SB(0, 1), b2 + hstep, voffB); PG8_STAGE(PG8_SA(0, 0), a2, voffA);
	s_addc_u32 s87, s13, 0
	s_add_i32 s88, s76, s64
	global_load_lds_dwordx4 v166, s[12:13]

; #define PG8_STAGE(bufoff, gbase, voff) do { _Pragma("unroll") for (int _i = 0; _i < 2; ++_i) \
;         __builtin_amdgcn_global_load_lds((const unsigned*)((const char*)(gbase) + (voff)[_i]), (PG8_LAS unsigned*)(lds + (bufoff) + ldsw + _i * 8192), 16, 0, 0); } while (0)
; #define PG8_LDA(dst, b, h) do { _Pragma("unroll") for (int m = 0; m < 4; ++m) _Pragma("unroll") for (int k = 0; k < 2; ++k) dst[m][k] = *(const PG8_LAS bf16x8*)(lds + PG8_SA(b, h) + aoff + m * 2048 + k * 1024); } while (0)
; template <class Epi, class Sched, bool ALIGN_EPI = false, bool SP2 = false>
; __device__ __forceinline__ void gemm_phase(PG8_LAS unsigned char* lds, const Gemm g, const Sched& S, const Epi& E) {
;     ...
;             PG8_LDA(At, 0, 1); PG8_STAGE(PG8_SB(0, 0), b2, voffB); PG8_STAGE(PG8_SB(0, 1), b2 + hstep, voffB); PG8_STAGE(PG8_SA(0, 0), a2, voffA);
	s_mov_b32 m0, s88
	s_nop 0
	global_load_lds_dwordx4 v162, s[86:87]

; #define PG8_STAGE(bufoff, gbase, voff) do { _Pragma("unroll") for (int _i = 0; _i < 2; ++_i) \
;         __builtin_amdgcn_global_load_lds((const unsigned*)((const char*)(gbase) + (voff)[_i]), (PG8_LAS unsigned*)(lds + (bufoff) + ldsw + _i * 8192), 16, 0, 0); } while (0)
; #define PG8_LDA(dst, b, h) do { _Pragma("unroll") for (int m = 0; m < 4; ++m) _Pragma("unroll") for (int k = 0; k < 2; ++k) dst[m][k] = *(const PG8_LAS bf16x8*)(lds + PG8_SA(b, h) + aoff + m * 2048 + k * 1024); } while (0)
; template <class Epi, class Sched, bool ALIGN_EPI = false, bool SP2 = false>
; __device__ __forceinline__ void gemm_phase(PG8_LAS unsigned char* lds, const Gemm g, const Sched& S, const Epi& E) {
;     ...
;             PG8_LDA(At, 0, 1); PG8_STAGE(PG8_SB(0, 0), b2, voffB); PG8_STAGE(PG8_SB(0, 1), b2 + hstep, voffB); PG8_STAGE(PG8_SA(0, 0), a2, voffA);
	s_add_i32 m0, s88, 0x2000
	s_nop 0
	global_load_lds_dwordx4 v166, s[86:87]
	s_mov_b64 s[98:99], s[60:61]

; #define PG8_STAGE(bufoff, gbase, voff) do { _Pragma("unroll") for (int _i = 0; _i < 2; ++_i) \
;         __builtin_amdgcn_global_load_lds((const unsigned*)((const char*)(gbase) + (voff)[_i]), (PG8_LAS unsigned*)(lds + (bufoff) + ldsw + _i * 8192), 16, 0, 0); } while (0)
; #define PG8_LDA(dst, b, h) do { _Pragma("unroll") for (int m = 0; m < 4; ++m) _Pragma("unroll") for (int k = 0; k < 2; ++k) dst[m][k] = *(const PG8_LAS bf16x8*)(lds + PG8_SA(b, h) + aoff + m * 2048 + k * 1024); } while (0)
; #define PG8_MMA(ai, bj, At, Bt) do { __builtin_amdgcn_s_setprio(1); _Pragma("unroll") for (int m = 0; m < 4; ++m) _Pragma("unroll") for (int n = 0; n < 2; ++n) _Pragma("unroll") for (int k = 0; k < 2; ++k) \
;         acc[ai][bj][m][n] = __builtin_amdgcn_mfma_f32_16x16x32_bf16(Bt[n][k], At[m][k], acc[ai][bj][m][n], 0, 0, 0); __builtin_amdgcn_s_setprio(0); } while (0)
; #define PG8_WAIT_V(n) asm volatile("s_waitcnt vmcnt(" #n ")" ::: "memory")
; #define PG8_WAIT_L(n) asm volatile("s_waitcnt lgkmcnt(" #n ")" ::: "memory")
; #define PG8_BAR __builtin_amdgcn_s_barrier()
; #define PG8_SCHED __builtin_amdgcn_sched_barrier(0)
; template <class Epi, class Sched, bool ALIGN_EPI = false, bool SP2 = false>
; __device__ __forceinline__ void gemm_phase(PG8_LAS unsigned char* lds, const Gemm g, const Sched& S, const Epi& E) {
;     ...
;             PG8_LDA(At, 0, 1); PG8_STAGE(PG8_SB(0, 0), b2, voffB); PG8_STAGE(PG8_SB(0, 1), b2 + hstep, voffB); PG8_STAGE(PG8_SA(0, 0), a2, voffA);
;             PG8_WAIT_V(8); PG8_WAIT_L(0); PG8_BAR; PG8_MMA(1, 0, At, B0); PG8_MMA(1, 1, At, B1); PG8_BAR; PG8_SCHED;
	s_mov_b32 m0, s65
	s_nop 0
	global_load_lds_dwordx4 v160, s[60:61]
	s_mov_b32 m0, s67
	s_nop 0
	global_load_lds_dwordx4 v164, s[60:61]
	s_waitcnt vmcnt(8) lgkmcnt(0)


; #define PG8_MMA(ai, bj, At, Bt) do { __builtin_amdgcn_s_setprio(1); _Pragma("unroll") for (int m = 0; m < 4; ++m) _Pragma("unroll") for (int n = 0; n < 2; ++n) _Pragma("unroll") for (int k = 0; k < 2; ++k) \
;         acc[ai][bj][m][n] = __builtin_amdgcn_mfma_f32_16x16x32_bf16(Bt[n][k], At[m][k], acc[ai][bj][m][n], 0, 0, 0); __builtin_amdgcn_s_setprio(0); } while (0)
; #define PG8_WAIT_V(n) asm volatile("s_waitcnt vmcnt(" #n ")" ::: "memory")
; #define PG8_WAIT_L(n) asm volatile("s_waitcnt lgkmcnt(" #n ")" ::: "memory")
; #define PG8_BAR __builtin_amdgcn_s_barrier()
; #define PG8_SCHED __builtin_amdgcn_sched_barrier(0)
; template <class Epi, class Sched, bool ALIGN_EPI = false, bool SP2 = false>
; __device__ __forceinline__ void gemm_phase(PG8_LAS unsigned char* lds, const Gemm g, const Sched& S, const Epi& E) {
;     ...
;             PG8_WAIT_V(8); PG8_WAIT_L(0); PG8_BAR; PG8_MMA(1, 0, At, B0); PG8_MMA(1, 1, At, B1); PG8_BAR; PG8_SCHED;
	s_barrier

; #define PG8_MMA(ai, bj, At, Bt) do { __builtin_amdgcn_s_setprio(1); _Pragma("unroll") for (int m = 0; m < 4; ++m) _Pragma("unroll") for (int n = 0; n < 2; ++n) _Pragma("unroll") for (int k = 0; k < 2; ++k) \
;         acc[ai][bj][m][n] = __builtin_amdgcn_mfma_f32_16x16x32_bf16(Bt[n][k], At[m][k], acc[ai][bj][m][n], 0, 0, 0); __builtin_amdgcn_s_setprio(0); } while (0)
; #define PG8_WAIT_V(n) asm volatile("s_waitcnt vmcnt(" #n ")" ::: "memory")
; #define PG8_WAIT_L(n) asm volatile("s_waitcnt lgkmcnt(" #n ")" ::: "memory")
; #define PG8_BAR __builtin_amdgcn_s_barrier()
; #define PG8_SCHED __builtin_amdgcn_sched_barrier(0)
; template <class Epi, class Sched, bool ALIGN_EPI = false, bool SP2 = false>
; __device__ __forceinline__ void gemm_phase(PG8_LAS unsigned char* lds, const Gemm g, const Sched& S, const Epi& E) {
;     ...
;             PG8_WAIT_V(8); PG8_WAIT_L(0); PG8_BAR; PG8_MMA(1, 0, At, B0); PG8_MMA(1, 1, At, B1); PG8_BAR; PG8_SCHED;
	v_mfma_f32_16x16x32_bf16 v[60:63], v[128:131], v[176:179], v[60:63]
	v_mfma_f32_16x16x32_bf16 v[56:59], v[136:139], v[176:179], v[56:59]
	v_mfma_f32_16x16x32_bf16 v[44:47], v[128:131], v[190:193], v[44:47]
	v_mfma_f32_16x16x32_bf16 v[40:43], v[136:139], v[190:193], v[40:43]
	v_mfma_f32_16x16x32_bf16 v[28:31], v[128:131], v[214:217], v[28:31]
	v_mfma_f32_16x16x32_bf16 v[24:27], v[136:139], v[214:217], v[24:27]
	v_mfma_f32_16x16x32_bf16 v[12:15], v[128:131], v[222:225], v[12:15]
	v_mfma_f32_16x16x32_bf16 v[8:11], v[136:139], v[222:225], v[8:11]
	v_mfma_f32_16x16x32_bf16 v[60:63], v[132:135], v[184:187], v[60:63]
	v_mfma_f32_16x16x32_bf16 v[56:59], v[140:143], v[184:187], v[56:59]
	v_mfma_f32_16x16x32_bf16 v[44:47], v[132:135], v[210:213], v[44:47]
	v_mfma_f32_16x16x32_bf16 v[40:43], v[140:143], v[210:213], v[40:43]
	v_mfma_f32_16x16x32_bf16 v[28:31], v[132:135], v[218:221], v[28:31]
	v_mfma_f32_16x16x32_bf16 v[24:27], v[140:143], v[218:221], v[24:27]
	v_mfma_f32_16x16x32_bf16 v[12:15], v[132:135], v[226:229], v[12:15]
	v_mfma_f32_16x16x32_bf16 v[8:11], v[140:143], v[226:229], v[8:11]


; #define PG8_MMA(ai, bj, At, Bt) do { __builtin_amdgcn_s_setprio(1); _Pragma("unroll") for (int m = 0; m < 4; ++m) _Pragma("unroll") for (int n = 0; n < 2; ++n) _Pragma("unroll") for (int k = 0; k < 2; ++k) \
;         acc[ai][bj][m][n] = __builtin_amdgcn_mfma_f32_16x16x32_bf16(Bt[n][k], At[m][k], acc[ai][bj][m][n], 0, 0, 0); __builtin_amdgcn_s_setprio(0); } while (0)
; #define PG8_WAIT_V(n) asm volatile("s_waitcnt vmcnt(" #n ")" ::: "memory")
; #define PG8_WAIT_L(n) asm volatile("s_waitcnt lgkmcnt(" #n ")" ::: "memory")
; #define PG8_BAR __builtin_amdgcn_s_barrier()
; #define PG8_SCHED __builtin_amdgcn_sched_barrier(0)
; template <class Epi, class Sched, bool ALIGN_EPI = false, bool SP2 = false>
; __device__ __forceinline__ void gemm_phase(PG8_LAS unsigned char* lds, const Gemm g, const Sched& S, const Epi& E) {
;     ...
;             PG8_WAIT_V(8); PG8_WAIT_L(0); PG8_BAR; PG8_MMA(1, 0, At, B0); PG8_MMA(1, 1, At, B1); PG8_BAR; PG8_SCHED;
	v_mfma_f32_16x16x32_bf16 v[52:55], v[144:147], v[176:179], v[52:55]
	v_mfma_f32_16x16x32_bf16 v[48:51], v[152:155], v[176:179], v[48:51]
	v_mfma_f32_16x16x32_bf16 v[36:39], v[144:147], v[190:193], v[36:39]
	v_mfma_f32_16x16x32_bf16 v[32:35], v[152:155], v[190:193], v[32:35]
	v_mfma_f32_16x16x32_bf16 v[20:23], v[144:147], v[214:217], v[20:23]
	v_mfma_f32_16x16x32_bf16 v[16:19], v[152:155], v[214:217], v[16:19]
	v_mfma_f32_16x16x32_bf16 v[4:7], v[144:147], v[222:225], v[4:7]
	v_mfma_f32_16x16x32_bf16 v[0:3], v[152:155], v[222:225], v[0:3]
	v_mfma_f32_16x16x32_bf16 v[52:55], v[148:151], v[184:187], v[52:55]
	v_mfma_f32_16x16x32_bf16 v[48:51], v[156:159], v[184:187], v[48:51]
	v_mfma_f32_16x16x32_bf16 v[36:39], v[148:151], v[210:213], v[36:39]
	v_mfma_f32_16x16x32_bf16 v[32:35], v[156:159], v[210:213], v[32:35]
	v_mfma_f32_16x16x32_bf16 v[20:23], v[148:151], v[218:221], v[20:23]
	v_mfma_f32_16x16x32_bf16 v[16:19], v[156:159], v[218:221], v[16:19]
	v_mfma_f32_16x16x32_bf16 v[4:7], v[148:151], v[226:229], v[4:7]
	v_mfma_f32_16x16x32_bf16 v[0:3], v[156:159], v[226:229], v[0:3]

; #define PG8_STAGE(bufoff, gbase, voff) do { _Pragma("unroll") for (int _i = 0; _i < 2; ++_i) \
;         __builtin_amdgcn_global_load_lds((const unsigned*)((const char*)(gbase) + (voff)[_i]), (PG8_LAS unsigned*)(lds + (bufoff) + ldsw + _i * 8192), 16, 0, 0); } while (0)
; #define PG8_LDA(dst, b, h) do { _Pragma("unroll") for (int m = 0; m < 4; ++m) _Pragma("unroll") for (int k = 0; k < 2; ++k) dst[m][k] = *(const PG8_LAS bf16x8*)(lds + PG8_SA(b, h) + aoff + m * 2048 + k * 1024); } while (0)
; #define PG8_MMA(ai, bj, At, Bt) do { __builtin_amdgcn_s_setprio(1); _Pragma("unroll") for (int m = 0; m < 4; ++m) _Pragma("unroll") for (int n = 0; n < 2; ++n) _Pragma("unroll") for (int k = 0; k < 2; ++k) \
;         acc[ai][bj][m][n] = __builtin_amdgcn_mfma_f32_16x16x32_bf16(Bt[n][k], At[m][k], acc[ai][bj][m][n], 0, 0, 0); __builtin_amdgcn_s_setprio(0); } while (0)
; #define PG8_WAIT_V(n) asm volatile("s_waitcnt vmcnt(" #n ")" ::: "memory")
; #define PG8_WAIT_L(n) asm volatile("s_waitcnt lgkmcnt(" #n ")" ::: "memory")
; #define PG8_BAR __builtin_amdgcn_s_barrier()
; #define PG8_SCHED __builtin_amdgcn_sched_barrier(0)
; template <class Epi, class Sched, bool ALIGN_EPI = false, bool SP2 = false>
; __device__ __forceinline__ void gemm_phase(PG8_LAS unsigned char* lds, const Gemm g, const Sched& S, const Epi& E) {
;     ...
;             PG8_WAIT_V(8); PG8_WAIT_L(0); PG8_BAR; PG8_MMA(1, 0, At, B0); PG8_MMA(1, 1, At, B1); PG8_BAR; PG8_SCHED;
;     ...
;             PG8_LDA(At, 1, 1); PG8_STAGE(PG8_SB(1, 0), b3, voffB); PG8_STAGE(PG8_SB(1, 1), b3 + hstep, voffB); PG8_STAGE(PG8_SA(1, 0), a3, voffA);
	s_barrier
	s_add_i32 s86, 0, 0x18000
	s_add_i32 s87, 0, 0x1c000


; #define PG8_STAGE(bufoff, gbase, voff) do { _Pragma("unroll") for (int _i = 0; _i < 2; ++_i) \
;         __builtin_amdgcn_global_load_lds((const unsigned*)((const char*)(gbase) + (voff)[_i]), (PG8_LAS unsigned*)(lds + (bufoff) + ldsw + _i * 8192), 16, 0, 0); } while (0)
; #define PG8_LDA(dst, b, h) do { _Pragma("unroll") for (int m = 0; m < 4; ++m) _Pragma("unroll") for (int k = 0; k < 2; ++k) dst[m][k] = *(const PG8_LAS bf16x8*)(lds + PG8_SA(b, h) + aoff + m * 2048 + k * 1024); } while (0)
; #define PG8_LDB(dst, b, h) do { _Pragma("unroll") for (int n = 0; n < 2; ++n) _Pragma("unroll") for (int k = 0; k < 2; ++k) dst[n][k] = *(const PG8_LAS bf16x8*)(lds + PG8_SB(b, h) + boff + n * 2048 + k * 1024); } while (0)
; #define PG8_SCHED __builtin_amdgcn_sched_barrier(0)
; template <class Epi, class Sched, bool ALIGN_EPI = false, bool SP2 = false>
; __device__ __forceinline__ void gemm_phase(PG8_LAS unsigned char* lds, const Gemm g, const Sched& S, const Epi& E) {
;     ...
;             PG8_LDB(B0, 1, 0); PG8_LDB(B1, 1, 1); PG8_SCHED; PG8_LDA(At, 1, 0); PG8_STAGE(PG8_SA(0, 1), a2 + hstep, voffA);
	ds_read_b128 v[128:131], v254
	ds_read_b128 v[132:135], v254 offset:1024
	ds_read_b128 v[136:139], v254 offset:2048
	ds_read_b128 v[140:143], v254 offset:3072
	ds_read_b128 v[144:147], v255
	ds_read_b128 v[148:151], v255 offset:1024
	ds_read_b128 v[152:155], v255 offset:2048
	ds_read_b128 v[156:159], v255 offset:3072
	s_add_u32 s60, s60, 0x80000
	s_addc_u32 s61, s61, 0
	s_mov_b32 m0, s68

; #define PG8_STAGE(bufoff, gbase, voff) do { _Pragma("unroll") for (int _i = 0; _i < 2; ++_i) \
;         __builtin_amdgcn_global_load_lds((const unsigned*)((const char*)(gbase) + (voff)[_i]), (PG8_LAS unsigned*)(lds + (bufoff) + ldsw + _i * 8192), 16, 0, 0); } while (0)
; #define PG8_LDA(dst, b, h) do { _Pragma("unroll") for (int m = 0; m < 4; ++m) _Pragma("unroll") for (int k = 0; k < 2; ++k) dst[m][k] = *(const PG8_LAS bf16x8*)(lds + PG8_SA(b, h) + aoff + m * 2048 + k * 1024); } while (0)
; #define PG8_LDB(dst, b, h) do { _Pragma("unroll") for (int n = 0; n < 2; ++n) _Pragma("unroll") for (int k = 0; k < 2; ++k) dst[n][k] = *(const PG8_LAS bf16x8*)(lds + PG8_SB(b, h) + boff + n * 2048 + k * 1024); } while (0)
; #define PG8_SCHED __builtin_amdgcn_sched_barrier(0)
; template <class Epi, class Sched, bool ALIGN_EPI = false, bool SP2 = false>
; __device__ __forceinline__ void gemm_phase(PG8_LAS unsigned char* lds, const Gemm g, const Sched& S, const Epi& E) {
;     ...
;             PG8_LDB(B0, 1, 0); PG8_LDB(B1, 1, 1); PG8_SCHED; PG8_LDA(At, 1, 0); PG8_STAGE(PG8_SA(0, 1), a2 + hstep, voffA);
	ds_read_b128 v[176:179], v207 offset:32768
	ds_read_b128 v[184:187], v207 offset:33792
	ds_read_b128 v[190:193], v207 offset:34816
	ds_read_b128 v[210:213], v207 offset:35840
	ds_read_b128 v[214:217], v207 offset:36864
	ds_read_b128 v[218:221], v207 offset:37888
	ds_read_b128 v[222:225], v207 offset:38912
	ds_read_b128 v[226:229], v207 offset:39936
	global_load_lds_dwordx4 v160, s[60:61]

; #define PG8_STAGE(bufoff, gbase, voff) do { _Pragma("unroll") for (int _i = 0; _i < 2; ++_i) \
;         __builtin_amdgcn_global_load_lds((const unsigned*)((const char*)(gbase) + (voff)[_i]), (PG8_LAS unsigned*)(lds + (bufoff) + ldsw + _i * 8192), 16, 0, 0); } while (0)
; #define PG8_LDA(dst, b, h) do { _Pragma("unroll") for (int m = 0; m < 4; ++m) _Pragma("unroll") for (int k = 0; k < 2; ++k) dst[m][k] = *(const PG8_LAS bf16x8*)(lds + PG8_SA(b, h) + aoff + m * 2048 + k * 1024); } while (0)
; #define PG8_LDB(dst, b, h) do { _Pragma("unroll") for (int n = 0; n < 2; ++n) _Pragma("unroll") for (int k = 0; k < 2; ++k) dst[n][k] = *(const PG8_LAS bf16x8*)(lds + PG8_SB(b, h) + boff + n * 2048 + k * 1024); } while (0)
; #define PG8_MMA(ai, bj, At, Bt) do { __builtin_amdgcn_s_setprio(1); _Pragma("unroll") for (int m = 0; m < 4; ++m) _Pragma("unroll") for (int n = 0; n < 2; ++n) _Pragma("unroll") for (int k = 0; k < 2; ++k) \
;         acc[ai][bj][m][n] = __builtin_amdgcn_mfma_f32_16x16x32_bf16(Bt[n][k], At[m][k], acc[ai][bj][m][n], 0, 0, 0); __builtin_amdgcn_s_setprio(0); } while (0)
; #define PG8_WAIT_V(n) asm volatile("s_waitcnt vmcnt(" #n ")" ::: "memory")
; #define PG8_WAIT_L(n) asm volatile("s_waitcnt lgkmcnt(" #n ")" ::: "memory")
; #define PG8_BAR __builtin_amdgcn_s_barrier()
; #define PG8_SCHED __builtin_amdgcn_sched_barrier(0)
; template <class Epi, class Sched, bool ALIGN_EPI = false, bool SP2 = false>
; __device__ __forceinline__ void gemm_phase(PG8_LAS unsigned char* lds, const Gemm g, const Sched& S, const Epi& E) {
;     ...
;             PG8_LDB(B0, 1, 0); PG8_LDB(B1, 1, 1); PG8_SCHED; PG8_LDA(At, 1, 0); PG8_STAGE(PG8_SA(0, 1), a2 + hstep, voffA);
;             PG8_WAIT_V(8); PG8_WAIT_L(0); PG8_BAR; PG8_MMA(0, 0, At, B0); PG8_MMA(0, 1, At, B1); PG8_BAR; PG8_SCHED;
	s_mov_b32 m0, s69
	s_nop 0
	global_load_lds_dwordx4 v164, s[60:61]
	s_waitcnt vmcnt(8) lgkmcnt(0)


; #define PG8_MMA(ai, bj, At, Bt) do { __builtin_amdgcn_s_setprio(1); _Pragma("unroll") for (int m = 0; m < 4; ++m) _Pragma("unroll") for (int n = 0; n < 2; ++n) _Pragma("unroll") for (int k = 0; k < 2; ++k) \
;         acc[ai][bj][m][n] = __builtin_amdgcn_mfma_f32_16x16x32_bf16(Bt[n][k], At[m][k], acc[ai][bj][m][n], 0, 0, 0); __builtin_amdgcn_s_setprio(0); } while (0)
; #define PG8_WAIT_V(n) asm volatile("s_waitcnt vmcnt(" #n ")" ::: "memory")
; #define PG8_WAIT_L(n) asm volatile("s_waitcnt lgkmcnt(" #n ")" ::: "memory")
; #define PG8_BAR __builtin_amdgcn_s_barrier()
; #define PG8_SCHED __builtin_amdgcn_sched_barrier(0)
; template <class Epi, class Sched, bool ALIGN_EPI = false, bool SP2 = false>
; __device__ __forceinline__ void gemm_phase(PG8_LAS unsigned char* lds, const Gemm g, const Sched& S, const Epi& E) {
;     ...
;             PG8_WAIT_V(8); PG8_WAIT_L(0); PG8_BAR; PG8_MMA(0, 0, At, B0); PG8_MMA(0, 1, At, B1); PG8_BAR; PG8_SCHED;
	s_barrier

; #define PG8_MMA(ai, bj, At, Bt) do { __builtin_amdgcn_s_setprio(1); _Pragma("unroll") for (int m = 0; m < 4; ++m) _Pragma("unroll") for (int n = 0; n < 2; ++n) _Pragma("unroll") for (int k = 0; k < 2; ++k) \
;         acc[ai][bj][m][n] = __builtin_amdgcn_mfma_f32_16x16x32_bf16(Bt[n][k], At[m][k], acc[ai][bj][m][n], 0, 0, 0); __builtin_amdgcn_s_setprio(0); } while (0)
; #define PG8_WAIT_V(n) asm volatile("s_waitcnt vmcnt(" #n ")" ::: "memory")
; #define PG8_WAIT_L(n) asm volatile("s_waitcnt lgkmcnt(" #n ")" ::: "memory")
; #define PG8_BAR __builtin_amdgcn_s_barrier()
; #define PG8_SCHED __builtin_amdgcn_sched_barrier(0)
; template <class Epi, class Sched, bool ALIGN_EPI = false, bool SP2 = false>
; __device__ __forceinline__ void gemm_phase(PG8_LAS unsigned char* lds, const Gemm g, const Sched& S, const Epi& E) {
;     ...
;             PG8_WAIT_V(8); PG8_WAIT_L(0); PG8_BAR; PG8_MMA(0, 0, At, B0); PG8_MMA(0, 1, At, B1); PG8_BAR; PG8_SCHED;
	v_mfma_f32_16x16x32_bf16 v[124:127], v[128:131], v[176:179], v[124:127]
	v_mfma_f32_16x16x32_bf16 v[120:123], v[136:139], v[176:179], v[120:123]
	v_mfma_f32_16x16x32_bf16 v[108:111], v[128:131], v[190:193], v[108:111]
	v_mfma_f32_16x16x32_bf16 v[104:107], v[136:139], v[190:193], v[104:107]
	v_mfma_f32_16x16x32_bf16 v[92:95], v[128:131], v[214:217], v[92:95]
	v_mfma_f32_16x16x32_bf16 v[88:91], v[136:139], v[214:217], v[88:91]
	v_mfma_f32_16x16x32_bf16 v[76:79], v[128:131], v[222:225], v[76:79]
	v_mfma_f32_16x16x32_bf16 v[72:75], v[136:139], v[222:225], v[72:75]
	v_mfma_f32_16x16x32_bf16 v[124:127], v[132:135], v[184:187], v[124:127]
	v_mfma_f32_16x16x32_bf16 v[120:123], v[140:143], v[184:187], v[120:123]
	v_mfma_f32_16x16x32_bf16 v[108:111], v[132:135], v[210:213], v[108:111]
	v_mfma_f32_16x16x32_bf16 v[104:107], v[140:143], v[210:213], v[104:107]
	v_mfma_f32_16x16x32_bf16 v[92:95], v[132:135], v[218:221], v[92:95]
	v_mfma_f32_16x16x32_bf16 v[88:91], v[140:143], v[218:221], v[88:91]
	v_mfma_f32_16x16x32_bf16 v[76:79], v[132:135], v[226:229], v[76:79]
	v_mfma_f32_16x16x32_bf16 v[72:75], v[140:143], v[226:229], v[72:75]


; #define PG8_MMA(ai, bj, At, Bt) do { __builtin_amdgcn_s_setprio(1); _Pragma("unroll") for (int m = 0; m < 4; ++m) _Pragma("unroll") for (int n = 0; n < 2; ++n) _Pragma("unroll") for (int k = 0; k < 2; ++k) \
;         acc[ai][bj][m][n] = __builtin_amdgcn_mfma_f32_16x16x32_bf16(Bt[n][k], At[m][k], acc[ai][bj][m][n], 0, 0, 0); __builtin_amdgcn_s_setprio(0); } while (0)
; #define PG8_WAIT_V(n) asm volatile("s_waitcnt vmcnt(" #n ")" ::: "memory")
; #define PG8_WAIT_L(n) asm volatile("s_waitcnt lgkmcnt(" #n ")" ::: "memory")
; #define PG8_BAR __builtin_amdgcn_s_barrier()
; #define PG8_SCHED __builtin_amdgcn_sched_barrier(0)
; template <class Epi, class Sched, bool ALIGN_EPI = false, bool SP2 = false>
; __device__ __forceinline__ void gemm_phase(PG8_LAS unsigned char* lds, const Gemm g, const Sched& S, const Epi& E) {
;     ...
;             PG8_WAIT_V(8); PG8_WAIT_L(0); PG8_BAR; PG8_MMA(0, 0, At, B0); PG8_MMA(0, 1, At, B1); PG8_BAR; PG8_SCHED;
	v_mfma_f32_16x16x32_bf16 v[116:119], v[144:147], v[176:179], v[116:119]
	v_mfma_f32_16x16x32_bf16 v[112:115], v[152:155], v[176:179], v[112:115]
	v_mfma_f32_16x16x32_bf16 v[100:103], v[144:147], v[190:193], v[100:103]
	v_mfma_f32_16x16x32_bf16 v[96:99], v[152:155], v[190:193], v[96:99]
	v_mfma_f32_16x16x32_bf16 v[84:87], v[144:147], v[214:217], v[84:87]
	v_mfma_f32_16x16x32_bf16 v[80:83], v[152:155], v[214:217], v[80:83]
	v_mfma_f32_16x16x32_bf16 v[68:71], v[144:147], v[222:225], v[68:71]
	v_mfma_f32_16x16x32_bf16 v[64:67], v[152:155], v[222:225], v[64:67]
	v_mfma_f32_16x16x32_bf16 v[116:119], v[148:151], v[184:187], v[116:119]
	v_mfma_f32_16x16x32_bf16 v[112:115], v[156:159], v[184:187], v[112:115]
	v_mfma_f32_16x16x32_bf16 v[100:103], v[148:151], v[210:213], v[100:103]
	v_mfma_f32_16x16x32_bf16 v[96:99], v[156:159], v[210:213], v[96:99]
	v_mfma_f32_16x16x32_bf16 v[84:87], v[148:151], v[218:221], v[84:87]
	v_mfma_f32_16x16x32_bf16 v[80:83], v[156:159], v[218:221], v[80:83]
	v_mfma_f32_16x16x32_bf16 v[68:71], v[148:151], v[226:229], v[68:71]
	v_mfma_f32_16x16x32_bf16 v[64:67], v[156:159], v[226:229], v[64:67]

; #define PG8_STAGE(bufoff, gbase, voff) do { _Pragma("unroll") for (int _i = 0; _i < 2; ++_i) \
;         __builtin_amdgcn_global_load_lds((const unsigned*)((const char*)(gbase) + (voff)[_i]), (PG8_LAS unsigned*)(lds + (bufoff) + ldsw + _i * 8192), 16, 0, 0); } while (0)
; #define PG8_LDA(dst, b, h) do { _Pragma("unroll") for (int m = 0; m < 4; ++m) _Pragma("unroll") for (int k = 0; k < 2; ++k) dst[m][k] = *(const PG8_LAS bf16x8*)(lds + PG8_SA(b, h) + aoff + m * 2048 + k * 1024); } while (0)
; #define PG8_MMA(ai, bj, At, Bt) do { __builtin_amdgcn_s_setprio(1); _Pragma("unroll") for (int m = 0; m < 4; ++m) _Pragma("unroll") for (int n = 0; n < 2; ++n) _Pragma("unroll") for (int k = 0; k < 2; ++k) \
;         acc[ai][bj][m][n] = __builtin_amdgcn_mfma_f32_16x16x32_bf16(Bt[n][k], At[m][k], acc[ai][bj][m][n], 0, 0, 0); __builtin_amdgcn_s_setprio(0); } while (0)
; #define PG8_WAIT_V(n) asm volatile("s_waitcnt vmcnt(" #n ")" ::: "memory")
; #define PG8_WAIT_L(n) asm volatile("s_waitcnt lgkmcnt(" #n ")" ::: "memory")
; #define PG8_BAR __builtin_amdgcn_s_barrier()
; #define PG8_SCHED __builtin_amdgcn_sched_barrier(0)
; template <class Epi, class Sched, bool ALIGN_EPI = false, bool SP2 = false>
; __device__ __forceinline__ void gemm_phase(PG8_LAS unsigned char* lds, const Gemm g, const Sched& S, const Epi& E) {
;     ...
;             PG8_WAIT_V(8); PG8_WAIT_L(0); PG8_BAR; PG8_MMA(0, 0, At, B0); PG8_MMA(0, 1, At, B1); PG8_BAR; PG8_SCHED;
;             PG8_LDA(At, 1, 1); PG8_STAGE(PG8_SB(1, 0), b3, voffB); PG8_STAGE(PG8_SB(1, 1), b3 + hstep, voffB); PG8_STAGE(PG8_SA(1, 0), a3, voffA);
	s_barrier
	s_add_i32 s60, s86, s64

; #define PG8_STAGE(bufoff, gbase, voff) do { _Pragma("unroll") for (int _i = 0; _i < 2; ++_i) \
;         __builtin_amdgcn_global_load_lds((const unsigned*)((const char*)(gbase) + (voff)[_i]), (PG8_LAS unsigned*)(lds + (bufoff) + ldsw + _i * 8192), 16, 0, 0); } while (0)
; #define PG8_LDA(dst, b, h) do { _Pragma("unroll") for (int m = 0; m < 4; ++m) _Pragma("unroll") for (int k = 0; k < 2; ++k) dst[m][k] = *(const PG8_LAS bf16x8*)(lds + PG8_SA(b, h) + aoff + m * 2048 + k * 1024); } while (0)
; template <class Epi, class Sched, bool ALIGN_EPI = false, bool SP2 = false>
; __device__ __forceinline__ void gemm_phase(PG8_LAS unsigned char* lds, const Gemm g, const Sched& S, const Epi& E) {
;     ...
;             PG8_LDA(At, 1, 1); PG8_STAGE(PG8_SB(1, 0), b3, voffB); PG8_STAGE(PG8_SB(1, 1), b3 + hstep, voffB); PG8_STAGE(PG8_SA(1, 0), a3, voffA);
	s_mov_b32 m0, s60
	ds_read_b128 v[176:179], v207 offset:49152
	ds_read_b128 v[184:187], v207 offset:50176
	ds_read_b128 v[190:193], v207 offset:51200
	ds_read_b128 v[210:213], v207 offset:52224
	ds_read_b128 v[214:217], v207 offset:53248
	ds_read_b128 v[218:221], v207 offset:54272
	ds_read_b128 v[222:225], v207 offset:55296
	ds_read_b128 v[226:229], v207 offset:56320
	global_load_lds_dwordx4 v250, s[96:97]
	s_add_i32 m0, s60, 0x2000
	s_add_u32 s12, s12, 0x80080

; #define PG8_STAGE(bufoff, gbase, voff) do { _Pragma("unroll") for (int _i = 0; _i < 2; ++_i) \
;         __builtin_amdgcn_global_load_lds((const unsigned*)((const char*)(gbase) + (voff)[_i]), (PG8_LAS unsigned*)(lds + (bufoff) + ldsw + _i * 8192), 16, 0, 0); } while (0)
; #define PG8_LDA(dst, b, h) do { _Pragma("unroll") for (int m = 0; m < 4; ++m) _Pragma("unroll") for (int k = 0; k < 2; ++k) dst[m][k] = *(const PG8_LAS bf16x8*)(lds + PG8_SA(b, h) + aoff + m * 2048 + k * 1024); } while (0)
; template <class Epi, class Sched, bool ALIGN_EPI = false, bool SP2 = false>
; __device__ __forceinline__ void gemm_phase(PG8_LAS unsigned char* lds, const Gemm g, const Sched& S, const Epi& E) {
;     ...
;             PG8_LDA(At, 1, 1); PG8_STAGE(PG8_SB(1, 0), b3, voffB); PG8_STAGE(PG8_SB(1, 1), b3 + hstep, voffB); PG8_STAGE(PG8_SA(1, 0), a3, voffA);
	s_addc_u32 s13, s13, 0
	s_add_i32 s60, s87, s64
	global_load_lds_dwordx4 v251, s[96:97]

; #define PG8_STAGE(bufoff, gbase, voff) do { _Pragma("unroll") for (int _i = 0; _i < 2; ++_i) \
;         __builtin_amdgcn_global_load_lds((const unsigned*)((const char*)(gbase) + (voff)[_i]), (PG8_LAS unsigned*)(lds + (bufoff) + ldsw + _i * 8192), 16, 0, 0); } while (0)
; #define PG8_LDA(dst, b, h) do { _Pragma("unroll") for (int m = 0; m < 4; ++m) _Pragma("unroll") for (int k = 0; k < 2; ++k) dst[m][k] = *(const PG8_LAS bf16x8*)(lds + PG8_SA(b, h) + aoff + m * 2048 + k * 1024); } while (0)
; template <class Epi, class Sched, bool ALIGN_EPI = false, bool SP2 = false>
; __device__ __forceinline__ void gemm_phase(PG8_LAS unsigned char* lds, const Gemm g, const Sched& S, const Epi& E) {
;     ...
;             PG8_LDA(At, 1, 1); PG8_STAGE(PG8_SB(1, 0), b3, voffB); PG8_STAGE(PG8_SB(1, 1), b3 + hstep, voffB); PG8_STAGE(PG8_SA(1, 0), a3, voffA);
	s_mov_b32 m0, s60
	s_nop 0
	global_load_lds_dwordx4 v162, s[12:13]

; #define PG8_STAGE(bufoff, gbase, voff) do { _Pragma("unroll") for (int _i = 0; _i < 2; ++_i) \
;         __builtin_amdgcn_global_load_lds((const unsigned*)((const char*)(gbase) + (voff)[_i]), (PG8_LAS unsigned*)(lds + (bufoff) + ldsw + _i * 8192), 16, 0, 0); } while (0)
; #define PG8_LDA(dst, b, h) do { _Pragma("unroll") for (int m = 0; m < 4; ++m) _Pragma("unroll") for (int k = 0; k < 2; ++k) dst[m][k] = *(const PG8_LAS bf16x8*)(lds + PG8_SA(b, h) + aoff + m * 2048 + k * 1024); } while (0)
; template <class Epi, class Sched, bool ALIGN_EPI = false, bool SP2 = false>
; __device__ __forceinline__ void gemm_phase(PG8_LAS unsigned char* lds, const Gemm g, const Sched& S, const Epi& E) {
;     ...
;             PG8_LDA(At, 1, 1); PG8_STAGE(PG8_SB(1, 0), b3, voffB); PG8_STAGE(PG8_SB(1, 1), b3 + hstep, voffB); PG8_STAGE(PG8_SA(1, 0), a3, voffA);
	s_add_i32 m0, s60, 0x2000
	s_nop 0
	global_load_lds_dwordx4 v166, s[12:13]

; #define PG8_STAGE(bufoff, gbase, voff) do { _Pragma("unroll") for (int _i = 0; _i < 2; ++_i) \
;         __builtin_amdgcn_global_load_lds((const unsigned*)((const char*)(gbase) + (voff)[_i]), (PG8_LAS unsigned*)(lds + (bufoff) + ldsw + _i * 8192), 16, 0, 0); } while (0)
; #define PG8_LDA(dst, b, h) do { _Pragma("unroll") for (int m = 0; m < 4; ++m) _Pragma("unroll") for (int k = 0; k < 2; ++k) dst[m][k] = *(const PG8_LAS bf16x8*)(lds + PG8_SA(b, h) + aoff + m * 2048 + k * 1024); } while (0)
; template <class Epi, class Sched, bool ALIGN_EPI = false, bool SP2 = false>
; __device__ __forceinline__ void gemm_phase(PG8_LAS unsigned char* lds, const Gemm g, const Sched& S, const Epi& E) {
;     ...
;             PG8_LDA(At, 1, 1); PG8_STAGE(PG8_SB(1, 0), b3, voffB); PG8_STAGE(PG8_SB(1, 1), b3 + hstep, voffB); PG8_STAGE(PG8_SA(1, 0), a3, voffA);
	s_mov_b32 m0, s71
	s_nop 0
	global_load_lds_dwordx4 v252, s[98:99]

; #define PG8_STAGE(bufoff, gbase, voff) do { _Pragma("unroll") for (int _i = 0; _i < 2; ++_i) \
;         __builtin_amdgcn_global_load_lds((const unsigned*)((const char*)(gbase) + (voff)[_i]), (PG8_LAS unsigned*)(lds + (bufoff) + ldsw + _i * 8192), 16, 0, 0); } while (0)
; #define PG8_LDA(dst, b, h) do { _Pragma("unroll") for (int m = 0; m < 4; ++m) _Pragma("unroll") for (int k = 0; k < 2; ++k) dst[m][k] = *(const PG8_LAS bf16x8*)(lds + PG8_SA(b, h) + aoff + m * 2048 + k * 1024); } while (0)
; #define PG8_MMA(ai, bj, At, Bt) do { __builtin_amdgcn_s_setprio(1); _Pragma("unroll") for (int m = 0; m < 4; ++m) _Pragma("unroll") for (int n = 0; n < 2; ++n) _Pragma("unroll") for (int k = 0; k < 2; ++k) \
;         acc[ai][bj][m][n] = __builtin_amdgcn_mfma_f32_16x16x32_bf16(Bt[n][k], At[m][k], acc[ai][bj][m][n], 0, 0, 0); __builtin_amdgcn_s_setprio(0); } while (0)
; #define PG8_WAIT_V(n) asm volatile("s_waitcnt vmcnt(" #n ")" ::: "memory")
; #define PG8_WAIT_L(n) asm volatile("s_waitcnt lgkmcnt(" #n ")" ::: "memory")
; #define PG8_BAR __builtin_amdgcn_s_barrier()
; #define PG8_SCHED __builtin_amdgcn_sched_barrier(0)
; template <class Epi, class Sched, bool ALIGN_EPI = false, bool SP2 = false>
; __device__ __forceinline__ void gemm_phase(PG8_LAS unsigned char* lds, const Gemm g, const Sched& S, const Epi& E) {
;     ...
;             PG8_LDA(At, 1, 1); PG8_STAGE(PG8_SB(1, 0), b3, voffB); PG8_STAGE(PG8_SB(1, 1), b3 + hstep, voffB); PG8_STAGE(PG8_SA(1, 0), a3, voffA);
;             PG8_WAIT_V(8); PG8_WAIT_L(0); PG8_BAR; PG8_MMA(1, 0, At, B0); PG8_MMA(1, 1, At, B1); PG8_BAR; PG8_SCHED;
	s_mov_b32 m0, s72
	s_nop 0
	global_load_lds_dwordx4 v253, s[98:99]
	s_waitcnt vmcnt(8) lgkmcnt(0)


; #define PG8_MMA(ai, bj, At, Bt) do { __builtin_amdgcn_s_setprio(1); _Pragma("unroll") for (int m = 0; m < 4; ++m) _Pragma("unroll") for (int n = 0; n < 2; ++n) _Pragma("unroll") for (int k = 0; k < 2; ++k) \
;         acc[ai][bj][m][n] = __builtin_amdgcn_mfma_f32_16x16x32_bf16(Bt[n][k], At[m][k], acc[ai][bj][m][n], 0, 0, 0); __builtin_amdgcn_s_setprio(0); } while (0)
; #define PG8_WAIT_V(n) asm volatile("s_waitcnt vmcnt(" #n ")" ::: "memory")
; #define PG8_WAIT_L(n) asm volatile("s_waitcnt lgkmcnt(" #n ")" ::: "memory")
; #define PG8_BAR __builtin_amdgcn_s_barrier()
; #define PG8_SCHED __builtin_amdgcn_sched_barrier(0)
; template <class Epi, class Sched, bool ALIGN_EPI = false, bool SP2 = false>
; __device__ __forceinline__ void gemm_phase(PG8_LAS unsigned char* lds, const Gemm g, const Sched& S, const Epi& E) {
;     ...
;             PG8_WAIT_V(8); PG8_WAIT_L(0); PG8_BAR; PG8_MMA(1, 0, At, B0); PG8_MMA(1, 1, At, B1); PG8_BAR; PG8_SCHED;
	s_barrier

; #define PG8_MMA(ai, bj, At, Bt) do { __builtin_amdgcn_s_setprio(1); _Pragma("unroll") for (int m = 0; m < 4; ++m) _Pragma("unroll") for (int n = 0; n < 2; ++n) _Pragma("unroll") for (int k = 0; k < 2; ++k) \
;         acc[ai][bj][m][n] = __builtin_amdgcn_mfma_f32_16x16x32_bf16(Bt[n][k], At[m][k], acc[ai][bj][m][n], 0, 0, 0); __builtin_amdgcn_s_setprio(0); } while (0)
; #define PG8_WAIT_V(n) asm volatile("s_waitcnt vmcnt(" #n ")" ::: "memory")
; #define PG8_WAIT_L(n) asm volatile("s_waitcnt lgkmcnt(" #n ")" ::: "memory")
; #define PG8_BAR __builtin_amdgcn_s_barrier()
; #define PG8_SCHED __builtin_amdgcn_sched_barrier(0)
; template <class Epi, class Sched, bool ALIGN_EPI = false, bool SP2 = false>
; __device__ __forceinline__ void gemm_phase(PG8_LAS unsigned char* lds, const Gemm g, const Sched& S, const Epi& E) {
;     ...
;             PG8_WAIT_V(8); PG8_WAIT_L(0); PG8_BAR; PG8_MMA(1, 0, At, B0); PG8_MMA(1, 1, At, B1); PG8_BAR; PG8_SCHED;
	v_mfma_f32_16x16x32_bf16 v[60:63], v[128:131], v[176:179], v[60:63]
	v_mfma_f32_16x16x32_bf16 v[56:59], v[136:139], v[176:179], v[56:59]
	v_mfma_f32_16x16x32_bf16 v[44:47], v[128:131], v[190:193], v[44:47]
	v_mfma_f32_16x16x32_bf16 v[40:43], v[136:139], v[190:193], v[40:43]
	v_mfma_f32_16x16x32_bf16 v[28:31], v[128:131], v[214:217], v[28:31]
	v_mfma_f32_16x16x32_bf16 v[24:27], v[136:139], v[214:217], v[24:27]
	v_mfma_f32_16x16x32_bf16 v[12:15], v[128:131], v[222:225], v[12:15]
	v_mfma_f32_16x16x32_bf16 v[8:11], v[136:139], v[222:225], v[8:11]
	v_mfma_f32_16x16x32_bf16 v[60:63], v[132:135], v[184:187], v[60:63]
	v_mfma_f32_16x16x32_bf16 v[56:59], v[140:143], v[184:187], v[56:59]
	v_mfma_f32_16x16x32_bf16 v[44:47], v[132:135], v[210:213], v[44:47]
	v_mfma_f32_16x16x32_bf16 v[40:43], v[140:143], v[210:213], v[40:43]
	v_mfma_f32_16x16x32_bf16 v[28:31], v[132:135], v[218:221], v[28:31]
	v_mfma_f32_16x16x32_bf16 v[24:27], v[140:143], v[218:221], v[24:27]
	v_mfma_f32_16x16x32_bf16 v[12:15], v[132:135], v[226:229], v[12:15]
	v_mfma_f32_16x16x32_bf16 v[8:11], v[140:143], v[226:229], v[8:11]


; #define PG8_MMA(ai, bj, At, Bt) do { __builtin_amdgcn_s_setprio(1); _Pragma("unroll") for (int m = 0; m < 4; ++m) _Pragma("unroll") for (int n = 0; n < 2; ++n) _Pragma("unroll") for (int k = 0; k < 2; ++k) \
;         acc[ai][bj][m][n] = __builtin_amdgcn_mfma_f32_16x16x32_bf16(Bt[n][k], At[m][k], acc[ai][bj][m][n], 0, 0, 0); __builtin_amdgcn_s_setprio(0); } while (0)
; #define PG8_WAIT_V(n) asm volatile("s_waitcnt vmcnt(" #n ")" ::: "memory")
; #define PG8_WAIT_L(n) asm volatile("s_waitcnt lgkmcnt(" #n ")" ::: "memory")
; #define PG8_BAR __builtin_amdgcn_s_barrier()
; #define PG8_SCHED __builtin_amdgcn_sched_barrier(0)
; template <class Epi, class Sched, bool ALIGN_EPI = false, bool SP2 = false>
; __device__ __forceinline__ void gemm_phase(PG8_LAS unsigned char* lds, const Gemm g, const Sched& S, const Epi& E) {
;     ...
;             PG8_WAIT_V(8); PG8_WAIT_L(0); PG8_BAR; PG8_MMA(1, 0, At, B0); PG8_MMA(1, 1, At, B1); PG8_BAR; PG8_SCHED;
	v_mfma_f32_16x16x32_bf16 v[52:55], v[144:147], v[176:179], v[52:55]
	v_mfma_f32_16x16x32_bf16 v[48:51], v[152:155], v[176:179], v[48:51]
	v_mfma_f32_16x16x32_bf16 v[36:39], v[144:147], v[190:193], v[36:39]
	v_mfma_f32_16x16x32_bf16 v[32:35], v[152:155], v[190:193], v[32:35]
	v_mfma_f32_16x16x32_bf16 v[20:23], v[144:147], v[214:217], v[20:23]
	v_mfma_f32_16x16x32_bf16 v[16:19], v[152:155], v[214:217], v[16:19]
	v_mfma_f32_16x16x32_bf16 v[4:7], v[144:147], v[222:225], v[4:7]
	v_mfma_f32_16x16x32_bf16 v[0:3], v[152:155], v[222:225], v[0:3]
	v_mfma_f32_16x16x32_bf16 v[52:55], v[148:151], v[184:187], v[52:55]
	v_mfma_f32_16x16x32_bf16 v[48:51], v[156:159], v[184:187], v[48:51]
	v_mfma_f32_16x16x32_bf16 v[36:39], v[148:151], v[210:213], v[36:39]
	v_mfma_f32_16x16x32_bf16 v[32:35], v[156:159], v[210:213], v[32:35]
	v_mfma_f32_16x16x32_bf16 v[20:23], v[148:151], v[218:221], v[20:23]
	v_mfma_f32_16x16x32_bf16 v[16:19], v[156:159], v[218:221], v[16:19]
	v_mfma_f32_16x16x32_bf16 v[4:7], v[148:151], v[226:229], v[4:7]
	v_mfma_f32_16x16x32_bf16 v[0:3], v[156:159], v[226:229], v[0:3]

; #define PG8_STAGE(bufoff, gbase, voff) do { _Pragma("unroll") for (int _i = 0; _i < 2; ++_i) \
;         __builtin_amdgcn_global_load_lds((const unsigned*)((const char*)(gbase) + (voff)[_i]), (PG8_LAS unsigned*)(lds + (bufoff) + ldsw + _i * 8192), 16, 0, 0); } while (0)
; #define PG8_LDA(dst, b, h) do { _Pragma("unroll") for (int m = 0; m < 4; ++m) _Pragma("unroll") for (int k = 0; k < 2; ++k) dst[m][k] = *(const PG8_LAS bf16x8*)(lds + PG8_SA(b, h) + aoff + m * 2048 + k * 1024); } while (0)
; #define PG8_WAIT_V(n) asm volatile("s_waitcnt vmcnt(" #n ")" ::: "memory")
; #define PG8_WAIT_L(n) asm volatile("s_waitcnt lgkmcnt(" #n ")" ::: "memory")
; template <class Epi, class Sched, bool ALIGN_EPI = false, bool SP2 = false>
; __device__ __forceinline__ void gemm_phase(PG8_LAS unsigned char* lds, const Gemm g, const Sched& S, const Epi& E) {
;     ...
;         for (int t = 0; t < nt; t += 2) {
;             const bool last = (t == nt - 2);
;             const char* a1 = cA + (size_t)(t + 1) * kstep;
;             const char* a2 = last ? nA : cA + (size_t)(t + 2) * kstep; const char* b2 = last ? nB : cB + (size_t)(t + 2) * kstep;
;             const char* a3 = a2 + kstep; const char* b3 = b2 + kstep;
;             if (last && has_next) S.a_ready(nxt);
;             if constexpr (SP2) {
;             PG8_LDB(B0, 0, 0); PG8_LDB(B1, 0, 1); PG8_SCHED; PG8_LDA(At, 0, 0); PG8_STAGE(PG8_SA(1, 1), a1 + hstep, voffA);
;             PG8_WAIT_V(8); PG8_WAIT_L(0); PG8_BAR; PG8_MMA(0, 0, At, B0); PG8_MMA(0, 1, At, B1); PG8_BAR; PG8_SCHED;
;             PG8_LDA(At, 0, 1); PG8_STAGE(PG8_SB(0, 0), b2, voffB); PG8_STAGE(PG8_SB(0, 1), b2 + hstep, voffB); PG8_STAGE(PG8_SA(0, 0), a2, voffA);
;             PG8_WAIT_V(8); PG8_WAIT_L(0); PG8_BAR; PG8_MMA(1, 0, At, B0); PG8_MMA(1, 1, At, B1); PG8_BAR; PG8_SCHED;
;             PG8_LDB(B0, 1, 0); PG8_LDB(B1, 1, 1); PG8_SCHED; PG8_LDA(At, 1, 0); PG8_STAGE(PG8_SA(0, 1), a2 + hstep, voffA);
;             PG8_WAIT_V(8); PG8_WAIT_L(0); PG8_BAR; PG8_MMA(0, 0, At, B0); PG8_MMA(0, 1, At, B1); PG8_BAR; PG8_SCHED;
;             PG8_LDA(At, 1, 1); PG8_STAGE(PG8_SB(1, 0), b3, voffB); PG8_STAGE(PG8_SB(1, 1), b3 + hstep, voffB); PG8_STAGE(PG8_SA(1, 0), a3, voffA);
;             PG8_WAIT_V(8); PG8_WAIT_L(0); PG8_BAR; PG8_MMA(1, 0, At, B0); PG8_MMA(1, 1, At, B1); PG8_BAR; PG8_SCHED;
;     ...
;         if constexpr (ALIGN_EPI) { if (wr == 0) PG8_BAR; }
	s_barrier
	s_add_i32 s85, s85, 2
	s_add_u32 s10, s10, 0x100
	s_addc_u32 s11, s11, 0
	s_add_u32 s83, s83, 0x100
	s_addc_u32 s84, s84, 0
	s_cmp_gt_u32 s85, 29
	s_cbranch_scc0 .LBB0_428
	s_and_b64 vcc, exec, s[42:43]
	s_cbranch_vccz .LBB0_431
	s_barrier

; #define PG8_STAGE(bufoff, gbase, voff) do { _Pragma("unroll") for (int _i = 0; _i < 2; ++_i) \
;         __builtin_amdgcn_global_load_lds((const unsigned*)((const char*)(gbase) + (voff)[_i]), (PG8_LAS unsigned*)(lds + (bufoff) + ldsw + _i * 8192), 16, 0, 0); } while (0)
; #define PG8_LDA(dst, b, h) do { _Pragma("unroll") for (int m = 0; m < 4; ++m) _Pragma("unroll") for (int k = 0; k < 2; ++k) dst[m][k] = *(const PG8_LAS bf16x8*)(lds + PG8_SA(b, h) + aoff + m * 2048 + k * 1024); } while (0)
; #define PG8_LDB(dst, b, h) do { _Pragma("unroll") for (int n = 0; n < 2; ++n) _Pragma("unroll") for (int k = 0; k < 2; ++k) dst[n][k] = *(const PG8_LAS bf16x8*)(lds + PG8_SB(b, h) + boff + n * 2048 + k * 1024); } while (0)
; #define PG8_SCHED __builtin_amdgcn_sched_barrier(0)
; template <class Epi, class Sched, bool ALIGN_EPI = false, bool SP2 = false>
; __device__ __forceinline__ void gemm_phase(PG8_LAS unsigned char* lds, const Gemm g, const Sched& S, const Epi& E) {
;     ...
;             const char* a1 = cA + (size_t)(t + 1) * kstep;
;             const char* a2 = last ? nA : cA + (size_t)(t + 2) * kstep; const char* b2 = last ? nB : cB + (size_t)(t + 2) * kstep;
;             const char* a3 = a2 + kstep; const char* b3 = b2 + kstep;
;             if (last && has_next) S.a_ready(nxt);
;             if constexpr (SP2) {
;             PG8_LDB(B0, 0, 0); PG8_LDB(B1, 0, 1); PG8_SCHED; PG8_LDA(At, 0, 0); PG8_STAGE(PG8_SA(1, 1), a1 + hstep, voffA);
.LBB0_509:
	ds_read_b128 v[64:67], v213
	ds_read_b128 v[68:71], v213 offset:1024
	ds_read_b128 v[72:75], v213 offset:2048
	ds_read_b128 v[76:79], v213 offset:3072
	ds_read_b128 v[144:147], v214
	ds_read_b128 v[148:151], v214 offset:1024
	ds_read_b128 v[152:155], v214 offset:2048
	ds_read_b128 v[156:159], v214 offset:3072
	s_add_u32 s60, s58, 0xffe00080
	s_addc_u32 s61, s59, -1
	s_cmpk_eq_i32 s81, 0x7c
	s_cselect_b32 s63, s11, s61
	s_cselect_b32 s62, s51, s60
	s_cselect_b32 s61, s49, s80
	s_cselect_b32 s60, s78, s79

; #define PG8_STAGE(bufoff, gbase, voff) do { _Pragma("unroll") for (int _i = 0; _i < 2; ++_i) \
;         __builtin_amdgcn_global_load_lds((const unsigned*)((const char*)(gbase) + (voff)[_i]), (PG8_LAS unsigned*)(lds + (bufoff) + ldsw + _i * 8192), 16, 0, 0); } while (0)
; #define PG8_LDA(dst, b, h) do { _Pragma("unroll") for (int m = 0; m < 4; ++m) _Pragma("unroll") for (int k = 0; k < 2; ++k) dst[m][k] = *(const PG8_LAS bf16x8*)(lds + PG8_SA(b, h) + aoff + m * 2048 + k * 1024); } while (0)
; #define PG8_LDB(dst, b, h) do { _Pragma("unroll") for (int n = 0; n < 2; ++n) _Pragma("unroll") for (int k = 0; k < 2; ++k) dst[n][k] = *(const PG8_LAS bf16x8*)(lds + PG8_SB(b, h) + boff + n * 2048 + k * 1024); } while (0)
; #define PG8_SCHED __builtin_amdgcn_sched_barrier(0)
; template <class Epi, class Sched, bool ALIGN_EPI = false, bool SP2 = false>
; __device__ __forceinline__ void gemm_phase(PG8_LAS unsigned char* lds, const Gemm g, const Sched& S, const Epi& E) {
;     ...
;             PG8_LDB(B0, 0, 0); PG8_LDB(B1, 0, 1); PG8_SCHED; PG8_LDA(At, 0, 0); PG8_STAGE(PG8_SA(1, 1), a1 + hstep, voffA);
	s_add_i32 m0, s57, 0xc000
	ds_read_b128 v[176:179], v215
	ds_read_b128 v[180:183], v215 offset:1024
	ds_read_b128 v[184:187], v215 offset:2048
	ds_read_b128 v[188:191], v215 offset:3072
	ds_read_b128 v[192:195], v215 offset:4096
	ds_read_b128 v[196:199], v215 offset:5120
	ds_read_b128 v[200:203], v215 offset:6144
	ds_read_b128 v[204:207], v215 offset:7168
	global_load_lds_dwordx4 v168, s[58:59]

; #define PG8_STAGE(bufoff, gbase, voff) do { _Pragma("unroll") for (int _i = 0; _i < 2; ++_i) \
;         __builtin_amdgcn_global_load_lds((const unsigned*)((const char*)(gbase) + (voff)[_i]), (PG8_LAS unsigned*)(lds + (bufoff) + ldsw + _i * 8192), 16, 0, 0); } while (0)
; #define PG8_LDA(dst, b, h) do { _Pragma("unroll") for (int m = 0; m < 4; ++m) _Pragma("unroll") for (int k = 0; k < 2; ++k) dst[m][k] = *(const PG8_LAS bf16x8*)(lds + PG8_SA(b, h) + aoff + m * 2048 + k * 1024); } while (0)
; #define PG8_LDB(dst, b, h) do { _Pragma("unroll") for (int n = 0; n < 2; ++n) _Pragma("unroll") for (int k = 0; k < 2; ++k) dst[n][k] = *(const PG8_LAS bf16x8*)(lds + PG8_SB(b, h) + boff + n * 2048 + k * 1024); } while (0)
; #define PG8_MMA(ai, bj, At, Bt) do { __builtin_amdgcn_s_setprio(1); _Pragma("unroll") for (int m = 0; m < 4; ++m) _Pragma("unroll") for (int n = 0; n < 2; ++n) _Pragma("unroll") for (int k = 0; k < 2; ++k) \
;         acc[ai][bj][m][n] = __builtin_amdgcn_mfma_f32_16x16x32_bf16(Bt[n][k], At[m][k], acc[ai][bj][m][n], 0, 0, 0); __builtin_amdgcn_s_setprio(0); } while (0)
; #define PG8_WAIT_V(n) asm volatile("s_waitcnt vmcnt(" #n ")" ::: "memory")
; #define PG8_WAIT_L(n) asm volatile("s_waitcnt lgkmcnt(" #n ")" ::: "memory")
; #define PG8_BAR __builtin_amdgcn_s_barrier()
; #define PG8_SCHED __builtin_amdgcn_sched_barrier(0)
; template <class Epi, class Sched, bool ALIGN_EPI = false, bool SP2 = false>
; __device__ __forceinline__ void gemm_phase(PG8_LAS unsigned char* lds, const Gemm g, const Sched& S, const Epi& E) {
;     ...
;             PG8_LDB(B0, 0, 0); PG8_LDB(B1, 0, 1); PG8_SCHED; PG8_LDA(At, 0, 0); PG8_STAGE(PG8_SA(1, 1), a1 + hstep, voffA);
;             PG8_WAIT_V(8); PG8_WAIT_L(0); PG8_BAR; PG8_MMA(0, 0, At, B0); PG8_MMA(0, 1, At, B1); PG8_BAR; PG8_SCHED;
	s_add_i32 m0, s57, 0xe000
	s_nop 0
	global_load_lds_dwordx4 v170, s[58:59]
	s_waitcnt vmcnt(8) lgkmcnt(0)


; #define PG8_MMA(ai, bj, At, Bt) do { __builtin_amdgcn_s_setprio(1); _Pragma("unroll") for (int m = 0; m < 4; ++m) _Pragma("unroll") for (int n = 0; n < 2; ++n) _Pragma("unroll") for (int k = 0; k < 2; ++k) \
;         acc[ai][bj][m][n] = __builtin_amdgcn_mfma_f32_16x16x32_bf16(Bt[n][k], At[m][k], acc[ai][bj][m][n], 0, 0, 0); __builtin_amdgcn_s_setprio(0); } while (0)
; #define PG8_WAIT_V(n) asm volatile("s_waitcnt vmcnt(" #n ")" ::: "memory")
; #define PG8_WAIT_L(n) asm volatile("s_waitcnt lgkmcnt(" #n ")" ::: "memory")
; #define PG8_BAR __builtin_amdgcn_s_barrier()
; #define PG8_SCHED __builtin_amdgcn_sched_barrier(0)
; template <class Epi, class Sched, bool ALIGN_EPI = false, bool SP2 = false>
; __device__ __forceinline__ void gemm_phase(PG8_LAS unsigned char* lds, const Gemm g, const Sched& S, const Epi& E) {
;     ...
;             PG8_WAIT_V(8); PG8_WAIT_L(0); PG8_BAR; PG8_MMA(0, 0, At, B0); PG8_MMA(0, 1, At, B1); PG8_BAR; PG8_SCHED;
	s_barrier

; #define PG8_MMA(ai, bj, At, Bt) do { __builtin_amdgcn_s_setprio(1); _Pragma("unroll") for (int m = 0; m < 4; ++m) _Pragma("unroll") for (int n = 0; n < 2; ++n) _Pragma("unroll") for (int k = 0; k < 2; ++k) \
;         acc[ai][bj][m][n] = __builtin_amdgcn_mfma_f32_16x16x32_bf16(Bt[n][k], At[m][k], acc[ai][bj][m][n], 0, 0, 0); __builtin_amdgcn_s_setprio(0); } while (0)
; #define PG8_WAIT_V(n) asm volatile("s_waitcnt vmcnt(" #n ")" ::: "memory")
; #define PG8_WAIT_L(n) asm volatile("s_waitcnt lgkmcnt(" #n ")" ::: "memory")
; #define PG8_BAR __builtin_amdgcn_s_barrier()
; #define PG8_SCHED __builtin_amdgcn_sched_barrier(0)
; template <class Epi, class Sched, bool ALIGN_EPI = false, bool SP2 = false>
; __device__ __forceinline__ void gemm_phase(PG8_LAS unsigned char* lds, const Gemm g, const Sched& S, const Epi& E) {
;     ...
;             PG8_WAIT_V(8); PG8_WAIT_L(0); PG8_BAR; PG8_MMA(0, 0, At, B0); PG8_MMA(0, 1, At, B1); PG8_BAR; PG8_SCHED;
	v_mfma_f32_16x16x32_bf16 v[140:143], v[64:67], v[176:179], v[140:143]
	v_mfma_f32_16x16x32_bf16 v[136:139], v[72:75], v[176:179], v[136:139]
	v_mfma_f32_16x16x32_bf16 v[124:127], v[64:67], v[184:187], v[124:127]
	v_mfma_f32_16x16x32_bf16 v[120:123], v[72:75], v[184:187], v[120:123]
	v_mfma_f32_16x16x32_bf16 v[108:111], v[64:67], v[192:195], v[108:111]
	v_mfma_f32_16x16x32_bf16 v[104:107], v[72:75], v[192:195], v[104:107]
	v_mfma_f32_16x16x32_bf16 v[92:95], v[64:67], v[200:203], v[92:95]
	v_mfma_f32_16x16x32_bf16 v[88:91], v[72:75], v[200:203], v[88:91]
	v_mfma_f32_16x16x32_bf16 v[140:143], v[68:71], v[180:183], v[140:143]
	v_mfma_f32_16x16x32_bf16 v[136:139], v[76:79], v[180:183], v[136:139]
	v_mfma_f32_16x16x32_bf16 v[124:127], v[68:71], v[188:191], v[124:127]
	v_mfma_f32_16x16x32_bf16 v[120:123], v[76:79], v[188:191], v[120:123]
	v_mfma_f32_16x16x32_bf16 v[108:111], v[68:71], v[196:199], v[108:111]
	v_mfma_f32_16x16x32_bf16 v[104:107], v[76:79], v[196:199], v[104:107]
	v_mfma_f32_16x16x32_bf16 v[92:95], v[68:71], v[204:207], v[92:95]
	v_mfma_f32_16x16x32_bf16 v[88:91], v[76:79], v[204:207], v[88:91]


; #define PG8_MMA(ai, bj, At, Bt) do { __builtin_amdgcn_s_setprio(1); _Pragma("unroll") for (int m = 0; m < 4; ++m) _Pragma("unroll") for (int n = 0; n < 2; ++n) _Pragma("unroll") for (int k = 0; k < 2; ++k) \
;         acc[ai][bj][m][n] = __builtin_amdgcn_mfma_f32_16x16x32_bf16(Bt[n][k], At[m][k], acc[ai][bj][m][n], 0, 0, 0); __builtin_amdgcn_s_setprio(0); } while (0)
; #define PG8_WAIT_V(n) asm volatile("s_waitcnt vmcnt(" #n ")" ::: "memory")
; #define PG8_WAIT_L(n) asm volatile("s_waitcnt lgkmcnt(" #n ")" ::: "memory")
; #define PG8_BAR __builtin_amdgcn_s_barrier()
; #define PG8_SCHED __builtin_amdgcn_sched_barrier(0)
; template <class Epi, class Sched, bool ALIGN_EPI = false, bool SP2 = false>
; __device__ __forceinline__ void gemm_phase(PG8_LAS unsigned char* lds, const Gemm g, const Sched& S, const Epi& E) {
;     ...
;             PG8_WAIT_V(8); PG8_WAIT_L(0); PG8_BAR; PG8_MMA(0, 0, At, B0); PG8_MMA(0, 1, At, B1); PG8_BAR; PG8_SCHED;
	v_mfma_f32_16x16x32_bf16 v[132:135], v[144:147], v[176:179], v[132:135]
	v_mfma_f32_16x16x32_bf16 v[128:131], v[152:155], v[176:179], v[128:131]
	v_mfma_f32_16x16x32_bf16 v[116:119], v[144:147], v[184:187], v[116:119]
	v_mfma_f32_16x16x32_bf16 v[112:115], v[152:155], v[184:187], v[112:115]
	v_mfma_f32_16x16x32_bf16 v[100:103], v[144:147], v[192:195], v[100:103]
	v_mfma_f32_16x16x32_bf16 v[96:99], v[152:155], v[192:195], v[96:99]
	v_mfma_f32_16x16x32_bf16 v[84:87], v[144:147], v[200:203], v[84:87]
	v_mfma_f32_16x16x32_bf16 v[80:83], v[152:155], v[200:203], v[80:83]
	v_mfma_f32_16x16x32_bf16 v[132:135], v[148:151], v[180:183], v[132:135]
	v_mfma_f32_16x16x32_bf16 v[128:131], v[156:159], v[180:183], v[128:131]
	v_mfma_f32_16x16x32_bf16 v[116:119], v[148:151], v[188:191], v[116:119]
	v_mfma_f32_16x16x32_bf16 v[112:115], v[156:159], v[188:191], v[112:115]
	v_mfma_f32_16x16x32_bf16 v[100:103], v[148:151], v[196:199], v[100:103]
	v_mfma_f32_16x16x32_bf16 v[96:99], v[156:159], v[196:199], v[96:99]
	v_mfma_f32_16x16x32_bf16 v[84:87], v[148:151], v[204:207], v[84:87]
	v_mfma_f32_16x16x32_bf16 v[80:83], v[156:159], v[204:207], v[80:83]

; #define PG8_STAGE(bufoff, gbase, voff) do { _Pragma("unroll") for (int _i = 0; _i < 2; ++_i) \
;         __builtin_amdgcn_global_load_lds((const unsigned*)((const char*)(gbase) + (voff)[_i]), (PG8_LAS unsigned*)(lds + (bufoff) + ldsw + _i * 8192), 16, 0, 0); } while (0)
; #define PG8_LDA(dst, b, h) do { _Pragma("unroll") for (int m = 0; m < 4; ++m) _Pragma("unroll") for (int k = 0; k < 2; ++k) dst[m][k] = *(const PG8_LAS bf16x8*)(lds + PG8_SA(b, h) + aoff + m * 2048 + k * 1024); } while (0)
; #define PG8_MMA(ai, bj, At, Bt) do { __builtin_amdgcn_s_setprio(1); _Pragma("unroll") for (int m = 0; m < 4; ++m) _Pragma("unroll") for (int n = 0; n < 2; ++n) _Pragma("unroll") for (int k = 0; k < 2; ++k) \
;         acc[ai][bj][m][n] = __builtin_amdgcn_mfma_f32_16x16x32_bf16(Bt[n][k], At[m][k], acc[ai][bj][m][n], 0, 0, 0); __builtin_amdgcn_s_setprio(0); } while (0)
; #define PG8_WAIT_V(n) asm volatile("s_waitcnt vmcnt(" #n ")" ::: "memory")
; #define PG8_WAIT_L(n) asm volatile("s_waitcnt lgkmcnt(" #n ")" ::: "memory")
; #define PG8_BAR __builtin_amdgcn_s_barrier()
; #define PG8_SCHED __builtin_amdgcn_sched_barrier(0)
; template <class Epi, class Sched, bool ALIGN_EPI = false, bool SP2 = false>
; __device__ __forceinline__ void gemm_phase(PG8_LAS unsigned char* lds, const Gemm g, const Sched& S, const Epi& E) {
;     ...
;             PG8_WAIT_V(8); PG8_WAIT_L(0); PG8_BAR; PG8_MMA(0, 0, At, B0); PG8_MMA(0, 1, At, B1); PG8_BAR; PG8_SCHED;
;             PG8_LDA(At, 0, 1); PG8_STAGE(PG8_SB(0, 0), b2, voffB); PG8_STAGE(PG8_SB(0, 1), b2 + hstep, voffB); PG8_STAGE(PG8_SA(0, 0), a2, voffA);
	s_barrier
	s_add_i32 s82, s75, s64
	s_mov_b64 s[96:97], s[60:61]

; #define PG8_STAGE(bufoff, gbase, voff) do { _Pragma("unroll") for (int _i = 0; _i < 2; ++_i) \
;         __builtin_amdgcn_global_load_lds((const unsigned*)((const char*)(gbase) + (voff)[_i]), (PG8_LAS unsigned*)(lds + (bufoff) + ldsw + _i * 8192), 16, 0, 0); } while (0)
; #define PG8_LDA(dst, b, h) do { _Pragma("unroll") for (int m = 0; m < 4; ++m) _Pragma("unroll") for (int k = 0; k < 2; ++k) dst[m][k] = *(const PG8_LAS bf16x8*)(lds + PG8_SA(b, h) + aoff + m * 2048 + k * 1024); } while (0)
; template <class Epi, class Sched, bool ALIGN_EPI = false, bool SP2 = false>
; __device__ __forceinline__ void gemm_phase(PG8_LAS unsigned char* lds, const Gemm g, const Sched& S, const Epi& E) {
;     ...
;             PG8_LDA(At, 0, 1); PG8_STAGE(PG8_SB(0, 0), b2, voffB); PG8_STAGE(PG8_SB(0, 1), b2 + hstep, voffB); PG8_STAGE(PG8_SA(0, 0), a2, voffA);
	s_mov_b32 m0, s82
	ds_read_b128 v[176:179], v215 offset:16384
	ds_read_b128 v[180:183], v215 offset:17408
	ds_read_b128 v[184:187], v215 offset:18432
	ds_read_b128 v[188:191], v215 offset:19456
	ds_read_b128 v[192:195], v215 offset:20480
	ds_read_b128 v[196:199], v215 offset:21504
	ds_read_b128 v[200:203], v215 offset:22528
	ds_read_b128 v[204:207], v215 offset:23552
	global_load_lds_dwordx4 v162, s[60:61]
	s_add_i32 m0, s82, 0x2000
	s_add_u32 s82, s60, 0x200000

; #define PG8_STAGE(bufoff, gbase, voff) do { _Pragma("unroll") for (int _i = 0; _i < 2; ++_i) \
;         __builtin_amdgcn_global_load_lds((const unsigned*)((const char*)(gbase) + (voff)[_i]), (PG8_LAS unsigned*)(lds + (bufoff) + ldsw + _i * 8192), 16, 0, 0); } while (0)
; #define PG8_LDA(dst, b, h) do { _Pragma("unroll") for (int m = 0; m < 4; ++m) _Pragma("unroll") for (int k = 0; k < 2; ++k) dst[m][k] = *(const PG8_LAS bf16x8*)(lds + PG8_SA(b, h) + aoff + m * 2048 + k * 1024); } while (0)
; template <class Epi, class Sched, bool ALIGN_EPI = false, bool SP2 = false>
; __device__ __forceinline__ void gemm_phase(PG8_LAS unsigned char* lds, const Gemm g, const Sched& S, const Epi& E) {
;     ...
;             PG8_LDA(At, 0, 1); PG8_STAGE(PG8_SB(0, 0), b2, voffB); PG8_STAGE(PG8_SB(0, 1), b2 + hstep, voffB); PG8_STAGE(PG8_SA(0, 0), a2, voffA);
	s_addc_u32 s83, s61, 0
	s_add_i32 s84, s76, s64
	global_load_lds_dwordx4 v166, s[60:61]

; #define PG8_STAGE(bufoff, gbase, voff) do { _Pragma("unroll") for (int _i = 0; _i < 2; ++_i) \
;         __builtin_amdgcn_global_load_lds((const unsigned*)((const char*)(gbase) + (voff)[_i]), (PG8_LAS unsigned*)(lds + (bufoff) + ldsw + _i * 8192), 16, 0, 0); } while (0)
; #define PG8_LDA(dst, b, h) do { _Pragma("unroll") for (int m = 0; m < 4; ++m) _Pragma("unroll") for (int k = 0; k < 2; ++k) dst[m][k] = *(const PG8_LAS bf16x8*)(lds + PG8_SA(b, h) + aoff + m * 2048 + k * 1024); } while (0)
; template <class Epi, class Sched, bool ALIGN_EPI = false, bool SP2 = false>
; __device__ __forceinline__ void gemm_phase(PG8_LAS unsigned char* lds, const Gemm g, const Sched& S, const Epi& E) {
;     ...
;             PG8_LDA(At, 0, 1); PG8_STAGE(PG8_SB(0, 0), b2, voffB); PG8_STAGE(PG8_SB(0, 1), b2 + hstep, voffB); PG8_STAGE(PG8_SA(0, 0), a2, voffA);
	s_mov_b32 m0, s84
	s_nop 0
	global_load_lds_dwordx4 v162, s[82:83]

; #define PG8_STAGE(bufoff, gbase, voff) do { _Pragma("unroll") for (int _i = 0; _i < 2; ++_i) \
;         __builtin_amdgcn_global_load_lds((const unsigned*)((const char*)(gbase) + (voff)[_i]), (PG8_LAS unsigned*)(lds + (bufoff) + ldsw + _i * 8192), 16, 0, 0); } while (0)
; #define PG8_LDA(dst, b, h) do { _Pragma("unroll") for (int m = 0; m < 4; ++m) _Pragma("unroll") for (int k = 0; k < 2; ++k) dst[m][k] = *(const PG8_LAS bf16x8*)(lds + PG8_SA(b, h) + aoff + m * 2048 + k * 1024); } while (0)
; template <class Epi, class Sched, bool ALIGN_EPI = false, bool SP2 = false>
; __device__ __forceinline__ void gemm_phase(PG8_LAS unsigned char* lds, const Gemm g, const Sched& S, const Epi& E) {
;     ...
;             PG8_LDA(At, 0, 1); PG8_STAGE(PG8_SB(0, 0), b2, voffB); PG8_STAGE(PG8_SB(0, 1), b2 + hstep, voffB); PG8_STAGE(PG8_SA(0, 0), a2, voffA);
	s_add_i32 m0, s84, 0x2000
	s_nop 0
	global_load_lds_dwordx4 v166, s[82:83]
	s_mov_b64 s[98:99], s[62:63]

; #define PG8_STAGE(bufoff, gbase, voff) do { _Pragma("unroll") for (int _i = 0; _i < 2; ++_i) \
;         __builtin_amdgcn_global_load_lds((const unsigned*)((const char*)(gbase) + (voff)[_i]), (PG8_LAS unsigned*)(lds + (bufoff) + ldsw + _i * 8192), 16, 0, 0); } while (0)
; #define PG8_LDA(dst, b, h) do { _Pragma("unroll") for (int m = 0; m < 4; ++m) _Pragma("unroll") for (int k = 0; k < 2; ++k) dst[m][k] = *(const PG8_LAS bf16x8*)(lds + PG8_SA(b, h) + aoff + m * 2048 + k * 1024); } while (0)
; #define PG8_MMA(ai, bj, At, Bt) do { __builtin_amdgcn_s_setprio(1); _Pragma("unroll") for (int m = 0; m < 4; ++m) _Pragma("unroll") for (int n = 0; n < 2; ++n) _Pragma("unroll") for (int k = 0; k < 2; ++k) \
;         acc[ai][bj][m][n] = __builtin_amdgcn_mfma_f32_16x16x32_bf16(Bt[n][k], At[m][k], acc[ai][bj][m][n], 0, 0, 0); __builtin_amdgcn_s_setprio(0); } while (0)
; #define PG8_WAIT_V(n) asm volatile("s_waitcnt vmcnt(" #n ")" ::: "memory")
; #define PG8_WAIT_L(n) asm volatile("s_waitcnt lgkmcnt(" #n ")" ::: "memory")
; #define PG8_BAR __builtin_amdgcn_s_barrier()
; #define PG8_SCHED __builtin_amdgcn_sched_barrier(0)
; template <class Epi, class Sched, bool ALIGN_EPI = false, bool SP2 = false>
; __device__ __forceinline__ void gemm_phase(PG8_LAS unsigned char* lds, const Gemm g, const Sched& S, const Epi& E) {
;     ...
;             PG8_LDA(At, 0, 1); PG8_STAGE(PG8_SB(0, 0), b2, voffB); PG8_STAGE(PG8_SB(0, 1), b2 + hstep, voffB); PG8_STAGE(PG8_SA(0, 0), a2, voffA);
;             PG8_WAIT_V(8); PG8_WAIT_L(0); PG8_BAR; PG8_MMA(1, 0, At, B0); PG8_MMA(1, 1, At, B1); PG8_BAR; PG8_SCHED;
	s_mov_b32 m0, s57
	s_nop 0
	global_load_lds_dwordx4 v160, s[62:63]
	s_mov_b32 m0, s65
	s_nop 0
	global_load_lds_dwordx4 v164, s[62:63]
	s_waitcnt vmcnt(8) lgkmcnt(0)


; #define PG8_MMA(ai, bj, At, Bt) do { __builtin_amdgcn_s_setprio(1); _Pragma("unroll") for (int m = 0; m < 4; ++m) _Pragma("unroll") for (int n = 0; n < 2; ++n) _Pragma("unroll") for (int k = 0; k < 2; ++k) \
;         acc[ai][bj][m][n] = __builtin_amdgcn_mfma_f32_16x16x32_bf16(Bt[n][k], At[m][k], acc[ai][bj][m][n], 0, 0, 0); __builtin_amdgcn_s_setprio(0); } while (0)
; #define PG8_WAIT_V(n) asm volatile("s_waitcnt vmcnt(" #n ")" ::: "memory")
; #define PG8_WAIT_L(n) asm volatile("s_waitcnt lgkmcnt(" #n ")" ::: "memory")
; #define PG8_BAR __builtin_amdgcn_s_barrier()
; #define PG8_SCHED __builtin_amdgcn_sched_barrier(0)
; template <class Epi, class Sched, bool ALIGN_EPI = false, bool SP2 = false>
; __device__ __forceinline__ void gemm_phase(PG8_LAS unsigned char* lds, const Gemm g, const Sched& S, const Epi& E) {
;     ...
;             PG8_WAIT_V(8); PG8_WAIT_L(0); PG8_BAR; PG8_MMA(1, 0, At, B0); PG8_MMA(1, 1, At, B1); PG8_BAR; PG8_SCHED;
	s_barrier

; #define PG8_MMA(ai, bj, At, Bt) do { __builtin_amdgcn_s_setprio(1); _Pragma("unroll") for (int m = 0; m < 4; ++m) _Pragma("unroll") for (int n = 0; n < 2; ++n) _Pragma("unroll") for (int k = 0; k < 2; ++k) \
;         acc[ai][bj][m][n] = __builtin_amdgcn_mfma_f32_16x16x32_bf16(Bt[n][k], At[m][k], acc[ai][bj][m][n], 0, 0, 0); __builtin_amdgcn_s_setprio(0); } while (0)
; #define PG8_WAIT_V(n) asm volatile("s_waitcnt vmcnt(" #n ")" ::: "memory")
; #define PG8_WAIT_L(n) asm volatile("s_waitcnt lgkmcnt(" #n ")" ::: "memory")
; #define PG8_BAR __builtin_amdgcn_s_barrier()
; #define PG8_SCHED __builtin_amdgcn_sched_barrier(0)
; template <class Epi, class Sched, bool ALIGN_EPI = false, bool SP2 = false>
; __device__ __forceinline__ void gemm_phase(PG8_LAS unsigned char* lds, const Gemm g, const Sched& S, const Epi& E) {
;     ...
;             PG8_WAIT_V(8); PG8_WAIT_L(0); PG8_BAR; PG8_MMA(1, 0, At, B0); PG8_MMA(1, 1, At, B1); PG8_BAR; PG8_SCHED;
	v_mfma_f32_16x16x32_bf16 v[60:63], v[64:67], v[176:179], v[60:63]
	v_mfma_f32_16x16x32_bf16 v[56:59], v[72:75], v[176:179], v[56:59]
	v_mfma_f32_16x16x32_bf16 v[44:47], v[64:67], v[184:187], v[44:47]
	v_mfma_f32_16x16x32_bf16 v[40:43], v[72:75], v[184:187], v[40:43]
	v_mfma_f32_16x16x32_bf16 v[28:31], v[64:67], v[192:195], v[28:31]
	v_mfma_f32_16x16x32_bf16 v[24:27], v[72:75], v[192:195], v[24:27]
	v_mfma_f32_16x16x32_bf16 v[12:15], v[64:67], v[200:203], v[12:15]
	v_mfma_f32_16x16x32_bf16 v[8:11], v[72:75], v[200:203], v[8:11]
	v_mfma_f32_16x16x32_bf16 v[60:63], v[68:71], v[180:183], v[60:63]
	v_mfma_f32_16x16x32_bf16 v[56:59], v[76:79], v[180:183], v[56:59]
	v_mfma_f32_16x16x32_bf16 v[44:47], v[68:71], v[188:191], v[44:47]
	v_mfma_f32_16x16x32_bf16 v[40:43], v[76:79], v[188:191], v[40:43]
	v_mfma_f32_16x16x32_bf16 v[28:31], v[68:71], v[196:199], v[28:31]
	v_mfma_f32_16x16x32_bf16 v[24:27], v[76:79], v[196:199], v[24:27]
	v_mfma_f32_16x16x32_bf16 v[12:15], v[68:71], v[204:207], v[12:15]
	v_mfma_f32_16x16x32_bf16 v[8:11], v[76:79], v[204:207], v[8:11]


; #define PG8_MMA(ai, bj, At, Bt) do { __builtin_amdgcn_s_setprio(1); _Pragma("unroll") for (int m = 0; m < 4; ++m) _Pragma("unroll") for (int n = 0; n < 2; ++n) _Pragma("unroll") for (int k = 0; k < 2; ++k) \
;         acc[ai][bj][m][n] = __builtin_amdgcn_mfma_f32_16x16x32_bf16(Bt[n][k], At[m][k], acc[ai][bj][m][n], 0, 0, 0); __builtin_amdgcn_s_setprio(0); } while (0)
; #define PG8_WAIT_V(n) asm volatile("s_waitcnt vmcnt(" #n ")" ::: "memory")
; #define PG8_WAIT_L(n) asm volatile("s_waitcnt lgkmcnt(" #n ")" ::: "memory")
; #define PG8_BAR __builtin_amdgcn_s_barrier()
; #define PG8_SCHED __builtin_amdgcn_sched_barrier(0)
; template <class Epi, class Sched, bool ALIGN_EPI = false, bool SP2 = false>
; __device__ __forceinline__ void gemm_phase(PG8_LAS unsigned char* lds, const Gemm g, const Sched& S, const Epi& E) {
;     ...
;             PG8_WAIT_V(8); PG8_WAIT_L(0); PG8_BAR; PG8_MMA(1, 0, At, B0); PG8_MMA(1, 1, At, B1); PG8_BAR; PG8_SCHED;
	v_mfma_f32_16x16x32_bf16 v[52:55], v[144:147], v[176:179], v[52:55]
	v_mfma_f32_16x16x32_bf16 v[48:51], v[152:155], v[176:179], v[48:51]
	v_mfma_f32_16x16x32_bf16 v[36:39], v[144:147], v[184:187], v[36:39]
	v_mfma_f32_16x16x32_bf16 v[32:35], v[152:155], v[184:187], v[32:35]
	v_mfma_f32_16x16x32_bf16 v[20:23], v[144:147], v[192:195], v[20:23]
	v_mfma_f32_16x16x32_bf16 v[16:19], v[152:155], v[192:195], v[16:19]
	v_mfma_f32_16x16x32_bf16 v[4:7], v[144:147], v[200:203], v[4:7]
	v_mfma_f32_16x16x32_bf16 v[0:3], v[152:155], v[200:203], v[0:3]
	v_mfma_f32_16x16x32_bf16 v[52:55], v[148:151], v[180:183], v[52:55]
	v_mfma_f32_16x16x32_bf16 v[48:51], v[156:159], v[180:183], v[48:51]
	v_mfma_f32_16x16x32_bf16 v[36:39], v[148:151], v[188:191], v[36:39]
	v_mfma_f32_16x16x32_bf16 v[32:35], v[156:159], v[188:191], v[32:35]
	v_mfma_f32_16x16x32_bf16 v[20:23], v[148:151], v[196:199], v[20:23]
	v_mfma_f32_16x16x32_bf16 v[16:19], v[156:159], v[196:199], v[16:19]
	v_mfma_f32_16x16x32_bf16 v[4:7], v[148:151], v[204:207], v[4:7]
	v_mfma_f32_16x16x32_bf16 v[0:3], v[156:159], v[204:207], v[0:3]

; #define PG8_STAGE(bufoff, gbase, voff) do { _Pragma("unroll") for (int _i = 0; _i < 2; ++_i) \
;         __builtin_amdgcn_global_load_lds((const unsigned*)((const char*)(gbase) + (voff)[_i]), (PG8_LAS unsigned*)(lds + (bufoff) + ldsw + _i * 8192), 16, 0, 0); } while (0)
; #define PG8_LDA(dst, b, h) do { _Pragma("unroll") for (int m = 0; m < 4; ++m) _Pragma("unroll") for (int k = 0; k < 2; ++k) dst[m][k] = *(const PG8_LAS bf16x8*)(lds + PG8_SA(b, h) + aoff + m * 2048 + k * 1024); } while (0)
; #define PG8_LDB(dst, b, h) do { _Pragma("unroll") for (int n = 0; n < 2; ++n) _Pragma("unroll") for (int k = 0; k < 2; ++k) dst[n][k] = *(const PG8_LAS bf16x8*)(lds + PG8_SB(b, h) + boff + n * 2048 + k * 1024); } while (0)
; #define PG8_MMA(ai, bj, At, Bt) do { __builtin_amdgcn_s_setprio(1); _Pragma("unroll") for (int m = 0; m < 4; ++m) _Pragma("unroll") for (int n = 0; n < 2; ++n) _Pragma("unroll") for (int k = 0; k < 2; ++k) \
;         acc[ai][bj][m][n] = __builtin_amdgcn_mfma_f32_16x16x32_bf16(Bt[n][k], At[m][k], acc[ai][bj][m][n], 0, 0, 0); __builtin_amdgcn_s_setprio(0); } while (0)
; #define PG8_WAIT_V(n) asm volatile("s_waitcnt vmcnt(" #n ")" ::: "memory")
; #define PG8_WAIT_L(n) asm volatile("s_waitcnt lgkmcnt(" #n ")" ::: "memory")
; #define PG8_BAR __builtin_amdgcn_s_barrier()
; #define PG8_SCHED __builtin_amdgcn_sched_barrier(0)
; template <class Epi, class Sched, bool ALIGN_EPI = false, bool SP2 = false>
; __device__ __forceinline__ void gemm_phase(PG8_LAS unsigned char* lds, const Gemm g, const Sched& S, const Epi& E) {
;     ...
;             PG8_WAIT_V(8); PG8_WAIT_L(0); PG8_BAR; PG8_MMA(1, 0, At, B0); PG8_MMA(1, 1, At, B1); PG8_BAR; PG8_SCHED;
;             PG8_LDB(B0, 1, 0); PG8_LDB(B1, 1, 1); PG8_SCHED; PG8_LDA(At, 1, 0); PG8_STAGE(PG8_SA(0, 1), a2 + hstep, voffA);
	s_barrier
	s_add_i32 s82, 0, 0x18000
	s_add_i32 s83, 0, 0x1c000


; #define PG8_STAGE(bufoff, gbase, voff) do { _Pragma("unroll") for (int _i = 0; _i < 2; ++_i) \
;         __builtin_amdgcn_global_load_lds((const unsigned*)((const char*)(gbase) + (voff)[_i]), (PG8_LAS unsigned*)(lds + (bufoff) + ldsw + _i * 8192), 16, 0, 0); } while (0)
; #define PG8_LDA(dst, b, h) do { _Pragma("unroll") for (int m = 0; m < 4; ++m) _Pragma("unroll") for (int k = 0; k < 2; ++k) dst[m][k] = *(const PG8_LAS bf16x8*)(lds + PG8_SA(b, h) + aoff + m * 2048 + k * 1024); } while (0)
; #define PG8_LDB(dst, b, h) do { _Pragma("unroll") for (int n = 0; n < 2; ++n) _Pragma("unroll") for (int k = 0; k < 2; ++k) dst[n][k] = *(const PG8_LAS bf16x8*)(lds + PG8_SB(b, h) + boff + n * 2048 + k * 1024); } while (0)
; #define PG8_SCHED __builtin_amdgcn_sched_barrier(0)
; template <class Epi, class Sched, bool ALIGN_EPI = false, bool SP2 = false>
; __device__ __forceinline__ void gemm_phase(PG8_LAS unsigned char* lds, const Gemm g, const Sched& S, const Epi& E) {
;     ...
;             PG8_LDB(B0, 1, 0); PG8_LDB(B1, 1, 1); PG8_SCHED; PG8_LDA(At, 1, 0); PG8_STAGE(PG8_SA(0, 1), a2 + hstep, voffA);
	ds_read_b128 v[64:67], v254
	ds_read_b128 v[68:71], v254 offset:1024
	ds_read_b128 v[72:75], v254 offset:2048
	ds_read_b128 v[76:79], v254 offset:3072
	ds_read_b128 v[144:147], v255
	ds_read_b128 v[148:151], v255 offset:1024
	ds_read_b128 v[152:155], v255 offset:2048
	ds_read_b128 v[156:159], v255 offset:3072
	s_add_u32 s62, s62, 0x200000
	s_addc_u32 s63, s63, 0
	s_mov_b32 m0, s67

; #define PG8_STAGE(bufoff, gbase, voff) do { _Pragma("unroll") for (int _i = 0; _i < 2; ++_i) \
;         __builtin_amdgcn_global_load_lds((const unsigned*)((const char*)(gbase) + (voff)[_i]), (PG8_LAS unsigned*)(lds + (bufoff) + ldsw + _i * 8192), 16, 0, 0); } while (0)
; #define PG8_LDA(dst, b, h) do { _Pragma("unroll") for (int m = 0; m < 4; ++m) _Pragma("unroll") for (int k = 0; k < 2; ++k) dst[m][k] = *(const PG8_LAS bf16x8*)(lds + PG8_SA(b, h) + aoff + m * 2048 + k * 1024); } while (0)
; #define PG8_LDB(dst, b, h) do { _Pragma("unroll") for (int n = 0; n < 2; ++n) _Pragma("unroll") for (int k = 0; k < 2; ++k) dst[n][k] = *(const PG8_LAS bf16x8*)(lds + PG8_SB(b, h) + boff + n * 2048 + k * 1024); } while (0)
; #define PG8_SCHED __builtin_amdgcn_sched_barrier(0)
; template <class Epi, class Sched, bool ALIGN_EPI = false, bool SP2 = false>
; __device__ __forceinline__ void gemm_phase(PG8_LAS unsigned char* lds, const Gemm g, const Sched& S, const Epi& E) {
;     ...
;             PG8_LDB(B0, 1, 0); PG8_LDB(B1, 1, 1); PG8_SCHED; PG8_LDA(At, 1, 0); PG8_STAGE(PG8_SA(0, 1), a2 + hstep, voffA);
	ds_read_b128 v[176:179], v215 offset:32768
	ds_read_b128 v[180:183], v215 offset:33792
	ds_read_b128 v[184:187], v215 offset:34816
	ds_read_b128 v[188:191], v215 offset:35840
	ds_read_b128 v[192:195], v215 offset:36864
	ds_read_b128 v[196:199], v215 offset:37888
	ds_read_b128 v[200:203], v215 offset:38912
	ds_read_b128 v[204:207], v215 offset:39936
	global_load_lds_dwordx4 v160, s[62:63]

; #define PG8_STAGE(bufoff, gbase, voff) do { _Pragma("unroll") for (int _i = 0; _i < 2; ++_i) \
;         __builtin_amdgcn_global_load_lds((const unsigned*)((const char*)(gbase) + (voff)[_i]), (PG8_LAS unsigned*)(lds + (bufoff) + ldsw + _i * 8192), 16, 0, 0); } while (0)
; #define PG8_LDA(dst, b, h) do { _Pragma("unroll") for (int m = 0; m < 4; ++m) _Pragma("unroll") for (int k = 0; k < 2; ++k) dst[m][k] = *(const PG8_LAS bf16x8*)(lds + PG8_SA(b, h) + aoff + m * 2048 + k * 1024); } while (0)
; #define PG8_LDB(dst, b, h) do { _Pragma("unroll") for (int n = 0; n < 2; ++n) _Pragma("unroll") for (int k = 0; k < 2; ++k) dst[n][k] = *(const PG8_LAS bf16x8*)(lds + PG8_SB(b, h) + boff + n * 2048 + k * 1024); } while (0)
; #define PG8_MMA(ai, bj, At, Bt) do { __builtin_amdgcn_s_setprio(1); _Pragma("unroll") for (int m = 0; m < 4; ++m) _Pragma("unroll") for (int n = 0; n < 2; ++n) _Pragma("unroll") for (int k = 0; k < 2; ++k) \
;         acc[ai][bj][m][n] = __builtin_amdgcn_mfma_f32_16x16x32_bf16(Bt[n][k], At[m][k], acc[ai][bj][m][n], 0, 0, 0); __builtin_amdgcn_s_setprio(0); } while (0)
; #define PG8_WAIT_V(n) asm volatile("s_waitcnt vmcnt(" #n ")" ::: "memory")
; #define PG8_WAIT_L(n) asm volatile("s_waitcnt lgkmcnt(" #n ")" ::: "memory")
; #define PG8_BAR __builtin_amdgcn_s_barrier()
; #define PG8_SCHED __builtin_amdgcn_sched_barrier(0)
; template <class Epi, class Sched, bool ALIGN_EPI = false, bool SP2 = false>
; __device__ __forceinline__ void gemm_phase(PG8_LAS unsigned char* lds, const Gemm g, const Sched& S, const Epi& E) {
;     ...
;             PG8_LDB(B0, 1, 0); PG8_LDB(B1, 1, 1); PG8_SCHED; PG8_LDA(At, 1, 0); PG8_STAGE(PG8_SA(0, 1), a2 + hstep, voffA);
;             PG8_WAIT_V(8); PG8_WAIT_L(0); PG8_BAR; PG8_MMA(0, 0, At, B0); PG8_MMA(0, 1, At, B1); PG8_BAR; PG8_SCHED;
	s_mov_b32 m0, s68
	s_nop 0
	global_load_lds_dwordx4 v164, s[62:63]
	s_waitcnt vmcnt(8) lgkmcnt(0)


; #define PG8_MMA(ai, bj, At, Bt) do { __builtin_amdgcn_s_setprio(1); _Pragma("unroll") for (int m = 0; m < 4; ++m) _Pragma("unroll") for (int n = 0; n < 2; ++n) _Pragma("unroll") for (int k = 0; k < 2; ++k) \
;         acc[ai][bj][m][n] = __builtin_amdgcn_mfma_f32_16x16x32_bf16(Bt[n][k], At[m][k], acc[ai][bj][m][n], 0, 0, 0); __builtin_amdgcn_s_setprio(0); } while (0)
; #define PG8_WAIT_V(n) asm volatile("s_waitcnt vmcnt(" #n ")" ::: "memory")
; #define PG8_WAIT_L(n) asm volatile("s_waitcnt lgkmcnt(" #n ")" ::: "memory")
; #define PG8_BAR __builtin_amdgcn_s_barrier()
; #define PG8_SCHED __builtin_amdgcn_sched_barrier(0)
; template <class Epi, class Sched, bool ALIGN_EPI = false, bool SP2 = false>
; __device__ __forceinline__ void gemm_phase(PG8_LAS unsigned char* lds, const Gemm g, const Sched& S, const Epi& E) {
;     ...
;             PG8_WAIT_V(8); PG8_WAIT_L(0); PG8_BAR; PG8_MMA(0, 0, At, B0); PG8_MMA(0, 1, At, B1); PG8_BAR; PG8_SCHED;
	s_barrier

; #define PG8_MMA(ai, bj, At, Bt) do { __builtin_amdgcn_s_setprio(1); _Pragma("unroll") for (int m = 0; m < 4; ++m) _Pragma("unroll") for (int n = 0; n < 2; ++n) _Pragma("unroll") for (int k = 0; k < 2; ++k) \
;         acc[ai][bj][m][n] = __builtin_amdgcn_mfma_f32_16x16x32_bf16(Bt[n][k], At[m][k], acc[ai][bj][m][n], 0, 0, 0); __builtin_amdgcn_s_setprio(0); } while (0)
; #define PG8_WAIT_V(n) asm volatile("s_waitcnt vmcnt(" #n ")" ::: "memory")
; #define PG8_WAIT_L(n) asm volatile("s_waitcnt lgkmcnt(" #n ")" ::: "memory")
; #define PG8_BAR __builtin_amdgcn_s_barrier()
; #define PG8_SCHED __builtin_amdgcn_sched_barrier(0)
; template <class Epi, class Sched, bool ALIGN_EPI = false, bool SP2 = false>
; __device__ __forceinline__ void gemm_phase(PG8_LAS unsigned char* lds, const Gemm g, const Sched& S, const Epi& E) {
;     ...
;             PG8_WAIT_V(8); PG8_WAIT_L(0); PG8_BAR; PG8_MMA(0, 0, At, B0); PG8_MMA(0, 1, At, B1); PG8_BAR; PG8_SCHED;
	v_mfma_f32_16x16x32_bf16 v[140:143], v[64:67], v[176:179], v[140:143]
	v_mfma_f32_16x16x32_bf16 v[136:139], v[72:75], v[176:179], v[136:139]
	v_mfma_f32_16x16x32_bf16 v[124:127], v[64:67], v[184:187], v[124:127]
	v_mfma_f32_16x16x32_bf16 v[120:123], v[72:75], v[184:187], v[120:123]
	v_mfma_f32_16x16x32_bf16 v[108:111], v[64:67], v[192:195], v[108:111]
	v_mfma_f32_16x16x32_bf16 v[104:107], v[72:75], v[192:195], v[104:107]
	v_mfma_f32_16x16x32_bf16 v[92:95], v[64:67], v[200:203], v[92:95]
	v_mfma_f32_16x16x32_bf16 v[88:91], v[72:75], v[200:203], v[88:91]
	v_mfma_f32_16x16x32_bf16 v[140:143], v[68:71], v[180:183], v[140:143]
	v_mfma_f32_16x16x32_bf16 v[136:139], v[76:79], v[180:183], v[136:139]
	v_mfma_f32_16x16x32_bf16 v[124:127], v[68:71], v[188:191], v[124:127]
	v_mfma_f32_16x16x32_bf16 v[120:123], v[76:79], v[188:191], v[120:123]
	v_mfma_f32_16x16x32_bf16 v[108:111], v[68:71], v[196:199], v[108:111]
	v_mfma_f32_16x16x32_bf16 v[104:107], v[76:79], v[196:199], v[104:107]
	v_mfma_f32_16x16x32_bf16 v[92:95], v[68:71], v[204:207], v[92:95]
	v_mfma_f32_16x16x32_bf16 v[88:91], v[76:79], v[204:207], v[88:91]


; #define PG8_MMA(ai, bj, At, Bt) do { __builtin_amdgcn_s_setprio(1); _Pragma("unroll") for (int m = 0; m < 4; ++m) _Pragma("unroll") for (int n = 0; n < 2; ++n) _Pragma("unroll") for (int k = 0; k < 2; ++k) \
;         acc[ai][bj][m][n] = __builtin_amdgcn_mfma_f32_16x16x32_bf16(Bt[n][k], At[m][k], acc[ai][bj][m][n], 0, 0, 0); __builtin_amdgcn_s_setprio(0); } while (0)
; #define PG8_WAIT_V(n) asm volatile("s_waitcnt vmcnt(" #n ")" ::: "memory")
; #define PG8_WAIT_L(n) asm volatile("s_waitcnt lgkmcnt(" #n ")" ::: "memory")
; #define PG8_BAR __builtin_amdgcn_s_barrier()
; #define PG8_SCHED __builtin_amdgcn_sched_barrier(0)
; template <class Epi, class Sched, bool ALIGN_EPI = false, bool SP2 = false>
; __device__ __forceinline__ void gemm_phase(PG8_LAS unsigned char* lds, const Gemm g, const Sched& S, const Epi& E) {
;     ...
;             PG8_WAIT_V(8); PG8_WAIT_L(0); PG8_BAR; PG8_MMA(0, 0, At, B0); PG8_MMA(0, 1, At, B1); PG8_BAR; PG8_SCHED;
	v_mfma_f32_16x16x32_bf16 v[132:135], v[144:147], v[176:179], v[132:135]
	v_mfma_f32_16x16x32_bf16 v[128:131], v[152:155], v[176:179], v[128:131]
	v_mfma_f32_16x16x32_bf16 v[116:119], v[144:147], v[184:187], v[116:119]
	v_mfma_f32_16x16x32_bf16 v[112:115], v[152:155], v[184:187], v[112:115]
	v_mfma_f32_16x16x32_bf16 v[100:103], v[144:147], v[192:195], v[100:103]
	v_mfma_f32_16x16x32_bf16 v[96:99], v[152:155], v[192:195], v[96:99]
	v_mfma_f32_16x16x32_bf16 v[84:87], v[144:147], v[200:203], v[84:87]
	v_mfma_f32_16x16x32_bf16 v[80:83], v[152:155], v[200:203], v[80:83]
	v_mfma_f32_16x16x32_bf16 v[132:135], v[148:151], v[180:183], v[132:135]
	v_mfma_f32_16x16x32_bf16 v[128:131], v[156:159], v[180:183], v[128:131]
	v_mfma_f32_16x16x32_bf16 v[116:119], v[148:151], v[188:191], v[116:119]
	v_mfma_f32_16x16x32_bf16 v[112:115], v[156:159], v[188:191], v[112:115]
	v_mfma_f32_16x16x32_bf16 v[100:103], v[148:151], v[196:199], v[100:103]
	v_mfma_f32_16x16x32_bf16 v[96:99], v[156:159], v[196:199], v[96:99]
	v_mfma_f32_16x16x32_bf16 v[84:87], v[148:151], v[204:207], v[84:87]
	v_mfma_f32_16x16x32_bf16 v[80:83], v[156:159], v[204:207], v[80:83]

; #define PG8_STAGE(bufoff, gbase, voff) do { _Pragma("unroll") for (int _i = 0; _i < 2; ++_i) \
;         __builtin_amdgcn_global_load_lds((const unsigned*)((const char*)(gbase) + (voff)[_i]), (PG8_LAS unsigned*)(lds + (bufoff) + ldsw + _i * 8192), 16, 0, 0); } while (0)
; #define PG8_LDA(dst, b, h) do { _Pragma("unroll") for (int m = 0; m < 4; ++m) _Pragma("unroll") for (int k = 0; k < 2; ++k) dst[m][k] = *(const PG8_LAS bf16x8*)(lds + PG8_SA(b, h) + aoff + m * 2048 + k * 1024); } while (0)
; #define PG8_MMA(ai, bj, At, Bt) do { __builtin_amdgcn_s_setprio(1); _Pragma("unroll") for (int m = 0; m < 4; ++m) _Pragma("unroll") for (int n = 0; n < 2; ++n) _Pragma("unroll") for (int k = 0; k < 2; ++k) \
;         acc[ai][bj][m][n] = __builtin_amdgcn_mfma_f32_16x16x32_bf16(Bt[n][k], At[m][k], acc[ai][bj][m][n], 0, 0, 0); __builtin_amdgcn_s_setprio(0); } while (0)
; #define PG8_WAIT_V(n) asm volatile("s_waitcnt vmcnt(" #n ")" ::: "memory")
; #define PG8_WAIT_L(n) asm volatile("s_waitcnt lgkmcnt(" #n ")" ::: "memory")
; #define PG8_BAR __builtin_amdgcn_s_barrier()
; #define PG8_SCHED __builtin_amdgcn_sched_barrier(0)
; template <class Epi, class Sched, bool ALIGN_EPI = false, bool SP2 = false>
; __device__ __forceinline__ void gemm_phase(PG8_LAS unsigned char* lds, const Gemm g, const Sched& S, const Epi& E) {
;     ...
;             PG8_WAIT_V(8); PG8_WAIT_L(0); PG8_BAR; PG8_MMA(0, 0, At, B0); PG8_MMA(0, 1, At, B1); PG8_BAR; PG8_SCHED;
;             PG8_LDA(At, 1, 1); PG8_STAGE(PG8_SB(1, 0), b3, voffB); PG8_STAGE(PG8_SB(1, 1), b3 + hstep, voffB); PG8_STAGE(PG8_SA(1, 0), a3, voffA);
	s_barrier
	s_add_i32 s62, s82, s64

; #define PG8_STAGE(bufoff, gbase, voff) do { _Pragma("unroll") for (int _i = 0; _i < 2; ++_i) \
;         __builtin_amdgcn_global_load_lds((const unsigned*)((const char*)(gbase) + (voff)[_i]), (PG8_LAS unsigned*)(lds + (bufoff) + ldsw + _i * 8192), 16, 0, 0); } while (0)
; #define PG8_LDA(dst, b, h) do { _Pragma("unroll") for (int m = 0; m < 4; ++m) _Pragma("unroll") for (int k = 0; k < 2; ++k) dst[m][k] = *(const PG8_LAS bf16x8*)(lds + PG8_SA(b, h) + aoff + m * 2048 + k * 1024); } while (0)
; template <class Epi, class Sched, bool ALIGN_EPI = false, bool SP2 = false>
; __device__ __forceinline__ void gemm_phase(PG8_LAS unsigned char* lds, const Gemm g, const Sched& S, const Epi& E) {
;     ...
;             PG8_LDA(At, 1, 1); PG8_STAGE(PG8_SB(1, 0), b3, voffB); PG8_STAGE(PG8_SB(1, 1), b3 + hstep, voffB); PG8_STAGE(PG8_SA(1, 0), a3, voffA);
	s_mov_b32 m0, s62
	ds_read_b128 v[176:179], v215 offset:49152
	ds_read_b128 v[180:183], v215 offset:50176
	ds_read_b128 v[184:187], v215 offset:51200
	ds_read_b128 v[188:191], v215 offset:52224
	ds_read_b128 v[192:195], v215 offset:53248
	ds_read_b128 v[196:199], v215 offset:54272
	ds_read_b128 v[200:203], v215 offset:55296
	ds_read_b128 v[204:207], v215 offset:56320
	global_load_lds_dwordx4 v250, s[96:97]
	s_add_i32 m0, s62, 0x2000
	s_add_u32 s60, s60, 0x200080

; #define PG8_STAGE(bufoff, gbase, voff) do { _Pragma("unroll") for (int _i = 0; _i < 2; ++_i) \
;         __builtin_amdgcn_global_load_lds((const unsigned*)((const char*)(gbase) + (voff)[_i]), (PG8_LAS unsigned*)(lds + (bufoff) + ldsw + _i * 8192), 16, 0, 0); } while (0)
; #define PG8_LDA(dst, b, h) do { _Pragma("unroll") for (int m = 0; m < 4; ++m) _Pragma("unroll") for (int k = 0; k < 2; ++k) dst[m][k] = *(const PG8_LAS bf16x8*)(lds + PG8_SA(b, h) + aoff + m * 2048 + k * 1024); } while (0)
; template <class Epi, class Sched, bool ALIGN_EPI = false, bool SP2 = false>
; __device__ __forceinline__ void gemm_phase(PG8_LAS unsigned char* lds, const Gemm g, const Sched& S, const Epi& E) {
;     ...
;             PG8_LDA(At, 1, 1); PG8_STAGE(PG8_SB(1, 0), b3, voffB); PG8_STAGE(PG8_SB(1, 1), b3 + hstep, voffB); PG8_STAGE(PG8_SA(1, 0), a3, voffA);
	s_addc_u32 s61, s61, 0
	s_add_i32 s62, s83, s64
	global_load_lds_dwordx4 v251, s[96:97]

; #define PG8_STAGE(bufoff, gbase, voff) do { _Pragma("unroll") for (int _i = 0; _i < 2; ++_i) \
;         __builtin_amdgcn_global_load_lds((const unsigned*)((const char*)(gbase) + (voff)[_i]), (PG8_LAS unsigned*)(lds + (bufoff) + ldsw + _i * 8192), 16, 0, 0); } while (0)
; #define PG8_LDA(dst, b, h) do { _Pragma("unroll") for (int m = 0; m < 4; ++m) _Pragma("unroll") for (int k = 0; k < 2; ++k) dst[m][k] = *(const PG8_LAS bf16x8*)(lds + PG8_SA(b, h) + aoff + m * 2048 + k * 1024); } while (0)
; template <class Epi, class Sched, bool ALIGN_EPI = false, bool SP2 = false>
; __device__ __forceinline__ void gemm_phase(PG8_LAS unsigned char* lds, const Gemm g, const Sched& S, const Epi& E) {
;     ...
;             PG8_LDA(At, 1, 1); PG8_STAGE(PG8_SB(1, 0), b3, voffB); PG8_STAGE(PG8_SB(1, 1), b3 + hstep, voffB); PG8_STAGE(PG8_SA(1, 0), a3, voffA);
	s_mov_b32 m0, s62
	s_nop 0
	global_load_lds_dwordx4 v162, s[60:61]

; #define PG8_STAGE(bufoff, gbase, voff) do { _Pragma("unroll") for (int _i = 0; _i < 2; ++_i) \
;         __builtin_amdgcn_global_load_lds((const unsigned*)((const char*)(gbase) + (voff)[_i]), (PG8_LAS unsigned*)(lds + (bufoff) + ldsw + _i * 8192), 16, 0, 0); } while (0)
; #define PG8_LDA(dst, b, h) do { _Pragma("unroll") for (int m = 0; m < 4; ++m) _Pragma("unroll") for (int k = 0; k < 2; ++k) dst[m][k] = *(const PG8_LAS bf16x8*)(lds + PG8_SA(b, h) + aoff + m * 2048 + k * 1024); } while (0)
; template <class Epi, class Sched, bool ALIGN_EPI = false, bool SP2 = false>
; __device__ __forceinline__ void gemm_phase(PG8_LAS unsigned char* lds, const Gemm g, const Sched& S, const Epi& E) {
;     ...
;             PG8_LDA(At, 1, 1); PG8_STAGE(PG8_SB(1, 0), b3, voffB); PG8_STAGE(PG8_SB(1, 1), b3 + hstep, voffB); PG8_STAGE(PG8_SA(1, 0), a3, voffA);
	s_add_i32 m0, s62, 0x2000
	s_nop 0
	global_load_lds_dwordx4 v166, s[60:61]

; #define PG8_STAGE(bufoff, gbase, voff) do { _Pragma("unroll") for (int _i = 0; _i < 2; ++_i) \
;         __builtin_amdgcn_global_load_lds((const unsigned*)((const char*)(gbase) + (voff)[_i]), (PG8_LAS unsigned*)(lds + (bufoff) + ldsw + _i * 8192), 16, 0, 0); } while (0)
; #define PG8_LDA(dst, b, h) do { _Pragma("unroll") for (int m = 0; m < 4; ++m) _Pragma("unroll") for (int k = 0; k < 2; ++k) dst[m][k] = *(const PG8_LAS bf16x8*)(lds + PG8_SA(b, h) + aoff + m * 2048 + k * 1024); } while (0)
; template <class Epi, class Sched, bool ALIGN_EPI = false, bool SP2 = false>
; __device__ __forceinline__ void gemm_phase(PG8_LAS unsigned char* lds, const Gemm g, const Sched& S, const Epi& E) {
;     ...
;             PG8_LDA(At, 1, 1); PG8_STAGE(PG8_SB(1, 0), b3, voffB); PG8_STAGE(PG8_SB(1, 1), b3 + hstep, voffB); PG8_STAGE(PG8_SA(1, 0), a3, voffA);
	s_mov_b32 m0, s70
	s_nop 0
	global_load_lds_dwordx4 v252, s[98:99]

; #define PG8_STAGE(bufoff, gbase, voff) do { _Pragma("unroll") for (int _i = 0; _i < 2; ++_i) \
;         __builtin_amdgcn_global_load_lds((const unsigned*)((const char*)(gbase) + (voff)[_i]), (PG8_LAS unsigned*)(lds + (bufoff) + ldsw + _i * 8192), 16, 0, 0); } while (0)
; #define PG8_LDA(dst, b, h) do { _Pragma("unroll") for (int m = 0; m < 4; ++m) _Pragma("unroll") for (int k = 0; k < 2; ++k) dst[m][k] = *(const PG8_LAS bf16x8*)(lds + PG8_SA(b, h) + aoff + m * 2048 + k * 1024); } while (0)
; #define PG8_MMA(ai, bj, At, Bt) do { __builtin_amdgcn_s_setprio(1); _Pragma("unroll") for (int m = 0; m < 4; ++m) _Pragma("unroll") for (int n = 0; n < 2; ++n) _Pragma("unroll") for (int k = 0; k < 2; ++k) \
;         acc[ai][bj][m][n] = __builtin_amdgcn_mfma_f32_16x16x32_bf16(Bt[n][k], At[m][k], acc[ai][bj][m][n], 0, 0, 0); __builtin_amdgcn_s_setprio(0); } while (0)
; #define PG8_WAIT_V(n) asm volatile("s_waitcnt vmcnt(" #n ")" ::: "memory")
; #define PG8_WAIT_L(n) asm volatile("s_waitcnt lgkmcnt(" #n ")" ::: "memory")
; #define PG8_BAR __builtin_amdgcn_s_barrier()
; #define PG8_SCHED __builtin_amdgcn_sched_barrier(0)
; template <class Epi, class Sched, bool ALIGN_EPI = false, bool SP2 = false>
; __device__ __forceinline__ void gemm_phase(PG8_LAS unsigned char* lds, const Gemm g, const Sched& S, const Epi& E) {
;     ...
;             PG8_LDA(At, 1, 1); PG8_STAGE(PG8_SB(1, 0), b3, voffB); PG8_STAGE(PG8_SB(1, 1), b3 + hstep, voffB); PG8_STAGE(PG8_SA(1, 0), a3, voffA);
;             PG8_WAIT_V(8); PG8_WAIT_L(0); PG8_BAR; PG8_MMA(1, 0, At, B0); PG8_MMA(1, 1, At, B1); PG8_BAR; PG8_SCHED;
	s_mov_b32 m0, s71
	s_nop 0
	global_load_lds_dwordx4 v253, s[98:99]
	s_waitcnt vmcnt(8) lgkmcnt(0)


; #define PG8_MMA(ai, bj, At, Bt) do { __builtin_amdgcn_s_setprio(1); _Pragma("unroll") for (int m = 0; m < 4; ++m) _Pragma("unroll") for (int n = 0; n < 2; ++n) _Pragma("unroll") for (int k = 0; k < 2; ++k) \
;         acc[ai][bj][m][n] = __builtin_amdgcn_mfma_f32_16x16x32_bf16(Bt[n][k], At[m][k], acc[ai][bj][m][n], 0, 0, 0); __builtin_amdgcn_s_setprio(0); } while (0)
; #define PG8_WAIT_V(n) asm volatile("s_waitcnt vmcnt(" #n ")" ::: "memory")
; #define PG8_WAIT_L(n) asm volatile("s_waitcnt lgkmcnt(" #n ")" ::: "memory")
; #define PG8_BAR __builtin_amdgcn_s_barrier()
; #define PG8_SCHED __builtin_amdgcn_sched_barrier(0)
; template <class Epi, class Sched, bool ALIGN_EPI = false, bool SP2 = false>
; __device__ __forceinline__ void gemm_phase(PG8_LAS unsigned char* lds, const Gemm g, const Sched& S, const Epi& E) {
;     ...
;             PG8_WAIT_V(8); PG8_WAIT_L(0); PG8_BAR; PG8_MMA(1, 0, At, B0); PG8_MMA(1, 1, At, B1); PG8_BAR; PG8_SCHED;
	s_barrier

; #define PG8_MMA(ai, bj, At, Bt) do { __builtin_amdgcn_s_setprio(1); _Pragma("unroll") for (int m = 0; m < 4; ++m) _Pragma("unroll") for (int n = 0; n < 2; ++n) _Pragma("unroll") for (int k = 0; k < 2; ++k) \
;         acc[ai][bj][m][n] = __builtin_amdgcn_mfma_f32_16x16x32_bf16(Bt[n][k], At[m][k], acc[ai][bj][m][n], 0, 0, 0); __builtin_amdgcn_s_setprio(0); } while (0)
; #define PG8_WAIT_V(n) asm volatile("s_waitcnt vmcnt(" #n ")" ::: "memory")
; #define PG8_WAIT_L(n) asm volatile("s_waitcnt lgkmcnt(" #n ")" ::: "memory")
; #define PG8_BAR __builtin_amdgcn_s_barrier()
; #define PG8_SCHED __builtin_amdgcn_sched_barrier(0)
; template <class Epi, class Sched, bool ALIGN_EPI = false, bool SP2 = false>
; __device__ __forceinline__ void gemm_phase(PG8_LAS unsigned char* lds, const Gemm g, const Sched& S, const Epi& E) {
;     ...
;             PG8_WAIT_V(8); PG8_WAIT_L(0); PG8_BAR; PG8_MMA(1, 0, At, B0); PG8_MMA(1, 1, At, B1); PG8_BAR; PG8_SCHED;
	v_mfma_f32_16x16x32_bf16 v[60:63], v[64:67], v[176:179], v[60:63]
	v_mfma_f32_16x16x32_bf16 v[56:59], v[72:75], v[176:179], v[56:59]
	v_mfma_f32_16x16x32_bf16 v[44:47], v[64:67], v[184:187], v[44:47]
	v_mfma_f32_16x16x32_bf16 v[40:43], v[72:75], v[184:187], v[40:43]
	v_mfma_f32_16x16x32_bf16 v[28:31], v[64:67], v[192:195], v[28:31]
	v_mfma_f32_16x16x32_bf16 v[24:27], v[72:75], v[192:195], v[24:27]
	v_mfma_f32_16x16x32_bf16 v[12:15], v[64:67], v[200:203], v[12:15]
	v_mfma_f32_16x16x32_bf16 v[8:11], v[72:75], v[200:203], v[8:11]
	v_mfma_f32_16x16x32_bf16 v[60:63], v[68:71], v[180:183], v[60:63]
	v_mfma_f32_16x16x32_bf16 v[56:59], v[76:79], v[180:183], v[56:59]
	v_mfma_f32_16x16x32_bf16 v[44:47], v[68:71], v[188:191], v[44:47]
	v_mfma_f32_16x16x32_bf16 v[40:43], v[76:79], v[188:191], v[40:43]
	v_mfma_f32_16x16x32_bf16 v[28:31], v[68:71], v[196:199], v[28:31]
	v_mfma_f32_16x16x32_bf16 v[24:27], v[76:79], v[196:199], v[24:27]
	v_mfma_f32_16x16x32_bf16 v[12:15], v[68:71], v[204:207], v[12:15]
	v_mfma_f32_16x16x32_bf16 v[8:11], v[76:79], v[204:207], v[8:11]


; #define PG8_MMA(ai, bj, At, Bt) do { __builtin_amdgcn_s_setprio(1); _Pragma("unroll") for (int m = 0; m < 4; ++m) _Pragma("unroll") for (int n = 0; n < 2; ++n) _Pragma("unroll") for (int k = 0; k < 2; ++k) \
;         acc[ai][bj][m][n] = __builtin_amdgcn_mfma_f32_16x16x32_bf16(Bt[n][k], At[m][k], acc[ai][bj][m][n], 0, 0, 0); __builtin_amdgcn_s_setprio(0); } while (0)
; #define PG8_WAIT_V(n) asm volatile("s_waitcnt vmcnt(" #n ")" ::: "memory")
; #define PG8_WAIT_L(n) asm volatile("s_waitcnt lgkmcnt(" #n ")" ::: "memory")
; #define PG8_BAR __builtin_amdgcn_s_barrier()
; #define PG8_SCHED __builtin_amdgcn_sched_barrier(0)
; template <class Epi, class Sched, bool ALIGN_EPI = false, bool SP2 = false>
; __device__ __forceinline__ void gemm_phase(PG8_LAS unsigned char* lds, const Gemm g, const Sched& S, const Epi& E) {
;     ...
;             PG8_WAIT_V(8); PG8_WAIT_L(0); PG8_BAR; PG8_MMA(1, 0, At, B0); PG8_MMA(1, 1, At, B1); PG8_BAR; PG8_SCHED;
	v_mfma_f32_16x16x32_bf16 v[52:55], v[144:147], v[176:179], v[52:55]
	v_mfma_f32_16x16x32_bf16 v[48:51], v[152:155], v[176:179], v[48:51]
	v_mfma_f32_16x16x32_bf16 v[36:39], v[144:147], v[184:187], v[36:39]
	v_mfma_f32_16x16x32_bf16 v[32:35], v[152:155], v[184:187], v[32:35]
	v_mfma_f32_16x16x32_bf16 v[20:23], v[144:147], v[192:195], v[20:23]
	v_mfma_f32_16x16x32_bf16 v[16:19], v[152:155], v[192:195], v[16:19]
	v_mfma_f32_16x16x32_bf16 v[4:7], v[144:147], v[200:203], v[4:7]
	v_mfma_f32_16x16x32_bf16 v[0:3], v[152:155], v[200:203], v[0:3]
	v_mfma_f32_16x16x32_bf16 v[52:55], v[148:151], v[180:183], v[52:55]
	v_mfma_f32_16x16x32_bf16 v[48:51], v[156:159], v[180:183], v[48:51]
	v_mfma_f32_16x16x32_bf16 v[36:39], v[148:151], v[188:191], v[36:39]
	v_mfma_f32_16x16x32_bf16 v[32:35], v[156:159], v[188:191], v[32:35]
	v_mfma_f32_16x16x32_bf16 v[20:23], v[148:151], v[196:199], v[20:23]
	v_mfma_f32_16x16x32_bf16 v[16:19], v[156:159], v[196:199], v[16:19]
	v_mfma_f32_16x16x32_bf16 v[4:7], v[148:151], v[204:207], v[4:7]
	v_mfma_f32_16x16x32_bf16 v[0:3], v[156:159], v[204:207], v[0:3]

; #define PG8_STAGE(bufoff, gbase, voff) do { _Pragma("unroll") for (int _i = 0; _i < 2; ++_i) \
;         __builtin_amdgcn_global_load_lds((const unsigned*)((const char*)(gbase) + (voff)[_i]), (PG8_LAS unsigned*)(lds + (bufoff) + ldsw + _i * 8192), 16, 0, 0); } while (0)
; #define PG8_LDA(dst, b, h) do { _Pragma("unroll") for (int m = 0; m < 4; ++m) _Pragma("unroll") for (int k = 0; k < 2; ++k) dst[m][k] = *(const PG8_LAS bf16x8*)(lds + PG8_SA(b, h) + aoff + m * 2048 + k * 1024); } while (0)
; #define PG8_WAIT_V(n) asm volatile("s_waitcnt vmcnt(" #n ")" ::: "memory")
; #define PG8_WAIT_L(n) asm volatile("s_waitcnt lgkmcnt(" #n ")" ::: "memory")
; template <class Epi, class Sched, bool ALIGN_EPI = false, bool SP2 = false>
; __device__ __forceinline__ void gemm_phase(PG8_LAS unsigned char* lds, const Gemm g, const Sched& S, const Epi& E) {
;     ...
;         for (int t = 0; t < nt; t += 2) {
;             const bool last = (t == nt - 2);
;             const char* a1 = cA + (size_t)(t + 1) * kstep;
;             const char* a2 = last ? nA : cA + (size_t)(t + 2) * kstep; const char* b2 = last ? nB : cB + (size_t)(t + 2) * kstep;
;             const char* a3 = a2 + kstep; const char* b3 = b2 + kstep;
;             if (last && has_next) S.a_ready(nxt);
;             if constexpr (SP2) {
;             PG8_LDB(B0, 0, 0); PG8_LDB(B1, 0, 1); PG8_SCHED; PG8_LDA(At, 0, 0); PG8_STAGE(PG8_SA(1, 1), a1 + hstep, voffA);
;             PG8_WAIT_V(8); PG8_WAIT_L(0); PG8_BAR; PG8_MMA(0, 0, At, B0); PG8_MMA(0, 1, At, B1); PG8_BAR; PG8_SCHED;
;             PG8_LDA(At, 0, 1); PG8_STAGE(PG8_SB(0, 0), b2, voffB); PG8_STAGE(PG8_SB(0, 1), b2 + hstep, voffB); PG8_STAGE(PG8_SA(0, 0), a2, voffA);
;             PG8_WAIT_V(8); PG8_WAIT_L(0); PG8_BAR; PG8_MMA(1, 0, At, B0); PG8_MMA(1, 1, At, B1); PG8_BAR; PG8_SCHED;
;             PG8_LDB(B0, 1, 0); PG8_LDB(B1, 1, 1); PG8_SCHED; PG8_LDA(At, 1, 0); PG8_STAGE(PG8_SA(0, 1), a2 + hstep, voffA);
;             PG8_WAIT_V(8); PG8_WAIT_L(0); PG8_BAR; PG8_MMA(0, 0, At, B0); PG8_MMA(0, 1, At, B1); PG8_BAR; PG8_SCHED;
;             PG8_LDA(At, 1, 1); PG8_STAGE(PG8_SB(1, 0), b3, voffB); PG8_STAGE(PG8_SB(1, 1), b3 + hstep, voffB); PG8_STAGE(PG8_SA(1, 0), a3, voffA);
;             PG8_WAIT_V(8); PG8_WAIT_L(0); PG8_BAR; PG8_MMA(1, 0, At, B0); PG8_MMA(1, 1, At, B1); PG8_BAR; PG8_SCHED;
;     ...
;         if constexpr (ALIGN_EPI) { if (wr == 0) PG8_BAR; }
	s_barrier
	s_add_i32 s81, s81, 2
	s_add_u32 s58, s58, 0x100
	s_addc_u32 s59, s59, 0
	s_add_u32 s79, s79, 0x100
	s_addc_u32 s80, s80, 0
	s_cmpk_gt_u32 s81, 0x7d
	s_cbranch_scc0 .LBB0_509
	s_and_b64 vcc, exec, s[42:43]
	s_cbranch_vccz .LBB0_512
	s_barrier

; #define PG8_STAGE(bufoff, gbase, voff) do { _Pragma("unroll") for (int _i = 0; _i < 2; ++_i) \
;         __builtin_amdgcn_global_load_lds((const unsigned*)((const char*)(gbase) + (voff)[_i]), (PG8_LAS unsigned*)(lds + (bufoff) + ldsw + _i * 8192), 16, 0, 0); } while (0)
; #define PG8_LDA(dst, b, h) do { _Pragma("unroll") for (int m = 0; m < 4; ++m) _Pragma("unroll") for (int k = 0; k < 2; ++k) dst[m][k] = *(const PG8_LAS bf16x8*)(lds + PG8_SA(b, h) + aoff + m * 2048 + k * 1024); } while (0)
; #define PG8_LDB(dst, b, h) do { _Pragma("unroll") for (int n = 0; n < 2; ++n) _Pragma("unroll") for (int k = 0; k < 2; ++k) dst[n][k] = *(const PG8_LAS bf16x8*)(lds + PG8_SB(b, h) + boff + n * 2048 + k * 1024); } while (0)
; #define PG8_SCHED __builtin_amdgcn_sched_barrier(0)
; template <class Epi, class Sched, bool ALIGN_EPI = false, bool SP2 = false>
; __device__ __forceinline__ void gemm_phase(PG8_LAS unsigned char* lds, const Gemm g, const Sched& S, const Epi& E) {
;     ...
;             const char* a1 = cA + (size_t)(t + 1) * kstep;
;             const char* a2 = last ? nA : cA + (size_t)(t + 2) * kstep; const char* b2 = last ? nB : cB + (size_t)(t + 2) * kstep;
;             const char* a3 = a2 + kstep; const char* b3 = b2 + kstep;
;             if (last && has_next) S.a_ready(nxt);
;             if constexpr (SP2) {
;             PG8_LDB(B0, 0, 0); PG8_LDB(B1, 0, 1); PG8_SCHED; PG8_LDA(At, 0, 0); PG8_STAGE(PG8_SA(1, 1), a1 + hstep, voffA);
.LBB0_679:
	ds_read_b128 v[128:131], v203
	ds_read_b128 v[132:135], v203 offset:1024
	ds_read_b128 v[136:139], v203 offset:2048
	ds_read_b128 v[140:143], v203 offset:3072
	ds_read_b128 v[144:147], v205
	ds_read_b128 v[148:151], v205 offset:1024
	ds_read_b128 v[152:155], v205 offset:2048
	ds_read_b128 v[156:159], v205 offset:3072
	s_add_u32 s12, s10, 0xfff80080
	s_addc_u32 s13, s11, -1
	s_cmp_eq_u32 s78, 28
	s_cselect_b32 s55, s49, s13
	s_cselect_b32 s54, s74, s12
	s_cselect_b32 s13, s47, s77
	s_cselect_b32 s12, s75, s76

; #define PG8_STAGE(bufoff, gbase, voff) do { _Pragma("unroll") for (int _i = 0; _i < 2; ++_i) \
;         __builtin_amdgcn_global_load_lds((const unsigned*)((const char*)(gbase) + (voff)[_i]), (PG8_LAS unsigned*)(lds + (bufoff) + ldsw + _i * 8192), 16, 0, 0); } while (0)
; #define PG8_LDA(dst, b, h) do { _Pragma("unroll") for (int m = 0; m < 4; ++m) _Pragma("unroll") for (int k = 0; k < 2; ++k) dst[m][k] = *(const PG8_LAS bf16x8*)(lds + PG8_SA(b, h) + aoff + m * 2048 + k * 1024); } while (0)
; #define PG8_LDB(dst, b, h) do { _Pragma("unroll") for (int n = 0; n < 2; ++n) _Pragma("unroll") for (int k = 0; k < 2; ++k) dst[n][k] = *(const PG8_LAS bf16x8*)(lds + PG8_SB(b, h) + boff + n * 2048 + k * 1024); } while (0)
; #define PG8_SCHED __builtin_amdgcn_sched_barrier(0)
; template <class Epi, class Sched, bool ALIGN_EPI = false, bool SP2 = false>
; __device__ __forceinline__ void gemm_phase(PG8_LAS unsigned char* lds, const Gemm g, const Sched& S, const Epi& E) {
;     ...
;             PG8_LDB(B0, 0, 0); PG8_LDB(B1, 0, 1); PG8_SCHED; PG8_LDA(At, 0, 0); PG8_STAGE(PG8_SA(1, 1), a1 + hstep, voffA);
	s_add_i32 m0, s60, 0xc000
	ds_read_b128 v[176:179], v207
	ds_read_b128 v[180:183], v207 offset:1024
	ds_read_b128 v[184:187], v207 offset:2048
	ds_read_b128 v[192:195], v207 offset:3072
	ds_read_b128 v[210:213], v207 offset:4096
	ds_read_b128 v[214:217], v207 offset:5120
	ds_read_b128 v[218:221], v207 offset:6144
	ds_read_b128 v[222:225], v207 offset:7168
	global_load_lds_dwordx4 v168, s[10:11]

; #define PG8_STAGE(bufoff, gbase, voff) do { _Pragma("unroll") for (int _i = 0; _i < 2; ++_i) \
;         __builtin_amdgcn_global_load_lds((const unsigned*)((const char*)(gbase) + (voff)[_i]), (PG8_LAS unsigned*)(lds + (bufoff) + ldsw + _i * 8192), 16, 0, 0); } while (0)
; #define PG8_LDA(dst, b, h) do { _Pragma("unroll") for (int m = 0; m < 4; ++m) _Pragma("unroll") for (int k = 0; k < 2; ++k) dst[m][k] = *(const PG8_LAS bf16x8*)(lds + PG8_SA(b, h) + aoff + m * 2048 + k * 1024); } while (0)
; #define PG8_LDB(dst, b, h) do { _Pragma("unroll") for (int n = 0; n < 2; ++n) _Pragma("unroll") for (int k = 0; k < 2; ++k) dst[n][k] = *(const PG8_LAS bf16x8*)(lds + PG8_SB(b, h) + boff + n * 2048 + k * 1024); } while (0)
; #define PG8_MMA(ai, bj, At, Bt) do { __builtin_amdgcn_s_setprio(1); _Pragma("unroll") for (int m = 0; m < 4; ++m) _Pragma("unroll") for (int n = 0; n < 2; ++n) _Pragma("unroll") for (int k = 0; k < 2; ++k) \
;         acc[ai][bj][m][n] = __builtin_amdgcn_mfma_f32_16x16x32_bf16(Bt[n][k], At[m][k], acc[ai][bj][m][n], 0, 0, 0); __builtin_amdgcn_s_setprio(0); } while (0)
; #define PG8_WAIT_V(n) asm volatile("s_waitcnt vmcnt(" #n ")" ::: "memory")
; #define PG8_WAIT_L(n) asm volatile("s_waitcnt lgkmcnt(" #n ")" ::: "memory")
; #define PG8_BAR __builtin_amdgcn_s_barrier()
; #define PG8_SCHED __builtin_amdgcn_sched_barrier(0)
; template <class Epi, class Sched, bool ALIGN_EPI = false, bool SP2 = false>
; __device__ __forceinline__ void gemm_phase(PG8_LAS unsigned char* lds, const Gemm g, const Sched& S, const Epi& E) {
;     ...
;             PG8_LDB(B0, 0, 0); PG8_LDB(B1, 0, 1); PG8_SCHED; PG8_LDA(At, 0, 0); PG8_STAGE(PG8_SA(1, 1), a1 + hstep, voffA);
;             PG8_WAIT_V(8); PG8_WAIT_L(0); PG8_BAR; PG8_MMA(0, 0, At, B0); PG8_MMA(0, 1, At, B1); PG8_BAR; PG8_SCHED;
	s_add_i32 m0, s60, 0xe000
	s_nop 0
	global_load_lds_dwordx4 v170, s[10:11]
	s_waitcnt vmcnt(8) lgkmcnt(0)


; #define PG8_MMA(ai, bj, At, Bt) do { __builtin_amdgcn_s_setprio(1); _Pragma("unroll") for (int m = 0; m < 4; ++m) _Pragma("unroll") for (int n = 0; n < 2; ++n) _Pragma("unroll") for (int k = 0; k < 2; ++k) \
;         acc[ai][bj][m][n] = __builtin_amdgcn_mfma_f32_16x16x32_bf16(Bt[n][k], At[m][k], acc[ai][bj][m][n], 0, 0, 0); __builtin_amdgcn_s_setprio(0); } while (0)
; #define PG8_WAIT_V(n) asm volatile("s_waitcnt vmcnt(" #n ")" ::: "memory")
; #define PG8_WAIT_L(n) asm volatile("s_waitcnt lgkmcnt(" #n ")" ::: "memory")
; #define PG8_BAR __builtin_amdgcn_s_barrier()
; #define PG8_SCHED __builtin_amdgcn_sched_barrier(0)
; template <class Epi, class Sched, bool ALIGN_EPI = false, bool SP2 = false>
; __device__ __forceinline__ void gemm_phase(PG8_LAS unsigned char* lds, const Gemm g, const Sched& S, const Epi& E) {
;     ...
;             PG8_WAIT_V(8); PG8_WAIT_L(0); PG8_BAR; PG8_MMA(0, 0, At, B0); PG8_MMA(0, 1, At, B1); PG8_BAR; PG8_SCHED;
	s_barrier

; #define PG8_MMA(ai, bj, At, Bt) do { __builtin_amdgcn_s_setprio(1); _Pragma("unroll") for (int m = 0; m < 4; ++m) _Pragma("unroll") for (int n = 0; n < 2; ++n) _Pragma("unroll") for (int k = 0; k < 2; ++k) \
;         acc[ai][bj][m][n] = __builtin_amdgcn_mfma_f32_16x16x32_bf16(Bt[n][k], At[m][k], acc[ai][bj][m][n], 0, 0, 0); __builtin_amdgcn_s_setprio(0); } while (0)
; #define PG8_WAIT_V(n) asm volatile("s_waitcnt vmcnt(" #n ")" ::: "memory")
; #define PG8_WAIT_L(n) asm volatile("s_waitcnt lgkmcnt(" #n ")" ::: "memory")
; #define PG8_BAR __builtin_amdgcn_s_barrier()
; #define PG8_SCHED __builtin_amdgcn_sched_barrier(0)
; template <class Epi, class Sched, bool ALIGN_EPI = false, bool SP2 = false>
; __device__ __forceinline__ void gemm_phase(PG8_LAS unsigned char* lds, const Gemm g, const Sched& S, const Epi& E) {
;     ...
;             PG8_WAIT_V(8); PG8_WAIT_L(0); PG8_BAR; PG8_MMA(0, 0, At, B0); PG8_MMA(0, 1, At, B1); PG8_BAR; PG8_SCHED;
	v_mfma_f32_16x16x32_bf16 v[124:127], v[128:131], v[176:179], v[124:127]
	v_mfma_f32_16x16x32_bf16 v[120:123], v[136:139], v[176:179], v[120:123]
	v_mfma_f32_16x16x32_bf16 v[112:115], v[128:131], v[184:187], v[112:115]
	v_mfma_f32_16x16x32_bf16 v[104:107], v[136:139], v[184:187], v[104:107]
	v_mfma_f32_16x16x32_bf16 v[100:103], v[128:131], v[210:213], v[100:103]
	v_mfma_f32_16x16x32_bf16 v[88:91], v[136:139], v[210:213], v[88:91]
	v_mfma_f32_16x16x32_bf16 v[84:87], v[128:131], v[218:221], v[84:87]
	v_mfma_f32_16x16x32_bf16 v[72:75], v[136:139], v[218:221], v[72:75]
	v_mfma_f32_16x16x32_bf16 v[124:127], v[132:135], v[180:183], v[124:127]
	v_mfma_f32_16x16x32_bf16 v[120:123], v[140:143], v[180:183], v[120:123]
	v_mfma_f32_16x16x32_bf16 v[112:115], v[132:135], v[192:195], v[112:115]
	v_mfma_f32_16x16x32_bf16 v[104:107], v[140:143], v[192:195], v[104:107]
	v_mfma_f32_16x16x32_bf16 v[100:103], v[132:135], v[214:217], v[100:103]
	v_mfma_f32_16x16x32_bf16 v[88:91], v[140:143], v[214:217], v[88:91]
	v_mfma_f32_16x16x32_bf16 v[84:87], v[132:135], v[222:225], v[84:87]
	v_mfma_f32_16x16x32_bf16 v[72:75], v[140:143], v[222:225], v[72:75]


; #define PG8_MMA(ai, bj, At, Bt) do { __builtin_amdgcn_s_setprio(1); _Pragma("unroll") for (int m = 0; m < 4; ++m) _Pragma("unroll") for (int n = 0; n < 2; ++n) _Pragma("unroll") for (int k = 0; k < 2; ++k) \
;         acc[ai][bj][m][n] = __builtin_amdgcn_mfma_f32_16x16x32_bf16(Bt[n][k], At[m][k], acc[ai][bj][m][n], 0, 0, 0); __builtin_amdgcn_s_setprio(0); } while (0)
; #define PG8_WAIT_V(n) asm volatile("s_waitcnt vmcnt(" #n ")" ::: "memory")
; #define PG8_WAIT_L(n) asm volatile("s_waitcnt lgkmcnt(" #n ")" ::: "memory")
; #define PG8_BAR __builtin_amdgcn_s_barrier()
; #define PG8_SCHED __builtin_amdgcn_sched_barrier(0)
; template <class Epi, class Sched, bool ALIGN_EPI = false, bool SP2 = false>
; __device__ __forceinline__ void gemm_phase(PG8_LAS unsigned char* lds, const Gemm g, const Sched& S, const Epi& E) {
;     ...
;             PG8_WAIT_V(8); PG8_WAIT_L(0); PG8_BAR; PG8_MMA(0, 0, At, B0); PG8_MMA(0, 1, At, B1); PG8_BAR; PG8_SCHED;
	v_mfma_f32_16x16x32_bf16 v[116:119], v[144:147], v[176:179], v[116:119]
	v_mfma_f32_16x16x32_bf16 v[108:111], v[152:155], v[176:179], v[108:111]
	v_mfma_f32_16x16x32_bf16 v[96:99], v[144:147], v[184:187], v[96:99]
	v_mfma_f32_16x16x32_bf16 v[92:95], v[152:155], v[184:187], v[92:95]
	v_mfma_f32_16x16x32_bf16 v[80:83], v[144:147], v[210:213], v[80:83]
	v_mfma_f32_16x16x32_bf16 v[76:79], v[152:155], v[210:213], v[76:79]
	v_mfma_f32_16x16x32_bf16 v[68:71], v[144:147], v[218:221], v[68:71]
	v_mfma_f32_16x16x32_bf16 v[64:67], v[152:155], v[218:221], v[64:67]
	v_mfma_f32_16x16x32_bf16 v[116:119], v[148:151], v[180:183], v[116:119]
	v_mfma_f32_16x16x32_bf16 v[108:111], v[156:159], v[180:183], v[108:111]
	v_mfma_f32_16x16x32_bf16 v[96:99], v[148:151], v[192:195], v[96:99]
	v_mfma_f32_16x16x32_bf16 v[92:95], v[156:159], v[192:195], v[92:95]
	v_mfma_f32_16x16x32_bf16 v[80:83], v[148:151], v[214:217], v[80:83]
	v_mfma_f32_16x16x32_bf16 v[76:79], v[156:159], v[214:217], v[76:79]
	v_mfma_f32_16x16x32_bf16 v[68:71], v[148:151], v[222:225], v[68:71]
	v_mfma_f32_16x16x32_bf16 v[64:67], v[156:159], v[222:225], v[64:67]

; #define PG8_STAGE(bufoff, gbase, voff) do { _Pragma("unroll") for (int _i = 0; _i < 2; ++_i) \
;         __builtin_amdgcn_global_load_lds((const unsigned*)((const char*)(gbase) + (voff)[_i]), (PG8_LAS unsigned*)(lds + (bufoff) + ldsw + _i * 8192), 16, 0, 0); } while (0)
; #define PG8_LDA(dst, b, h) do { _Pragma("unroll") for (int m = 0; m < 4; ++m) _Pragma("unroll") for (int k = 0; k < 2; ++k) dst[m][k] = *(const PG8_LAS bf16x8*)(lds + PG8_SA(b, h) + aoff + m * 2048 + k * 1024); } while (0)
; #define PG8_MMA(ai, bj, At, Bt) do { __builtin_amdgcn_s_setprio(1); _Pragma("unroll") for (int m = 0; m < 4; ++m) _Pragma("unroll") for (int n = 0; n < 2; ++n) _Pragma("unroll") for (int k = 0; k < 2; ++k) \
;         acc[ai][bj][m][n] = __builtin_amdgcn_mfma_f32_16x16x32_bf16(Bt[n][k], At[m][k], acc[ai][bj][m][n], 0, 0, 0); __builtin_amdgcn_s_setprio(0); } while (0)
; #define PG8_WAIT_V(n) asm volatile("s_waitcnt vmcnt(" #n ")" ::: "memory")
; #define PG8_WAIT_L(n) asm volatile("s_waitcnt lgkmcnt(" #n ")" ::: "memory")
; #define PG8_BAR __builtin_amdgcn_s_barrier()
; #define PG8_SCHED __builtin_amdgcn_sched_barrier(0)
; template <class Epi, class Sched, bool ALIGN_EPI = false, bool SP2 = false>
; __device__ __forceinline__ void gemm_phase(PG8_LAS unsigned char* lds, const Gemm g, const Sched& S, const Epi& E) {
;     ...
;             PG8_WAIT_V(8); PG8_WAIT_L(0); PG8_BAR; PG8_MMA(0, 0, At, B0); PG8_MMA(0, 1, At, B1); PG8_BAR; PG8_SCHED;
;             PG8_LDA(At, 0, 1); PG8_STAGE(PG8_SB(0, 0), b2, voffB); PG8_STAGE(PG8_SB(0, 1), b2 + hstep, voffB); PG8_STAGE(PG8_SA(0, 0), a2, voffA);
	s_barrier
	s_add_i32 s79, s70, s57
	s_mov_b64 s[96:97], s[12:13]

; #define PG8_STAGE(bufoff, gbase, voff) do { _Pragma("unroll") for (int _i = 0; _i < 2; ++_i) \
;         __builtin_amdgcn_global_load_lds((const unsigned*)((const char*)(gbase) + (voff)[_i]), (PG8_LAS unsigned*)(lds + (bufoff) + ldsw + _i * 8192), 16, 0, 0); } while (0)
; #define PG8_LDA(dst, b, h) do { _Pragma("unroll") for (int m = 0; m < 4; ++m) _Pragma("unroll") for (int k = 0; k < 2; ++k) dst[m][k] = *(const PG8_LAS bf16x8*)(lds + PG8_SA(b, h) + aoff + m * 2048 + k * 1024); } while (0)
; template <class Epi, class Sched, bool ALIGN_EPI = false, bool SP2 = false>
; __device__ __forceinline__ void gemm_phase(PG8_LAS unsigned char* lds, const Gemm g, const Sched& S, const Epi& E) {
;     ...
;             PG8_LDA(At, 0, 1); PG8_STAGE(PG8_SB(0, 0), b2, voffB); PG8_STAGE(PG8_SB(0, 1), b2 + hstep, voffB); PG8_STAGE(PG8_SA(0, 0), a2, voffA);
	s_mov_b32 m0, s79
	ds_read_b128 v[176:179], v207 offset:16384
	ds_read_b128 v[180:183], v207 offset:17408
	ds_read_b128 v[184:187], v207 offset:18432
	ds_read_b128 v[192:195], v207 offset:19456
	ds_read_b128 v[210:213], v207 offset:20480
	ds_read_b128 v[214:217], v207 offset:21504
	ds_read_b128 v[218:221], v207 offset:22528
	ds_read_b128 v[222:225], v207 offset:23552
	global_load_lds_dwordx4 v164, s[12:13]
	s_add_i32 m0, s79, 0x2000
	s_add_u32 s80, s12, 0x80000

; #define PG8_STAGE(bufoff, gbase, voff) do { _Pragma("unroll") for (int _i = 0; _i < 2; ++_i) \
;         __builtin_amdgcn_global_load_lds((const unsigned*)((const char*)(gbase) + (voff)[_i]), (PG8_LAS unsigned*)(lds + (bufoff) + ldsw + _i * 8192), 16, 0, 0); } while (0)
; #define PG8_LDA(dst, b, h) do { _Pragma("unroll") for (int m = 0; m < 4; ++m) _Pragma("unroll") for (int k = 0; k < 2; ++k) dst[m][k] = *(const PG8_LAS bf16x8*)(lds + PG8_SA(b, h) + aoff + m * 2048 + k * 1024); } while (0)
; template <class Epi, class Sched, bool ALIGN_EPI = false, bool SP2 = false>
; __device__ __forceinline__ void gemm_phase(PG8_LAS unsigned char* lds, const Gemm g, const Sched& S, const Epi& E) {
;     ...
;             PG8_LDA(At, 0, 1); PG8_STAGE(PG8_SB(0, 0), b2, voffB); PG8_STAGE(PG8_SB(0, 1), b2 + hstep, voffB); PG8_STAGE(PG8_SA(0, 0), a2, voffA);
	s_addc_u32 s81, s13, 0
	s_add_i32 s79, s71, s57
	global_load_lds_dwordx4 v160, s[12:13]

; #define PG8_STAGE(bufoff, gbase, voff) do { _Pragma("unroll") for (int _i = 0; _i < 2; ++_i) \
;         __builtin_amdgcn_global_load_lds((const unsigned*)((const char*)(gbase) + (voff)[_i]), (PG8_LAS unsigned*)(lds + (bufoff) + ldsw + _i * 8192), 16, 0, 0); } while (0)
; #define PG8_LDA(dst, b, h) do { _Pragma("unroll") for (int m = 0; m < 4; ++m) _Pragma("unroll") for (int k = 0; k < 2; ++k) dst[m][k] = *(const PG8_LAS bf16x8*)(lds + PG8_SA(b, h) + aoff + m * 2048 + k * 1024); } while (0)
; template <class Epi, class Sched, bool ALIGN_EPI = false, bool SP2 = false>
; __device__ __forceinline__ void gemm_phase(PG8_LAS unsigned char* lds, const Gemm g, const Sched& S, const Epi& E) {
;     ...
;             PG8_LDA(At, 0, 1); PG8_STAGE(PG8_SB(0, 0), b2, voffB); PG8_STAGE(PG8_SB(0, 1), b2 + hstep, voffB); PG8_STAGE(PG8_SA(0, 0), a2, voffA);
	s_mov_b32 m0, s79
	s_nop 0
	global_load_lds_dwordx4 v164, s[80:81]

; #define PG8_STAGE(bufoff, gbase, voff) do { _Pragma("unroll") for (int _i = 0; _i < 2; ++_i) \
;         __builtin_amdgcn_global_load_lds((const unsigned*)((const char*)(gbase) + (voff)[_i]), (PG8_LAS unsigned*)(lds + (bufoff) + ldsw + _i * 8192), 16, 0, 0); } while (0)
; #define PG8_LDA(dst, b, h) do { _Pragma("unroll") for (int m = 0; m < 4; ++m) _Pragma("unroll") for (int k = 0; k < 2; ++k) dst[m][k] = *(const PG8_LAS bf16x8*)(lds + PG8_SA(b, h) + aoff + m * 2048 + k * 1024); } while (0)
; template <class Epi, class Sched, bool ALIGN_EPI = false, bool SP2 = false>
; __device__ __forceinline__ void gemm_phase(PG8_LAS unsigned char* lds, const Gemm g, const Sched& S, const Epi& E) {
;     ...
;             PG8_LDA(At, 0, 1); PG8_STAGE(PG8_SB(0, 0), b2, voffB); PG8_STAGE(PG8_SB(0, 1), b2 + hstep, voffB); PG8_STAGE(PG8_SA(0, 0), a2, voffA);
	s_add_i32 m0, s79, 0x2000
	s_nop 0
	global_load_lds_dwordx4 v160, s[80:81]
	s_mov_b64 s[98:99], s[54:55]

; #define PG8_STAGE(bufoff, gbase, voff) do { _Pragma("unroll") for (int _i = 0; _i < 2; ++_i) \
;         __builtin_amdgcn_global_load_lds((const unsigned*)((const char*)(gbase) + (voff)[_i]), (PG8_LAS unsigned*)(lds + (bufoff) + ldsw + _i * 8192), 16, 0, 0); } while (0)
; #define PG8_LDA(dst, b, h) do { _Pragma("unroll") for (int m = 0; m < 4; ++m) _Pragma("unroll") for (int k = 0; k < 2; ++k) dst[m][k] = *(const PG8_LAS bf16x8*)(lds + PG8_SA(b, h) + aoff + m * 2048 + k * 1024); } while (0)
; #define PG8_MMA(ai, bj, At, Bt) do { __builtin_amdgcn_s_setprio(1); _Pragma("unroll") for (int m = 0; m < 4; ++m) _Pragma("unroll") for (int n = 0; n < 2; ++n) _Pragma("unroll") for (int k = 0; k < 2; ++k) \
;         acc[ai][bj][m][n] = __builtin_amdgcn_mfma_f32_16x16x32_bf16(Bt[n][k], At[m][k], acc[ai][bj][m][n], 0, 0, 0); __builtin_amdgcn_s_setprio(0); } while (0)
; #define PG8_WAIT_V(n) asm volatile("s_waitcnt vmcnt(" #n ")" ::: "memory")
; #define PG8_WAIT_L(n) asm volatile("s_waitcnt lgkmcnt(" #n ")" ::: "memory")
; #define PG8_BAR __builtin_amdgcn_s_barrier()
; #define PG8_SCHED __builtin_amdgcn_sched_barrier(0)
; template <class Epi, class Sched, bool ALIGN_EPI = false, bool SP2 = false>
; __device__ __forceinline__ void gemm_phase(PG8_LAS unsigned char* lds, const Gemm g, const Sched& S, const Epi& E) {
;     ...
;             PG8_LDA(At, 0, 1); PG8_STAGE(PG8_SB(0, 0), b2, voffB); PG8_STAGE(PG8_SB(0, 1), b2 + hstep, voffB); PG8_STAGE(PG8_SA(0, 0), a2, voffA);
;             PG8_WAIT_V(8); PG8_WAIT_L(0); PG8_BAR; PG8_MMA(1, 0, At, B0); PG8_MMA(1, 1, At, B1); PG8_BAR; PG8_SCHED;
	s_mov_b32 m0, s60
	s_nop 0
	global_load_lds_dwordx4 v166, s[54:55]
	s_mov_b32 m0, s61
	s_nop 0
	global_load_lds_dwordx4 v162, s[54:55]
	s_waitcnt vmcnt(8) lgkmcnt(0)


; #define PG8_MMA(ai, bj, At, Bt) do { __builtin_amdgcn_s_setprio(1); _Pragma("unroll") for (int m = 0; m < 4; ++m) _Pragma("unroll") for (int n = 0; n < 2; ++n) _Pragma("unroll") for (int k = 0; k < 2; ++k) \
;         acc[ai][bj][m][n] = __builtin_amdgcn_mfma_f32_16x16x32_bf16(Bt[n][k], At[m][k], acc[ai][bj][m][n], 0, 0, 0); __builtin_amdgcn_s_setprio(0); } while (0)
; #define PG8_WAIT_V(n) asm volatile("s_waitcnt vmcnt(" #n ")" ::: "memory")
; #define PG8_WAIT_L(n) asm volatile("s_waitcnt lgkmcnt(" #n ")" ::: "memory")
; #define PG8_BAR __builtin_amdgcn_s_barrier()
; #define PG8_SCHED __builtin_amdgcn_sched_barrier(0)
; template <class Epi, class Sched, bool ALIGN_EPI = false, bool SP2 = false>
; __device__ __forceinline__ void gemm_phase(PG8_LAS unsigned char* lds, const Gemm g, const Sched& S, const Epi& E) {
;     ...
;             PG8_WAIT_V(8); PG8_WAIT_L(0); PG8_BAR; PG8_MMA(1, 0, At, B0); PG8_MMA(1, 1, At, B1); PG8_BAR; PG8_SCHED;
	s_barrier

; #define PG8_MMA(ai, bj, At, Bt) do { __builtin_amdgcn_s_setprio(1); _Pragma("unroll") for (int m = 0; m < 4; ++m) _Pragma("unroll") for (int n = 0; n < 2; ++n) _Pragma("unroll") for (int k = 0; k < 2; ++k) \
;         acc[ai][bj][m][n] = __builtin_amdgcn_mfma_f32_16x16x32_bf16(Bt[n][k], At[m][k], acc[ai][bj][m][n], 0, 0, 0); __builtin_amdgcn_s_setprio(0); } while (0)
; #define PG8_WAIT_V(n) asm volatile("s_waitcnt vmcnt(" #n ")" ::: "memory")
; #define PG8_WAIT_L(n) asm volatile("s_waitcnt lgkmcnt(" #n ")" ::: "memory")
; #define PG8_BAR __builtin_amdgcn_s_barrier()
; #define PG8_SCHED __builtin_amdgcn_sched_barrier(0)
; template <class Epi, class Sched, bool ALIGN_EPI = false, bool SP2 = false>
; __device__ __forceinline__ void gemm_phase(PG8_LAS unsigned char* lds, const Gemm g, const Sched& S, const Epi& E) {
;     ...
;             PG8_WAIT_V(8); PG8_WAIT_L(0); PG8_BAR; PG8_MMA(1, 0, At, B0); PG8_MMA(1, 1, At, B1); PG8_BAR; PG8_SCHED;
	v_mfma_f32_16x16x32_bf16 v[60:63], v[128:131], v[176:179], v[60:63]
	v_mfma_f32_16x16x32_bf16 v[56:59], v[136:139], v[176:179], v[56:59]
	v_mfma_f32_16x16x32_bf16 v[52:55], v[128:131], v[184:187], v[52:55]
	v_mfma_f32_16x16x32_bf16 v[40:43], v[136:139], v[184:187], v[40:43]
	v_mfma_f32_16x16x32_bf16 v[36:39], v[128:131], v[210:213], v[36:39]
	v_mfma_f32_16x16x32_bf16 v[24:27], v[136:139], v[210:213], v[24:27]
	v_mfma_f32_16x16x32_bf16 v[20:23], v[128:131], v[218:221], v[20:23]
	v_mfma_f32_16x16x32_bf16 v[8:11], v[136:139], v[218:221], v[8:11]
	v_mfma_f32_16x16x32_bf16 v[60:63], v[132:135], v[180:183], v[60:63]
	v_mfma_f32_16x16x32_bf16 v[56:59], v[140:143], v[180:183], v[56:59]
	v_mfma_f32_16x16x32_bf16 v[52:55], v[132:135], v[192:195], v[52:55]
	v_mfma_f32_16x16x32_bf16 v[40:43], v[140:143], v[192:195], v[40:43]
	v_mfma_f32_16x16x32_bf16 v[36:39], v[132:135], v[214:217], v[36:39]
	v_mfma_f32_16x16x32_bf16 v[24:27], v[140:143], v[214:217], v[24:27]
	v_mfma_f32_16x16x32_bf16 v[20:23], v[132:135], v[222:225], v[20:23]
	v_mfma_f32_16x16x32_bf16 v[8:11], v[140:143], v[222:225], v[8:11]


; #define PG8_MMA(ai, bj, At, Bt) do { __builtin_amdgcn_s_setprio(1); _Pragma("unroll") for (int m = 0; m < 4; ++m) _Pragma("unroll") for (int n = 0; n < 2; ++n) _Pragma("unroll") for (int k = 0; k < 2; ++k) \
;         acc[ai][bj][m][n] = __builtin_amdgcn_mfma_f32_16x16x32_bf16(Bt[n][k], At[m][k], acc[ai][bj][m][n], 0, 0, 0); __builtin_amdgcn_s_setprio(0); } while (0)
; #define PG8_WAIT_V(n) asm volatile("s_waitcnt vmcnt(" #n ")" ::: "memory")
; #define PG8_WAIT_L(n) asm volatile("s_waitcnt lgkmcnt(" #n ")" ::: "memory")
; #define PG8_BAR __builtin_amdgcn_s_barrier()
; #define PG8_SCHED __builtin_amdgcn_sched_barrier(0)
; template <class Epi, class Sched, bool ALIGN_EPI = false, bool SP2 = false>
; __device__ __forceinline__ void gemm_phase(PG8_LAS unsigned char* lds, const Gemm g, const Sched& S, const Epi& E) {
;     ...
;             PG8_WAIT_V(8); PG8_WAIT_L(0); PG8_BAR; PG8_MMA(1, 0, At, B0); PG8_MMA(1, 1, At, B1); PG8_BAR; PG8_SCHED;
	v_mfma_f32_16x16x32_bf16 v[48:51], v[144:147], v[176:179], v[48:51]
	v_mfma_f32_16x16x32_bf16 v[44:47], v[152:155], v[176:179], v[44:47]
	v_mfma_f32_16x16x32_bf16 v[32:35], v[144:147], v[184:187], v[32:35]
	v_mfma_f32_16x16x32_bf16 v[28:31], v[152:155], v[184:187], v[28:31]
	v_mfma_f32_16x16x32_bf16 v[16:19], v[144:147], v[210:213], v[16:19]
	v_mfma_f32_16x16x32_bf16 v[12:15], v[152:155], v[210:213], v[12:15]
	v_mfma_f32_16x16x32_bf16 v[4:7], v[144:147], v[218:221], v[4:7]
	v_mfma_f32_16x16x32_bf16 v[0:3], v[152:155], v[218:221], v[0:3]
	v_mfma_f32_16x16x32_bf16 v[48:51], v[148:151], v[180:183], v[48:51]
	v_mfma_f32_16x16x32_bf16 v[44:47], v[156:159], v[180:183], v[44:47]
	v_mfma_f32_16x16x32_bf16 v[32:35], v[148:151], v[192:195], v[32:35]
	v_mfma_f32_16x16x32_bf16 v[28:31], v[156:159], v[192:195], v[28:31]
	v_mfma_f32_16x16x32_bf16 v[16:19], v[148:151], v[214:217], v[16:19]
	v_mfma_f32_16x16x32_bf16 v[12:15], v[156:159], v[214:217], v[12:15]
	v_mfma_f32_16x16x32_bf16 v[4:7], v[148:151], v[222:225], v[4:7]
	v_mfma_f32_16x16x32_bf16 v[0:3], v[156:159], v[222:225], v[0:3]

; #define PG8_STAGE(bufoff, gbase, voff) do { _Pragma("unroll") for (int _i = 0; _i < 2; ++_i) \
;         __builtin_amdgcn_global_load_lds((const unsigned*)((const char*)(gbase) + (voff)[_i]), (PG8_LAS unsigned*)(lds + (bufoff) + ldsw + _i * 8192), 16, 0, 0); } while (0)
; #define PG8_LDA(dst, b, h) do { _Pragma("unroll") for (int m = 0; m < 4; ++m) _Pragma("unroll") for (int k = 0; k < 2; ++k) dst[m][k] = *(const PG8_LAS bf16x8*)(lds + PG8_SA(b, h) + aoff + m * 2048 + k * 1024); } while (0)
; #define PG8_LDB(dst, b, h) do { _Pragma("unroll") for (int n = 0; n < 2; ++n) _Pragma("unroll") for (int k = 0; k < 2; ++k) dst[n][k] = *(const PG8_LAS bf16x8*)(lds + PG8_SB(b, h) + boff + n * 2048 + k * 1024); } while (0)
; #define PG8_MMA(ai, bj, At, Bt) do { __builtin_amdgcn_s_setprio(1); _Pragma("unroll") for (int m = 0; m < 4; ++m) _Pragma("unroll") for (int n = 0; n < 2; ++n) _Pragma("unroll") for (int k = 0; k < 2; ++k) \
;         acc[ai][bj][m][n] = __builtin_amdgcn_mfma_f32_16x16x32_bf16(Bt[n][k], At[m][k], acc[ai][bj][m][n], 0, 0, 0); __builtin_amdgcn_s_setprio(0); } while (0)
; #define PG8_WAIT_V(n) asm volatile("s_waitcnt vmcnt(" #n ")" ::: "memory")
; #define PG8_WAIT_L(n) asm volatile("s_waitcnt lgkmcnt(" #n ")" ::: "memory")
; #define PG8_BAR __builtin_amdgcn_s_barrier()
; #define PG8_SCHED __builtin_amdgcn_sched_barrier(0)
; template <class Epi, class Sched, bool ALIGN_EPI = false, bool SP2 = false>
; __device__ __forceinline__ void gemm_phase(PG8_LAS unsigned char* lds, const Gemm g, const Sched& S, const Epi& E) {
;     ...
;             PG8_WAIT_V(8); PG8_WAIT_L(0); PG8_BAR; PG8_MMA(1, 0, At, B0); PG8_MMA(1, 1, At, B1); PG8_BAR; PG8_SCHED;
;             PG8_LDB(B0, 1, 0); PG8_LDB(B1, 1, 1); PG8_SCHED; PG8_LDA(At, 1, 0); PG8_STAGE(PG8_SA(0, 1), a2 + hstep, voffA);
	s_barrier
	s_add_i32 s79, 0, 0x18000
	s_add_i32 s80, 0, 0x1c000


; #define PG8_STAGE(bufoff, gbase, voff) do { _Pragma("unroll") for (int _i = 0; _i < 2; ++_i) \
;         __builtin_amdgcn_global_load_lds((const unsigned*)((const char*)(gbase) + (voff)[_i]), (PG8_LAS unsigned*)(lds + (bufoff) + ldsw + _i * 8192), 16, 0, 0); } while (0)
; #define PG8_LDA(dst, b, h) do { _Pragma("unroll") for (int m = 0; m < 4; ++m) _Pragma("unroll") for (int k = 0; k < 2; ++k) dst[m][k] = *(const PG8_LAS bf16x8*)(lds + PG8_SA(b, h) + aoff + m * 2048 + k * 1024); } while (0)
; #define PG8_LDB(dst, b, h) do { _Pragma("unroll") for (int n = 0; n < 2; ++n) _Pragma("unroll") for (int k = 0; k < 2; ++k) dst[n][k] = *(const PG8_LAS bf16x8*)(lds + PG8_SB(b, h) + boff + n * 2048 + k * 1024); } while (0)
; #define PG8_SCHED __builtin_amdgcn_sched_barrier(0)
; template <class Epi, class Sched, bool ALIGN_EPI = false, bool SP2 = false>
; __device__ __forceinline__ void gemm_phase(PG8_LAS unsigned char* lds, const Gemm g, const Sched& S, const Epi& E) {
;     ...
;             PG8_LDB(B0, 1, 0); PG8_LDB(B1, 1, 1); PG8_SCHED; PG8_LDA(At, 1, 0); PG8_STAGE(PG8_SA(0, 1), a2 + hstep, voffA);
	ds_read_b128 v[128:131], v254
	ds_read_b128 v[132:135], v254 offset:1024
	ds_read_b128 v[136:139], v254 offset:2048
	ds_read_b128 v[140:143], v254 offset:3072
	ds_read_b128 v[144:147], v255
	ds_read_b128 v[148:151], v255 offset:1024
	ds_read_b128 v[152:155], v255 offset:2048
	ds_read_b128 v[156:159], v255 offset:3072
	s_add_u32 s54, s54, 0x80000
	s_addc_u32 s55, s55, 0
	s_mov_b32 m0, s62

; #define PG8_STAGE(bufoff, gbase, voff) do { _Pragma("unroll") for (int _i = 0; _i < 2; ++_i) \
;         __builtin_amdgcn_global_load_lds((const unsigned*)((const char*)(gbase) + (voff)[_i]), (PG8_LAS unsigned*)(lds + (bufoff) + ldsw + _i * 8192), 16, 0, 0); } while (0)
; #define PG8_LDA(dst, b, h) do { _Pragma("unroll") for (int m = 0; m < 4; ++m) _Pragma("unroll") for (int k = 0; k < 2; ++k) dst[m][k] = *(const PG8_LAS bf16x8*)(lds + PG8_SA(b, h) + aoff + m * 2048 + k * 1024); } while (0)
; #define PG8_LDB(dst, b, h) do { _Pragma("unroll") for (int n = 0; n < 2; ++n) _Pragma("unroll") for (int k = 0; k < 2; ++k) dst[n][k] = *(const PG8_LAS bf16x8*)(lds + PG8_SB(b, h) + boff + n * 2048 + k * 1024); } while (0)
; #define PG8_SCHED __builtin_amdgcn_sched_barrier(0)
; template <class Epi, class Sched, bool ALIGN_EPI = false, bool SP2 = false>
; __device__ __forceinline__ void gemm_phase(PG8_LAS unsigned char* lds, const Gemm g, const Sched& S, const Epi& E) {
;     ...
;             PG8_LDB(B0, 1, 0); PG8_LDB(B1, 1, 1); PG8_SCHED; PG8_LDA(At, 1, 0); PG8_STAGE(PG8_SA(0, 1), a2 + hstep, voffA);
	ds_read_b128 v[176:179], v207 offset:32768
	ds_read_b128 v[180:183], v207 offset:33792
	ds_read_b128 v[184:187], v207 offset:34816
	ds_read_b128 v[192:195], v207 offset:35840
	ds_read_b128 v[210:213], v207 offset:36864
	ds_read_b128 v[214:217], v207 offset:37888
	ds_read_b128 v[218:221], v207 offset:38912
	ds_read_b128 v[222:225], v207 offset:39936
	global_load_lds_dwordx4 v166, s[54:55]

; #define PG8_STAGE(bufoff, gbase, voff) do { _Pragma("unroll") for (int _i = 0; _i < 2; ++_i) \
;         __builtin_amdgcn_global_load_lds((const unsigned*)((const char*)(gbase) + (voff)[_i]), (PG8_LAS unsigned*)(lds + (bufoff) + ldsw + _i * 8192), 16, 0, 0); } while (0)
; #define PG8_LDA(dst, b, h) do { _Pragma("unroll") for (int m = 0; m < 4; ++m) _Pragma("unroll") for (int k = 0; k < 2; ++k) dst[m][k] = *(const PG8_LAS bf16x8*)(lds + PG8_SA(b, h) + aoff + m * 2048 + k * 1024); } while (0)
; #define PG8_LDB(dst, b, h) do { _Pragma("unroll") for (int n = 0; n < 2; ++n) _Pragma("unroll") for (int k = 0; k < 2; ++k) dst[n][k] = *(const PG8_LAS bf16x8*)(lds + PG8_SB(b, h) + boff + n * 2048 + k * 1024); } while (0)
; #define PG8_MMA(ai, bj, At, Bt) do { __builtin_amdgcn_s_setprio(1); _Pragma("unroll") for (int m = 0; m < 4; ++m) _Pragma("unroll") for (int n = 0; n < 2; ++n) _Pragma("unroll") for (int k = 0; k < 2; ++k) \
;         acc[ai][bj][m][n] = __builtin_amdgcn_mfma_f32_16x16x32_bf16(Bt[n][k], At[m][k], acc[ai][bj][m][n], 0, 0, 0); __builtin_amdgcn_s_setprio(0); } while (0)
; #define PG8_WAIT_V(n) asm volatile("s_waitcnt vmcnt(" #n ")" ::: "memory")
; #define PG8_WAIT_L(n) asm volatile("s_waitcnt lgkmcnt(" #n ")" ::: "memory")
; #define PG8_BAR __builtin_amdgcn_s_barrier()
; #define PG8_SCHED __builtin_amdgcn_sched_barrier(0)
; template <class Epi, class Sched, bool ALIGN_EPI = false, bool SP2 = false>
; __device__ __forceinline__ void gemm_phase(PG8_LAS unsigned char* lds, const Gemm g, const Sched& S, const Epi& E) {
;     ...
;             PG8_LDB(B0, 1, 0); PG8_LDB(B1, 1, 1); PG8_SCHED; PG8_LDA(At, 1, 0); PG8_STAGE(PG8_SA(0, 1), a2 + hstep, voffA);
;             PG8_WAIT_V(8); PG8_WAIT_L(0); PG8_BAR; PG8_MMA(0, 0, At, B0); PG8_MMA(0, 1, At, B1); PG8_BAR; PG8_SCHED;
	s_mov_b32 m0, s63
	s_nop 0
	global_load_lds_dwordx4 v162, s[54:55]
	s_waitcnt vmcnt(8) lgkmcnt(0)


; #define PG8_MMA(ai, bj, At, Bt) do { __builtin_amdgcn_s_setprio(1); _Pragma("unroll") for (int m = 0; m < 4; ++m) _Pragma("unroll") for (int n = 0; n < 2; ++n) _Pragma("unroll") for (int k = 0; k < 2; ++k) \
;         acc[ai][bj][m][n] = __builtin_amdgcn_mfma_f32_16x16x32_bf16(Bt[n][k], At[m][k], acc[ai][bj][m][n], 0, 0, 0); __builtin_amdgcn_s_setprio(0); } while (0)
; #define PG8_WAIT_V(n) asm volatile("s_waitcnt vmcnt(" #n ")" ::: "memory")
; #define PG8_WAIT_L(n) asm volatile("s_waitcnt lgkmcnt(" #n ")" ::: "memory")
; #define PG8_BAR __builtin_amdgcn_s_barrier()
; #define PG8_SCHED __builtin_amdgcn_sched_barrier(0)
; template <class Epi, class Sched, bool ALIGN_EPI = false, bool SP2 = false>
; __device__ __forceinline__ void gemm_phase(PG8_LAS unsigned char* lds, const Gemm g, const Sched& S, const Epi& E) {
;     ...
;             PG8_WAIT_V(8); PG8_WAIT_L(0); PG8_BAR; PG8_MMA(0, 0, At, B0); PG8_MMA(0, 1, At, B1); PG8_BAR; PG8_SCHED;
	s_barrier

; #define PG8_MMA(ai, bj, At, Bt) do { __builtin_amdgcn_s_setprio(1); _Pragma("unroll") for (int m = 0; m < 4; ++m) _Pragma("unroll") for (int n = 0; n < 2; ++n) _Pragma("unroll") for (int k = 0; k < 2; ++k) \
;         acc[ai][bj][m][n] = __builtin_amdgcn_mfma_f32_16x16x32_bf16(Bt[n][k], At[m][k], acc[ai][bj][m][n], 0, 0, 0); __builtin_amdgcn_s_setprio(0); } while (0)
; #define PG8_WAIT_V(n) asm volatile("s_waitcnt vmcnt(" #n ")" ::: "memory")
; #define PG8_WAIT_L(n) asm volatile("s_waitcnt lgkmcnt(" #n ")" ::: "memory")
; #define PG8_BAR __builtin_amdgcn_s_barrier()
; #define PG8_SCHED __builtin_amdgcn_sched_barrier(0)
; template <class Epi, class Sched, bool ALIGN_EPI = false, bool SP2 = false>
; __device__ __forceinline__ void gemm_phase(PG8_LAS unsigned char* lds, const Gemm g, const Sched& S, const Epi& E) {
;     ...
;             PG8_WAIT_V(8); PG8_WAIT_L(0); PG8_BAR; PG8_MMA(0, 0, At, B0); PG8_MMA(0, 1, At, B1); PG8_BAR; PG8_SCHED;
	v_mfma_f32_16x16x32_bf16 v[124:127], v[128:131], v[176:179], v[124:127]
	v_mfma_f32_16x16x32_bf16 v[120:123], v[136:139], v[176:179], v[120:123]
	v_mfma_f32_16x16x32_bf16 v[112:115], v[128:131], v[184:187], v[112:115]
	v_mfma_f32_16x16x32_bf16 v[104:107], v[136:139], v[184:187], v[104:107]
	v_mfma_f32_16x16x32_bf16 v[100:103], v[128:131], v[210:213], v[100:103]
	v_mfma_f32_16x16x32_bf16 v[88:91], v[136:139], v[210:213], v[88:91]
	v_mfma_f32_16x16x32_bf16 v[84:87], v[128:131], v[218:221], v[84:87]
	v_mfma_f32_16x16x32_bf16 v[72:75], v[136:139], v[218:221], v[72:75]
	v_mfma_f32_16x16x32_bf16 v[124:127], v[132:135], v[180:183], v[124:127]
	v_mfma_f32_16x16x32_bf16 v[120:123], v[140:143], v[180:183], v[120:123]
	v_mfma_f32_16x16x32_bf16 v[112:115], v[132:135], v[192:195], v[112:115]
	v_mfma_f32_16x16x32_bf16 v[104:107], v[140:143], v[192:195], v[104:107]
	v_mfma_f32_16x16x32_bf16 v[100:103], v[132:135], v[214:217], v[100:103]
	v_mfma_f32_16x16x32_bf16 v[88:91], v[140:143], v[214:217], v[88:91]
	v_mfma_f32_16x16x32_bf16 v[84:87], v[132:135], v[222:225], v[84:87]
	v_mfma_f32_16x16x32_bf16 v[72:75], v[140:143], v[222:225], v[72:75]


; #define PG8_MMA(ai, bj, At, Bt) do { __builtin_amdgcn_s_setprio(1); _Pragma("unroll") for (int m = 0; m < 4; ++m) _Pragma("unroll") for (int n = 0; n < 2; ++n) _Pragma("unroll") for (int k = 0; k < 2; ++k) \
;         acc[ai][bj][m][n] = __builtin_amdgcn_mfma_f32_16x16x32_bf16(Bt[n][k], At[m][k], acc[ai][bj][m][n], 0, 0, 0); __builtin_amdgcn_s_setprio(0); } while (0)
; #define PG8_WAIT_V(n) asm volatile("s_waitcnt vmcnt(" #n ")" ::: "memory")
; #define PG8_WAIT_L(n) asm volatile("s_waitcnt lgkmcnt(" #n ")" ::: "memory")
; #define PG8_BAR __builtin_amdgcn_s_barrier()
; #define PG8_SCHED __builtin_amdgcn_sched_barrier(0)
; template <class Epi, class Sched, bool ALIGN_EPI = false, bool SP2 = false>
; __device__ __forceinline__ void gemm_phase(PG8_LAS unsigned char* lds, const Gemm g, const Sched& S, const Epi& E) {
;     ...
;             PG8_WAIT_V(8); PG8_WAIT_L(0); PG8_BAR; PG8_MMA(0, 0, At, B0); PG8_MMA(0, 1, At, B1); PG8_BAR; PG8_SCHED;
	v_mfma_f32_16x16x32_bf16 v[116:119], v[144:147], v[176:179], v[116:119]
	v_mfma_f32_16x16x32_bf16 v[108:111], v[152:155], v[176:179], v[108:111]
	v_mfma_f32_16x16x32_bf16 v[96:99], v[144:147], v[184:187], v[96:99]
	v_mfma_f32_16x16x32_bf16 v[92:95], v[152:155], v[184:187], v[92:95]
	v_mfma_f32_16x16x32_bf16 v[80:83], v[144:147], v[210:213], v[80:83]
	v_mfma_f32_16x16x32_bf16 v[76:79], v[152:155], v[210:213], v[76:79]
	v_mfma_f32_16x16x32_bf16 v[68:71], v[144:147], v[218:221], v[68:71]
	v_mfma_f32_16x16x32_bf16 v[64:67], v[152:155], v[218:221], v[64:67]
	v_mfma_f32_16x16x32_bf16 v[116:119], v[148:151], v[180:183], v[116:119]
	v_mfma_f32_16x16x32_bf16 v[108:111], v[156:159], v[180:183], v[108:111]
	v_mfma_f32_16x16x32_bf16 v[96:99], v[148:151], v[192:195], v[96:99]
	v_mfma_f32_16x16x32_bf16 v[92:95], v[156:159], v[192:195], v[92:95]
	v_mfma_f32_16x16x32_bf16 v[80:83], v[148:151], v[214:217], v[80:83]
	v_mfma_f32_16x16x32_bf16 v[76:79], v[156:159], v[214:217], v[76:79]
	v_mfma_f32_16x16x32_bf16 v[68:71], v[148:151], v[222:225], v[68:71]
	v_mfma_f32_16x16x32_bf16 v[64:67], v[156:159], v[222:225], v[64:67]

; #define PG8_STAGE(bufoff, gbase, voff) do { _Pragma("unroll") for (int _i = 0; _i < 2; ++_i) \
;         __builtin_amdgcn_global_load_lds((const unsigned*)((const char*)(gbase) + (voff)[_i]), (PG8_LAS unsigned*)(lds + (bufoff) + ldsw + _i * 8192), 16, 0, 0); } while (0)
; #define PG8_LDA(dst, b, h) do { _Pragma("unroll") for (int m = 0; m < 4; ++m) _Pragma("unroll") for (int k = 0; k < 2; ++k) dst[m][k] = *(const PG8_LAS bf16x8*)(lds + PG8_SA(b, h) + aoff + m * 2048 + k * 1024); } while (0)
; #define PG8_MMA(ai, bj, At, Bt) do { __builtin_amdgcn_s_setprio(1); _Pragma("unroll") for (int m = 0; m < 4; ++m) _Pragma("unroll") for (int n = 0; n < 2; ++n) _Pragma("unroll") for (int k = 0; k < 2; ++k) \
;         acc[ai][bj][m][n] = __builtin_amdgcn_mfma_f32_16x16x32_bf16(Bt[n][k], At[m][k], acc[ai][bj][m][n], 0, 0, 0); __builtin_amdgcn_s_setprio(0); } while (0)
; #define PG8_WAIT_V(n) asm volatile("s_waitcnt vmcnt(" #n ")" ::: "memory")
; #define PG8_WAIT_L(n) asm volatile("s_waitcnt lgkmcnt(" #n ")" ::: "memory")
; #define PG8_BAR __builtin_amdgcn_s_barrier()
; #define PG8_SCHED __builtin_amdgcn_sched_barrier(0)
; template <class Epi, class Sched, bool ALIGN_EPI = false, bool SP2 = false>
; __device__ __forceinline__ void gemm_phase(PG8_LAS unsigned char* lds, const Gemm g, const Sched& S, const Epi& E) {
;     ...
;             PG8_WAIT_V(8); PG8_WAIT_L(0); PG8_BAR; PG8_MMA(0, 0, At, B0); PG8_MMA(0, 1, At, B1); PG8_BAR; PG8_SCHED;
;             PG8_LDA(At, 1, 1); PG8_STAGE(PG8_SB(1, 0), b3, voffB); PG8_STAGE(PG8_SB(1, 1), b3 + hstep, voffB); PG8_STAGE(PG8_SA(1, 0), a3, voffA);
	s_barrier
	s_add_i32 s54, s79, s57

; #define PG8_STAGE(bufoff, gbase, voff) do { _Pragma("unroll") for (int _i = 0; _i < 2; ++_i) \
;         __builtin_amdgcn_global_load_lds((const unsigned*)((const char*)(gbase) + (voff)[_i]), (PG8_LAS unsigned*)(lds + (bufoff) + ldsw + _i * 8192), 16, 0, 0); } while (0)
; #define PG8_LDA(dst, b, h) do { _Pragma("unroll") for (int m = 0; m < 4; ++m) _Pragma("unroll") for (int k = 0; k < 2; ++k) dst[m][k] = *(const PG8_LAS bf16x8*)(lds + PG8_SA(b, h) + aoff + m * 2048 + k * 1024); } while (0)
; template <class Epi, class Sched, bool ALIGN_EPI = false, bool SP2 = false>
; __device__ __forceinline__ void gemm_phase(PG8_LAS unsigned char* lds, const Gemm g, const Sched& S, const Epi& E) {
;     ...
;             PG8_LDA(At, 1, 1); PG8_STAGE(PG8_SB(1, 0), b3, voffB); PG8_STAGE(PG8_SB(1, 1), b3 + hstep, voffB); PG8_STAGE(PG8_SA(1, 0), a3, voffA);
	s_mov_b32 m0, s54
	ds_read_b128 v[176:179], v207 offset:49152
	ds_read_b128 v[180:183], v207 offset:50176
	ds_read_b128 v[184:187], v207 offset:51200
	ds_read_b128 v[192:195], v207 offset:52224
	ds_read_b128 v[210:213], v207 offset:53248
	ds_read_b128 v[214:217], v207 offset:54272
	ds_read_b128 v[218:221], v207 offset:55296
	ds_read_b128 v[222:225], v207 offset:56320
	global_load_lds_dwordx4 v250, s[96:97]
	s_add_i32 m0, s54, 0x2000
	s_add_u32 s12, s12, 0x80080

; #define PG8_STAGE(bufoff, gbase, voff) do { _Pragma("unroll") for (int _i = 0; _i < 2; ++_i) \
;         __builtin_amdgcn_global_load_lds((const unsigned*)((const char*)(gbase) + (voff)[_i]), (PG8_LAS unsigned*)(lds + (bufoff) + ldsw + _i * 8192), 16, 0, 0); } while (0)
; #define PG8_LDA(dst, b, h) do { _Pragma("unroll") for (int m = 0; m < 4; ++m) _Pragma("unroll") for (int k = 0; k < 2; ++k) dst[m][k] = *(const PG8_LAS bf16x8*)(lds + PG8_SA(b, h) + aoff + m * 2048 + k * 1024); } while (0)
; template <class Epi, class Sched, bool ALIGN_EPI = false, bool SP2 = false>
; __device__ __forceinline__ void gemm_phase(PG8_LAS unsigned char* lds, const Gemm g, const Sched& S, const Epi& E) {
;     ...
;             PG8_LDA(At, 1, 1); PG8_STAGE(PG8_SB(1, 0), b3, voffB); PG8_STAGE(PG8_SB(1, 1), b3 + hstep, voffB); PG8_STAGE(PG8_SA(1, 0), a3, voffA);
	s_addc_u32 s13, s13, 0
	s_add_i32 s54, s80, s57
	global_load_lds_dwordx4 v251, s[96:97]

; #define PG8_STAGE(bufoff, gbase, voff) do { _Pragma("unroll") for (int _i = 0; _i < 2; ++_i) \
;         __builtin_amdgcn_global_load_lds((const unsigned*)((const char*)(gbase) + (voff)[_i]), (PG8_LAS unsigned*)(lds + (bufoff) + ldsw + _i * 8192), 16, 0, 0); } while (0)
; #define PG8_LDA(dst, b, h) do { _Pragma("unroll") for (int m = 0; m < 4; ++m) _Pragma("unroll") for (int k = 0; k < 2; ++k) dst[m][k] = *(const PG8_LAS bf16x8*)(lds + PG8_SA(b, h) + aoff + m * 2048 + k * 1024); } while (0)
; template <class Epi, class Sched, bool ALIGN_EPI = false, bool SP2 = false>
; __device__ __forceinline__ void gemm_phase(PG8_LAS unsigned char* lds, const Gemm g, const Sched& S, const Epi& E) {
;     ...
;             PG8_LDA(At, 1, 1); PG8_STAGE(PG8_SB(1, 0), b3, voffB); PG8_STAGE(PG8_SB(1, 1), b3 + hstep, voffB); PG8_STAGE(PG8_SA(1, 0), a3, voffA);
	s_mov_b32 m0, s54
	s_nop 0
	global_load_lds_dwordx4 v164, s[12:13]

; #define PG8_STAGE(bufoff, gbase, voff) do { _Pragma("unroll") for (int _i = 0; _i < 2; ++_i) \
;         __builtin_amdgcn_global_load_lds((const unsigned*)((const char*)(gbase) + (voff)[_i]), (PG8_LAS unsigned*)(lds + (bufoff) + ldsw + _i * 8192), 16, 0, 0); } while (0)
; #define PG8_LDA(dst, b, h) do { _Pragma("unroll") for (int m = 0; m < 4; ++m) _Pragma("unroll") for (int k = 0; k < 2; ++k) dst[m][k] = *(const PG8_LAS bf16x8*)(lds + PG8_SA(b, h) + aoff + m * 2048 + k * 1024); } while (0)
; template <class Epi, class Sched, bool ALIGN_EPI = false, bool SP2 = false>
; __device__ __forceinline__ void gemm_phase(PG8_LAS unsigned char* lds, const Gemm g, const Sched& S, const Epi& E) {
;     ...
;             PG8_LDA(At, 1, 1); PG8_STAGE(PG8_SB(1, 0), b3, voffB); PG8_STAGE(PG8_SB(1, 1), b3 + hstep, voffB); PG8_STAGE(PG8_SA(1, 0), a3, voffA);
	s_add_i32 m0, s54, 0x2000
	s_nop 0
	global_load_lds_dwordx4 v160, s[12:13]

; #define PG8_STAGE(bufoff, gbase, voff) do { _Pragma("unroll") for (int _i = 0; _i < 2; ++_i) \
;         __builtin_amdgcn_global_load_lds((const unsigned*)((const char*)(gbase) + (voff)[_i]), (PG8_LAS unsigned*)(lds + (bufoff) + ldsw + _i * 8192), 16, 0, 0); } while (0)
; #define PG8_LDA(dst, b, h) do { _Pragma("unroll") for (int m = 0; m < 4; ++m) _Pragma("unroll") for (int k = 0; k < 2; ++k) dst[m][k] = *(const PG8_LAS bf16x8*)(lds + PG8_SA(b, h) + aoff + m * 2048 + k * 1024); } while (0)
; template <class Epi, class Sched, bool ALIGN_EPI = false, bool SP2 = false>
; __device__ __forceinline__ void gemm_phase(PG8_LAS unsigned char* lds, const Gemm g, const Sched& S, const Epi& E) {
;     ...
;             PG8_LDA(At, 1, 1); PG8_STAGE(PG8_SB(1, 0), b3, voffB); PG8_STAGE(PG8_SB(1, 1), b3 + hstep, voffB); PG8_STAGE(PG8_SA(1, 0), a3, voffA);
	s_mov_b32 m0, s65
	s_nop 0
	global_load_lds_dwordx4 v252, s[98:99]

; #define PG8_STAGE(bufoff, gbase, voff) do { _Pragma("unroll") for (int _i = 0; _i < 2; ++_i) \
;         __builtin_amdgcn_global_load_lds((const unsigned*)((const char*)(gbase) + (voff)[_i]), (PG8_LAS unsigned*)(lds + (bufoff) + ldsw + _i * 8192), 16, 0, 0); } while (0)
; #define PG8_LDA(dst, b, h) do { _Pragma("unroll") for (int m = 0; m < 4; ++m) _Pragma("unroll") for (int k = 0; k < 2; ++k) dst[m][k] = *(const PG8_LAS bf16x8*)(lds + PG8_SA(b, h) + aoff + m * 2048 + k * 1024); } while (0)
; #define PG8_MMA(ai, bj, At, Bt) do { __builtin_amdgcn_s_setprio(1); _Pragma("unroll") for (int m = 0; m < 4; ++m) _Pragma("unroll") for (int n = 0; n < 2; ++n) _Pragma("unroll") for (int k = 0; k < 2; ++k) \
;         acc[ai][bj][m][n] = __builtin_amdgcn_mfma_f32_16x16x32_bf16(Bt[n][k], At[m][k], acc[ai][bj][m][n], 0, 0, 0); __builtin_amdgcn_s_setprio(0); } while (0)
; #define PG8_WAIT_V(n) asm volatile("s_waitcnt vmcnt(" #n ")" ::: "memory")
; #define PG8_WAIT_L(n) asm volatile("s_waitcnt lgkmcnt(" #n ")" ::: "memory")
; #define PG8_BAR __builtin_amdgcn_s_barrier()
; #define PG8_SCHED __builtin_amdgcn_sched_barrier(0)
; template <class Epi, class Sched, bool ALIGN_EPI = false, bool SP2 = false>
; __device__ __forceinline__ void gemm_phase(PG8_LAS unsigned char* lds, const Gemm g, const Sched& S, const Epi& E) {
;     ...
;             PG8_LDA(At, 1, 1); PG8_STAGE(PG8_SB(1, 0), b3, voffB); PG8_STAGE(PG8_SB(1, 1), b3 + hstep, voffB); PG8_STAGE(PG8_SA(1, 0), a3, voffA);
;             PG8_WAIT_V(8); PG8_WAIT_L(0); PG8_BAR; PG8_MMA(1, 0, At, B0); PG8_MMA(1, 1, At, B1); PG8_BAR; PG8_SCHED;
	s_mov_b32 m0, s67
	s_nop 0
	global_load_lds_dwordx4 v253, s[98:99]
	s_waitcnt vmcnt(8) lgkmcnt(0)


; #define PG8_MMA(ai, bj, At, Bt) do { __builtin_amdgcn_s_setprio(1); _Pragma("unroll") for (int m = 0; m < 4; ++m) _Pragma("unroll") for (int n = 0; n < 2; ++n) _Pragma("unroll") for (int k = 0; k < 2; ++k) \
;         acc[ai][bj][m][n] = __builtin_amdgcn_mfma_f32_16x16x32_bf16(Bt[n][k], At[m][k], acc[ai][bj][m][n], 0, 0, 0); __builtin_amdgcn_s_setprio(0); } while (0)
; #define PG8_WAIT_V(n) asm volatile("s_waitcnt vmcnt(" #n ")" ::: "memory")
; #define PG8_WAIT_L(n) asm volatile("s_waitcnt lgkmcnt(" #n ")" ::: "memory")
; #define PG8_BAR __builtin_amdgcn_s_barrier()
; #define PG8_SCHED __builtin_amdgcn_sched_barrier(0)
; template <class Epi, class Sched, bool ALIGN_EPI = false, bool SP2 = false>
; __device__ __forceinline__ void gemm_phase(PG8_LAS unsigned char* lds, const Gemm g, const Sched& S, const Epi& E) {
;     ...
;             PG8_WAIT_V(8); PG8_WAIT_L(0); PG8_BAR; PG8_MMA(1, 0, At, B0); PG8_MMA(1, 1, At, B1); PG8_BAR; PG8_SCHED;
	s_barrier

; #define PG8_MMA(ai, bj, At, Bt) do { __builtin_amdgcn_s_setprio(1); _Pragma("unroll") for (int m = 0; m < 4; ++m) _Pragma("unroll") for (int n = 0; n < 2; ++n) _Pragma("unroll") for (int k = 0; k < 2; ++k) \
;         acc[ai][bj][m][n] = __builtin_amdgcn_mfma_f32_16x16x32_bf16(Bt[n][k], At[m][k], acc[ai][bj][m][n], 0, 0, 0); __builtin_amdgcn_s_setprio(0); } while (0)
; #define PG8_WAIT_V(n) asm volatile("s_waitcnt vmcnt(" #n ")" ::: "memory")
; #define PG8_WAIT_L(n) asm volatile("s_waitcnt lgkmcnt(" #n ")" ::: "memory")
; #define PG8_BAR __builtin_amdgcn_s_barrier()
; #define PG8_SCHED __builtin_amdgcn_sched_barrier(0)
; template <class Epi, class Sched, bool ALIGN_EPI = false, bool SP2 = false>
; __device__ __forceinline__ void gemm_phase(PG8_LAS unsigned char* lds, const Gemm g, const Sched& S, const Epi& E) {
;     ...
;             PG8_WAIT_V(8); PG8_WAIT_L(0); PG8_BAR; PG8_MMA(1, 0, At, B0); PG8_MMA(1, 1, At, B1); PG8_BAR; PG8_SCHED;
	v_mfma_f32_16x16x32_bf16 v[60:63], v[128:131], v[176:179], v[60:63]
	v_mfma_f32_16x16x32_bf16 v[56:59], v[136:139], v[176:179], v[56:59]
	v_mfma_f32_16x16x32_bf16 v[52:55], v[128:131], v[184:187], v[52:55]
	v_mfma_f32_16x16x32_bf16 v[40:43], v[136:139], v[184:187], v[40:43]
	v_mfma_f32_16x16x32_bf16 v[36:39], v[128:131], v[210:213], v[36:39]
	v_mfma_f32_16x16x32_bf16 v[24:27], v[136:139], v[210:213], v[24:27]
	v_mfma_f32_16x16x32_bf16 v[20:23], v[128:131], v[218:221], v[20:23]
	v_mfma_f32_16x16x32_bf16 v[8:11], v[136:139], v[218:221], v[8:11]
	v_mfma_f32_16x16x32_bf16 v[60:63], v[132:135], v[180:183], v[60:63]
	v_mfma_f32_16x16x32_bf16 v[56:59], v[140:143], v[180:183], v[56:59]
	v_mfma_f32_16x16x32_bf16 v[52:55], v[132:135], v[192:195], v[52:55]
	v_mfma_f32_16x16x32_bf16 v[40:43], v[140:143], v[192:195], v[40:43]
	v_mfma_f32_16x16x32_bf16 v[36:39], v[132:135], v[214:217], v[36:39]
	v_mfma_f32_16x16x32_bf16 v[24:27], v[140:143], v[214:217], v[24:27]
	v_mfma_f32_16x16x32_bf16 v[20:23], v[132:135], v[222:225], v[20:23]
	v_mfma_f32_16x16x32_bf16 v[8:11], v[140:143], v[222:225], v[8:11]


; #define PG8_MMA(ai, bj, At, Bt) do { __builtin_amdgcn_s_setprio(1); _Pragma("unroll") for (int m = 0; m < 4; ++m) _Pragma("unroll") for (int n = 0; n < 2; ++n) _Pragma("unroll") for (int k = 0; k < 2; ++k) \
;         acc[ai][bj][m][n] = __builtin_amdgcn_mfma_f32_16x16x32_bf16(Bt[n][k], At[m][k], acc[ai][bj][m][n], 0, 0, 0); __builtin_amdgcn_s_setprio(0); } while (0)
; #define PG8_WAIT_V(n) asm volatile("s_waitcnt vmcnt(" #n ")" ::: "memory")
; #define PG8_WAIT_L(n) asm volatile("s_waitcnt lgkmcnt(" #n ")" ::: "memory")
; #define PG8_BAR __builtin_amdgcn_s_barrier()
; #define PG8_SCHED __builtin_amdgcn_sched_barrier(0)
; template <class Epi, class Sched, bool ALIGN_EPI = false, bool SP2 = false>
; __device__ __forceinline__ void gemm_phase(PG8_LAS unsigned char* lds, const Gemm g, const Sched& S, const Epi& E) {
;     ...
;             PG8_WAIT_V(8); PG8_WAIT_L(0); PG8_BAR; PG8_MMA(1, 0, At, B0); PG8_MMA(1, 1, At, B1); PG8_BAR; PG8_SCHED;
	v_mfma_f32_16x16x32_bf16 v[48:51], v[144:147], v[176:179], v[48:51]
	v_mfma_f32_16x16x32_bf16 v[44:47], v[152:155], v[176:179], v[44:47]
	v_mfma_f32_16x16x32_bf16 v[32:35], v[144:147], v[184:187], v[32:35]
	v_mfma_f32_16x16x32_bf16 v[28:31], v[152:155], v[184:187], v[28:31]
	v_mfma_f32_16x16x32_bf16 v[16:19], v[144:147], v[210:213], v[16:19]
	v_mfma_f32_16x16x32_bf16 v[12:15], v[152:155], v[210:213], v[12:15]
	v_mfma_f32_16x16x32_bf16 v[4:7], v[144:147], v[218:221], v[4:7]
	v_mfma_f32_16x16x32_bf16 v[0:3], v[152:155], v[218:221], v[0:3]
	v_mfma_f32_16x16x32_bf16 v[48:51], v[148:151], v[180:183], v[48:51]
	v_mfma_f32_16x16x32_bf16 v[44:47], v[156:159], v[180:183], v[44:47]
	v_mfma_f32_16x16x32_bf16 v[32:35], v[148:151], v[192:195], v[32:35]
	v_mfma_f32_16x16x32_bf16 v[28:31], v[156:159], v[192:195], v[28:31]
	v_mfma_f32_16x16x32_bf16 v[16:19], v[148:151], v[214:217], v[16:19]
	v_mfma_f32_16x16x32_bf16 v[12:15], v[156:159], v[214:217], v[12:15]
	v_mfma_f32_16x16x32_bf16 v[4:7], v[148:151], v[222:225], v[4:7]
	v_mfma_f32_16x16x32_bf16 v[0:3], v[156:159], v[222:225], v[0:3]

; #define PG8_STAGE(bufoff, gbase, voff) do { _Pragma("unroll") for (int _i = 0; _i < 2; ++_i) \
;         __builtin_amdgcn_global_load_lds((const unsigned*)((const char*)(gbase) + (voff)[_i]), (PG8_LAS unsigned*)(lds + (bufoff) + ldsw + _i * 8192), 16, 0, 0); } while (0)
; #define PG8_LDA(dst, b, h) do { _Pragma("unroll") for (int m = 0; m < 4; ++m) _Pragma("unroll") for (int k = 0; k < 2; ++k) dst[m][k] = *(const PG8_LAS bf16x8*)(lds + PG8_SA(b, h) + aoff + m * 2048 + k * 1024); } while (0)
; #define PG8_WAIT_V(n) asm volatile("s_waitcnt vmcnt(" #n ")" ::: "memory")
; #define PG8_WAIT_L(n) asm volatile("s_waitcnt lgkmcnt(" #n ")" ::: "memory")
; template <class Epi, class Sched, bool ALIGN_EPI = false, bool SP2 = false>
; __device__ __forceinline__ void gemm_phase(PG8_LAS unsigned char* lds, const Gemm g, const Sched& S, const Epi& E) {
;     ...
;         for (int t = 0; t < nt; t += 2) {
;             const bool last = (t == nt - 2);
;             const char* a1 = cA + (size_t)(t + 1) * kstep;
;             const char* a2 = last ? nA : cA + (size_t)(t + 2) * kstep; const char* b2 = last ? nB : cB + (size_t)(t + 2) * kstep;
;             const char* a3 = a2 + kstep; const char* b3 = b2 + kstep;
;             if (last && has_next) S.a_ready(nxt);
;             if constexpr (SP2) {
;             PG8_LDB(B0, 0, 0); PG8_LDB(B1, 0, 1); PG8_SCHED; PG8_LDA(At, 0, 0); PG8_STAGE(PG8_SA(1, 1), a1 + hstep, voffA);
;             PG8_WAIT_V(8); PG8_WAIT_L(0); PG8_BAR; PG8_MMA(0, 0, At, B0); PG8_MMA(0, 1, At, B1); PG8_BAR; PG8_SCHED;
;             PG8_LDA(At, 0, 1); PG8_STAGE(PG8_SB(0, 0), b2, voffB); PG8_STAGE(PG8_SB(0, 1), b2 + hstep, voffB); PG8_STAGE(PG8_SA(0, 0), a2, voffA);
;             PG8_WAIT_V(8); PG8_WAIT_L(0); PG8_BAR; PG8_MMA(1, 0, At, B0); PG8_MMA(1, 1, At, B1); PG8_BAR; PG8_SCHED;
;             PG8_LDB(B0, 1, 0); PG8_LDB(B1, 1, 1); PG8_SCHED; PG8_LDA(At, 1, 0); PG8_STAGE(PG8_SA(0, 1), a2 + hstep, voffA);
;             PG8_WAIT_V(8); PG8_WAIT_L(0); PG8_BAR; PG8_MMA(0, 0, At, B0); PG8_MMA(0, 1, At, B1); PG8_BAR; PG8_SCHED;
;             PG8_LDA(At, 1, 1); PG8_STAGE(PG8_SB(1, 0), b3, voffB); PG8_STAGE(PG8_SB(1, 1), b3 + hstep, voffB); PG8_STAGE(PG8_SA(1, 0), a3, voffA);
;             PG8_WAIT_V(8); PG8_WAIT_L(0); PG8_BAR; PG8_MMA(1, 0, At, B0); PG8_MMA(1, 1, At, B1); PG8_BAR; PG8_SCHED;
;     ...
;         if constexpr (ALIGN_EPI) { if (wr == 0) PG8_BAR; }
	s_barrier
	s_add_i32 s78, s78, 2
	s_add_u32 s10, s10, 0x100
	s_addc_u32 s11, s11, 0
	s_add_u32 s76, s76, 0x100
	s_addc_u32 s77, s77, 0
	s_cmp_gt_u32 s78, 29
	s_cbranch_scc0 .LBB0_679
	s_and_b64 vcc, exec, s[42:43]
	s_cbranch_vccz .LBB0_682
	s_barrier

; #define PG8_STAGE(bufoff, gbase, voff) do { _Pragma("unroll") for (int _i = 0; _i < 2; ++_i) \
;         __builtin_amdgcn_global_load_lds((const unsigned*)((const char*)(gbase) + (voff)[_i]), (PG8_LAS unsigned*)(lds + (bufoff) + ldsw + _i * 8192), 16, 0, 0); } while (0)
; #define PG8_LDA(dst, b, h) do { _Pragma("unroll") for (int m = 0; m < 4; ++m) _Pragma("unroll") for (int k = 0; k < 2; ++k) dst[m][k] = *(const PG8_LAS bf16x8*)(lds + PG8_SA(b, h) + aoff + m * 2048 + k * 1024); } while (0)
; #define PG8_LDB(dst, b, h) do { _Pragma("unroll") for (int n = 0; n < 2; ++n) _Pragma("unroll") for (int k = 0; k < 2; ++k) dst[n][k] = *(const PG8_LAS bf16x8*)(lds + PG8_SB(b, h) + boff + n * 2048 + k * 1024); } while (0)
; #define PG8_SCHED __builtin_amdgcn_sched_barrier(0)
; template <class Epi, class Sched, bool ALIGN_EPI = false, bool SP2 = false>
; __device__ __forceinline__ void gemm_phase(PG8_LAS unsigned char* lds, const Gemm g, const Sched& S, const Epi& E) {
;     ...
;             const char* a1 = cA + (size_t)(t + 1) * kstep;
;             const char* a2 = last ? nA : cA + (size_t)(t + 2) * kstep; const char* b2 = last ? nB : cB + (size_t)(t + 2) * kstep;
;             const char* a3 = a2 + kstep; const char* b3 = b2 + kstep;
;             if (last && has_next) S.a_ready(nxt);
;             if constexpr (SP2) {
;             PG8_LDB(B0, 0, 0); PG8_LDB(B1, 0, 1); PG8_SCHED; PG8_LDA(At, 0, 0); PG8_STAGE(PG8_SA(1, 1), a1 + hstep, voffA);
.LBB0_939:
	ds_read_b128 v[64:67], v213
	ds_read_b128 v[68:71], v213 offset:1024
	ds_read_b128 v[72:75], v213 offset:2048
	ds_read_b128 v[76:79], v213 offset:3072
	ds_read_b128 v[144:147], v214
	ds_read_b128 v[148:151], v214 offset:1024
	ds_read_b128 v[152:155], v214 offset:2048
	ds_read_b128 v[156:159], v214 offset:3072
	s_add_u32 s60, s58, 0xfff80080
	s_addc_u32 s61, s59, -1
	s_cmp_eq_u32 s81, 28
	s_cselect_b32 s63, s11, s61
	s_cselect_b32 s62, s51, s60
	s_cselect_b32 s61, s49, s80
	s_cselect_b32 s60, s78, s79

; #define PG8_STAGE(bufoff, gbase, voff) do { _Pragma("unroll") for (int _i = 0; _i < 2; ++_i) \
;         __builtin_amdgcn_global_load_lds((const unsigned*)((const char*)(gbase) + (voff)[_i]), (PG8_LAS unsigned*)(lds + (bufoff) + ldsw + _i * 8192), 16, 0, 0); } while (0)
; #define PG8_LDA(dst, b, h) do { _Pragma("unroll") for (int m = 0; m < 4; ++m) _Pragma("unroll") for (int k = 0; k < 2; ++k) dst[m][k] = *(const PG8_LAS bf16x8*)(lds + PG8_SA(b, h) + aoff + m * 2048 + k * 1024); } while (0)
; #define PG8_LDB(dst, b, h) do { _Pragma("unroll") for (int n = 0; n < 2; ++n) _Pragma("unroll") for (int k = 0; k < 2; ++k) dst[n][k] = *(const PG8_LAS bf16x8*)(lds + PG8_SB(b, h) + boff + n * 2048 + k * 1024); } while (0)
; #define PG8_SCHED __builtin_amdgcn_sched_barrier(0)
; template <class Epi, class Sched, bool ALIGN_EPI = false, bool SP2 = false>
; __device__ __forceinline__ void gemm_phase(PG8_LAS unsigned char* lds, const Gemm g, const Sched& S, const Epi& E) {
;     ...
;             PG8_LDB(B0, 0, 0); PG8_LDB(B1, 0, 1); PG8_SCHED; PG8_LDA(At, 0, 0); PG8_STAGE(PG8_SA(1, 1), a1 + hstep, voffA);
	s_add_i32 m0, s57, 0xc000
	ds_read_b128 v[176:179], v215
	ds_read_b128 v[180:183], v215 offset:1024
	ds_read_b128 v[184:187], v215 offset:2048
	ds_read_b128 v[188:191], v215 offset:3072
	ds_read_b128 v[192:195], v215 offset:4096
	ds_read_b128 v[196:199], v215 offset:5120
	ds_read_b128 v[200:203], v215 offset:6144
	ds_read_b128 v[204:207], v215 offset:7168
	global_load_lds_dwordx4 v168, s[58:59]

; #define PG8_STAGE(bufoff, gbase, voff) do { _Pragma("unroll") for (int _i = 0; _i < 2; ++_i) \
;         __builtin_amdgcn_global_load_lds((const unsigned*)((const char*)(gbase) + (voff)[_i]), (PG8_LAS unsigned*)(lds + (bufoff) + ldsw + _i * 8192), 16, 0, 0); } while (0)
; #define PG8_LDA(dst, b, h) do { _Pragma("unroll") for (int m = 0; m < 4; ++m) _Pragma("unroll") for (int k = 0; k < 2; ++k) dst[m][k] = *(const PG8_LAS bf16x8*)(lds + PG8_SA(b, h) + aoff + m * 2048 + k * 1024); } while (0)
; #define PG8_LDB(dst, b, h) do { _Pragma("unroll") for (int n = 0; n < 2; ++n) _Pragma("unroll") for (int k = 0; k < 2; ++k) dst[n][k] = *(const PG8_LAS bf16x8*)(lds + PG8_SB(b, h) + boff + n * 2048 + k * 1024); } while (0)
; #define PG8_MMA(ai, bj, At, Bt) do { __builtin_amdgcn_s_setprio(1); _Pragma("unroll") for (int m = 0; m < 4; ++m) _Pragma("unroll") for (int n = 0; n < 2; ++n) _Pragma("unroll") for (int k = 0; k < 2; ++k) \
;         acc[ai][bj][m][n] = __builtin_amdgcn_mfma_f32_16x16x32_bf16(Bt[n][k], At[m][k], acc[ai][bj][m][n], 0, 0, 0); __builtin_amdgcn_s_setprio(0); } while (0)
; #define PG8_WAIT_V(n) asm volatile("s_waitcnt vmcnt(" #n ")" ::: "memory")
; #define PG8_WAIT_L(n) asm volatile("s_waitcnt lgkmcnt(" #n ")" ::: "memory")
; #define PG8_BAR __builtin_amdgcn_s_barrier()
; #define PG8_SCHED __builtin_amdgcn_sched_barrier(0)
; template <class Epi, class Sched, bool ALIGN_EPI = false, bool SP2 = false>
; __device__ __forceinline__ void gemm_phase(PG8_LAS unsigned char* lds, const Gemm g, const Sched& S, const Epi& E) {
;     ...
;             PG8_LDB(B0, 0, 0); PG8_LDB(B1, 0, 1); PG8_SCHED; PG8_LDA(At, 0, 0); PG8_STAGE(PG8_SA(1, 1), a1 + hstep, voffA);
;             PG8_WAIT_V(8); PG8_WAIT_L(0); PG8_BAR; PG8_MMA(0, 0, At, B0); PG8_MMA(0, 1, At, B1); PG8_BAR; PG8_SCHED;
	s_add_i32 m0, s57, 0xe000
	s_nop 0
	global_load_lds_dwordx4 v170, s[58:59]
	s_waitcnt vmcnt(8) lgkmcnt(0)


; #define PG8_MMA(ai, bj, At, Bt) do { __builtin_amdgcn_s_setprio(1); _Pragma("unroll") for (int m = 0; m < 4; ++m) _Pragma("unroll") for (int n = 0; n < 2; ++n) _Pragma("unroll") for (int k = 0; k < 2; ++k) \
;         acc[ai][bj][m][n] = __builtin_amdgcn_mfma_f32_16x16x32_bf16(Bt[n][k], At[m][k], acc[ai][bj][m][n], 0, 0, 0); __builtin_amdgcn_s_setprio(0); } while (0)
; #define PG8_WAIT_V(n) asm volatile("s_waitcnt vmcnt(" #n ")" ::: "memory")
; #define PG8_WAIT_L(n) asm volatile("s_waitcnt lgkmcnt(" #n ")" ::: "memory")
; #define PG8_BAR __builtin_amdgcn_s_barrier()
; #define PG8_SCHED __builtin_amdgcn_sched_barrier(0)
; template <class Epi, class Sched, bool ALIGN_EPI = false, bool SP2 = false>
; __device__ __forceinline__ void gemm_phase(PG8_LAS unsigned char* lds, const Gemm g, const Sched& S, const Epi& E) {
;     ...
;             PG8_WAIT_V(8); PG8_WAIT_L(0); PG8_BAR; PG8_MMA(0, 0, At, B0); PG8_MMA(0, 1, At, B1); PG8_BAR; PG8_SCHED;
	s_barrier

; #define PG8_MMA(ai, bj, At, Bt) do { __builtin_amdgcn_s_setprio(1); _Pragma("unroll") for (int m = 0; m < 4; ++m) _Pragma("unroll") for (int n = 0; n < 2; ++n) _Pragma("unroll") for (int k = 0; k < 2; ++k) \
;         acc[ai][bj][m][n] = __builtin_amdgcn_mfma_f32_16x16x32_bf16(Bt[n][k], At[m][k], acc[ai][bj][m][n], 0, 0, 0); __builtin_amdgcn_s_setprio(0); } while (0)
; #define PG8_WAIT_V(n) asm volatile("s_waitcnt vmcnt(" #n ")" ::: "memory")
; #define PG8_WAIT_L(n) asm volatile("s_waitcnt lgkmcnt(" #n ")" ::: "memory")
; #define PG8_BAR __builtin_amdgcn_s_barrier()
; #define PG8_SCHED __builtin_amdgcn_sched_barrier(0)
; template <class Epi, class Sched, bool ALIGN_EPI = false, bool SP2 = false>
; __device__ __forceinline__ void gemm_phase(PG8_LAS unsigned char* lds, const Gemm g, const Sched& S, const Epi& E) {
;     ...
;             PG8_WAIT_V(8); PG8_WAIT_L(0); PG8_BAR; PG8_MMA(0, 0, At, B0); PG8_MMA(0, 1, At, B1); PG8_BAR; PG8_SCHED;
	v_mfma_f32_16x16x32_bf16 v[140:143], v[64:67], v[176:179], v[140:143]
	v_mfma_f32_16x16x32_bf16 v[136:139], v[72:75], v[176:179], v[136:139]
	v_mfma_f32_16x16x32_bf16 v[124:127], v[64:67], v[184:187], v[124:127]
	v_mfma_f32_16x16x32_bf16 v[120:123], v[72:75], v[184:187], v[120:123]
	v_mfma_f32_16x16x32_bf16 v[108:111], v[64:67], v[192:195], v[108:111]
	v_mfma_f32_16x16x32_bf16 v[104:107], v[72:75], v[192:195], v[104:107]
	v_mfma_f32_16x16x32_bf16 v[92:95], v[64:67], v[200:203], v[92:95]
	v_mfma_f32_16x16x32_bf16 v[88:91], v[72:75], v[200:203], v[88:91]
	v_mfma_f32_16x16x32_bf16 v[140:143], v[68:71], v[180:183], v[140:143]
	v_mfma_f32_16x16x32_bf16 v[136:139], v[76:79], v[180:183], v[136:139]
	v_mfma_f32_16x16x32_bf16 v[124:127], v[68:71], v[188:191], v[124:127]
	v_mfma_f32_16x16x32_bf16 v[120:123], v[76:79], v[188:191], v[120:123]
	v_mfma_f32_16x16x32_bf16 v[108:111], v[68:71], v[196:199], v[108:111]
	v_mfma_f32_16x16x32_bf16 v[104:107], v[76:79], v[196:199], v[104:107]
	v_mfma_f32_16x16x32_bf16 v[92:95], v[68:71], v[204:207], v[92:95]
	v_mfma_f32_16x16x32_bf16 v[88:91], v[76:79], v[204:207], v[88:91]


; #define PG8_MMA(ai, bj, At, Bt) do { __builtin_amdgcn_s_setprio(1); _Pragma("unroll") for (int m = 0; m < 4; ++m) _Pragma("unroll") for (int n = 0; n < 2; ++n) _Pragma("unroll") for (int k = 0; k < 2; ++k) \
;         acc[ai][bj][m][n] = __builtin_amdgcn_mfma_f32_16x16x32_bf16(Bt[n][k], At[m][k], acc[ai][bj][m][n], 0, 0, 0); __builtin_amdgcn_s_setprio(0); } while (0)
; #define PG8_WAIT_V(n) asm volatile("s_waitcnt vmcnt(" #n ")" ::: "memory")
; #define PG8_WAIT_L(n) asm volatile("s_waitcnt lgkmcnt(" #n ")" ::: "memory")
; #define PG8_BAR __builtin_amdgcn_s_barrier()
; #define PG8_SCHED __builtin_amdgcn_sched_barrier(0)
; template <class Epi, class Sched, bool ALIGN_EPI = false, bool SP2 = false>
; __device__ __forceinline__ void gemm_phase(PG8_LAS unsigned char* lds, const Gemm g, const Sched& S, const Epi& E) {
;     ...
;             PG8_WAIT_V(8); PG8_WAIT_L(0); PG8_BAR; PG8_MMA(0, 0, At, B0); PG8_MMA(0, 1, At, B1); PG8_BAR; PG8_SCHED;
	v_mfma_f32_16x16x32_bf16 v[132:135], v[144:147], v[176:179], v[132:135]
	v_mfma_f32_16x16x32_bf16 v[128:131], v[152:155], v[176:179], v[128:131]
	v_mfma_f32_16x16x32_bf16 v[116:119], v[144:147], v[184:187], v[116:119]
	v_mfma_f32_16x16x32_bf16 v[112:115], v[152:155], v[184:187], v[112:115]
	v_mfma_f32_16x16x32_bf16 v[100:103], v[144:147], v[192:195], v[100:103]
	v_mfma_f32_16x16x32_bf16 v[96:99], v[152:155], v[192:195], v[96:99]
	v_mfma_f32_16x16x32_bf16 v[84:87], v[144:147], v[200:203], v[84:87]
	v_mfma_f32_16x16x32_bf16 v[80:83], v[152:155], v[200:203], v[80:83]
	v_mfma_f32_16x16x32_bf16 v[132:135], v[148:151], v[180:183], v[132:135]
	v_mfma_f32_16x16x32_bf16 v[128:131], v[156:159], v[180:183], v[128:131]
	v_mfma_f32_16x16x32_bf16 v[116:119], v[148:151], v[188:191], v[116:119]
	v_mfma_f32_16x16x32_bf16 v[112:115], v[156:159], v[188:191], v[112:115]
	v_mfma_f32_16x16x32_bf16 v[100:103], v[148:151], v[196:199], v[100:103]
	v_mfma_f32_16x16x32_bf16 v[96:99], v[156:159], v[196:199], v[96:99]
	v_mfma_f32_16x16x32_bf16 v[84:87], v[148:151], v[204:207], v[84:87]
	v_mfma_f32_16x16x32_bf16 v[80:83], v[156:159], v[204:207], v[80:83]

; #define PG8_STAGE(bufoff, gbase, voff) do { _Pragma("unroll") for (int _i = 0; _i < 2; ++_i) \
;         __builtin_amdgcn_global_load_lds((const unsigned*)((const char*)(gbase) + (voff)[_i]), (PG8_LAS unsigned*)(lds + (bufoff) + ldsw + _i * 8192), 16, 0, 0); } while (0)
; #define PG8_LDA(dst, b, h) do { _Pragma("unroll") for (int m = 0; m < 4; ++m) _Pragma("unroll") for (int k = 0; k < 2; ++k) dst[m][k] = *(const PG8_LAS bf16x8*)(lds + PG8_SA(b, h) + aoff + m * 2048 + k * 1024); } while (0)
; #define PG8_MMA(ai, bj, At, Bt) do { __builtin_amdgcn_s_setprio(1); _Pragma("unroll") for (int m = 0; m < 4; ++m) _Pragma("unroll") for (int n = 0; n < 2; ++n) _Pragma("unroll") for (int k = 0; k < 2; ++k) \
;         acc[ai][bj][m][n] = __builtin_amdgcn_mfma_f32_16x16x32_bf16(Bt[n][k], At[m][k], acc[ai][bj][m][n], 0, 0, 0); __builtin_amdgcn_s_setprio(0); } while (0)
; #define PG8_WAIT_V(n) asm volatile("s_waitcnt vmcnt(" #n ")" ::: "memory")
; #define PG8_WAIT_L(n) asm volatile("s_waitcnt lgkmcnt(" #n ")" ::: "memory")
; #define PG8_BAR __builtin_amdgcn_s_barrier()
; #define PG8_SCHED __builtin_amdgcn_sched_barrier(0)
; template <class Epi, class Sched, bool ALIGN_EPI = false, bool SP2 = false>
; __device__ __forceinline__ void gemm_phase(PG8_LAS unsigned char* lds, const Gemm g, const Sched& S, const Epi& E) {
;     ...
;             PG8_WAIT_V(8); PG8_WAIT_L(0); PG8_BAR; PG8_MMA(0, 0, At, B0); PG8_MMA(0, 1, At, B1); PG8_BAR; PG8_SCHED;
;             PG8_LDA(At, 0, 1); PG8_STAGE(PG8_SB(0, 0), b2, voffB); PG8_STAGE(PG8_SB(0, 1), b2 + hstep, voffB); PG8_STAGE(PG8_SA(0, 0), a2, voffA);
	s_barrier
	s_add_i32 s82, s75, s64
	s_mov_b64 s[96:97], s[60:61]

; #define PG8_STAGE(bufoff, gbase, voff) do { _Pragma("unroll") for (int _i = 0; _i < 2; ++_i) \
;         __builtin_amdgcn_global_load_lds((const unsigned*)((const char*)(gbase) + (voff)[_i]), (PG8_LAS unsigned*)(lds + (bufoff) + ldsw + _i * 8192), 16, 0, 0); } while (0)
; #define PG8_LDA(dst, b, h) do { _Pragma("unroll") for (int m = 0; m < 4; ++m) _Pragma("unroll") for (int k = 0; k < 2; ++k) dst[m][k] = *(const PG8_LAS bf16x8*)(lds + PG8_SA(b, h) + aoff + m * 2048 + k * 1024); } while (0)
; template <class Epi, class Sched, bool ALIGN_EPI = false, bool SP2 = false>
; __device__ __forceinline__ void gemm_phase(PG8_LAS unsigned char* lds, const Gemm g, const Sched& S, const Epi& E) {
;     ...
;             PG8_LDA(At, 0, 1); PG8_STAGE(PG8_SB(0, 0), b2, voffB); PG8_STAGE(PG8_SB(0, 1), b2 + hstep, voffB); PG8_STAGE(PG8_SA(0, 0), a2, voffA);
	s_mov_b32 m0, s82
	ds_read_b128 v[176:179], v215 offset:16384
	ds_read_b128 v[180:183], v215 offset:17408
	ds_read_b128 v[184:187], v215 offset:18432
	ds_read_b128 v[188:191], v215 offset:19456
	ds_read_b128 v[192:195], v215 offset:20480
	ds_read_b128 v[196:199], v215 offset:21504
	ds_read_b128 v[200:203], v215 offset:22528
	ds_read_b128 v[204:207], v215 offset:23552
	global_load_lds_dwordx4 v162, s[60:61]
	s_add_i32 m0, s82, 0x2000
	s_add_u32 s82, s60, 0x80000

; #define PG8_STAGE(bufoff, gbase, voff) do { _Pragma("unroll") for (int _i = 0; _i < 2; ++_i) \
;         __builtin_amdgcn_global_load_lds((const unsigned*)((const char*)(gbase) + (voff)[_i]), (PG8_LAS unsigned*)(lds + (bufoff) + ldsw + _i * 8192), 16, 0, 0); } while (0)
; #define PG8_LDA(dst, b, h) do { _Pragma("unroll") for (int m = 0; m < 4; ++m) _Pragma("unroll") for (int k = 0; k < 2; ++k) dst[m][k] = *(const PG8_LAS bf16x8*)(lds + PG8_SA(b, h) + aoff + m * 2048 + k * 1024); } while (0)
; template <class Epi, class Sched, bool ALIGN_EPI = false, bool SP2 = false>
; __device__ __forceinline__ void gemm_phase(PG8_LAS unsigned char* lds, const Gemm g, const Sched& S, const Epi& E) {
;     ...
;             PG8_LDA(At, 0, 1); PG8_STAGE(PG8_SB(0, 0), b2, voffB); PG8_STAGE(PG8_SB(0, 1), b2 + hstep, voffB); PG8_STAGE(PG8_SA(0, 0), a2, voffA);
	s_addc_u32 s83, s61, 0
	s_add_i32 s84, s76, s64
	global_load_lds_dwordx4 v166, s[60:61]

; #define PG8_STAGE(bufoff, gbase, voff) do { _Pragma("unroll") for (int _i = 0; _i < 2; ++_i) \
;         __builtin_amdgcn_global_load_lds((const unsigned*)((const char*)(gbase) + (voff)[_i]), (PG8_LAS unsigned*)(lds + (bufoff) + ldsw + _i * 8192), 16, 0, 0); } while (0)
; #define PG8_LDA(dst, b, h) do { _Pragma("unroll") for (int m = 0; m < 4; ++m) _Pragma("unroll") for (int k = 0; k < 2; ++k) dst[m][k] = *(const PG8_LAS bf16x8*)(lds + PG8_SA(b, h) + aoff + m * 2048 + k * 1024); } while (0)
; template <class Epi, class Sched, bool ALIGN_EPI = false, bool SP2 = false>
; __device__ __forceinline__ void gemm_phase(PG8_LAS unsigned char* lds, const Gemm g, const Sched& S, const Epi& E) {
;     ...
;             PG8_LDA(At, 0, 1); PG8_STAGE(PG8_SB(0, 0), b2, voffB); PG8_STAGE(PG8_SB(0, 1), b2 + hstep, voffB); PG8_STAGE(PG8_SA(0, 0), a2, voffA);
	s_mov_b32 m0, s84
	s_nop 0
	global_load_lds_dwordx4 v162, s[82:83]

; #define PG8_STAGE(bufoff, gbase, voff) do { _Pragma("unroll") for (int _i = 0; _i < 2; ++_i) \
;         __builtin_amdgcn_global_load_lds((const unsigned*)((const char*)(gbase) + (voff)[_i]), (PG8_LAS unsigned*)(lds + (bufoff) + ldsw + _i * 8192), 16, 0, 0); } while (0)
; #define PG8_LDA(dst, b, h) do { _Pragma("unroll") for (int m = 0; m < 4; ++m) _Pragma("unroll") for (int k = 0; k < 2; ++k) dst[m][k] = *(const PG8_LAS bf16x8*)(lds + PG8_SA(b, h) + aoff + m * 2048 + k * 1024); } while (0)
; template <class Epi, class Sched, bool ALIGN_EPI = false, bool SP2 = false>
; __device__ __forceinline__ void gemm_phase(PG8_LAS unsigned char* lds, const Gemm g, const Sched& S, const Epi& E) {
;     ...
;             PG8_LDA(At, 0, 1); PG8_STAGE(PG8_SB(0, 0), b2, voffB); PG8_STAGE(PG8_SB(0, 1), b2 + hstep, voffB); PG8_STAGE(PG8_SA(0, 0), a2, voffA);
	s_add_i32 m0, s84, 0x2000
	s_nop 0
	global_load_lds_dwordx4 v166, s[82:83]
	s_mov_b64 s[98:99], s[62:63]

; #define PG8_STAGE(bufoff, gbase, voff) do { _Pragma("unroll") for (int _i = 0; _i < 2; ++_i) \
;         __builtin_amdgcn_global_load_lds((const unsigned*)((const char*)(gbase) + (voff)[_i]), (PG8_LAS unsigned*)(lds + (bufoff) + ldsw + _i * 8192), 16, 0, 0); } while (0)
; #define PG8_LDA(dst, b, h) do { _Pragma("unroll") for (int m = 0; m < 4; ++m) _Pragma("unroll") for (int k = 0; k < 2; ++k) dst[m][k] = *(const PG8_LAS bf16x8*)(lds + PG8_SA(b, h) + aoff + m * 2048 + k * 1024); } while (0)
; #define PG8_MMA(ai, bj, At, Bt) do { __builtin_amdgcn_s_setprio(1); _Pragma("unroll") for (int m = 0; m < 4; ++m) _Pragma("unroll") for (int n = 0; n < 2; ++n) _Pragma("unroll") for (int k = 0; k < 2; ++k) \
;         acc[ai][bj][m][n] = __builtin_amdgcn_mfma_f32_16x16x32_bf16(Bt[n][k], At[m][k], acc[ai][bj][m][n], 0, 0, 0); __builtin_amdgcn_s_setprio(0); } while (0)
; #define PG8_WAIT_V(n) asm volatile("s_waitcnt vmcnt(" #n ")" ::: "memory")
; #define PG8_WAIT_L(n) asm volatile("s_waitcnt lgkmcnt(" #n ")" ::: "memory")
; #define PG8_BAR __builtin_amdgcn_s_barrier()
; #define PG8_SCHED __builtin_amdgcn_sched_barrier(0)
; template <class Epi, class Sched, bool ALIGN_EPI = false, bool SP2 = false>
; __device__ __forceinline__ void gemm_phase(PG8_LAS unsigned char* lds, const Gemm g, const Sched& S, const Epi& E) {
;     ...
;             PG8_LDA(At, 0, 1); PG8_STAGE(PG8_SB(0, 0), b2, voffB); PG8_STAGE(PG8_SB(0, 1), b2 + hstep, voffB); PG8_STAGE(PG8_SA(0, 0), a2, voffA);
;             PG8_WAIT_V(8); PG8_WAIT_L(0); PG8_BAR; PG8_MMA(1, 0, At, B0); PG8_MMA(1, 1, At, B1); PG8_BAR; PG8_SCHED;
	s_mov_b32 m0, s57
	s_nop 0
	global_load_lds_dwordx4 v160, s[62:63]
	s_mov_b32 m0, s65
	s_nop 0
	global_load_lds_dwordx4 v164, s[62:63]
	s_waitcnt vmcnt(8) lgkmcnt(0)


; #define PG8_MMA(ai, bj, At, Bt) do { __builtin_amdgcn_s_setprio(1); _Pragma("unroll") for (int m = 0; m < 4; ++m) _Pragma("unroll") for (int n = 0; n < 2; ++n) _Pragma("unroll") for (int k = 0; k < 2; ++k) \
;         acc[ai][bj][m][n] = __builtin_amdgcn_mfma_f32_16x16x32_bf16(Bt[n][k], At[m][k], acc[ai][bj][m][n], 0, 0, 0); __builtin_amdgcn_s_setprio(0); } while (0)
; #define PG8_WAIT_V(n) asm volatile("s_waitcnt vmcnt(" #n ")" ::: "memory")
; #define PG8_WAIT_L(n) asm volatile("s_waitcnt lgkmcnt(" #n ")" ::: "memory")
; #define PG8_BAR __builtin_amdgcn_s_barrier()
; #define PG8_SCHED __builtin_amdgcn_sched_barrier(0)
; template <class Epi, class Sched, bool ALIGN_EPI = false, bool SP2 = false>
; __device__ __forceinline__ void gemm_phase(PG8_LAS unsigned char* lds, const Gemm g, const Sched& S, const Epi& E) {
;     ...
;             PG8_WAIT_V(8); PG8_WAIT_L(0); PG8_BAR; PG8_MMA(1, 0, At, B0); PG8_MMA(1, 1, At, B1); PG8_BAR; PG8_SCHED;
	s_barrier

; #define PG8_MMA(ai, bj, At, Bt) do { __builtin_amdgcn_s_setprio(1); _Pragma("unroll") for (int m = 0; m < 4; ++m) _Pragma("unroll") for (int n = 0; n < 2; ++n) _Pragma("unroll") for (int k = 0; k < 2; ++k) \
;         acc[ai][bj][m][n] = __builtin_amdgcn_mfma_f32_16x16x32_bf16(Bt[n][k], At[m][k], acc[ai][bj][m][n], 0, 0, 0); __builtin_amdgcn_s_setprio(0); } while (0)
; #define PG8_WAIT_V(n) asm volatile("s_waitcnt vmcnt(" #n ")" ::: "memory")
; #define PG8_WAIT_L(n) asm volatile("s_waitcnt lgkmcnt(" #n ")" ::: "memory")
; #define PG8_BAR __builtin_amdgcn_s_barrier()
; #define PG8_SCHED __builtin_amdgcn_sched_barrier(0)
; template <class Epi, class Sched, bool ALIGN_EPI = false, bool SP2 = false>
; __device__ __forceinline__ void gemm_phase(PG8_LAS unsigned char* lds, const Gemm g, const Sched& S, const Epi& E) {
;     ...
;             PG8_WAIT_V(8); PG8_WAIT_L(0); PG8_BAR; PG8_MMA(1, 0, At, B0); PG8_MMA(1, 1, At, B1); PG8_BAR; PG8_SCHED;
	v_mfma_f32_16x16x32_bf16 v[60:63], v[64:67], v[176:179], v[60:63]
	v_mfma_f32_16x16x32_bf16 v[56:59], v[72:75], v[176:179], v[56:59]
	v_mfma_f32_16x16x32_bf16 v[44:47], v[64:67], v[184:187], v[44:47]
	v_mfma_f32_16x16x32_bf16 v[40:43], v[72:75], v[184:187], v[40:43]
	v_mfma_f32_16x16x32_bf16 v[28:31], v[64:67], v[192:195], v[28:31]
	v_mfma_f32_16x16x32_bf16 v[24:27], v[72:75], v[192:195], v[24:27]
	v_mfma_f32_16x16x32_bf16 v[12:15], v[64:67], v[200:203], v[12:15]
	v_mfma_f32_16x16x32_bf16 v[8:11], v[72:75], v[200:203], v[8:11]
	v_mfma_f32_16x16x32_bf16 v[60:63], v[68:71], v[180:183], v[60:63]
	v_mfma_f32_16x16x32_bf16 v[56:59], v[76:79], v[180:183], v[56:59]
	v_mfma_f32_16x16x32_bf16 v[44:47], v[68:71], v[188:191], v[44:47]
	v_mfma_f32_16x16x32_bf16 v[40:43], v[76:79], v[188:191], v[40:43]
	v_mfma_f32_16x16x32_bf16 v[28:31], v[68:71], v[196:199], v[28:31]
	v_mfma_f32_16x16x32_bf16 v[24:27], v[76:79], v[196:199], v[24:27]
	v_mfma_f32_16x16x32_bf16 v[12:15], v[68:71], v[204:207], v[12:15]
	v_mfma_f32_16x16x32_bf16 v[8:11], v[76:79], v[204:207], v[8:11]


; #define PG8_MMA(ai, bj, At, Bt) do { __builtin_amdgcn_s_setprio(1); _Pragma("unroll") for (int m = 0; m < 4; ++m) _Pragma("unroll") for (int n = 0; n < 2; ++n) _Pragma("unroll") for (int k = 0; k < 2; ++k) \
;         acc[ai][bj][m][n] = __builtin_amdgcn_mfma_f32_16x16x32_bf16(Bt[n][k], At[m][k], acc[ai][bj][m][n], 0, 0, 0); __builtin_amdgcn_s_setprio(0); } while (0)
; #define PG8_WAIT_V(n) asm volatile("s_waitcnt vmcnt(" #n ")" ::: "memory")
; #define PG8_WAIT_L(n) asm volatile("s_waitcnt lgkmcnt(" #n ")" ::: "memory")
; #define PG8_BAR __builtin_amdgcn_s_barrier()
; #define PG8_SCHED __builtin_amdgcn_sched_barrier(0)
; template <class Epi, class Sched, bool ALIGN_EPI = false, bool SP2 = false>
; __device__ __forceinline__ void gemm_phase(PG8_LAS unsigned char* lds, const Gemm g, const Sched& S, const Epi& E) {
;     ...
;             PG8_WAIT_V(8); PG8_WAIT_L(0); PG8_BAR; PG8_MMA(1, 0, At, B0); PG8_MMA(1, 1, At, B1); PG8_BAR; PG8_SCHED;
	v_mfma_f32_16x16x32_bf16 v[52:55], v[144:147], v[176:179], v[52:55]
	v_mfma_f32_16x16x32_bf16 v[48:51], v[152:155], v[176:179], v[48:51]
	v_mfma_f32_16x16x32_bf16 v[36:39], v[144:147], v[184:187], v[36:39]
	v_mfma_f32_16x16x32_bf16 v[32:35], v[152:155], v[184:187], v[32:35]
	v_mfma_f32_16x16x32_bf16 v[20:23], v[144:147], v[192:195], v[20:23]
	v_mfma_f32_16x16x32_bf16 v[16:19], v[152:155], v[192:195], v[16:19]
	v_mfma_f32_16x16x32_bf16 v[4:7], v[144:147], v[200:203], v[4:7]
	v_mfma_f32_16x16x32_bf16 v[0:3], v[152:155], v[200:203], v[0:3]
	v_mfma_f32_16x16x32_bf16 v[52:55], v[148:151], v[180:183], v[52:55]
	v_mfma_f32_16x16x32_bf16 v[48:51], v[156:159], v[180:183], v[48:51]
	v_mfma_f32_16x16x32_bf16 v[36:39], v[148:151], v[188:191], v[36:39]
	v_mfma_f32_16x16x32_bf16 v[32:35], v[156:159], v[188:191], v[32:35]
	v_mfma_f32_16x16x32_bf16 v[20:23], v[148:151], v[196:199], v[20:23]
	v_mfma_f32_16x16x32_bf16 v[16:19], v[156:159], v[196:199], v[16:19]
	v_mfma_f32_16x16x32_bf16 v[4:7], v[148:151], v[204:207], v[4:7]
	v_mfma_f32_16x16x32_bf16 v[0:3], v[156:159], v[204:207], v[0:3]

; #define PG8_STAGE(bufoff, gbase, voff) do { _Pragma("unroll") for (int _i = 0; _i < 2; ++_i) \
;         __builtin_amdgcn_global_load_lds((const unsigned*)((const char*)(gbase) + (voff)[_i]), (PG8_LAS unsigned*)(lds + (bufoff) + ldsw + _i * 8192), 16, 0, 0); } while (0)
; #define PG8_LDA(dst, b, h) do { _Pragma("unroll") for (int m = 0; m < 4; ++m) _Pragma("unroll") for (int k = 0; k < 2; ++k) dst[m][k] = *(const PG8_LAS bf16x8*)(lds + PG8_SA(b, h) + aoff + m * 2048 + k * 1024); } while (0)
; #define PG8_LDB(dst, b, h) do { _Pragma("unroll") for (int n = 0; n < 2; ++n) _Pragma("unroll") for (int k = 0; k < 2; ++k) dst[n][k] = *(const PG8_LAS bf16x8*)(lds + PG8_SB(b, h) + boff + n * 2048 + k * 1024); } while (0)
; #define PG8_MMA(ai, bj, At, Bt) do { __builtin_amdgcn_s_setprio(1); _Pragma("unroll") for (int m = 0; m < 4; ++m) _Pragma("unroll") for (int n = 0; n < 2; ++n) _Pragma("unroll") for (int k = 0; k < 2; ++k) \
;         acc[ai][bj][m][n] = __builtin_amdgcn_mfma_f32_16x16x32_bf16(Bt[n][k], At[m][k], acc[ai][bj][m][n], 0, 0, 0); __builtin_amdgcn_s_setprio(0); } while (0)
; #define PG8_WAIT_V(n) asm volatile("s_waitcnt vmcnt(" #n ")" ::: "memory")
; #define PG8_WAIT_L(n) asm volatile("s_waitcnt lgkmcnt(" #n ")" ::: "memory")
; #define PG8_BAR __builtin_amdgcn_s_barrier()
; #define PG8_SCHED __builtin_amdgcn_sched_barrier(0)
; template <class Epi, class Sched, bool ALIGN_EPI = false, bool SP2 = false>
; __device__ __forceinline__ void gemm_phase(PG8_LAS unsigned char* lds, const Gemm g, const Sched& S, const Epi& E) {
;     ...
;             PG8_WAIT_V(8); PG8_WAIT_L(0); PG8_BAR; PG8_MMA(1, 0, At, B0); PG8_MMA(1, 1, At, B1); PG8_BAR; PG8_SCHED;
;             PG8_LDB(B0, 1, 0); PG8_LDB(B1, 1, 1); PG8_SCHED; PG8_LDA(At, 1, 0); PG8_STAGE(PG8_SA(0, 1), a2 + hstep, voffA);
;             PG8_WAIT_V(8); PG8_WAIT_L(0); PG8_BAR; PG8_MMA(0, 0, At, B0); PG8_MMA(0, 1, At, B1); PG8_BAR; PG8_SCHED;
;             PG8_LDA(At, 1, 1); PG8_STAGE(PG8_SB(1, 0), b3, voffB); PG8_STAGE(PG8_SB(1, 1), b3 + hstep, voffB); PG8_STAGE(PG8_SA(1, 0), a3, voffA);
	s_barrier
	s_add_i32 s82, 0, 0x18000
	s_add_i32 s83, 0, 0x1c000


; #define PG8_STAGE(bufoff, gbase, voff) do { _Pragma("unroll") for (int _i = 0; _i < 2; ++_i) \
;         __builtin_amdgcn_global_load_lds((const unsigned*)((const char*)(gbase) + (voff)[_i]), (PG8_LAS unsigned*)(lds + (bufoff) + ldsw + _i * 8192), 16, 0, 0); } while (0)
; #define PG8_LDA(dst, b, h) do { _Pragma("unroll") for (int m = 0; m < 4; ++m) _Pragma("unroll") for (int k = 0; k < 2; ++k) dst[m][k] = *(const PG8_LAS bf16x8*)(lds + PG8_SA(b, h) + aoff + m * 2048 + k * 1024); } while (0)
; #define PG8_LDB(dst, b, h) do { _Pragma("unroll") for (int n = 0; n < 2; ++n) _Pragma("unroll") for (int k = 0; k < 2; ++k) dst[n][k] = *(const PG8_LAS bf16x8*)(lds + PG8_SB(b, h) + boff + n * 2048 + k * 1024); } while (0)
; #define PG8_SCHED __builtin_amdgcn_sched_barrier(0)
; template <class Epi, class Sched, bool ALIGN_EPI = false, bool SP2 = false>
; __device__ __forceinline__ void gemm_phase(PG8_LAS unsigned char* lds, const Gemm g, const Sched& S, const Epi& E) {
;     ...
;             PG8_LDB(B0, 1, 0); PG8_LDB(B1, 1, 1); PG8_SCHED; PG8_LDA(At, 1, 0); PG8_STAGE(PG8_SA(0, 1), a2 + hstep, voffA);
	ds_read_b128 v[64:67], v254
	ds_read_b128 v[68:71], v254 offset:1024
	ds_read_b128 v[72:75], v254 offset:2048
	ds_read_b128 v[76:79], v254 offset:3072
	ds_read_b128 v[144:147], v255
	ds_read_b128 v[148:151], v255 offset:1024
	ds_read_b128 v[152:155], v255 offset:2048
	ds_read_b128 v[156:159], v255 offset:3072
	s_add_u32 s62, s62, 0x80000
	s_addc_u32 s63, s63, 0
	s_mov_b32 m0, s67

; #define PG8_STAGE(bufoff, gbase, voff) do { _Pragma("unroll") for (int _i = 0; _i < 2; ++_i) \
;         __builtin_amdgcn_global_load_lds((const unsigned*)((const char*)(gbase) + (voff)[_i]), (PG8_LAS unsigned*)(lds + (bufoff) + ldsw + _i * 8192), 16, 0, 0); } while (0)
; #define PG8_LDA(dst, b, h) do { _Pragma("unroll") for (int m = 0; m < 4; ++m) _Pragma("unroll") for (int k = 0; k < 2; ++k) dst[m][k] = *(const PG8_LAS bf16x8*)(lds + PG8_SA(b, h) + aoff + m * 2048 + k * 1024); } while (0)
; #define PG8_LDB(dst, b, h) do { _Pragma("unroll") for (int n = 0; n < 2; ++n) _Pragma("unroll") for (int k = 0; k < 2; ++k) dst[n][k] = *(const PG8_LAS bf16x8*)(lds + PG8_SB(b, h) + boff + n * 2048 + k * 1024); } while (0)
; #define PG8_SCHED __builtin_amdgcn_sched_barrier(0)
; template <class Epi, class Sched, bool ALIGN_EPI = false, bool SP2 = false>
; __device__ __forceinline__ void gemm_phase(PG8_LAS unsigned char* lds, const Gemm g, const Sched& S, const Epi& E) {
;     ...
;             PG8_LDB(B0, 1, 0); PG8_LDB(B1, 1, 1); PG8_SCHED; PG8_LDA(At, 1, 0); PG8_STAGE(PG8_SA(0, 1), a2 + hstep, voffA);
	ds_read_b128 v[176:179], v215 offset:32768
	ds_read_b128 v[180:183], v215 offset:33792
	ds_read_b128 v[184:187], v215 offset:34816
	ds_read_b128 v[188:191], v215 offset:35840
	ds_read_b128 v[192:195], v215 offset:36864
	ds_read_b128 v[196:199], v215 offset:37888
	ds_read_b128 v[200:203], v215 offset:38912
	ds_read_b128 v[204:207], v215 offset:39936
	global_load_lds_dwordx4 v160, s[62:63]

; #define PG8_STAGE(bufoff, gbase, voff) do { _Pragma("unroll") for (int _i = 0; _i < 2; ++_i) \
;         __builtin_amdgcn_global_load_lds((const unsigned*)((const char*)(gbase) + (voff)[_i]), (PG8_LAS unsigned*)(lds + (bufoff) + ldsw + _i * 8192), 16, 0, 0); } while (0)
; #define PG8_LDA(dst, b, h) do { _Pragma("unroll") for (int m = 0; m < 4; ++m) _Pragma("unroll") for (int k = 0; k < 2; ++k) dst[m][k] = *(const PG8_LAS bf16x8*)(lds + PG8_SA(b, h) + aoff + m * 2048 + k * 1024); } while (0)
; #define PG8_LDB(dst, b, h) do { _Pragma("unroll") for (int n = 0; n < 2; ++n) _Pragma("unroll") for (int k = 0; k < 2; ++k) dst[n][k] = *(const PG8_LAS bf16x8*)(lds + PG8_SB(b, h) + boff + n * 2048 + k * 1024); } while (0)
; #define PG8_MMA(ai, bj, At, Bt) do { __builtin_amdgcn_s_setprio(1); _Pragma("unroll") for (int m = 0; m < 4; ++m) _Pragma("unroll") for (int n = 0; n < 2; ++n) _Pragma("unroll") for (int k = 0; k < 2; ++k) \
;         acc[ai][bj][m][n] = __builtin_amdgcn_mfma_f32_16x16x32_bf16(Bt[n][k], At[m][k], acc[ai][bj][m][n], 0, 0, 0); __builtin_amdgcn_s_setprio(0); } while (0)
; #define PG8_WAIT_V(n) asm volatile("s_waitcnt vmcnt(" #n ")" ::: "memory")
; #define PG8_WAIT_L(n) asm volatile("s_waitcnt lgkmcnt(" #n ")" ::: "memory")
; #define PG8_BAR __builtin_amdgcn_s_barrier()
; #define PG8_SCHED __builtin_amdgcn_sched_barrier(0)
; template <class Epi, class Sched, bool ALIGN_EPI = false, bool SP2 = false>
; __device__ __forceinline__ void gemm_phase(PG8_LAS unsigned char* lds, const Gemm g, const Sched& S, const Epi& E) {
;     ...
;             PG8_LDB(B0, 1, 0); PG8_LDB(B1, 1, 1); PG8_SCHED; PG8_LDA(At, 1, 0); PG8_STAGE(PG8_SA(0, 1), a2 + hstep, voffA);
;             PG8_WAIT_V(8); PG8_WAIT_L(0); PG8_BAR; PG8_MMA(0, 0, At, B0); PG8_MMA(0, 1, At, B1); PG8_BAR; PG8_SCHED;
	s_mov_b32 m0, s68
	s_nop 0
	global_load_lds_dwordx4 v164, s[62:63]
	s_waitcnt vmcnt(8) lgkmcnt(0)


; #define PG8_MMA(ai, bj, At, Bt) do { __builtin_amdgcn_s_setprio(1); _Pragma("unroll") for (int m = 0; m < 4; ++m) _Pragma("unroll") for (int n = 0; n < 2; ++n) _Pragma("unroll") for (int k = 0; k < 2; ++k) \
;         acc[ai][bj][m][n] = __builtin_amdgcn_mfma_f32_16x16x32_bf16(Bt[n][k], At[m][k], acc[ai][bj][m][n], 0, 0, 0); __builtin_amdgcn_s_setprio(0); } while (0)
; #define PG8_WAIT_V(n) asm volatile("s_waitcnt vmcnt(" #n ")" ::: "memory")
; #define PG8_WAIT_L(n) asm volatile("s_waitcnt lgkmcnt(" #n ")" ::: "memory")
; #define PG8_BAR __builtin_amdgcn_s_barrier()
; #define PG8_SCHED __builtin_amdgcn_sched_barrier(0)
; template <class Epi, class Sched, bool ALIGN_EPI = false, bool SP2 = false>
; __device__ __forceinline__ void gemm_phase(PG8_LAS unsigned char* lds, const Gemm g, const Sched& S, const Epi& E) {
;     ...
;             PG8_WAIT_V(8); PG8_WAIT_L(0); PG8_BAR; PG8_MMA(0, 0, At, B0); PG8_MMA(0, 1, At, B1); PG8_BAR; PG8_SCHED;
	s_barrier

; #define PG8_MMA(ai, bj, At, Bt) do { __builtin_amdgcn_s_setprio(1); _Pragma("unroll") for (int m = 0; m < 4; ++m) _Pragma("unroll") for (int n = 0; n < 2; ++n) _Pragma("unroll") for (int k = 0; k < 2; ++k) \
;         acc[ai][bj][m][n] = __builtin_amdgcn_mfma_f32_16x16x32_bf16(Bt[n][k], At[m][k], acc[ai][bj][m][n], 0, 0, 0); __builtin_amdgcn_s_setprio(0); } while (0)
; #define PG8_WAIT_V(n) asm volatile("s_waitcnt vmcnt(" #n ")" ::: "memory")
; #define PG8_WAIT_L(n) asm volatile("s_waitcnt lgkmcnt(" #n ")" ::: "memory")
; #define PG8_BAR __builtin_amdgcn_s_barrier()
; #define PG8_SCHED __builtin_amdgcn_sched_barrier(0)
; template <class Epi, class Sched, bool ALIGN_EPI = false, bool SP2 = false>
; __device__ __forceinline__ void gemm_phase(PG8_LAS unsigned char* lds, const Gemm g, const Sched& S, const Epi& E) {
;     ...
;             PG8_WAIT_V(8); PG8_WAIT_L(0); PG8_BAR; PG8_MMA(0, 0, At, B0); PG8_MMA(0, 1, At, B1); PG8_BAR; PG8_SCHED;
	v_mfma_f32_16x16x32_bf16 v[140:143], v[64:67], v[176:179], v[140:143]
	v_mfma_f32_16x16x32_bf16 v[136:139], v[72:75], v[176:179], v[136:139]
	v_mfma_f32_16x16x32_bf16 v[124:127], v[64:67], v[184:187], v[124:127]
	v_mfma_f32_16x16x32_bf16 v[120:123], v[72:75], v[184:187], v[120:123]
	v_mfma_f32_16x16x32_bf16 v[108:111], v[64:67], v[192:195], v[108:111]
	v_mfma_f32_16x16x32_bf16 v[104:107], v[72:75], v[192:195], v[104:107]
	v_mfma_f32_16x16x32_bf16 v[92:95], v[64:67], v[200:203], v[92:95]
	v_mfma_f32_16x16x32_bf16 v[88:91], v[72:75], v[200:203], v[88:91]
	v_mfma_f32_16x16x32_bf16 v[140:143], v[68:71], v[180:183], v[140:143]
	v_mfma_f32_16x16x32_bf16 v[136:139], v[76:79], v[180:183], v[136:139]
	v_mfma_f32_16x16x32_bf16 v[124:127], v[68:71], v[188:191], v[124:127]
	v_mfma_f32_16x16x32_bf16 v[120:123], v[76:79], v[188:191], v[120:123]
	v_mfma_f32_16x16x32_bf16 v[108:111], v[68:71], v[196:199], v[108:111]
	v_mfma_f32_16x16x32_bf16 v[104:107], v[76:79], v[196:199], v[104:107]
	v_mfma_f32_16x16x32_bf16 v[92:95], v[68:71], v[204:207], v[92:95]
	v_mfma_f32_16x16x32_bf16 v[88:91], v[76:79], v[204:207], v[88:91]


; #define PG8_MMA(ai, bj, At, Bt) do { __builtin_amdgcn_s_setprio(1); _Pragma("unroll") for (int m = 0; m < 4; ++m) _Pragma("unroll") for (int n = 0; n < 2; ++n) _Pragma("unroll") for (int k = 0; k < 2; ++k) \
;         acc[ai][bj][m][n] = __builtin_amdgcn_mfma_f32_16x16x32_bf16(Bt[n][k], At[m][k], acc[ai][bj][m][n], 0, 0, 0); __builtin_amdgcn_s_setprio(0); } while (0)
; #define PG8_WAIT_V(n) asm volatile("s_waitcnt vmcnt(" #n ")" ::: "memory")
; #define PG8_WAIT_L(n) asm volatile("s_waitcnt lgkmcnt(" #n ")" ::: "memory")
; #define PG8_BAR __builtin_amdgcn_s_barrier()
; #define PG8_SCHED __builtin_amdgcn_sched_barrier(0)
; template <class Epi, class Sched, bool ALIGN_EPI = false, bool SP2 = false>
; __device__ __forceinline__ void gemm_phase(PG8_LAS unsigned char* lds, const Gemm g, const Sched& S, const Epi& E) {
;     ...
;             PG8_WAIT_V(8); PG8_WAIT_L(0); PG8_BAR; PG8_MMA(0, 0, At, B0); PG8_MMA(0, 1, At, B1); PG8_BAR; PG8_SCHED;
	v_mfma_f32_16x16x32_bf16 v[132:135], v[144:147], v[176:179], v[132:135]
	v_mfma_f32_16x16x32_bf16 v[128:131], v[152:155], v[176:179], v[128:131]
	v_mfma_f32_16x16x32_bf16 v[116:119], v[144:147], v[184:187], v[116:119]
	v_mfma_f32_16x16x32_bf16 v[112:115], v[152:155], v[184:187], v[112:115]
	v_mfma_f32_16x16x32_bf16 v[100:103], v[144:147], v[192:195], v[100:103]
	v_mfma_f32_16x16x32_bf16 v[96:99], v[152:155], v[192:195], v[96:99]
	v_mfma_f32_16x16x32_bf16 v[84:87], v[144:147], v[200:203], v[84:87]
	v_mfma_f32_16x16x32_bf16 v[80:83], v[152:155], v[200:203], v[80:83]
	v_mfma_f32_16x16x32_bf16 v[132:135], v[148:151], v[180:183], v[132:135]
	v_mfma_f32_16x16x32_bf16 v[128:131], v[156:159], v[180:183], v[128:131]
	v_mfma_f32_16x16x32_bf16 v[116:119], v[148:151], v[188:191], v[116:119]
	v_mfma_f32_16x16x32_bf16 v[112:115], v[156:159], v[188:191], v[112:115]
	v_mfma_f32_16x16x32_bf16 v[100:103], v[148:151], v[196:199], v[100:103]
	v_mfma_f32_16x16x32_bf16 v[96:99], v[156:159], v[196:199], v[96:99]
	v_mfma_f32_16x16x32_bf16 v[84:87], v[148:151], v[204:207], v[84:87]
	v_mfma_f32_16x16x32_bf16 v[80:83], v[156:159], v[204:207], v[80:83]

; #define PG8_STAGE(bufoff, gbase, voff) do { _Pragma("unroll") for (int _i = 0; _i < 2; ++_i) \
;         __builtin_amdgcn_global_load_lds((const unsigned*)((const char*)(gbase) + (voff)[_i]), (PG8_LAS unsigned*)(lds + (bufoff) + ldsw + _i * 8192), 16, 0, 0); } while (0)
; #define PG8_LDA(dst, b, h) do { _Pragma("unroll") for (int m = 0; m < 4; ++m) _Pragma("unroll") for (int k = 0; k < 2; ++k) dst[m][k] = *(const PG8_LAS bf16x8*)(lds + PG8_SA(b, h) + aoff + m * 2048 + k * 1024); } while (0)
; #define PG8_MMA(ai, bj, At, Bt) do { __builtin_amdgcn_s_setprio(1); _Pragma("unroll") for (int m = 0; m < 4; ++m) _Pragma("unroll") for (int n = 0; n < 2; ++n) _Pragma("unroll") for (int k = 0; k < 2; ++k) \
;         acc[ai][bj][m][n] = __builtin_amdgcn_mfma_f32_16x16x32_bf16(Bt[n][k], At[m][k], acc[ai][bj][m][n], 0, 0, 0); __builtin_amdgcn_s_setprio(0); } while (0)
; #define PG8_WAIT_V(n) asm volatile("s_waitcnt vmcnt(" #n ")" ::: "memory")
; #define PG8_WAIT_L(n) asm volatile("s_waitcnt lgkmcnt(" #n ")" ::: "memory")
; #define PG8_BAR __builtin_amdgcn_s_barrier()
; #define PG8_SCHED __builtin_amdgcn_sched_barrier(0)
; template <class Epi, class Sched, bool ALIGN_EPI = false, bool SP2 = false>
; __device__ __forceinline__ void gemm_phase(PG8_LAS unsigned char* lds, const Gemm g, const Sched& S, const Epi& E) {
;     ...
;             PG8_WAIT_V(8); PG8_WAIT_L(0); PG8_BAR; PG8_MMA(0, 0, At, B0); PG8_MMA(0, 1, At, B1); PG8_BAR; PG8_SCHED;
;             PG8_LDA(At, 1, 1); PG8_STAGE(PG8_SB(1, 0), b3, voffB); PG8_STAGE(PG8_SB(1, 1), b3 + hstep, voffB); PG8_STAGE(PG8_SA(1, 0), a3, voffA);
	s_barrier
	s_add_i32 s62, s82, s64

; #define PG8_STAGE(bufoff, gbase, voff) do { _Pragma("unroll") for (int _i = 0; _i < 2; ++_i) \
;         __builtin_amdgcn_global_load_lds((const unsigned*)((const char*)(gbase) + (voff)[_i]), (PG8_LAS unsigned*)(lds + (bufoff) + ldsw + _i * 8192), 16, 0, 0); } while (0)
; #define PG8_LDA(dst, b, h) do { _Pragma("unroll") for (int m = 0; m < 4; ++m) _Pragma("unroll") for (int k = 0; k < 2; ++k) dst[m][k] = *(const PG8_LAS bf16x8*)(lds + PG8_SA(b, h) + aoff + m * 2048 + k * 1024); } while (0)
; template <class Epi, class Sched, bool ALIGN_EPI = false, bool SP2 = false>
; __device__ __forceinline__ void gemm_phase(PG8_LAS unsigned char* lds, const Gemm g, const Sched& S, const Epi& E) {
;     ...
;             PG8_LDA(At, 1, 1); PG8_STAGE(PG8_SB(1, 0), b3, voffB); PG8_STAGE(PG8_SB(1, 1), b3 + hstep, voffB); PG8_STAGE(PG8_SA(1, 0), a3, voffA);
	s_mov_b32 m0, s62
	ds_read_b128 v[176:179], v215 offset:49152
	ds_read_b128 v[180:183], v215 offset:50176
	ds_read_b128 v[184:187], v215 offset:51200
	ds_read_b128 v[188:191], v215 offset:52224
	ds_read_b128 v[192:195], v215 offset:53248
	ds_read_b128 v[196:199], v215 offset:54272
	ds_read_b128 v[200:203], v215 offset:55296
	ds_read_b128 v[204:207], v215 offset:56320
	global_load_lds_dwordx4 v250, s[96:97]
	s_add_i32 m0, s62, 0x2000
	s_add_u32 s60, s60, 0x80080

; #define PG8_STAGE(bufoff, gbase, voff) do { _Pragma("unroll") for (int _i = 0; _i < 2; ++_i) \
;         __builtin_amdgcn_global_load_lds((const unsigned*)((const char*)(gbase) + (voff)[_i]), (PG8_LAS unsigned*)(lds + (bufoff) + ldsw + _i * 8192), 16, 0, 0); } while (0)
; #define PG8_LDA(dst, b, h) do { _Pragma("unroll") for (int m = 0; m < 4; ++m) _Pragma("unroll") for (int k = 0; k < 2; ++k) dst[m][k] = *(const PG8_LAS bf16x8*)(lds + PG8_SA(b, h) + aoff + m * 2048 + k * 1024); } while (0)
; template <class Epi, class Sched, bool ALIGN_EPI = false, bool SP2 = false>
; __device__ __forceinline__ void gemm_phase(PG8_LAS unsigned char* lds, const Gemm g, const Sched& S, const Epi& E) {
;     ...
;             PG8_LDA(At, 1, 1); PG8_STAGE(PG8_SB(1, 0), b3, voffB); PG8_STAGE(PG8_SB(1, 1), b3 + hstep, voffB); PG8_STAGE(PG8_SA(1, 0), a3, voffA);
	s_addc_u32 s61, s61, 0
	s_add_i32 s62, s83, s64
	global_load_lds_dwordx4 v251, s[96:97]

; #define PG8_STAGE(bufoff, gbase, voff) do { _Pragma("unroll") for (int _i = 0; _i < 2; ++_i) \
;         __builtin_amdgcn_global_load_lds((const unsigned*)((const char*)(gbase) + (voff)[_i]), (PG8_LAS unsigned*)(lds + (bufoff) + ldsw + _i * 8192), 16, 0, 0); } while (0)
; #define PG8_LDA(dst, b, h) do { _Pragma("unroll") for (int m = 0; m < 4; ++m) _Pragma("unroll") for (int k = 0; k < 2; ++k) dst[m][k] = *(const PG8_LAS bf16x8*)(lds + PG8_SA(b, h) + aoff + m * 2048 + k * 1024); } while (0)
; template <class Epi, class Sched, bool ALIGN_EPI = false, bool SP2 = false>
; __device__ __forceinline__ void gemm_phase(PG8_LAS unsigned char* lds, const Gemm g, const Sched& S, const Epi& E) {
;     ...
;             PG8_LDA(At, 1, 1); PG8_STAGE(PG8_SB(1, 0), b3, voffB); PG8_STAGE(PG8_SB(1, 1), b3 + hstep, voffB); PG8_STAGE(PG8_SA(1, 0), a3, voffA);
	s_mov_b32 m0, s62
	s_nop 0
	global_load_lds_dwordx4 v162, s[60:61]

; #define PG8_STAGE(bufoff, gbase, voff) do { _Pragma("unroll") for (int _i = 0; _i < 2; ++_i) \
;         __builtin_amdgcn_global_load_lds((const unsigned*)((const char*)(gbase) + (voff)[_i]), (PG8_LAS unsigned*)(lds + (bufoff) + ldsw + _i * 8192), 16, 0, 0); } while (0)
; #define PG8_LDA(dst, b, h) do { _Pragma("unroll") for (int m = 0; m < 4; ++m) _Pragma("unroll") for (int k = 0; k < 2; ++k) dst[m][k] = *(const PG8_LAS bf16x8*)(lds + PG8_SA(b, h) + aoff + m * 2048 + k * 1024); } while (0)
; template <class Epi, class Sched, bool ALIGN_EPI = false, bool SP2 = false>
; __device__ __forceinline__ void gemm_phase(PG8_LAS unsigned char* lds, const Gemm g, const Sched& S, const Epi& E) {
;     ...
;             PG8_LDA(At, 1, 1); PG8_STAGE(PG8_SB(1, 0), b3, voffB); PG8_STAGE(PG8_SB(1, 1), b3 + hstep, voffB); PG8_STAGE(PG8_SA(1, 0), a3, voffA);
	s_add_i32 m0, s62, 0x2000
	s_nop 0
	global_load_lds_dwordx4 v166, s[60:61]

; #define PG8_STAGE(bufoff, gbase, voff) do { _Pragma("unroll") for (int _i = 0; _i < 2; ++_i) \
;         __builtin_amdgcn_global_load_lds((const unsigned*)((const char*)(gbase) + (voff)[_i]), (PG8_LAS unsigned*)(lds + (bufoff) + ldsw + _i * 8192), 16, 0, 0); } while (0)
; #define PG8_LDA(dst, b, h) do { _Pragma("unroll") for (int m = 0; m < 4; ++m) _Pragma("unroll") for (int k = 0; k < 2; ++k) dst[m][k] = *(const PG8_LAS bf16x8*)(lds + PG8_SA(b, h) + aoff + m * 2048 + k * 1024); } while (0)
; template <class Epi, class Sched, bool ALIGN_EPI = false, bool SP2 = false>
; __device__ __forceinline__ void gemm_phase(PG8_LAS unsigned char* lds, const Gemm g, const Sched& S, const Epi& E) {
;     ...
;             PG8_LDA(At, 1, 1); PG8_STAGE(PG8_SB(1, 0), b3, voffB); PG8_STAGE(PG8_SB(1, 1), b3 + hstep, voffB); PG8_STAGE(PG8_SA(1, 0), a3, voffA);
	s_mov_b32 m0, s70
	s_nop 0
	global_load_lds_dwordx4 v252, s[98:99]

; #define PG8_STAGE(bufoff, gbase, voff) do { _Pragma("unroll") for (int _i = 0; _i < 2; ++_i) \
;         __builtin_amdgcn_global_load_lds((const unsigned*)((const char*)(gbase) + (voff)[_i]), (PG8_LAS unsigned*)(lds + (bufoff) + ldsw + _i * 8192), 16, 0, 0); } while (0)
; #define PG8_LDA(dst, b, h) do { _Pragma("unroll") for (int m = 0; m < 4; ++m) _Pragma("unroll") for (int k = 0; k < 2; ++k) dst[m][k] = *(const PG8_LAS bf16x8*)(lds + PG8_SA(b, h) + aoff + m * 2048 + k * 1024); } while (0)
; #define PG8_MMA(ai, bj, At, Bt) do { __builtin_amdgcn_s_setprio(1); _Pragma("unroll") for (int m = 0; m < 4; ++m) _Pragma("unroll") for (int n = 0; n < 2; ++n) _Pragma("unroll") for (int k = 0; k < 2; ++k) \
;         acc[ai][bj][m][n] = __builtin_amdgcn_mfma_f32_16x16x32_bf16(Bt[n][k], At[m][k], acc[ai][bj][m][n], 0, 0, 0); __builtin_amdgcn_s_setprio(0); } while (0)
; #define PG8_WAIT_V(n) asm volatile("s_waitcnt vmcnt(" #n ")" ::: "memory")
; #define PG8_WAIT_L(n) asm volatile("s_waitcnt lgkmcnt(" #n ")" ::: "memory")
; #define PG8_BAR __builtin_amdgcn_s_barrier()
; #define PG8_SCHED __builtin_amdgcn_sched_barrier(0)
; template <class Epi, class Sched, bool ALIGN_EPI = false, bool SP2 = false>
; __device__ __forceinline__ void gemm_phase(PG8_LAS unsigned char* lds, const Gemm g, const Sched& S, const Epi& E) {
;     ...
;             PG8_LDA(At, 1, 1); PG8_STAGE(PG8_SB(1, 0), b3, voffB); PG8_STAGE(PG8_SB(1, 1), b3 + hstep, voffB); PG8_STAGE(PG8_SA(1, 0), a3, voffA);
;             PG8_WAIT_V(8); PG8_WAIT_L(0); PG8_BAR; PG8_MMA(1, 0, At, B0); PG8_MMA(1, 1, At, B1); PG8_BAR; PG8_SCHED;
	s_mov_b32 m0, s71
	s_nop 0
	global_load_lds_dwordx4 v253, s[98:99]
	s_waitcnt vmcnt(8) lgkmcnt(0)


; #define PG8_MMA(ai, bj, At, Bt) do { __builtin_amdgcn_s_setprio(1); _Pragma("unroll") for (int m = 0; m < 4; ++m) _Pragma("unroll") for (int n = 0; n < 2; ++n) _Pragma("unroll") for (int k = 0; k < 2; ++k) \
;         acc[ai][bj][m][n] = __builtin_amdgcn_mfma_f32_16x16x32_bf16(Bt[n][k], At[m][k], acc[ai][bj][m][n], 0, 0, 0); __builtin_amdgcn_s_setprio(0); } while (0)
; #define PG8_WAIT_V(n) asm volatile("s_waitcnt vmcnt(" #n ")" ::: "memory")
; #define PG8_WAIT_L(n) asm volatile("s_waitcnt lgkmcnt(" #n ")" ::: "memory")
; #define PG8_BAR __builtin_amdgcn_s_barrier()
; #define PG8_SCHED __builtin_amdgcn_sched_barrier(0)
; template <class Epi, class Sched, bool ALIGN_EPI = false, bool SP2 = false>
; __device__ __forceinline__ void gemm_phase(PG8_LAS unsigned char* lds, const Gemm g, const Sched& S, const Epi& E) {
;     ...
;             PG8_WAIT_V(8); PG8_WAIT_L(0); PG8_BAR; PG8_MMA(1, 0, At, B0); PG8_MMA(1, 1, At, B1); PG8_BAR; PG8_SCHED;
	s_barrier

; #define PG8_MMA(ai, bj, At, Bt) do { __builtin_amdgcn_s_setprio(1); _Pragma("unroll") for (int m = 0; m < 4; ++m) _Pragma("unroll") for (int n = 0; n < 2; ++n) _Pragma("unroll") for (int k = 0; k < 2; ++k) \
;         acc[ai][bj][m][n] = __builtin_amdgcn_mfma_f32_16x16x32_bf16(Bt[n][k], At[m][k], acc[ai][bj][m][n], 0, 0, 0); __builtin_amdgcn_s_setprio(0); } while (0)
; #define PG8_WAIT_V(n) asm volatile("s_waitcnt vmcnt(" #n ")" ::: "memory")
; #define PG8_WAIT_L(n) asm volatile("s_waitcnt lgkmcnt(" #n ")" ::: "memory")
; #define PG8_BAR __builtin_amdgcn_s_barrier()
; #define PG8_SCHED __builtin_amdgcn_sched_barrier(0)
; template <class Epi, class Sched, bool ALIGN_EPI = false, bool SP2 = false>
; __device__ __forceinline__ void gemm_phase(PG8_LAS unsigned char* lds, const Gemm g, const Sched& S, const Epi& E) {
;     ...
;             PG8_WAIT_V(8); PG8_WAIT_L(0); PG8_BAR; PG8_MMA(1, 0, At, B0); PG8_MMA(1, 1, At, B1); PG8_BAR; PG8_SCHED;
	v_mfma_f32_16x16x32_bf16 v[60:63], v[64:67], v[176:179], v[60:63]
	v_mfma_f32_16x16x32_bf16 v[56:59], v[72:75], v[176:179], v[56:59]
	v_mfma_f32_16x16x32_bf16 v[44:47], v[64:67], v[184:187], v[44:47]
	v_mfma_f32_16x16x32_bf16 v[40:43], v[72:75], v[184:187], v[40:43]
	v_mfma_f32_16x16x32_bf16 v[28:31], v[64:67], v[192:195], v[28:31]
	v_mfma_f32_16x16x32_bf16 v[24:27], v[72:75], v[192:195], v[24:27]
	v_mfma_f32_16x16x32_bf16 v[12:15], v[64:67], v[200:203], v[12:15]
	v_mfma_f32_16x16x32_bf16 v[8:11], v[72:75], v[200:203], v[8:11]
	v_mfma_f32_16x16x32_bf16 v[60:63], v[68:71], v[180:183], v[60:63]
	v_mfma_f32_16x16x32_bf16 v[56:59], v[76:79], v[180:183], v[56:59]
	v_mfma_f32_16x16x32_bf16 v[44:47], v[68:71], v[188:191], v[44:47]
	v_mfma_f32_16x16x32_bf16 v[40:43], v[76:79], v[188:191], v[40:43]
	v_mfma_f32_16x16x32_bf16 v[28:31], v[68:71], v[196:199], v[28:31]
	v_mfma_f32_16x16x32_bf16 v[24:27], v[76:79], v[196:199], v[24:27]
	v_mfma_f32_16x16x32_bf16 v[12:15], v[68:71], v[204:207], v[12:15]
	v_mfma_f32_16x16x32_bf16 v[8:11], v[76:79], v[204:207], v[8:11]


; #define PG8_MMA(ai, bj, At, Bt) do { __builtin_amdgcn_s_setprio(1); _Pragma("unroll") for (int m = 0; m < 4; ++m) _Pragma("unroll") for (int n = 0; n < 2; ++n) _Pragma("unroll") for (int k = 0; k < 2; ++k) \
;         acc[ai][bj][m][n] = __builtin_amdgcn_mfma_f32_16x16x32_bf16(Bt[n][k], At[m][k], acc[ai][bj][m][n], 0, 0, 0); __builtin_amdgcn_s_setprio(0); } while (0)
; #define PG8_WAIT_V(n) asm volatile("s_waitcnt vmcnt(" #n ")" ::: "memory")
; #define PG8_WAIT_L(n) asm volatile("s_waitcnt lgkmcnt(" #n ")" ::: "memory")
; #define PG8_BAR __builtin_amdgcn_s_barrier()
; #define PG8_SCHED __builtin_amdgcn_sched_barrier(0)
; template <class Epi, class Sched, bool ALIGN_EPI = false, bool SP2 = false>
; __device__ __forceinline__ void gemm_phase(PG8_LAS unsigned char* lds, const Gemm g, const Sched& S, const Epi& E) {
;     ...
;             PG8_WAIT_V(8); PG8_WAIT_L(0); PG8_BAR; PG8_MMA(1, 0, At, B0); PG8_MMA(1, 1, At, B1); PG8_BAR; PG8_SCHED;
	v_mfma_f32_16x16x32_bf16 v[52:55], v[144:147], v[176:179], v[52:55]
	v_mfma_f32_16x16x32_bf16 v[48:51], v[152:155], v[176:179], v[48:51]
	v_mfma_f32_16x16x32_bf16 v[36:39], v[144:147], v[184:187], v[36:39]
	v_mfma_f32_16x16x32_bf16 v[32:35], v[152:155], v[184:187], v[32:35]
	v_mfma_f32_16x16x32_bf16 v[20:23], v[144:147], v[192:195], v[20:23]
	v_mfma_f32_16x16x32_bf16 v[16:19], v[152:155], v[192:195], v[16:19]
	v_mfma_f32_16x16x32_bf16 v[4:7], v[144:147], v[200:203], v[4:7]
	v_mfma_f32_16x16x32_bf16 v[0:3], v[152:155], v[200:203], v[0:3]
	v_mfma_f32_16x16x32_bf16 v[52:55], v[148:151], v[180:183], v[52:55]
	v_mfma_f32_16x16x32_bf16 v[48:51], v[156:159], v[180:183], v[48:51]
	v_mfma_f32_16x16x32_bf16 v[36:39], v[148:151], v[188:191], v[36:39]
	v_mfma_f32_16x16x32_bf16 v[32:35], v[156:159], v[188:191], v[32:35]
	v_mfma_f32_16x16x32_bf16 v[20:23], v[148:151], v[196:199], v[20:23]
	v_mfma_f32_16x16x32_bf16 v[16:19], v[156:159], v[196:199], v[16:19]
	v_mfma_f32_16x16x32_bf16 v[4:7], v[148:151], v[204:207], v[4:7]
	v_mfma_f32_16x16x32_bf16 v[0:3], v[156:159], v[204:207], v[0:3]

; #define PG8_STAGE(bufoff, gbase, voff) do { _Pragma("unroll") for (int _i = 0; _i < 2; ++_i) \
;         __builtin_amdgcn_global_load_lds((const unsigned*)((const char*)(gbase) + (voff)[_i]), (PG8_LAS unsigned*)(lds + (bufoff) + ldsw + _i * 8192), 16, 0, 0); } while (0)
; #define PG8_LDA(dst, b, h) do { _Pragma("unroll") for (int m = 0; m < 4; ++m) _Pragma("unroll") for (int k = 0; k < 2; ++k) dst[m][k] = *(const PG8_LAS bf16x8*)(lds + PG8_SA(b, h) + aoff + m * 2048 + k * 1024); } while (0)
; #define PG8_WAIT_V(n) asm volatile("s_waitcnt vmcnt(" #n ")" ::: "memory")
; #define PG8_WAIT_L(n) asm volatile("s_waitcnt lgkmcnt(" #n ")" ::: "memory")
; template <class Epi, class Sched, bool ALIGN_EPI = false, bool SP2 = false>
; __device__ __forceinline__ void gemm_phase(PG8_LAS unsigned char* lds, const Gemm g, const Sched& S, const Epi& E) {
;     ...
;         for (int t = 0; t < nt; t += 2) {
;             const bool last = (t == nt - 2);
;             const char* a1 = cA + (size_t)(t + 1) * kstep;
;             const char* a2 = last ? nA : cA + (size_t)(t + 2) * kstep; const char* b2 = last ? nB : cB + (size_t)(t + 2) * kstep;
;             const char* a3 = a2 + kstep; const char* b3 = b2 + kstep;
;             if (last && has_next) S.a_ready(nxt);
;             if constexpr (SP2) {
;             PG8_LDB(B0, 0, 0); PG8_LDB(B1, 0, 1); PG8_SCHED; PG8_LDA(At, 0, 0); PG8_STAGE(PG8_SA(1, 1), a1 + hstep, voffA);
;             PG8_WAIT_V(8); PG8_WAIT_L(0); PG8_BAR; PG8_MMA(0, 0, At, B0); PG8_MMA(0, 1, At, B1); PG8_BAR; PG8_SCHED;
;             PG8_LDA(At, 0, 1); PG8_STAGE(PG8_SB(0, 0), b2, voffB); PG8_STAGE(PG8_SB(0, 1), b2 + hstep, voffB); PG8_STAGE(PG8_SA(0, 0), a2, voffA);
;             PG8_WAIT_V(8); PG8_WAIT_L(0); PG8_BAR; PG8_MMA(1, 0, At, B0); PG8_MMA(1, 1, At, B1); PG8_BAR; PG8_SCHED;
;             PG8_LDB(B0, 1, 0); PG8_LDB(B1, 1, 1); PG8_SCHED; PG8_LDA(At, 1, 0); PG8_STAGE(PG8_SA(0, 1), a2 + hstep, voffA);
;             PG8_WAIT_V(8); PG8_WAIT_L(0); PG8_BAR; PG8_MMA(0, 0, At, B0); PG8_MMA(0, 1, At, B1); PG8_BAR; PG8_SCHED;
;             PG8_LDA(At, 1, 1); PG8_STAGE(PG8_SB(1, 0), b3, voffB); PG8_STAGE(PG8_SB(1, 1), b3 + hstep, voffB); PG8_STAGE(PG8_SA(1, 0), a3, voffA);
;             PG8_WAIT_V(8); PG8_WAIT_L(0); PG8_BAR; PG8_MMA(1, 0, At, B0); PG8_MMA(1, 1, At, B1); PG8_BAR; PG8_SCHED;
;     ...
;         if constexpr (ALIGN_EPI) { if (wr == 0) PG8_BAR; }
	s_barrier
	s_add_i32 s81, s81, 2
	s_add_u32 s58, s58, 0x100
	s_addc_u32 s59, s59, 0
	s_add_u32 s79, s79, 0x100
	s_addc_u32 s80, s80, 0
	s_cmp_gt_u32 s81, 29
	s_cbranch_scc0 .LBB0_939
	s_and_b64 vcc, exec, s[42:43]
	s_cbranch_vccz .LBB0_942
	s_barrier

; #define PG8_STAGE(bufoff, gbase, voff) do { _Pragma("unroll") for (int _i = 0; _i < 2; ++_i) \
;         __builtin_amdgcn_global_load_lds((const unsigned*)((const char*)(gbase) + (voff)[_i]), (PG8_LAS unsigned*)(lds + (bufoff) + ldsw + _i * 8192), 16, 0, 0); } while (0)
; #define PG8_LDA(dst, b, h) do { _Pragma("unroll") for (int m = 0; m < 4; ++m) _Pragma("unroll") for (int k = 0; k < 2; ++k) dst[m][k] = *(const PG8_LAS bf16x8*)(lds + PG8_SA(b, h) + aoff + m * 2048 + k * 1024); } while (0)
; #define PG8_LDB(dst, b, h) do { _Pragma("unroll") for (int n = 0; n < 2; ++n) _Pragma("unroll") for (int k = 0; k < 2; ++k) dst[n][k] = *(const PG8_LAS bf16x8*)(lds + PG8_SB(b, h) + boff + n * 2048 + k * 1024); } while (0)
; #define PG8_SCHED __builtin_amdgcn_sched_barrier(0)
; template <class Epi, class Sched, bool ALIGN_EPI = false, bool SP2 = false>
; __device__ __forceinline__ void gemm_phase(PG8_LAS unsigned char* lds, const Gemm g, const Sched& S, const Epi& E) {
;     ...
;             const char* a1 = cA + (size_t)(t + 1) * kstep;
;             const char* a2 = last ? nA : cA + (size_t)(t + 2) * kstep; const char* b2 = last ? nB : cB + (size_t)(t + 2) * kstep;
;             const char* a3 = a2 + kstep; const char* b3 = b2 + kstep;
;             if (last && has_next) S.a_ready(nxt);
;             if constexpr (SP2) {
;             PG8_LDB(B0, 0, 0); PG8_LDB(B1, 0, 1); PG8_SCHED; PG8_LDA(At, 0, 0); PG8_STAGE(PG8_SA(1, 1), a1 + hstep, voffA);
.LBB0_1034:
	ds_read_b128 v[128:131], v201
	ds_read_b128 v[132:135], v201 offset:1024
	ds_read_b128 v[136:139], v201 offset:2048
	ds_read_b128 v[140:143], v201 offset:3072
	ds_read_b128 v[144:147], v205
	ds_read_b128 v[148:151], v205 offset:1024
	ds_read_b128 v[152:155], v205 offset:2048
	ds_read_b128 v[156:159], v205 offset:3072
	s_add_u32 s12, s10, 0xfff80080
	s_addc_u32 s13, s11, -1
	s_cmp_eq_u32 s83, 28
	s_cselect_b32 s59, s53, s13
	s_cselect_b32 s58, s79, s12
	s_cselect_b32 s13, s51, s82
	s_cselect_b32 s12, s80, s81

; #define PG8_STAGE(bufoff, gbase, voff) do { _Pragma("unroll") for (int _i = 0; _i < 2; ++_i) \
;         __builtin_amdgcn_global_load_lds((const unsigned*)((const char*)(gbase) + (voff)[_i]), (PG8_LAS unsigned*)(lds + (bufoff) + ldsw + _i * 8192), 16, 0, 0); } while (0)
; #define PG8_LDA(dst, b, h) do { _Pragma("unroll") for (int m = 0; m < 4; ++m) _Pragma("unroll") for (int k = 0; k < 2; ++k) dst[m][k] = *(const PG8_LAS bf16x8*)(lds + PG8_SA(b, h) + aoff + m * 2048 + k * 1024); } while (0)
; #define PG8_LDB(dst, b, h) do { _Pragma("unroll") for (int n = 0; n < 2; ++n) _Pragma("unroll") for (int k = 0; k < 2; ++k) dst[n][k] = *(const PG8_LAS bf16x8*)(lds + PG8_SB(b, h) + boff + n * 2048 + k * 1024); } while (0)
; #define PG8_SCHED __builtin_amdgcn_sched_barrier(0)
; template <class Epi, class Sched, bool ALIGN_EPI = false, bool SP2 = false>
; __device__ __forceinline__ void gemm_phase(PG8_LAS unsigned char* lds, const Gemm g, const Sched& S, const Epi& E) {
;     ...
;             PG8_LDB(B0, 0, 0); PG8_LDB(B1, 0, 1); PG8_SCHED; PG8_LDA(At, 0, 0); PG8_STAGE(PG8_SA(1, 1), a1 + hstep, voffA);
	s_add_i32 m0, s63, 0xc000
	ds_read_b128 v[176:179], v207
	ds_read_b128 v[184:187], v207 offset:1024
	ds_read_b128 v[190:193], v207 offset:2048
	ds_read_b128 v[210:213], v207 offset:3072
	ds_read_b128 v[214:217], v207 offset:4096
	ds_read_b128 v[218:221], v207 offset:5120
	ds_read_b128 v[222:225], v207 offset:6144
	ds_read_b128 v[226:229], v207 offset:7168
	global_load_lds_dwordx4 v168, s[10:11]

; #define PG8_STAGE(bufoff, gbase, voff) do { _Pragma("unroll") for (int _i = 0; _i < 2; ++_i) \
;         __builtin_amdgcn_global_load_lds((const unsigned*)((const char*)(gbase) + (voff)[_i]), (PG8_LAS unsigned*)(lds + (bufoff) + ldsw + _i * 8192), 16, 0, 0); } while (0)
; #define PG8_LDA(dst, b, h) do { _Pragma("unroll") for (int m = 0; m < 4; ++m) _Pragma("unroll") for (int k = 0; k < 2; ++k) dst[m][k] = *(const PG8_LAS bf16x8*)(lds + PG8_SA(b, h) + aoff + m * 2048 + k * 1024); } while (0)
; #define PG8_LDB(dst, b, h) do { _Pragma("unroll") for (int n = 0; n < 2; ++n) _Pragma("unroll") for (int k = 0; k < 2; ++k) dst[n][k] = *(const PG8_LAS bf16x8*)(lds + PG8_SB(b, h) + boff + n * 2048 + k * 1024); } while (0)
; #define PG8_MMA(ai, bj, At, Bt) do { __builtin_amdgcn_s_setprio(1); _Pragma("unroll") for (int m = 0; m < 4; ++m) _Pragma("unroll") for (int n = 0; n < 2; ++n) _Pragma("unroll") for (int k = 0; k < 2; ++k) \
;         acc[ai][bj][m][n] = __builtin_amdgcn_mfma_f32_16x16x32_bf16(Bt[n][k], At[m][k], acc[ai][bj][m][n], 0, 0, 0); __builtin_amdgcn_s_setprio(0); } while (0)
; #define PG8_WAIT_V(n) asm volatile("s_waitcnt vmcnt(" #n ")" ::: "memory")
; #define PG8_WAIT_L(n) asm volatile("s_waitcnt lgkmcnt(" #n ")" ::: "memory")
; #define PG8_BAR __builtin_amdgcn_s_barrier()
; #define PG8_SCHED __builtin_amdgcn_sched_barrier(0)
; template <class Epi, class Sched, bool ALIGN_EPI = false, bool SP2 = false>
; __device__ __forceinline__ void gemm_phase(PG8_LAS unsigned char* lds, const Gemm g, const Sched& S, const Epi& E) {
;     ...
;             PG8_LDB(B0, 0, 0); PG8_LDB(B1, 0, 1); PG8_SCHED; PG8_LDA(At, 0, 0); PG8_STAGE(PG8_SA(1, 1), a1 + hstep, voffA);
;             PG8_WAIT_V(8); PG8_WAIT_L(0); PG8_BAR; PG8_MMA(0, 0, At, B0); PG8_MMA(0, 1, At, B1); PG8_BAR; PG8_SCHED;
	s_add_i32 m0, s63, 0xe000
	s_nop 0
	global_load_lds_dwordx4 v170, s[10:11]
	s_waitcnt vmcnt(8) lgkmcnt(0)


; #define PG8_MMA(ai, bj, At, Bt) do { __builtin_amdgcn_s_setprio(1); _Pragma("unroll") for (int m = 0; m < 4; ++m) _Pragma("unroll") for (int n = 0; n < 2; ++n) _Pragma("unroll") for (int k = 0; k < 2; ++k) \
;         acc[ai][bj][m][n] = __builtin_amdgcn_mfma_f32_16x16x32_bf16(Bt[n][k], At[m][k], acc[ai][bj][m][n], 0, 0, 0); __builtin_amdgcn_s_setprio(0); } while (0)
; #define PG8_WAIT_V(n) asm volatile("s_waitcnt vmcnt(" #n ")" ::: "memory")
; #define PG8_WAIT_L(n) asm volatile("s_waitcnt lgkmcnt(" #n ")" ::: "memory")
; #define PG8_BAR __builtin_amdgcn_s_barrier()
; #define PG8_SCHED __builtin_amdgcn_sched_barrier(0)
; template <class Epi, class Sched, bool ALIGN_EPI = false, bool SP2 = false>
; __device__ __forceinline__ void gemm_phase(PG8_LAS unsigned char* lds, const Gemm g, const Sched& S, const Epi& E) {
;     ...
;             PG8_WAIT_V(8); PG8_WAIT_L(0); PG8_BAR; PG8_MMA(0, 0, At, B0); PG8_MMA(0, 1, At, B1); PG8_BAR; PG8_SCHED;
	s_barrier

; #define PG8_MMA(ai, bj, At, Bt) do { __builtin_amdgcn_s_setprio(1); _Pragma("unroll") for (int m = 0; m < 4; ++m) _Pragma("unroll") for (int n = 0; n < 2; ++n) _Pragma("unroll") for (int k = 0; k < 2; ++k) \
;         acc[ai][bj][m][n] = __builtin_amdgcn_mfma_f32_16x16x32_bf16(Bt[n][k], At[m][k], acc[ai][bj][m][n], 0, 0, 0); __builtin_amdgcn_s_setprio(0); } while (0)
; #define PG8_WAIT_V(n) asm volatile("s_waitcnt vmcnt(" #n ")" ::: "memory")
; #define PG8_WAIT_L(n) asm volatile("s_waitcnt lgkmcnt(" #n ")" ::: "memory")
; #define PG8_BAR __builtin_amdgcn_s_barrier()
; #define PG8_SCHED __builtin_amdgcn_sched_barrier(0)
; template <class Epi, class Sched, bool ALIGN_EPI = false, bool SP2 = false>
; __device__ __forceinline__ void gemm_phase(PG8_LAS unsigned char* lds, const Gemm g, const Sched& S, const Epi& E) {
;     ...
;             PG8_WAIT_V(8); PG8_WAIT_L(0); PG8_BAR; PG8_MMA(0, 0, At, B0); PG8_MMA(0, 1, At, B1); PG8_BAR; PG8_SCHED;
	v_mfma_f32_16x16x32_bf16 v[124:127], v[128:131], v[176:179], v[124:127]
	v_mfma_f32_16x16x32_bf16 v[120:123], v[136:139], v[176:179], v[120:123]
	v_mfma_f32_16x16x32_bf16 v[108:111], v[128:131], v[190:193], v[108:111]
	v_mfma_f32_16x16x32_bf16 v[104:107], v[136:139], v[190:193], v[104:107]
	v_mfma_f32_16x16x32_bf16 v[92:95], v[128:131], v[214:217], v[92:95]
	v_mfma_f32_16x16x32_bf16 v[88:91], v[136:139], v[214:217], v[88:91]
	v_mfma_f32_16x16x32_bf16 v[76:79], v[128:131], v[222:225], v[76:79]
	v_mfma_f32_16x16x32_bf16 v[72:75], v[136:139], v[222:225], v[72:75]
	v_mfma_f32_16x16x32_bf16 v[124:127], v[132:135], v[184:187], v[124:127]
	v_mfma_f32_16x16x32_bf16 v[120:123], v[140:143], v[184:187], v[120:123]
	v_mfma_f32_16x16x32_bf16 v[108:111], v[132:135], v[210:213], v[108:111]
	v_mfma_f32_16x16x32_bf16 v[104:107], v[140:143], v[210:213], v[104:107]
	v_mfma_f32_16x16x32_bf16 v[92:95], v[132:135], v[218:221], v[92:95]
	v_mfma_f32_16x16x32_bf16 v[88:91], v[140:143], v[218:221], v[88:91]
	v_mfma_f32_16x16x32_bf16 v[76:79], v[132:135], v[226:229], v[76:79]
	v_mfma_f32_16x16x32_bf16 v[72:75], v[140:143], v[226:229], v[72:75]


; #define PG8_MMA(ai, bj, At, Bt) do { __builtin_amdgcn_s_setprio(1); _Pragma("unroll") for (int m = 0; m < 4; ++m) _Pragma("unroll") for (int n = 0; n < 2; ++n) _Pragma("unroll") for (int k = 0; k < 2; ++k) \
;         acc[ai][bj][m][n] = __builtin_amdgcn_mfma_f32_16x16x32_bf16(Bt[n][k], At[m][k], acc[ai][bj][m][n], 0, 0, 0); __builtin_amdgcn_s_setprio(0); } while (0)
; #define PG8_WAIT_V(n) asm volatile("s_waitcnt vmcnt(" #n ")" ::: "memory")
; #define PG8_WAIT_L(n) asm volatile("s_waitcnt lgkmcnt(" #n ")" ::: "memory")
; #define PG8_BAR __builtin_amdgcn_s_barrier()
; #define PG8_SCHED __builtin_amdgcn_sched_barrier(0)
; template <class Epi, class Sched, bool ALIGN_EPI = false, bool SP2 = false>
; __device__ __forceinline__ void gemm_phase(PG8_LAS unsigned char* lds, const Gemm g, const Sched& S, const Epi& E) {
;     ...
;             PG8_WAIT_V(8); PG8_WAIT_L(0); PG8_BAR; PG8_MMA(0, 0, At, B0); PG8_MMA(0, 1, At, B1); PG8_BAR; PG8_SCHED;
	v_mfma_f32_16x16x32_bf16 v[116:119], v[144:147], v[176:179], v[116:119]
	v_mfma_f32_16x16x32_bf16 v[112:115], v[152:155], v[176:179], v[112:115]
	v_mfma_f32_16x16x32_bf16 v[100:103], v[144:147], v[190:193], v[100:103]
	v_mfma_f32_16x16x32_bf16 v[96:99], v[152:155], v[190:193], v[96:99]
	v_mfma_f32_16x16x32_bf16 v[84:87], v[144:147], v[214:217], v[84:87]
	v_mfma_f32_16x16x32_bf16 v[80:83], v[152:155], v[214:217], v[80:83]
	v_mfma_f32_16x16x32_bf16 v[68:71], v[144:147], v[222:225], v[68:71]
	v_mfma_f32_16x16x32_bf16 v[64:67], v[152:155], v[222:225], v[64:67]
	v_mfma_f32_16x16x32_bf16 v[116:119], v[148:151], v[184:187], v[116:119]
	v_mfma_f32_16x16x32_bf16 v[112:115], v[156:159], v[184:187], v[112:115]
	v_mfma_f32_16x16x32_bf16 v[100:103], v[148:151], v[210:213], v[100:103]
	v_mfma_f32_16x16x32_bf16 v[96:99], v[156:159], v[210:213], v[96:99]
	v_mfma_f32_16x16x32_bf16 v[84:87], v[148:151], v[218:221], v[84:87]
	v_mfma_f32_16x16x32_bf16 v[80:83], v[156:159], v[218:221], v[80:83]
	v_mfma_f32_16x16x32_bf16 v[68:71], v[148:151], v[226:229], v[68:71]
	v_mfma_f32_16x16x32_bf16 v[64:67], v[156:159], v[226:229], v[64:67]

; #define PG8_STAGE(bufoff, gbase, voff) do { _Pragma("unroll") for (int _i = 0; _i < 2; ++_i) \
;         __builtin_amdgcn_global_load_lds((const unsigned*)((const char*)(gbase) + (voff)[_i]), (PG8_LAS unsigned*)(lds + (bufoff) + ldsw + _i * 8192), 16, 0, 0); } while (0)
; #define PG8_LDA(dst, b, h) do { _Pragma("unroll") for (int m = 0; m < 4; ++m) _Pragma("unroll") for (int k = 0; k < 2; ++k) dst[m][k] = *(const PG8_LAS bf16x8*)(lds + PG8_SA(b, h) + aoff + m * 2048 + k * 1024); } while (0)
; #define PG8_MMA(ai, bj, At, Bt) do { __builtin_amdgcn_s_setprio(1); _Pragma("unroll") for (int m = 0; m < 4; ++m) _Pragma("unroll") for (int n = 0; n < 2; ++n) _Pragma("unroll") for (int k = 0; k < 2; ++k) \
;         acc[ai][bj][m][n] = __builtin_amdgcn_mfma_f32_16x16x32_bf16(Bt[n][k], At[m][k], acc[ai][bj][m][n], 0, 0, 0); __builtin_amdgcn_s_setprio(0); } while (0)
; #define PG8_WAIT_V(n) asm volatile("s_waitcnt vmcnt(" #n ")" ::: "memory")
; #define PG8_WAIT_L(n) asm volatile("s_waitcnt lgkmcnt(" #n ")" ::: "memory")
; #define PG8_BAR __builtin_amdgcn_s_barrier()
; #define PG8_SCHED __builtin_amdgcn_sched_barrier(0)
; template <class Epi, class Sched, bool ALIGN_EPI = false, bool SP2 = false>
; __device__ __forceinline__ void gemm_phase(PG8_LAS unsigned char* lds, const Gemm g, const Sched& S, const Epi& E) {
;     ...
;             PG8_WAIT_V(8); PG8_WAIT_L(0); PG8_BAR; PG8_MMA(0, 0, At, B0); PG8_MMA(0, 1, At, B1); PG8_BAR; PG8_SCHED;
;             PG8_LDA(At, 0, 1); PG8_STAGE(PG8_SB(0, 0), b2, voffB); PG8_STAGE(PG8_SB(0, 1), b2 + hstep, voffB); PG8_STAGE(PG8_SA(0, 0), a2, voffA);
	s_barrier
	s_add_i32 s84, s73, s62
	s_mov_b64 s[96:97], s[12:13]

; #define PG8_STAGE(bufoff, gbase, voff) do { _Pragma("unroll") for (int _i = 0; _i < 2; ++_i) \
;         __builtin_amdgcn_global_load_lds((const unsigned*)((const char*)(gbase) + (voff)[_i]), (PG8_LAS unsigned*)(lds + (bufoff) + ldsw + _i * 8192), 16, 0, 0); } while (0)
; #define PG8_LDA(dst, b, h) do { _Pragma("unroll") for (int m = 0; m < 4; ++m) _Pragma("unroll") for (int k = 0; k < 2; ++k) dst[m][k] = *(const PG8_LAS bf16x8*)(lds + PG8_SA(b, h) + aoff + m * 2048 + k * 1024); } while (0)
; template <class Epi, class Sched, bool ALIGN_EPI = false, bool SP2 = false>
; __device__ __forceinline__ void gemm_phase(PG8_LAS unsigned char* lds, const Gemm g, const Sched& S, const Epi& E) {
;     ...
;             PG8_LDA(At, 0, 1); PG8_STAGE(PG8_SB(0, 0), b2, voffB); PG8_STAGE(PG8_SB(0, 1), b2 + hstep, voffB); PG8_STAGE(PG8_SA(0, 0), a2, voffA);
	s_mov_b32 m0, s84
	ds_read_b128 v[176:179], v207 offset:16384
	ds_read_b128 v[184:187], v207 offset:17408
	ds_read_b128 v[190:193], v207 offset:18432
	ds_read_b128 v[210:213], v207 offset:19456
	ds_read_b128 v[214:217], v207 offset:20480
	ds_read_b128 v[218:221], v207 offset:21504
	ds_read_b128 v[222:225], v207 offset:22528
	ds_read_b128 v[226:229], v207 offset:23552
	global_load_lds_dwordx4 v162, s[12:13]
	s_add_i32 m0, s84, 0x2000
	s_add_u32 s84, s12, 0x80000

; #define PG8_STAGE(bufoff, gbase, voff) do { _Pragma("unroll") for (int _i = 0; _i < 2; ++_i) \
;         __builtin_amdgcn_global_load_lds((const unsigned*)((const char*)(gbase) + (voff)[_i]), (PG8_LAS unsigned*)(lds + (bufoff) + ldsw + _i * 8192), 16, 0, 0); } while (0)
; #define PG8_LDA(dst, b, h) do { _Pragma("unroll") for (int m = 0; m < 4; ++m) _Pragma("unroll") for (int k = 0; k < 2; ++k) dst[m][k] = *(const PG8_LAS bf16x8*)(lds + PG8_SA(b, h) + aoff + m * 2048 + k * 1024); } while (0)
; template <class Epi, class Sched, bool ALIGN_EPI = false, bool SP2 = false>
; __device__ __forceinline__ void gemm_phase(PG8_LAS unsigned char* lds, const Gemm g, const Sched& S, const Epi& E) {
;     ...
;             PG8_LDA(At, 0, 1); PG8_STAGE(PG8_SB(0, 0), b2, voffB); PG8_STAGE(PG8_SB(0, 1), b2 + hstep, voffB); PG8_STAGE(PG8_SA(0, 0), a2, voffA);
	s_addc_u32 s85, s13, 0
	s_add_i32 s86, s74, s62
	global_load_lds_dwordx4 v166, s[12:13]

; #define PG8_STAGE(bufoff, gbase, voff) do { _Pragma("unroll") for (int _i = 0; _i < 2; ++_i) \
;         __builtin_amdgcn_global_load_lds((const unsigned*)((const char*)(gbase) + (voff)[_i]), (PG8_LAS unsigned*)(lds + (bufoff) + ldsw + _i * 8192), 16, 0, 0); } while (0)
; #define PG8_LDA(dst, b, h) do { _Pragma("unroll") for (int m = 0; m < 4; ++m) _Pragma("unroll") for (int k = 0; k < 2; ++k) dst[m][k] = *(const PG8_LAS bf16x8*)(lds + PG8_SA(b, h) + aoff + m * 2048 + k * 1024); } while (0)
; template <class Epi, class Sched, bool ALIGN_EPI = false, bool SP2 = false>
; __device__ __forceinline__ void gemm_phase(PG8_LAS unsigned char* lds, const Gemm g, const Sched& S, const Epi& E) {
;     ...
;             PG8_LDA(At, 0, 1); PG8_STAGE(PG8_SB(0, 0), b2, voffB); PG8_STAGE(PG8_SB(0, 1), b2 + hstep, voffB); PG8_STAGE(PG8_SA(0, 0), a2, voffA);
	s_mov_b32 m0, s86
	s_nop 0
	global_load_lds_dwordx4 v162, s[84:85]

; #define PG8_STAGE(bufoff, gbase, voff) do { _Pragma("unroll") for (int _i = 0; _i < 2; ++_i) \
;         __builtin_amdgcn_global_load_lds((const unsigned*)((const char*)(gbase) + (voff)[_i]), (PG8_LAS unsigned*)(lds + (bufoff) + ldsw + _i * 8192), 16, 0, 0); } while (0)
; #define PG8_LDA(dst, b, h) do { _Pragma("unroll") for (int m = 0; m < 4; ++m) _Pragma("unroll") for (int k = 0; k < 2; ++k) dst[m][k] = *(const PG8_LAS bf16x8*)(lds + PG8_SA(b, h) + aoff + m * 2048 + k * 1024); } while (0)
; template <class Epi, class Sched, bool ALIGN_EPI = false, bool SP2 = false>
; __device__ __forceinline__ void gemm_phase(PG8_LAS unsigned char* lds, const Gemm g, const Sched& S, const Epi& E) {
;     ...
;             PG8_LDA(At, 0, 1); PG8_STAGE(PG8_SB(0, 0), b2, voffB); PG8_STAGE(PG8_SB(0, 1), b2 + hstep, voffB); PG8_STAGE(PG8_SA(0, 0), a2, voffA);
	s_add_i32 m0, s86, 0x2000
	s_nop 0
	global_load_lds_dwordx4 v166, s[84:85]
	s_mov_b64 s[98:99], s[58:59]

; #define PG8_STAGE(bufoff, gbase, voff) do { _Pragma("unroll") for (int _i = 0; _i < 2; ++_i) \
;         __builtin_amdgcn_global_load_lds((const unsigned*)((const char*)(gbase) + (voff)[_i]), (PG8_LAS unsigned*)(lds + (bufoff) + ldsw + _i * 8192), 16, 0, 0); } while (0)
; #define PG8_LDA(dst, b, h) do { _Pragma("unroll") for (int m = 0; m < 4; ++m) _Pragma("unroll") for (int k = 0; k < 2; ++k) dst[m][k] = *(const PG8_LAS bf16x8*)(lds + PG8_SA(b, h) + aoff + m * 2048 + k * 1024); } while (0)
; #define PG8_MMA(ai, bj, At, Bt) do { __builtin_amdgcn_s_setprio(1); _Pragma("unroll") for (int m = 0; m < 4; ++m) _Pragma("unroll") for (int n = 0; n < 2; ++n) _Pragma("unroll") for (int k = 0; k < 2; ++k) \
;         acc[ai][bj][m][n] = __builtin_amdgcn_mfma_f32_16x16x32_bf16(Bt[n][k], At[m][k], acc[ai][bj][m][n], 0, 0, 0); __builtin_amdgcn_s_setprio(0); } while (0)
; #define PG8_WAIT_V(n) asm volatile("s_waitcnt vmcnt(" #n ")" ::: "memory")
; #define PG8_WAIT_L(n) asm volatile("s_waitcnt lgkmcnt(" #n ")" ::: "memory")
; #define PG8_BAR __builtin_amdgcn_s_barrier()
; #define PG8_SCHED __builtin_amdgcn_sched_barrier(0)
; template <class Epi, class Sched, bool ALIGN_EPI = false, bool SP2 = false>
; __device__ __forceinline__ void gemm_phase(PG8_LAS unsigned char* lds, const Gemm g, const Sched& S, const Epi& E) {
;     ...
;             PG8_LDA(At, 0, 1); PG8_STAGE(PG8_SB(0, 0), b2, voffB); PG8_STAGE(PG8_SB(0, 1), b2 + hstep, voffB); PG8_STAGE(PG8_SA(0, 0), a2, voffA);
;             PG8_WAIT_V(8); PG8_WAIT_L(0); PG8_BAR; PG8_MMA(1, 0, At, B0); PG8_MMA(1, 1, At, B1); PG8_BAR; PG8_SCHED;
	s_mov_b32 m0, s63
	s_nop 0
	global_load_lds_dwordx4 v160, s[58:59]
	s_mov_b32 m0, s64
	s_nop 0
	global_load_lds_dwordx4 v164, s[58:59]
	s_waitcnt vmcnt(8) lgkmcnt(0)


; #define PG8_MMA(ai, bj, At, Bt) do { __builtin_amdgcn_s_setprio(1); _Pragma("unroll") for (int m = 0; m < 4; ++m) _Pragma("unroll") for (int n = 0; n < 2; ++n) _Pragma("unroll") for (int k = 0; k < 2; ++k) \
;         acc[ai][bj][m][n] = __builtin_amdgcn_mfma_f32_16x16x32_bf16(Bt[n][k], At[m][k], acc[ai][bj][m][n], 0, 0, 0); __builtin_amdgcn_s_setprio(0); } while (0)
; #define PG8_WAIT_V(n) asm volatile("s_waitcnt vmcnt(" #n ")" ::: "memory")
; #define PG8_WAIT_L(n) asm volatile("s_waitcnt lgkmcnt(" #n ")" ::: "memory")
; #define PG8_BAR __builtin_amdgcn_s_barrier()
; #define PG8_SCHED __builtin_amdgcn_sched_barrier(0)
; template <class Epi, class Sched, bool ALIGN_EPI = false, bool SP2 = false>
; __device__ __forceinline__ void gemm_phase(PG8_LAS unsigned char* lds, const Gemm g, const Sched& S, const Epi& E) {
;     ...
;             PG8_WAIT_V(8); PG8_WAIT_L(0); PG8_BAR; PG8_MMA(1, 0, At, B0); PG8_MMA(1, 1, At, B1); PG8_BAR; PG8_SCHED;
	s_barrier

; #define PG8_MMA(ai, bj, At, Bt) do { __builtin_amdgcn_s_setprio(1); _Pragma("unroll") for (int m = 0; m < 4; ++m) _Pragma("unroll") for (int n = 0; n < 2; ++n) _Pragma("unroll") for (int k = 0; k < 2; ++k) \
;         acc[ai][bj][m][n] = __builtin_amdgcn_mfma_f32_16x16x32_bf16(Bt[n][k], At[m][k], acc[ai][bj][m][n], 0, 0, 0); __builtin_amdgcn_s_setprio(0); } while (0)
; #define PG8_WAIT_V(n) asm volatile("s_waitcnt vmcnt(" #n ")" ::: "memory")
; #define PG8_WAIT_L(n) asm volatile("s_waitcnt lgkmcnt(" #n ")" ::: "memory")
; #define PG8_BAR __builtin_amdgcn_s_barrier()
; #define PG8_SCHED __builtin_amdgcn_sched_barrier(0)
; template <class Epi, class Sched, bool ALIGN_EPI = false, bool SP2 = false>
; __device__ __forceinline__ void gemm_phase(PG8_LAS unsigned char* lds, const Gemm g, const Sched& S, const Epi& E) {
;     ...
;             PG8_WAIT_V(8); PG8_WAIT_L(0); PG8_BAR; PG8_MMA(1, 0, At, B0); PG8_MMA(1, 1, At, B1); PG8_BAR; PG8_SCHED;
	v_mfma_f32_16x16x32_bf16 v[60:63], v[128:131], v[176:179], v[60:63]
	v_mfma_f32_16x16x32_bf16 v[56:59], v[136:139], v[176:179], v[56:59]
	v_mfma_f32_16x16x32_bf16 v[44:47], v[128:131], v[190:193], v[44:47]
	v_mfma_f32_16x16x32_bf16 v[40:43], v[136:139], v[190:193], v[40:43]
	v_mfma_f32_16x16x32_bf16 v[28:31], v[128:131], v[214:217], v[28:31]
	v_mfma_f32_16x16x32_bf16 v[24:27], v[136:139], v[214:217], v[24:27]
	v_mfma_f32_16x16x32_bf16 v[12:15], v[128:131], v[222:225], v[12:15]
	v_mfma_f32_16x16x32_bf16 v[8:11], v[136:139], v[222:225], v[8:11]
	v_mfma_f32_16x16x32_bf16 v[60:63], v[132:135], v[184:187], v[60:63]
	v_mfma_f32_16x16x32_bf16 v[56:59], v[140:143], v[184:187], v[56:59]
	v_mfma_f32_16x16x32_bf16 v[44:47], v[132:135], v[210:213], v[44:47]
	v_mfma_f32_16x16x32_bf16 v[40:43], v[140:143], v[210:213], v[40:43]
	v_mfma_f32_16x16x32_bf16 v[28:31], v[132:135], v[218:221], v[28:31]
	v_mfma_f32_16x16x32_bf16 v[24:27], v[140:143], v[218:221], v[24:27]
	v_mfma_f32_16x16x32_bf16 v[12:15], v[132:135], v[226:229], v[12:15]
	v_mfma_f32_16x16x32_bf16 v[8:11], v[140:143], v[226:229], v[8:11]


; #define PG8_MMA(ai, bj, At, Bt) do { __builtin_amdgcn_s_setprio(1); _Pragma("unroll") for (int m = 0; m < 4; ++m) _Pragma("unroll") for (int n = 0; n < 2; ++n) _Pragma("unroll") for (int k = 0; k < 2; ++k) \
;         acc[ai][bj][m][n] = __builtin_amdgcn_mfma_f32_16x16x32_bf16(Bt[n][k], At[m][k], acc[ai][bj][m][n], 0, 0, 0); __builtin_amdgcn_s_setprio(0); } while (0)
; #define PG8_WAIT_V(n) asm volatile("s_waitcnt vmcnt(" #n ")" ::: "memory")
; #define PG8_WAIT_L(n) asm volatile("s_waitcnt lgkmcnt(" #n ")" ::: "memory")
; #define PG8_BAR __builtin_amdgcn_s_barrier()
; #define PG8_SCHED __builtin_amdgcn_sched_barrier(0)
; template <class Epi, class Sched, bool ALIGN_EPI = false, bool SP2 = false>
; __device__ __forceinline__ void gemm_phase(PG8_LAS unsigned char* lds, const Gemm g, const Sched& S, const Epi& E) {
;     ...
;             PG8_WAIT_V(8); PG8_WAIT_L(0); PG8_BAR; PG8_MMA(1, 0, At, B0); PG8_MMA(1, 1, At, B1); PG8_BAR; PG8_SCHED;
	v_mfma_f32_16x16x32_bf16 v[52:55], v[144:147], v[176:179], v[52:55]
	v_mfma_f32_16x16x32_bf16 v[48:51], v[152:155], v[176:179], v[48:51]
	v_mfma_f32_16x16x32_bf16 v[36:39], v[144:147], v[190:193], v[36:39]
	v_mfma_f32_16x16x32_bf16 v[32:35], v[152:155], v[190:193], v[32:35]
	v_mfma_f32_16x16x32_bf16 v[20:23], v[144:147], v[214:217], v[20:23]
	v_mfma_f32_16x16x32_bf16 v[16:19], v[152:155], v[214:217], v[16:19]
	v_mfma_f32_16x16x32_bf16 v[4:7], v[144:147], v[222:225], v[4:7]
	v_mfma_f32_16x16x32_bf16 v[0:3], v[152:155], v[222:225], v[0:3]
	v_mfma_f32_16x16x32_bf16 v[52:55], v[148:151], v[184:187], v[52:55]
	v_mfma_f32_16x16x32_bf16 v[48:51], v[156:159], v[184:187], v[48:51]
	v_mfma_f32_16x16x32_bf16 v[36:39], v[148:151], v[210:213], v[36:39]
	v_mfma_f32_16x16x32_bf16 v[32:35], v[156:159], v[210:213], v[32:35]
	v_mfma_f32_16x16x32_bf16 v[20:23], v[148:151], v[218:221], v[20:23]
	v_mfma_f32_16x16x32_bf16 v[16:19], v[156:159], v[218:221], v[16:19]
	v_mfma_f32_16x16x32_bf16 v[4:7], v[148:151], v[226:229], v[4:7]
	v_mfma_f32_16x16x32_bf16 v[0:3], v[156:159], v[226:229], v[0:3]

; #define PG8_STAGE(bufoff, gbase, voff) do { _Pragma("unroll") for (int _i = 0; _i < 2; ++_i) \
;         __builtin_amdgcn_global_load_lds((const unsigned*)((const char*)(gbase) + (voff)[_i]), (PG8_LAS unsigned*)(lds + (bufoff) + ldsw + _i * 8192), 16, 0, 0); } while (0)
; #define PG8_LDA(dst, b, h) do { _Pragma("unroll") for (int m = 0; m < 4; ++m) _Pragma("unroll") for (int k = 0; k < 2; ++k) dst[m][k] = *(const PG8_LAS bf16x8*)(lds + PG8_SA(b, h) + aoff + m * 2048 + k * 1024); } while (0)
; #define PG8_LDB(dst, b, h) do { _Pragma("unroll") for (int n = 0; n < 2; ++n) _Pragma("unroll") for (int k = 0; k < 2; ++k) dst[n][k] = *(const PG8_LAS bf16x8*)(lds + PG8_SB(b, h) + boff + n * 2048 + k * 1024); } while (0)
; #define PG8_MMA(ai, bj, At, Bt) do { __builtin_amdgcn_s_setprio(1); _Pragma("unroll") for (int m = 0; m < 4; ++m) _Pragma("unroll") for (int n = 0; n < 2; ++n) _Pragma("unroll") for (int k = 0; k < 2; ++k) \
;         acc[ai][bj][m][n] = __builtin_amdgcn_mfma_f32_16x16x32_bf16(Bt[n][k], At[m][k], acc[ai][bj][m][n], 0, 0, 0); __builtin_amdgcn_s_setprio(0); } while (0)
; #define PG8_WAIT_V(n) asm volatile("s_waitcnt vmcnt(" #n ")" ::: "memory")
; #define PG8_WAIT_L(n) asm volatile("s_waitcnt lgkmcnt(" #n ")" ::: "memory")
; #define PG8_BAR __builtin_amdgcn_s_barrier()
; #define PG8_SCHED __builtin_amdgcn_sched_barrier(0)
; template <class Epi, class Sched, bool ALIGN_EPI = false, bool SP2 = false>
; __device__ __forceinline__ void gemm_phase(PG8_LAS unsigned char* lds, const Gemm g, const Sched& S, const Epi& E) {
;     ...
;             PG8_WAIT_V(8); PG8_WAIT_L(0); PG8_BAR; PG8_MMA(1, 0, At, B0); PG8_MMA(1, 1, At, B1); PG8_BAR; PG8_SCHED;
;             PG8_LDB(B0, 1, 0); PG8_LDB(B1, 1, 1); PG8_SCHED; PG8_LDA(At, 1, 0); PG8_STAGE(PG8_SA(0, 1), a2 + hstep, voffA);
;             PG8_WAIT_V(8); PG8_WAIT_L(0); PG8_BAR; PG8_MMA(0, 0, At, B0); PG8_MMA(0, 1, At, B1); PG8_BAR; PG8_SCHED;
;             PG8_LDA(At, 1, 1); PG8_STAGE(PG8_SB(1, 0), b3, voffB); PG8_STAGE(PG8_SB(1, 1), b3 + hstep, voffB); PG8_STAGE(PG8_SA(1, 0), a3, voffA);
	s_barrier
	s_add_i32 s84, 0, 0x18000
	s_add_i32 s85, 0, 0x1c000


; #define PG8_STAGE(bufoff, gbase, voff) do { _Pragma("unroll") for (int _i = 0; _i < 2; ++_i) \
;         __builtin_amdgcn_global_load_lds((const unsigned*)((const char*)(gbase) + (voff)[_i]), (PG8_LAS unsigned*)(lds + (bufoff) + ldsw + _i * 8192), 16, 0, 0); } while (0)
; #define PG8_LDA(dst, b, h) do { _Pragma("unroll") for (int m = 0; m < 4; ++m) _Pragma("unroll") for (int k = 0; k < 2; ++k) dst[m][k] = *(const PG8_LAS bf16x8*)(lds + PG8_SA(b, h) + aoff + m * 2048 + k * 1024); } while (0)
; #define PG8_LDB(dst, b, h) do { _Pragma("unroll") for (int n = 0; n < 2; ++n) _Pragma("unroll") for (int k = 0; k < 2; ++k) dst[n][k] = *(const PG8_LAS bf16x8*)(lds + PG8_SB(b, h) + boff + n * 2048 + k * 1024); } while (0)
; #define PG8_SCHED __builtin_amdgcn_sched_barrier(0)
; template <class Epi, class Sched, bool ALIGN_EPI = false, bool SP2 = false>
; __device__ __forceinline__ void gemm_phase(PG8_LAS unsigned char* lds, const Gemm g, const Sched& S, const Epi& E) {
;     ...
;             PG8_LDB(B0, 1, 0); PG8_LDB(B1, 1, 1); PG8_SCHED; PG8_LDA(At, 1, 0); PG8_STAGE(PG8_SA(0, 1), a2 + hstep, voffA);
	ds_read_b128 v[128:131], v254
	ds_read_b128 v[132:135], v254 offset:1024
	ds_read_b128 v[136:139], v254 offset:2048
	ds_read_b128 v[140:143], v254 offset:3072
	ds_read_b128 v[144:147], v255
	ds_read_b128 v[148:151], v255 offset:1024
	ds_read_b128 v[152:155], v255 offset:2048
	ds_read_b128 v[156:159], v255 offset:3072
	s_add_u32 s58, s58, 0x80000
	s_addc_u32 s59, s59, 0
	s_mov_b32 m0, s65

; #define PG8_STAGE(bufoff, gbase, voff) do { _Pragma("unroll") for (int _i = 0; _i < 2; ++_i) \
;         __builtin_amdgcn_global_load_lds((const unsigned*)((const char*)(gbase) + (voff)[_i]), (PG8_LAS unsigned*)(lds + (bufoff) + ldsw + _i * 8192), 16, 0, 0); } while (0)
; #define PG8_LDA(dst, b, h) do { _Pragma("unroll") for (int m = 0; m < 4; ++m) _Pragma("unroll") for (int k = 0; k < 2; ++k) dst[m][k] = *(const PG8_LAS bf16x8*)(lds + PG8_SA(b, h) + aoff + m * 2048 + k * 1024); } while (0)
; #define PG8_LDB(dst, b, h) do { _Pragma("unroll") for (int n = 0; n < 2; ++n) _Pragma("unroll") for (int k = 0; k < 2; ++k) dst[n][k] = *(const PG8_LAS bf16x8*)(lds + PG8_SB(b, h) + boff + n * 2048 + k * 1024); } while (0)
; #define PG8_SCHED __builtin_amdgcn_sched_barrier(0)
; template <class Epi, class Sched, bool ALIGN_EPI = false, bool SP2 = false>
; __device__ __forceinline__ void gemm_phase(PG8_LAS unsigned char* lds, const Gemm g, const Sched& S, const Epi& E) {
;     ...
;             PG8_LDB(B0, 1, 0); PG8_LDB(B1, 1, 1); PG8_SCHED; PG8_LDA(At, 1, 0); PG8_STAGE(PG8_SA(0, 1), a2 + hstep, voffA);
	ds_read_b128 v[176:179], v207 offset:32768
	ds_read_b128 v[184:187], v207 offset:33792
	ds_read_b128 v[190:193], v207 offset:34816
	ds_read_b128 v[210:213], v207 offset:35840
	ds_read_b128 v[214:217], v207 offset:36864
	ds_read_b128 v[218:221], v207 offset:37888
	ds_read_b128 v[222:225], v207 offset:38912
	ds_read_b128 v[226:229], v207 offset:39936
	global_load_lds_dwordx4 v160, s[58:59]

; #define PG8_STAGE(bufoff, gbase, voff) do { _Pragma("unroll") for (int _i = 0; _i < 2; ++_i) \
;         __builtin_amdgcn_global_load_lds((const unsigned*)((const char*)(gbase) + (voff)[_i]), (PG8_LAS unsigned*)(lds + (bufoff) + ldsw + _i * 8192), 16, 0, 0); } while (0)
; #define PG8_LDA(dst, b, h) do { _Pragma("unroll") for (int m = 0; m < 4; ++m) _Pragma("unroll") for (int k = 0; k < 2; ++k) dst[m][k] = *(const PG8_LAS bf16x8*)(lds + PG8_SA(b, h) + aoff + m * 2048 + k * 1024); } while (0)
; #define PG8_LDB(dst, b, h) do { _Pragma("unroll") for (int n = 0; n < 2; ++n) _Pragma("unroll") for (int k = 0; k < 2; ++k) dst[n][k] = *(const PG8_LAS bf16x8*)(lds + PG8_SB(b, h) + boff + n * 2048 + k * 1024); } while (0)
; #define PG8_MMA(ai, bj, At, Bt) do { __builtin_amdgcn_s_setprio(1); _Pragma("unroll") for (int m = 0; m < 4; ++m) _Pragma("unroll") for (int n = 0; n < 2; ++n) _Pragma("unroll") for (int k = 0; k < 2; ++k) \
;         acc[ai][bj][m][n] = __builtin_amdgcn_mfma_f32_16x16x32_bf16(Bt[n][k], At[m][k], acc[ai][bj][m][n], 0, 0, 0); __builtin_amdgcn_s_setprio(0); } while (0)
; #define PG8_WAIT_V(n) asm volatile("s_waitcnt vmcnt(" #n ")" ::: "memory")
; #define PG8_WAIT_L(n) asm volatile("s_waitcnt lgkmcnt(" #n ")" ::: "memory")
; #define PG8_BAR __builtin_amdgcn_s_barrier()
; #define PG8_SCHED __builtin_amdgcn_sched_barrier(0)
; template <class Epi, class Sched, bool ALIGN_EPI = false, bool SP2 = false>
; __device__ __forceinline__ void gemm_phase(PG8_LAS unsigned char* lds, const Gemm g, const Sched& S, const Epi& E) {
;     ...
;             PG8_LDB(B0, 1, 0); PG8_LDB(B1, 1, 1); PG8_SCHED; PG8_LDA(At, 1, 0); PG8_STAGE(PG8_SA(0, 1), a2 + hstep, voffA);
;             PG8_WAIT_V(8); PG8_WAIT_L(0); PG8_BAR; PG8_MMA(0, 0, At, B0); PG8_MMA(0, 1, At, B1); PG8_BAR; PG8_SCHED;
	s_mov_b32 m0, s67
	s_nop 0
	global_load_lds_dwordx4 v164, s[58:59]
	s_waitcnt vmcnt(8) lgkmcnt(0)


; #define PG8_MMA(ai, bj, At, Bt) do { __builtin_amdgcn_s_setprio(1); _Pragma("unroll") for (int m = 0; m < 4; ++m) _Pragma("unroll") for (int n = 0; n < 2; ++n) _Pragma("unroll") for (int k = 0; k < 2; ++k) \
;         acc[ai][bj][m][n] = __builtin_amdgcn_mfma_f32_16x16x32_bf16(Bt[n][k], At[m][k], acc[ai][bj][m][n], 0, 0, 0); __builtin_amdgcn_s_setprio(0); } while (0)
; #define PG8_WAIT_V(n) asm volatile("s_waitcnt vmcnt(" #n ")" ::: "memory")
; #define PG8_WAIT_L(n) asm volatile("s_waitcnt lgkmcnt(" #n ")" ::: "memory")
; #define PG8_BAR __builtin_amdgcn_s_barrier()
; #define PG8_SCHED __builtin_amdgcn_sched_barrier(0)
; template <class Epi, class Sched, bool ALIGN_EPI = false, bool SP2 = false>
; __device__ __forceinline__ void gemm_phase(PG8_LAS unsigned char* lds, const Gemm g, const Sched& S, const Epi& E) {
;     ...
;             PG8_WAIT_V(8); PG8_WAIT_L(0); PG8_BAR; PG8_MMA(0, 0, At, B0); PG8_MMA(0, 1, At, B1); PG8_BAR; PG8_SCHED;
	s_barrier

; #define PG8_MMA(ai, bj, At, Bt) do { __builtin_amdgcn_s_setprio(1); _Pragma("unroll") for (int m = 0; m < 4; ++m) _Pragma("unroll") for (int n = 0; n < 2; ++n) _Pragma("unroll") for (int k = 0; k < 2; ++k) \
;         acc[ai][bj][m][n] = __builtin_amdgcn_mfma_f32_16x16x32_bf16(Bt[n][k], At[m][k], acc[ai][bj][m][n], 0, 0, 0); __builtin_amdgcn_s_setprio(0); } while (0)
; #define PG8_WAIT_V(n) asm volatile("s_waitcnt vmcnt(" #n ")" ::: "memory")
; #define PG8_WAIT_L(n) asm volatile("s_waitcnt lgkmcnt(" #n ")" ::: "memory")
; #define PG8_BAR __builtin_amdgcn_s_barrier()
; #define PG8_SCHED __builtin_amdgcn_sched_barrier(0)
; template <class Epi, class Sched, bool ALIGN_EPI = false, bool SP2 = false>
; __device__ __forceinline__ void gemm_phase(PG8_LAS unsigned char* lds, const Gemm g, const Sched& S, const Epi& E) {
;     ...
;             PG8_WAIT_V(8); PG8_WAIT_L(0); PG8_BAR; PG8_MMA(0, 0, At, B0); PG8_MMA(0, 1, At, B1); PG8_BAR; PG8_SCHED;
	v_mfma_f32_16x16x32_bf16 v[124:127], v[128:131], v[176:179], v[124:127]
	v_mfma_f32_16x16x32_bf16 v[120:123], v[136:139], v[176:179], v[120:123]
	v_mfma_f32_16x16x32_bf16 v[108:111], v[128:131], v[190:193], v[108:111]
	v_mfma_f32_16x16x32_bf16 v[104:107], v[136:139], v[190:193], v[104:107]
	v_mfma_f32_16x16x32_bf16 v[92:95], v[128:131], v[214:217], v[92:95]
	v_mfma_f32_16x16x32_bf16 v[88:91], v[136:139], v[214:217], v[88:91]
	v_mfma_f32_16x16x32_bf16 v[76:79], v[128:131], v[222:225], v[76:79]
	v_mfma_f32_16x16x32_bf16 v[72:75], v[136:139], v[222:225], v[72:75]
	v_mfma_f32_16x16x32_bf16 v[124:127], v[132:135], v[184:187], v[124:127]
	v_mfma_f32_16x16x32_bf16 v[120:123], v[140:143], v[184:187], v[120:123]
	v_mfma_f32_16x16x32_bf16 v[108:111], v[132:135], v[210:213], v[108:111]
	v_mfma_f32_16x16x32_bf16 v[104:107], v[140:143], v[210:213], v[104:107]
	v_mfma_f32_16x16x32_bf16 v[92:95], v[132:135], v[218:221], v[92:95]
	v_mfma_f32_16x16x32_bf16 v[88:91], v[140:143], v[218:221], v[88:91]
	v_mfma_f32_16x16x32_bf16 v[76:79], v[132:135], v[226:229], v[76:79]
	v_mfma_f32_16x16x32_bf16 v[72:75], v[140:143], v[226:229], v[72:75]


; #define PG8_MMA(ai, bj, At, Bt) do { __builtin_amdgcn_s_setprio(1); _Pragma("unroll") for (int m = 0; m < 4; ++m) _Pragma("unroll") for (int n = 0; n < 2; ++n) _Pragma("unroll") for (int k = 0; k < 2; ++k) \
;         acc[ai][bj][m][n] = __builtin_amdgcn_mfma_f32_16x16x32_bf16(Bt[n][k], At[m][k], acc[ai][bj][m][n], 0, 0, 0); __builtin_amdgcn_s_setprio(0); } while (0)
; #define PG8_WAIT_V(n) asm volatile("s_waitcnt vmcnt(" #n ")" ::: "memory")
; #define PG8_WAIT_L(n) asm volatile("s_waitcnt lgkmcnt(" #n ")" ::: "memory")
; #define PG8_BAR __builtin_amdgcn_s_barrier()
; #define PG8_SCHED __builtin_amdgcn_sched_barrier(0)
; template <class Epi, class Sched, bool ALIGN_EPI = false, bool SP2 = false>
; __device__ __forceinline__ void gemm_phase(PG8_LAS unsigned char* lds, const Gemm g, const Sched& S, const Epi& E) {
;     ...
;             PG8_WAIT_V(8); PG8_WAIT_L(0); PG8_BAR; PG8_MMA(0, 0, At, B0); PG8_MMA(0, 1, At, B1); PG8_BAR; PG8_SCHED;
	v_mfma_f32_16x16x32_bf16 v[116:119], v[144:147], v[176:179], v[116:119]
	v_mfma_f32_16x16x32_bf16 v[112:115], v[152:155], v[176:179], v[112:115]
	v_mfma_f32_16x16x32_bf16 v[100:103], v[144:147], v[190:193], v[100:103]
	v_mfma_f32_16x16x32_bf16 v[96:99], v[152:155], v[190:193], v[96:99]
	v_mfma_f32_16x16x32_bf16 v[84:87], v[144:147], v[214:217], v[84:87]
	v_mfma_f32_16x16x32_bf16 v[80:83], v[152:155], v[214:217], v[80:83]
	v_mfma_f32_16x16x32_bf16 v[68:71], v[144:147], v[222:225], v[68:71]
	v_mfma_f32_16x16x32_bf16 v[64:67], v[152:155], v[222:225], v[64:67]
	v_mfma_f32_16x16x32_bf16 v[116:119], v[148:151], v[184:187], v[116:119]
	v_mfma_f32_16x16x32_bf16 v[112:115], v[156:159], v[184:187], v[112:115]
	v_mfma_f32_16x16x32_bf16 v[100:103], v[148:151], v[210:213], v[100:103]
	v_mfma_f32_16x16x32_bf16 v[96:99], v[156:159], v[210:213], v[96:99]
	v_mfma_f32_16x16x32_bf16 v[84:87], v[148:151], v[218:221], v[84:87]
	v_mfma_f32_16x16x32_bf16 v[80:83], v[156:159], v[218:221], v[80:83]
	v_mfma_f32_16x16x32_bf16 v[68:71], v[148:151], v[226:229], v[68:71]
	v_mfma_f32_16x16x32_bf16 v[64:67], v[156:159], v[226:229], v[64:67]

; #define PG8_STAGE(bufoff, gbase, voff) do { _Pragma("unroll") for (int _i = 0; _i < 2; ++_i) \
;         __builtin_amdgcn_global_load_lds((const unsigned*)((const char*)(gbase) + (voff)[_i]), (PG8_LAS unsigned*)(lds + (bufoff) + ldsw + _i * 8192), 16, 0, 0); } while (0)
; #define PG8_LDA(dst, b, h) do { _Pragma("unroll") for (int m = 0; m < 4; ++m) _Pragma("unroll") for (int k = 0; k < 2; ++k) dst[m][k] = *(const PG8_LAS bf16x8*)(lds + PG8_SA(b, h) + aoff + m * 2048 + k * 1024); } while (0)
; #define PG8_MMA(ai, bj, At, Bt) do { __builtin_amdgcn_s_setprio(1); _Pragma("unroll") for (int m = 0; m < 4; ++m) _Pragma("unroll") for (int n = 0; n < 2; ++n) _Pragma("unroll") for (int k = 0; k < 2; ++k) \
;         acc[ai][bj][m][n] = __builtin_amdgcn_mfma_f32_16x16x32_bf16(Bt[n][k], At[m][k], acc[ai][bj][m][n], 0, 0, 0); __builtin_amdgcn_s_setprio(0); } while (0)
; #define PG8_WAIT_V(n) asm volatile("s_waitcnt vmcnt(" #n ")" ::: "memory")
; #define PG8_WAIT_L(n) asm volatile("s_waitcnt lgkmcnt(" #n ")" ::: "memory")
; #define PG8_BAR __builtin_amdgcn_s_barrier()
; #define PG8_SCHED __builtin_amdgcn_sched_barrier(0)
; template <class Epi, class Sched, bool ALIGN_EPI = false, bool SP2 = false>
; __device__ __forceinline__ void gemm_phase(PG8_LAS unsigned char* lds, const Gemm g, const Sched& S, const Epi& E) {
;     ...
;             PG8_WAIT_V(8); PG8_WAIT_L(0); PG8_BAR; PG8_MMA(0, 0, At, B0); PG8_MMA(0, 1, At, B1); PG8_BAR; PG8_SCHED;
;             PG8_LDA(At, 1, 1); PG8_STAGE(PG8_SB(1, 0), b3, voffB); PG8_STAGE(PG8_SB(1, 1), b3 + hstep, voffB); PG8_STAGE(PG8_SA(1, 0), a3, voffA);
	s_barrier
	s_add_i32 s58, s84, s62

; #define PG8_STAGE(bufoff, gbase, voff) do { _Pragma("unroll") for (int _i = 0; _i < 2; ++_i) \
;         __builtin_amdgcn_global_load_lds((const unsigned*)((const char*)(gbase) + (voff)[_i]), (PG8_LAS unsigned*)(lds + (bufoff) + ldsw + _i * 8192), 16, 0, 0); } while (0)
; #define PG8_LDA(dst, b, h) do { _Pragma("unroll") for (int m = 0; m < 4; ++m) _Pragma("unroll") for (int k = 0; k < 2; ++k) dst[m][k] = *(const PG8_LAS bf16x8*)(lds + PG8_SA(b, h) + aoff + m * 2048 + k * 1024); } while (0)
; template <class Epi, class Sched, bool ALIGN_EPI = false, bool SP2 = false>
; __device__ __forceinline__ void gemm_phase(PG8_LAS unsigned char* lds, const Gemm g, const Sched& S, const Epi& E) {
;     ...
;             PG8_LDA(At, 1, 1); PG8_STAGE(PG8_SB(1, 0), b3, voffB); PG8_STAGE(PG8_SB(1, 1), b3 + hstep, voffB); PG8_STAGE(PG8_SA(1, 0), a3, voffA);
	s_mov_b32 m0, s58
	ds_read_b128 v[176:179], v207 offset:49152
	ds_read_b128 v[184:187], v207 offset:50176
	ds_read_b128 v[190:193], v207 offset:51200
	ds_read_b128 v[210:213], v207 offset:52224
	ds_read_b128 v[214:217], v207 offset:53248
	ds_read_b128 v[218:221], v207 offset:54272
	ds_read_b128 v[222:225], v207 offset:55296
	ds_read_b128 v[226:229], v207 offset:56320
	global_load_lds_dwordx4 v250, s[96:97]
	s_add_i32 m0, s58, 0x2000
	s_add_u32 s12, s12, 0x80080

; #define PG8_STAGE(bufoff, gbase, voff) do { _Pragma("unroll") for (int _i = 0; _i < 2; ++_i) \
;         __builtin_amdgcn_global_load_lds((const unsigned*)((const char*)(gbase) + (voff)[_i]), (PG8_LAS unsigned*)(lds + (bufoff) + ldsw + _i * 8192), 16, 0, 0); } while (0)
; #define PG8_LDA(dst, b, h) do { _Pragma("unroll") for (int m = 0; m < 4; ++m) _Pragma("unroll") for (int k = 0; k < 2; ++k) dst[m][k] = *(const PG8_LAS bf16x8*)(lds + PG8_SA(b, h) + aoff + m * 2048 + k * 1024); } while (0)
; template <class Epi, class Sched, bool ALIGN_EPI = false, bool SP2 = false>
; __device__ __forceinline__ void gemm_phase(PG8_LAS unsigned char* lds, const Gemm g, const Sched& S, const Epi& E) {
;     ...
;             PG8_LDA(At, 1, 1); PG8_STAGE(PG8_SB(1, 0), b3, voffB); PG8_STAGE(PG8_SB(1, 1), b3 + hstep, voffB); PG8_STAGE(PG8_SA(1, 0), a3, voffA);
	s_addc_u32 s13, s13, 0
	s_add_i32 s58, s85, s62
	global_load_lds_dwordx4 v251, s[96:97]

; #define PG8_STAGE(bufoff, gbase, voff) do { _Pragma("unroll") for (int _i = 0; _i < 2; ++_i) \
;         __builtin_amdgcn_global_load_lds((const unsigned*)((const char*)(gbase) + (voff)[_i]), (PG8_LAS unsigned*)(lds + (bufoff) + ldsw + _i * 8192), 16, 0, 0); } while (0)
; #define PG8_LDA(dst, b, h) do { _Pragma("unroll") for (int m = 0; m < 4; ++m) _Pragma("unroll") for (int k = 0; k < 2; ++k) dst[m][k] = *(const PG8_LAS bf16x8*)(lds + PG8_SA(b, h) + aoff + m * 2048 + k * 1024); } while (0)
; template <class Epi, class Sched, bool ALIGN_EPI = false, bool SP2 = false>
; __device__ __forceinline__ void gemm_phase(PG8_LAS unsigned char* lds, const Gemm g, const Sched& S, const Epi& E) {
;     ...
;             PG8_LDA(At, 1, 1); PG8_STAGE(PG8_SB(1, 0), b3, voffB); PG8_STAGE(PG8_SB(1, 1), b3 + hstep, voffB); PG8_STAGE(PG8_SA(1, 0), a3, voffA);
	s_mov_b32 m0, s58
	s_nop 0
	global_load_lds_dwordx4 v162, s[12:13]

; #define PG8_STAGE(bufoff, gbase, voff) do { _Pragma("unroll") for (int _i = 0; _i < 2; ++_i) \
;         __builtin_amdgcn_global_load_lds((const unsigned*)((const char*)(gbase) + (voff)[_i]), (PG8_LAS unsigned*)(lds + (bufoff) + ldsw + _i * 8192), 16, 0, 0); } while (0)
; #define PG8_LDA(dst, b, h) do { _Pragma("unroll") for (int m = 0; m < 4; ++m) _Pragma("unroll") for (int k = 0; k < 2; ++k) dst[m][k] = *(const PG8_LAS bf16x8*)(lds + PG8_SA(b, h) + aoff + m * 2048 + k * 1024); } while (0)
; template <class Epi, class Sched, bool ALIGN_EPI = false, bool SP2 = false>
; __device__ __forceinline__ void gemm_phase(PG8_LAS unsigned char* lds, const Gemm g, const Sched& S, const Epi& E) {
;     ...
;             PG8_LDA(At, 1, 1); PG8_STAGE(PG8_SB(1, 0), b3, voffB); PG8_STAGE(PG8_SB(1, 1), b3 + hstep, voffB); PG8_STAGE(PG8_SA(1, 0), a3, voffA);
	s_add_i32 m0, s58, 0x2000
	s_nop 0
	global_load_lds_dwordx4 v166, s[12:13]

; #define PG8_STAGE(bufoff, gbase, voff) do { _Pragma("unroll") for (int _i = 0; _i < 2; ++_i) \
;         __builtin_amdgcn_global_load_lds((const unsigned*)((const char*)(gbase) + (voff)[_i]), (PG8_LAS unsigned*)(lds + (bufoff) + ldsw + _i * 8192), 16, 0, 0); } while (0)
; #define PG8_LDA(dst, b, h) do { _Pragma("unroll") for (int m = 0; m < 4; ++m) _Pragma("unroll") for (int k = 0; k < 2; ++k) dst[m][k] = *(const PG8_LAS bf16x8*)(lds + PG8_SA(b, h) + aoff + m * 2048 + k * 1024); } while (0)
; template <class Epi, class Sched, bool ALIGN_EPI = false, bool SP2 = false>
; __device__ __forceinline__ void gemm_phase(PG8_LAS unsigned char* lds, const Gemm g, const Sched& S, const Epi& E) {
;     ...
;             PG8_LDA(At, 1, 1); PG8_STAGE(PG8_SB(1, 0), b3, voffB); PG8_STAGE(PG8_SB(1, 1), b3 + hstep, voffB); PG8_STAGE(PG8_SA(1, 0), a3, voffA);
	s_mov_b32 m0, s69
	s_nop 0
	global_load_lds_dwordx4 v252, s[98:99]

; #define PG8_STAGE(bufoff, gbase, voff) do { _Pragma("unroll") for (int _i = 0; _i < 2; ++_i) \
;         __builtin_amdgcn_global_load_lds((const unsigned*)((const char*)(gbase) + (voff)[_i]), (PG8_LAS unsigned*)(lds + (bufoff) + ldsw + _i * 8192), 16, 0, 0); } while (0)
; #define PG8_LDA(dst, b, h) do { _Pragma("unroll") for (int m = 0; m < 4; ++m) _Pragma("unroll") for (int k = 0; k < 2; ++k) dst[m][k] = *(const PG8_LAS bf16x8*)(lds + PG8_SA(b, h) + aoff + m * 2048 + k * 1024); } while (0)
; #define PG8_MMA(ai, bj, At, Bt) do { __builtin_amdgcn_s_setprio(1); _Pragma("unroll") for (int m = 0; m < 4; ++m) _Pragma("unroll") for (int n = 0; n < 2; ++n) _Pragma("unroll") for (int k = 0; k < 2; ++k) \
;         acc[ai][bj][m][n] = __builtin_amdgcn_mfma_f32_16x16x32_bf16(Bt[n][k], At[m][k], acc[ai][bj][m][n], 0, 0, 0); __builtin_amdgcn_s_setprio(0); } while (0)
; #define PG8_WAIT_V(n) asm volatile("s_waitcnt vmcnt(" #n ")" ::: "memory")
; #define PG8_WAIT_L(n) asm volatile("s_waitcnt lgkmcnt(" #n ")" ::: "memory")
; #define PG8_BAR __builtin_amdgcn_s_barrier()
; #define PG8_SCHED __builtin_amdgcn_sched_barrier(0)
; template <class Epi, class Sched, bool ALIGN_EPI = false, bool SP2 = false>
; __device__ __forceinline__ void gemm_phase(PG8_LAS unsigned char* lds, const Gemm g, const Sched& S, const Epi& E) {
;     ...
;             PG8_LDA(At, 1, 1); PG8_STAGE(PG8_SB(1, 0), b3, voffB); PG8_STAGE(PG8_SB(1, 1), b3 + hstep, voffB); PG8_STAGE(PG8_SA(1, 0), a3, voffA);
;             PG8_WAIT_V(8); PG8_WAIT_L(0); PG8_BAR; PG8_MMA(1, 0, At, B0); PG8_MMA(1, 1, At, B1); PG8_BAR; PG8_SCHED;
	s_mov_b32 m0, s70
	s_nop 0
	global_load_lds_dwordx4 v253, s[98:99]
	s_waitcnt vmcnt(8) lgkmcnt(0)


; #define PG8_MMA(ai, bj, At, Bt) do { __builtin_amdgcn_s_setprio(1); _Pragma("unroll") for (int m = 0; m < 4; ++m) _Pragma("unroll") for (int n = 0; n < 2; ++n) _Pragma("unroll") for (int k = 0; k < 2; ++k) \
;         acc[ai][bj][m][n] = __builtin_amdgcn_mfma_f32_16x16x32_bf16(Bt[n][k], At[m][k], acc[ai][bj][m][n], 0, 0, 0); __builtin_amdgcn_s_setprio(0); } while (0)
; #define PG8_WAIT_V(n) asm volatile("s_waitcnt vmcnt(" #n ")" ::: "memory")
; #define PG8_WAIT_L(n) asm volatile("s_waitcnt lgkmcnt(" #n ")" ::: "memory")
; #define PG8_BAR __builtin_amdgcn_s_barrier()
; #define PG8_SCHED __builtin_amdgcn_sched_barrier(0)
; template <class Epi, class Sched, bool ALIGN_EPI = false, bool SP2 = false>
; __device__ __forceinline__ void gemm_phase(PG8_LAS unsigned char* lds, const Gemm g, const Sched& S, const Epi& E) {
;     ...
;             PG8_WAIT_V(8); PG8_WAIT_L(0); PG8_BAR; PG8_MMA(1, 0, At, B0); PG8_MMA(1, 1, At, B1); PG8_BAR; PG8_SCHED;
	s_barrier

; #define PG8_MMA(ai, bj, At, Bt) do { __builtin_amdgcn_s_setprio(1); _Pragma("unroll") for (int m = 0; m < 4; ++m) _Pragma("unroll") for (int n = 0; n < 2; ++n) _Pragma("unroll") for (int k = 0; k < 2; ++k) \
;         acc[ai][bj][m][n] = __builtin_amdgcn_mfma_f32_16x16x32_bf16(Bt[n][k], At[m][k], acc[ai][bj][m][n], 0, 0, 0); __builtin_amdgcn_s_setprio(0); } while (0)
; #define PG8_WAIT_V(n) asm volatile("s_waitcnt vmcnt(" #n ")" ::: "memory")
; #define PG8_WAIT_L(n) asm volatile("s_waitcnt lgkmcnt(" #n ")" ::: "memory")
; #define PG8_BAR __builtin_amdgcn_s_barrier()
; #define PG8_SCHED __builtin_amdgcn_sched_barrier(0)
; template <class Epi, class Sched, bool ALIGN_EPI = false, bool SP2 = false>
; __device__ __forceinline__ void gemm_phase(PG8_LAS unsigned char* lds, const Gemm g, const Sched& S, const Epi& E) {
;     ...
;             PG8_WAIT_V(8); PG8_WAIT_L(0); PG8_BAR; PG8_MMA(1, 0, At, B0); PG8_MMA(1, 1, At, B1); PG8_BAR; PG8_SCHED;
	v_mfma_f32_16x16x32_bf16 v[60:63], v[128:131], v[176:179], v[60:63]
	v_mfma_f32_16x16x32_bf16 v[56:59], v[136:139], v[176:179], v[56:59]
	v_mfma_f32_16x16x32_bf16 v[44:47], v[128:131], v[190:193], v[44:47]
	v_mfma_f32_16x16x32_bf16 v[40:43], v[136:139], v[190:193], v[40:43]
	v_mfma_f32_16x16x32_bf16 v[28:31], v[128:131], v[214:217], v[28:31]
	v_mfma_f32_16x16x32_bf16 v[24:27], v[136:139], v[214:217], v[24:27]
	v_mfma_f32_16x16x32_bf16 v[12:15], v[128:131], v[222:225], v[12:15]
	v_mfma_f32_16x16x32_bf16 v[8:11], v[136:139], v[222:225], v[8:11]
	v_mfma_f32_16x16x32_bf16 v[60:63], v[132:135], v[184:187], v[60:63]
	v_mfma_f32_16x16x32_bf16 v[56:59], v[140:143], v[184:187], v[56:59]
	v_mfma_f32_16x16x32_bf16 v[44:47], v[132:135], v[210:213], v[44:47]
	v_mfma_f32_16x16x32_bf16 v[40:43], v[140:143], v[210:213], v[40:43]
	v_mfma_f32_16x16x32_bf16 v[28:31], v[132:135], v[218:221], v[28:31]
	v_mfma_f32_16x16x32_bf16 v[24:27], v[140:143], v[218:221], v[24:27]
	v_mfma_f32_16x16x32_bf16 v[12:15], v[132:135], v[226:229], v[12:15]
	v_mfma_f32_16x16x32_bf16 v[8:11], v[140:143], v[226:229], v[8:11]


; #define PG8_MMA(ai, bj, At, Bt) do { __builtin_amdgcn_s_setprio(1); _Pragma("unroll") for (int m = 0; m < 4; ++m) _Pragma("unroll") for (int n = 0; n < 2; ++n) _Pragma("unroll") for (int k = 0; k < 2; ++k) \
;         acc[ai][bj][m][n] = __builtin_amdgcn_mfma_f32_16x16x32_bf16(Bt[n][k], At[m][k], acc[ai][bj][m][n], 0, 0, 0); __builtin_amdgcn_s_setprio(0); } while (0)
; #define PG8_WAIT_V(n) asm volatile("s_waitcnt vmcnt(" #n ")" ::: "memory")
; #define PG8_WAIT_L(n) asm volatile("s_waitcnt lgkmcnt(" #n ")" ::: "memory")
; #define PG8_BAR __builtin_amdgcn_s_barrier()
; #define PG8_SCHED __builtin_amdgcn_sched_barrier(0)
; template <class Epi, class Sched, bool ALIGN_EPI = false, bool SP2 = false>
; __device__ __forceinline__ void gemm_phase(PG8_LAS unsigned char* lds, const Gemm g, const Sched& S, const Epi& E) {
;     ...
;             PG8_WAIT_V(8); PG8_WAIT_L(0); PG8_BAR; PG8_MMA(1, 0, At, B0); PG8_MMA(1, 1, At, B1); PG8_BAR; PG8_SCHED;
	v_mfma_f32_16x16x32_bf16 v[52:55], v[144:147], v[176:179], v[52:55]
	v_mfma_f32_16x16x32_bf16 v[48:51], v[152:155], v[176:179], v[48:51]
	v_mfma_f32_16x16x32_bf16 v[36:39], v[144:147], v[190:193], v[36:39]
	v_mfma_f32_16x16x32_bf16 v[32:35], v[152:155], v[190:193], v[32:35]
	v_mfma_f32_16x16x32_bf16 v[20:23], v[144:147], v[214:217], v[20:23]
	v_mfma_f32_16x16x32_bf16 v[16:19], v[152:155], v[214:217], v[16:19]
	v_mfma_f32_16x16x32_bf16 v[4:7], v[144:147], v[222:225], v[4:7]
	v_mfma_f32_16x16x32_bf16 v[0:3], v[152:155], v[222:225], v[0:3]
	v_mfma_f32_16x16x32_bf16 v[52:55], v[148:151], v[184:187], v[52:55]
	v_mfma_f32_16x16x32_bf16 v[48:51], v[156:159], v[184:187], v[48:51]
	v_mfma_f32_16x16x32_bf16 v[36:39], v[148:151], v[210:213], v[36:39]
	v_mfma_f32_16x16x32_bf16 v[32:35], v[156:159], v[210:213], v[32:35]
	v_mfma_f32_16x16x32_bf16 v[20:23], v[148:151], v[218:221], v[20:23]
	v_mfma_f32_16x16x32_bf16 v[16:19], v[156:159], v[218:221], v[16:19]
	v_mfma_f32_16x16x32_bf16 v[4:7], v[148:151], v[226:229], v[4:7]
	v_mfma_f32_16x16x32_bf16 v[0:3], v[156:159], v[226:229], v[0:3]

; #define PG8_MMA(ai, bj, At, Bt) do { __builtin_amdgcn_s_setprio(1); _Pragma("unroll") for (int m = 0; m < 4; ++m) _Pragma("unroll") for (int n = 0; n < 2; ++n) _Pragma("unroll") for (int k = 0; k < 2; ++k) \
;         acc[ai][bj][m][n] = __builtin_amdgcn_mfma_f32_16x16x32_bf16(Bt[n][k], At[m][k], acc[ai][bj][m][n], 0, 0, 0); __builtin_amdgcn_s_setprio(0); } while (0)
; #define PG8_WAIT_V(n) asm volatile("s_waitcnt vmcnt(" #n ")" ::: "memory")
; #define PG8_WAIT_L(n) asm volatile("s_waitcnt lgkmcnt(" #n ")" ::: "memory")
; #define PG8_BAR __builtin_amdgcn_s_barrier()
; #define PG8_SCHED __builtin_amdgcn_sched_barrier(0)
; template <class Epi, class Sched, bool ALIGN_EPI = false, bool SP2 = false>
; __device__ __forceinline__ void gemm_phase(PG8_LAS unsigned char* lds, const Gemm g, const Sched& S, const Epi& E) {
;     ...
;         for (int t = 0; t < nt; t += 2) {
;     ...
;             PG8_WAIT_V(8); PG8_WAIT_L(0); PG8_BAR; PG8_MMA(1, 0, At, B0); PG8_MMA(1, 1, At, B1); PG8_BAR; PG8_SCHED;
;     ...
;         if constexpr (ALIGN_EPI) { if (wr == 0) PG8_BAR; }
	s_barrier
	s_add_i32 s83, s83, 2
	s_add_u32 s10, s10, 0x100
	s_addc_u32 s11, s11, 0
	s_add_u32 s81, s81, 0x100
	s_addc_u32 s82, s82, 0
	s_cmp_gt_u32 s83, 29
	s_cbranch_scc0 .LBB0_1034
	s_and_b64 vcc, exec, s[40:41]
	s_cbranch_vccz .LBB0_1037
	s_barrier

; #define PG8_STAGE(bufoff, gbase, voff) do { _Pragma("unroll") for (int _i = 0; _i < 2; ++_i) \
;         __builtin_amdgcn_global_load_lds((const unsigned*)((const char*)(gbase) + (voff)[_i]), (PG8_LAS unsigned*)(lds + (bufoff) + ldsw + _i * 8192), 16, 0, 0); } while (0)
; #define PG8_LDA(dst, b, h) do { _Pragma("unroll") for (int m = 0; m < 4; ++m) _Pragma("unroll") for (int k = 0; k < 2; ++k) dst[m][k] = *(const PG8_LAS bf16x8*)(lds + PG8_SA(b, h) + aoff + m * 2048 + k * 1024); } while (0)
; #define PG8_LDB(dst, b, h) do { _Pragma("unroll") for (int n = 0; n < 2; ++n) _Pragma("unroll") for (int k = 0; k < 2; ++k) dst[n][k] = *(const PG8_LAS bf16x8*)(lds + PG8_SB(b, h) + boff + n * 2048 + k * 1024); } while (0)
; #define PG8_SCHED __builtin_amdgcn_sched_barrier(0)
; template <class Epi, class Sched, bool ALIGN_EPI = false, bool SP2 = false>
; __device__ __forceinline__ void gemm_phase(PG8_LAS unsigned char* lds, const Gemm g, const Sched& S, const Epi& E) {
;     ...
;             const bool last = (t == nt - 2);
;             const char* a1 = cA + (size_t)(t + 1) * kstep;
;             const char* a2 = last ? nA : cA + (size_t)(t + 2) * kstep; const char* b2 = last ? nB : cB + (size_t)(t + 2) * kstep;
;     ...
;             PG8_LDB(B0, 0, 0); PG8_LDB(B1, 0, 1); PG8_SCHED; PG8_LDA(At, 0, 0); PG8_STAGE(PG8_SA(1, 1), a1 + hstep, voffA);
.LBB0_1114:
	ds_read_b128 v[96:99], v197
	ds_read_b128 v[100:103], v197 offset:1024
	ds_read_b128 v[104:107], v197 offset:2048
	ds_read_b128 v[112:115], v197 offset:3072
	ds_read_b128 v[144:147], v198
	ds_read_b128 v[148:151], v198 offset:1024
	ds_read_b128 v[152:155], v198 offset:2048
	ds_read_b128 v[172:175], v198 offset:3072
	s_add_u32 s50, s48, 0xffe00080
	s_addc_u32 s51, s49, -1
	s_cmpk_eq_i32 s73, 0x7c
	s_cselect_b32 s53, s43, s51
	s_cselect_b32 s52, s69, s50
	s_cselect_b32 s51, s41, s72
	s_cselect_b32 s50, s70, s71

; #define PG8_STAGE(bufoff, gbase, voff) do { _Pragma("unroll") for (int _i = 0; _i < 2; ++_i) \
;         __builtin_amdgcn_global_load_lds((const unsigned*)((const char*)(gbase) + (voff)[_i]), (PG8_LAS unsigned*)(lds + (bufoff) + ldsw + _i * 8192), 16, 0, 0); } while (0)
; #define PG8_LDA(dst, b, h) do { _Pragma("unroll") for (int m = 0; m < 4; ++m) _Pragma("unroll") for (int k = 0; k < 2; ++k) dst[m][k] = *(const PG8_LAS bf16x8*)(lds + PG8_SA(b, h) + aoff + m * 2048 + k * 1024); } while (0)
; #define PG8_LDB(dst, b, h) do { _Pragma("unroll") for (int n = 0; n < 2; ++n) _Pragma("unroll") for (int k = 0; k < 2; ++k) dst[n][k] = *(const PG8_LAS bf16x8*)(lds + PG8_SB(b, h) + boff + n * 2048 + k * 1024); } while (0)
; #define PG8_SCHED __builtin_amdgcn_sched_barrier(0)
; template <class Epi, class Sched, bool ALIGN_EPI = false, bool SP2 = false>
; __device__ __forceinline__ void gemm_phase(PG8_LAS unsigned char* lds, const Gemm g, const Sched& S, const Epi& E) {
;     ...
;             PG8_LDB(B0, 0, 0); PG8_LDB(B1, 0, 1); PG8_SCHED; PG8_LDA(At, 0, 0); PG8_STAGE(PG8_SA(1, 1), a1 + hstep, voffA);
	s_add_i32 m0, s56, 0xc000
	ds_read_b128 v[176:179], v199
	ds_read_b128 v[180:183], v199 offset:1024
	ds_read_b128 v[184:187], v199 offset:2048
	ds_read_b128 v[188:191], v199 offset:3072
	ds_read_b128 v[202:205], v199 offset:4096
	ds_read_b128 v[206:209], v199 offset:5120
	ds_read_b128 v[210:213], v199 offset:6144
	ds_read_b128 v[214:217], v199 offset:7168
	global_load_lds_dwordx4 v164, s[48:49]

; #define PG8_STAGE(bufoff, gbase, voff) do { _Pragma("unroll") for (int _i = 0; _i < 2; ++_i) \
;         __builtin_amdgcn_global_load_lds((const unsigned*)((const char*)(gbase) + (voff)[_i]), (PG8_LAS unsigned*)(lds + (bufoff) + ldsw + _i * 8192), 16, 0, 0); } while (0)
; #define PG8_LDA(dst, b, h) do { _Pragma("unroll") for (int m = 0; m < 4; ++m) _Pragma("unroll") for (int k = 0; k < 2; ++k) dst[m][k] = *(const PG8_LAS bf16x8*)(lds + PG8_SA(b, h) + aoff + m * 2048 + k * 1024); } while (0)
; #define PG8_LDB(dst, b, h) do { _Pragma("unroll") for (int n = 0; n < 2; ++n) _Pragma("unroll") for (int k = 0; k < 2; ++k) dst[n][k] = *(const PG8_LAS bf16x8*)(lds + PG8_SB(b, h) + boff + n * 2048 + k * 1024); } while (0)
; #define PG8_MMA(ai, bj, At, Bt) do { __builtin_amdgcn_s_setprio(1); _Pragma("unroll") for (int m = 0; m < 4; ++m) _Pragma("unroll") for (int n = 0; n < 2; ++n) _Pragma("unroll") for (int k = 0; k < 2; ++k) \
;         acc[ai][bj][m][n] = __builtin_amdgcn_mfma_f32_16x16x32_bf16(Bt[n][k], At[m][k], acc[ai][bj][m][n], 0, 0, 0); __builtin_amdgcn_s_setprio(0); } while (0)
; #define PG8_WAIT_V(n) asm volatile("s_waitcnt vmcnt(" #n ")" ::: "memory")
; #define PG8_WAIT_L(n) asm volatile("s_waitcnt lgkmcnt(" #n ")" ::: "memory")
; #define PG8_BAR __builtin_amdgcn_s_barrier()
; #define PG8_SCHED __builtin_amdgcn_sched_barrier(0)
; template <class Epi, class Sched, bool ALIGN_EPI = false, bool SP2 = false>
; __device__ __forceinline__ void gemm_phase(PG8_LAS unsigned char* lds, const Gemm g, const Sched& S, const Epi& E) {
;     ...
;             PG8_LDB(B0, 0, 0); PG8_LDB(B1, 0, 1); PG8_SCHED; PG8_LDA(At, 0, 0); PG8_STAGE(PG8_SA(1, 1), a1 + hstep, voffA);
;             PG8_WAIT_V(8); PG8_WAIT_L(0); PG8_BAR; PG8_MMA(0, 0, At, B0); PG8_MMA(0, 1, At, B1); PG8_BAR; PG8_SCHED;
	s_add_i32 m0, s56, 0xe000
	s_nop 0
	global_load_lds_dwordx4 v166, s[48:49]
	s_waitcnt vmcnt(8) lgkmcnt(0)


; #define PG8_MMA(ai, bj, At, Bt) do { __builtin_amdgcn_s_setprio(1); _Pragma("unroll") for (int m = 0; m < 4; ++m) _Pragma("unroll") for (int n = 0; n < 2; ++n) _Pragma("unroll") for (int k = 0; k < 2; ++k) \
;         acc[ai][bj][m][n] = __builtin_amdgcn_mfma_f32_16x16x32_bf16(Bt[n][k], At[m][k], acc[ai][bj][m][n], 0, 0, 0); __builtin_amdgcn_s_setprio(0); } while (0)
; #define PG8_WAIT_V(n) asm volatile("s_waitcnt vmcnt(" #n ")" ::: "memory")
; #define PG8_WAIT_L(n) asm volatile("s_waitcnt lgkmcnt(" #n ")" ::: "memory")
; #define PG8_BAR __builtin_amdgcn_s_barrier()
; #define PG8_SCHED __builtin_amdgcn_sched_barrier(0)
; template <class Epi, class Sched, bool ALIGN_EPI = false, bool SP2 = false>
; __device__ __forceinline__ void gemm_phase(PG8_LAS unsigned char* lds, const Gemm g, const Sched& S, const Epi& E) {
;     ...
;             PG8_WAIT_V(8); PG8_WAIT_L(0); PG8_BAR; PG8_MMA(0, 0, At, B0); PG8_MMA(0, 1, At, B1); PG8_BAR; PG8_SCHED;
	s_barrier

; #define PG8_MMA(ai, bj, At, Bt) do { __builtin_amdgcn_s_setprio(1); _Pragma("unroll") for (int m = 0; m < 4; ++m) _Pragma("unroll") for (int n = 0; n < 2; ++n) _Pragma("unroll") for (int k = 0; k < 2; ++k) \
;         acc[ai][bj][m][n] = __builtin_amdgcn_mfma_f32_16x16x32_bf16(Bt[n][k], At[m][k], acc[ai][bj][m][n], 0, 0, 0); __builtin_amdgcn_s_setprio(0); } while (0)
; #define PG8_WAIT_V(n) asm volatile("s_waitcnt vmcnt(" #n ")" ::: "memory")
; #define PG8_WAIT_L(n) asm volatile("s_waitcnt lgkmcnt(" #n ")" ::: "memory")
; #define PG8_BAR __builtin_amdgcn_s_barrier()
; #define PG8_SCHED __builtin_amdgcn_sched_barrier(0)
; template <class Epi, class Sched, bool ALIGN_EPI = false, bool SP2 = false>
; __device__ __forceinline__ void gemm_phase(PG8_LAS unsigned char* lds, const Gemm g, const Sched& S, const Epi& E) {
;     ...
;             PG8_WAIT_V(8); PG8_WAIT_L(0); PG8_BAR; PG8_MMA(0, 0, At, B0); PG8_MMA(0, 1, At, B1); PG8_BAR; PG8_SCHED;
	v_mfma_f32_16x16x32_bf16 v[140:143], v[96:99], v[176:179], v[140:143]
	v_mfma_f32_16x16x32_bf16 v[136:139], v[104:107], v[176:179], v[136:139]
	v_mfma_f32_16x16x32_bf16 v[124:127], v[96:99], v[184:187], v[124:127]
	v_mfma_f32_16x16x32_bf16 v[120:123], v[104:107], v[184:187], v[120:123]
	v_mfma_f32_16x16x32_bf16 v[92:95], v[96:99], v[202:205], v[92:95]
	v_mfma_f32_16x16x32_bf16 v[88:91], v[104:107], v[202:205], v[88:91]
	v_mfma_f32_16x16x32_bf16 v[76:79], v[96:99], v[210:213], v[76:79]
	v_mfma_f32_16x16x32_bf16 v[72:75], v[104:107], v[210:213], v[72:75]
	v_mfma_f32_16x16x32_bf16 v[140:143], v[100:103], v[180:183], v[140:143]
	v_mfma_f32_16x16x32_bf16 v[136:139], v[112:115], v[180:183], v[136:139]
	v_mfma_f32_16x16x32_bf16 v[124:127], v[100:103], v[188:191], v[124:127]
	v_mfma_f32_16x16x32_bf16 v[120:123], v[112:115], v[188:191], v[120:123]
	v_mfma_f32_16x16x32_bf16 v[92:95], v[100:103], v[206:209], v[92:95]
	v_mfma_f32_16x16x32_bf16 v[88:91], v[112:115], v[206:209], v[88:91]
	v_mfma_f32_16x16x32_bf16 v[76:79], v[100:103], v[214:217], v[76:79]
	v_mfma_f32_16x16x32_bf16 v[72:75], v[112:115], v[214:217], v[72:75]


; #define PG8_MMA(ai, bj, At, Bt) do { __builtin_amdgcn_s_setprio(1); _Pragma("unroll") for (int m = 0; m < 4; ++m) _Pragma("unroll") for (int n = 0; n < 2; ++n) _Pragma("unroll") for (int k = 0; k < 2; ++k) \
;         acc[ai][bj][m][n] = __builtin_amdgcn_mfma_f32_16x16x32_bf16(Bt[n][k], At[m][k], acc[ai][bj][m][n], 0, 0, 0); __builtin_amdgcn_s_setprio(0); } while (0)
; #define PG8_WAIT_V(n) asm volatile("s_waitcnt vmcnt(" #n ")" ::: "memory")
; #define PG8_WAIT_L(n) asm volatile("s_waitcnt lgkmcnt(" #n ")" ::: "memory")
; #define PG8_BAR __builtin_amdgcn_s_barrier()
; #define PG8_SCHED __builtin_amdgcn_sched_barrier(0)
; template <class Epi, class Sched, bool ALIGN_EPI = false, bool SP2 = false>
; __device__ __forceinline__ void gemm_phase(PG8_LAS unsigned char* lds, const Gemm g, const Sched& S, const Epi& E) {
;     ...
;             PG8_WAIT_V(8); PG8_WAIT_L(0); PG8_BAR; PG8_MMA(0, 0, At, B0); PG8_MMA(0, 1, At, B1); PG8_BAR; PG8_SCHED;
	v_mfma_f32_16x16x32_bf16 v[132:135], v[144:147], v[176:179], v[132:135]
	v_mfma_f32_16x16x32_bf16 v[128:131], v[152:155], v[176:179], v[128:131]
	v_mfma_f32_16x16x32_bf16 v[116:119], v[144:147], v[184:187], v[116:119]
	v_mfma_f32_16x16x32_bf16 v[108:111], v[152:155], v[184:187], v[108:111]
	v_mfma_f32_16x16x32_bf16 v[84:87], v[144:147], v[202:205], v[84:87]
	v_mfma_f32_16x16x32_bf16 v[80:83], v[152:155], v[202:205], v[80:83]
	v_mfma_f32_16x16x32_bf16 v[68:71], v[144:147], v[210:213], v[68:71]
	v_mfma_f32_16x16x32_bf16 v[64:67], v[152:155], v[210:213], v[64:67]
	v_mfma_f32_16x16x32_bf16 v[132:135], v[148:151], v[180:183], v[132:135]
	v_mfma_f32_16x16x32_bf16 v[128:131], v[172:175], v[180:183], v[128:131]
	v_mfma_f32_16x16x32_bf16 v[116:119], v[148:151], v[188:191], v[116:119]
	v_mfma_f32_16x16x32_bf16 v[108:111], v[172:175], v[188:191], v[108:111]
	v_mfma_f32_16x16x32_bf16 v[84:87], v[148:151], v[206:209], v[84:87]
	v_mfma_f32_16x16x32_bf16 v[80:83], v[172:175], v[206:209], v[80:83]
	v_mfma_f32_16x16x32_bf16 v[68:71], v[148:151], v[214:217], v[68:71]
	v_mfma_f32_16x16x32_bf16 v[64:67], v[172:175], v[214:217], v[64:67]

; #define PG8_STAGE(bufoff, gbase, voff) do { _Pragma("unroll") for (int _i = 0; _i < 2; ++_i) \
;         __builtin_amdgcn_global_load_lds((const unsigned*)((const char*)(gbase) + (voff)[_i]), (PG8_LAS unsigned*)(lds + (bufoff) + ldsw + _i * 8192), 16, 0, 0); } while (0)
; #define PG8_LDA(dst, b, h) do { _Pragma("unroll") for (int m = 0; m < 4; ++m) _Pragma("unroll") for (int k = 0; k < 2; ++k) dst[m][k] = *(const PG8_LAS bf16x8*)(lds + PG8_SA(b, h) + aoff + m * 2048 + k * 1024); } while (0)
; #define PG8_MMA(ai, bj, At, Bt) do { __builtin_amdgcn_s_setprio(1); _Pragma("unroll") for (int m = 0; m < 4; ++m) _Pragma("unroll") for (int n = 0; n < 2; ++n) _Pragma("unroll") for (int k = 0; k < 2; ++k) \
;         acc[ai][bj][m][n] = __builtin_amdgcn_mfma_f32_16x16x32_bf16(Bt[n][k], At[m][k], acc[ai][bj][m][n], 0, 0, 0); __builtin_amdgcn_s_setprio(0); } while (0)
; #define PG8_WAIT_V(n) asm volatile("s_waitcnt vmcnt(" #n ")" ::: "memory")
; #define PG8_WAIT_L(n) asm volatile("s_waitcnt lgkmcnt(" #n ")" ::: "memory")
; #define PG8_BAR __builtin_amdgcn_s_barrier()
; #define PG8_SCHED __builtin_amdgcn_sched_barrier(0)
; template <class Epi, class Sched, bool ALIGN_EPI = false, bool SP2 = false>
; __device__ __forceinline__ void gemm_phase(PG8_LAS unsigned char* lds, const Gemm g, const Sched& S, const Epi& E) {
;     ...
;             PG8_WAIT_V(8); PG8_WAIT_L(0); PG8_BAR; PG8_MMA(0, 0, At, B0); PG8_MMA(0, 1, At, B1); PG8_BAR; PG8_SCHED;
;             PG8_LDA(At, 0, 1); PG8_STAGE(PG8_SB(0, 0), b2, voffB); PG8_STAGE(PG8_SB(0, 1), b2 + hstep, voffB); PG8_STAGE(PG8_SA(0, 0), a2, voffA);
	s_barrier
	s_add_i32 s74, s65, s55
	s_mov_b64 s[96:97], s[50:51]

; #define PG8_STAGE(bufoff, gbase, voff) do { _Pragma("unroll") for (int _i = 0; _i < 2; ++_i) \
;         __builtin_amdgcn_global_load_lds((const unsigned*)((const char*)(gbase) + (voff)[_i]), (PG8_LAS unsigned*)(lds + (bufoff) + ldsw + _i * 8192), 16, 0, 0); } while (0)
; #define PG8_LDA(dst, b, h) do { _Pragma("unroll") for (int m = 0; m < 4; ++m) _Pragma("unroll") for (int k = 0; k < 2; ++k) dst[m][k] = *(const PG8_LAS bf16x8*)(lds + PG8_SA(b, h) + aoff + m * 2048 + k * 1024); } while (0)
; template <class Epi, class Sched, bool ALIGN_EPI = false, bool SP2 = false>
; __device__ __forceinline__ void gemm_phase(PG8_LAS unsigned char* lds, const Gemm g, const Sched& S, const Epi& E) {
;     ...
;             PG8_LDA(At, 0, 1); PG8_STAGE(PG8_SB(0, 0), b2, voffB); PG8_STAGE(PG8_SB(0, 1), b2 + hstep, voffB); PG8_STAGE(PG8_SA(0, 0), a2, voffA);
	s_mov_b32 m0, s74
	ds_read_b128 v[176:179], v199 offset:16384
	ds_read_b128 v[180:183], v199 offset:17408
	ds_read_b128 v[184:187], v199 offset:18432
	ds_read_b128 v[188:191], v199 offset:19456
	ds_read_b128 v[202:205], v199 offset:20480
	ds_read_b128 v[206:209], v199 offset:21504
	ds_read_b128 v[210:213], v199 offset:22528
	ds_read_b128 v[214:217], v199 offset:23552
	global_load_lds_dwordx4 v158, s[50:51]
	s_add_i32 m0, s74, 0x2000
	s_add_u32 s74, s50, 0x200000

; #define PG8_STAGE(bufoff, gbase, voff) do { _Pragma("unroll") for (int _i = 0; _i < 2; ++_i) \
;         __builtin_amdgcn_global_load_lds((const unsigned*)((const char*)(gbase) + (voff)[_i]), (PG8_LAS unsigned*)(lds + (bufoff) + ldsw + _i * 8192), 16, 0, 0); } while (0)
; #define PG8_LDA(dst, b, h) do { _Pragma("unroll") for (int m = 0; m < 4; ++m) _Pragma("unroll") for (int k = 0; k < 2; ++k) dst[m][k] = *(const PG8_LAS bf16x8*)(lds + PG8_SA(b, h) + aoff + m * 2048 + k * 1024); } while (0)
; template <class Epi, class Sched, bool ALIGN_EPI = false, bool SP2 = false>
; __device__ __forceinline__ void gemm_phase(PG8_LAS unsigned char* lds, const Gemm g, const Sched& S, const Epi& E) {
;     ...
;             PG8_LDA(At, 0, 1); PG8_STAGE(PG8_SB(0, 0), b2, voffB); PG8_STAGE(PG8_SB(0, 1), b2 + hstep, voffB); PG8_STAGE(PG8_SA(0, 0), a2, voffA);
	s_addc_u32 s75, s51, 0
	s_add_i32 s76, s67, s55
	global_load_lds_dwordx4 v162, s[50:51]

; #define PG8_STAGE(bufoff, gbase, voff) do { _Pragma("unroll") for (int _i = 0; _i < 2; ++_i) \
;         __builtin_amdgcn_global_load_lds((const unsigned*)((const char*)(gbase) + (voff)[_i]), (PG8_LAS unsigned*)(lds + (bufoff) + ldsw + _i * 8192), 16, 0, 0); } while (0)
; #define PG8_LDA(dst, b, h) do { _Pragma("unroll") for (int m = 0; m < 4; ++m) _Pragma("unroll") for (int k = 0; k < 2; ++k) dst[m][k] = *(const PG8_LAS bf16x8*)(lds + PG8_SA(b, h) + aoff + m * 2048 + k * 1024); } while (0)
; template <class Epi, class Sched, bool ALIGN_EPI = false, bool SP2 = false>
; __device__ __forceinline__ void gemm_phase(PG8_LAS unsigned char* lds, const Gemm g, const Sched& S, const Epi& E) {
;     ...
;             PG8_LDA(At, 0, 1); PG8_STAGE(PG8_SB(0, 0), b2, voffB); PG8_STAGE(PG8_SB(0, 1), b2 + hstep, voffB); PG8_STAGE(PG8_SA(0, 0), a2, voffA);
	s_mov_b32 m0, s76
	s_nop 0
	global_load_lds_dwordx4 v158, s[74:75]

; #define PG8_STAGE(bufoff, gbase, voff) do { _Pragma("unroll") for (int _i = 0; _i < 2; ++_i) \
;         __builtin_amdgcn_global_load_lds((const unsigned*)((const char*)(gbase) + (voff)[_i]), (PG8_LAS unsigned*)(lds + (bufoff) + ldsw + _i * 8192), 16, 0, 0); } while (0)
; #define PG8_LDA(dst, b, h) do { _Pragma("unroll") for (int m = 0; m < 4; ++m) _Pragma("unroll") for (int k = 0; k < 2; ++k) dst[m][k] = *(const PG8_LAS bf16x8*)(lds + PG8_SA(b, h) + aoff + m * 2048 + k * 1024); } while (0)
; template <class Epi, class Sched, bool ALIGN_EPI = false, bool SP2 = false>
; __device__ __forceinline__ void gemm_phase(PG8_LAS unsigned char* lds, const Gemm g, const Sched& S, const Epi& E) {
;     ...
;             PG8_LDA(At, 0, 1); PG8_STAGE(PG8_SB(0, 0), b2, voffB); PG8_STAGE(PG8_SB(0, 1), b2 + hstep, voffB); PG8_STAGE(PG8_SA(0, 0), a2, voffA);
	s_add_i32 m0, s76, 0x2000
	s_nop 0
	global_load_lds_dwordx4 v162, s[74:75]
	s_mov_b64 s[98:99], s[52:53]

; #define PG8_STAGE(bufoff, gbase, voff) do { _Pragma("unroll") for (int _i = 0; _i < 2; ++_i) \
;         __builtin_amdgcn_global_load_lds((const unsigned*)((const char*)(gbase) + (voff)[_i]), (PG8_LAS unsigned*)(lds + (bufoff) + ldsw + _i * 8192), 16, 0, 0); } while (0)
; #define PG8_LDA(dst, b, h) do { _Pragma("unroll") for (int m = 0; m < 4; ++m) _Pragma("unroll") for (int k = 0; k < 2; ++k) dst[m][k] = *(const PG8_LAS bf16x8*)(lds + PG8_SA(b, h) + aoff + m * 2048 + k * 1024); } while (0)
; #define PG8_MMA(ai, bj, At, Bt) do { __builtin_amdgcn_s_setprio(1); _Pragma("unroll") for (int m = 0; m < 4; ++m) _Pragma("unroll") for (int n = 0; n < 2; ++n) _Pragma("unroll") for (int k = 0; k < 2; ++k) \
;         acc[ai][bj][m][n] = __builtin_amdgcn_mfma_f32_16x16x32_bf16(Bt[n][k], At[m][k], acc[ai][bj][m][n], 0, 0, 0); __builtin_amdgcn_s_setprio(0); } while (0)
; #define PG8_WAIT_V(n) asm volatile("s_waitcnt vmcnt(" #n ")" ::: "memory")
; #define PG8_WAIT_L(n) asm volatile("s_waitcnt lgkmcnt(" #n ")" ::: "memory")
; #define PG8_BAR __builtin_amdgcn_s_barrier()
; #define PG8_SCHED __builtin_amdgcn_sched_barrier(0)
; template <class Epi, class Sched, bool ALIGN_EPI = false, bool SP2 = false>
; __device__ __forceinline__ void gemm_phase(PG8_LAS unsigned char* lds, const Gemm g, const Sched& S, const Epi& E) {
;     ...
;             PG8_LDA(At, 0, 1); PG8_STAGE(PG8_SB(0, 0), b2, voffB); PG8_STAGE(PG8_SB(0, 1), b2 + hstep, voffB); PG8_STAGE(PG8_SA(0, 0), a2, voffA);
;             PG8_WAIT_V(8); PG8_WAIT_L(0); PG8_BAR; PG8_MMA(1, 0, At, B0); PG8_MMA(1, 1, At, B1); PG8_BAR; PG8_SCHED;
	s_mov_b32 m0, s56
	s_nop 0
	global_load_lds_dwordx4 v156, s[52:53]
	s_mov_b32 m0, s57
	s_nop 0
	global_load_lds_dwordx4 v160, s[52:53]
	s_waitcnt vmcnt(8) lgkmcnt(0)


; #define PG8_MMA(ai, bj, At, Bt) do { __builtin_amdgcn_s_setprio(1); _Pragma("unroll") for (int m = 0; m < 4; ++m) _Pragma("unroll") for (int n = 0; n < 2; ++n) _Pragma("unroll") for (int k = 0; k < 2; ++k) \
;         acc[ai][bj][m][n] = __builtin_amdgcn_mfma_f32_16x16x32_bf16(Bt[n][k], At[m][k], acc[ai][bj][m][n], 0, 0, 0); __builtin_amdgcn_s_setprio(0); } while (0)
; #define PG8_WAIT_V(n) asm volatile("s_waitcnt vmcnt(" #n ")" ::: "memory")
; #define PG8_WAIT_L(n) asm volatile("s_waitcnt lgkmcnt(" #n ")" ::: "memory")
; #define PG8_BAR __builtin_amdgcn_s_barrier()
; #define PG8_SCHED __builtin_amdgcn_sched_barrier(0)
; template <class Epi, class Sched, bool ALIGN_EPI = false, bool SP2 = false>
; __device__ __forceinline__ void gemm_phase(PG8_LAS unsigned char* lds, const Gemm g, const Sched& S, const Epi& E) {
;     ...
;             PG8_WAIT_V(8); PG8_WAIT_L(0); PG8_BAR; PG8_MMA(1, 0, At, B0); PG8_MMA(1, 1, At, B1); PG8_BAR; PG8_SCHED;
	s_barrier

; #define PG8_MMA(ai, bj, At, Bt) do { __builtin_amdgcn_s_setprio(1); _Pragma("unroll") for (int m = 0; m < 4; ++m) _Pragma("unroll") for (int n = 0; n < 2; ++n) _Pragma("unroll") for (int k = 0; k < 2; ++k) \
;         acc[ai][bj][m][n] = __builtin_amdgcn_mfma_f32_16x16x32_bf16(Bt[n][k], At[m][k], acc[ai][bj][m][n], 0, 0, 0); __builtin_amdgcn_s_setprio(0); } while (0)
; #define PG8_WAIT_V(n) asm volatile("s_waitcnt vmcnt(" #n ")" ::: "memory")
; #define PG8_WAIT_L(n) asm volatile("s_waitcnt lgkmcnt(" #n ")" ::: "memory")
; #define PG8_BAR __builtin_amdgcn_s_barrier()
; #define PG8_SCHED __builtin_amdgcn_sched_barrier(0)
; template <class Epi, class Sched, bool ALIGN_EPI = false, bool SP2 = false>
; __device__ __forceinline__ void gemm_phase(PG8_LAS unsigned char* lds, const Gemm g, const Sched& S, const Epi& E) {
;     ...
;             PG8_WAIT_V(8); PG8_WAIT_L(0); PG8_BAR; PG8_MMA(1, 0, At, B0); PG8_MMA(1, 1, At, B1); PG8_BAR; PG8_SCHED;
	v_mfma_f32_16x16x32_bf16 v[60:63], v[96:99], v[176:179], v[60:63]
	v_mfma_f32_16x16x32_bf16 v[56:59], v[104:107], v[176:179], v[56:59]
	v_mfma_f32_16x16x32_bf16 v[44:47], v[96:99], v[184:187], v[44:47]
	v_mfma_f32_16x16x32_bf16 v[40:43], v[104:107], v[184:187], v[40:43]
	v_mfma_f32_16x16x32_bf16 v[28:31], v[96:99], v[202:205], v[28:31]
	v_mfma_f32_16x16x32_bf16 v[24:27], v[104:107], v[202:205], v[24:27]
	v_mfma_f32_16x16x32_bf16 v[12:15], v[96:99], v[210:213], v[12:15]
	v_mfma_f32_16x16x32_bf16 v[8:11], v[104:107], v[210:213], v[8:11]
	v_mfma_f32_16x16x32_bf16 v[60:63], v[100:103], v[180:183], v[60:63]
	v_mfma_f32_16x16x32_bf16 v[56:59], v[112:115], v[180:183], v[56:59]
	v_mfma_f32_16x16x32_bf16 v[44:47], v[100:103], v[188:191], v[44:47]
	v_mfma_f32_16x16x32_bf16 v[40:43], v[112:115], v[188:191], v[40:43]
	v_mfma_f32_16x16x32_bf16 v[28:31], v[100:103], v[206:209], v[28:31]
	v_mfma_f32_16x16x32_bf16 v[24:27], v[112:115], v[206:209], v[24:27]
	v_mfma_f32_16x16x32_bf16 v[12:15], v[100:103], v[214:217], v[12:15]
	v_mfma_f32_16x16x32_bf16 v[8:11], v[112:115], v[214:217], v[8:11]


; #define PG8_MMA(ai, bj, At, Bt) do { __builtin_amdgcn_s_setprio(1); _Pragma("unroll") for (int m = 0; m < 4; ++m) _Pragma("unroll") for (int n = 0; n < 2; ++n) _Pragma("unroll") for (int k = 0; k < 2; ++k) \
;         acc[ai][bj][m][n] = __builtin_amdgcn_mfma_f32_16x16x32_bf16(Bt[n][k], At[m][k], acc[ai][bj][m][n], 0, 0, 0); __builtin_amdgcn_s_setprio(0); } while (0)
; #define PG8_WAIT_V(n) asm volatile("s_waitcnt vmcnt(" #n ")" ::: "memory")
; #define PG8_WAIT_L(n) asm volatile("s_waitcnt lgkmcnt(" #n ")" ::: "memory")
; #define PG8_BAR __builtin_amdgcn_s_barrier()
; #define PG8_SCHED __builtin_amdgcn_sched_barrier(0)
; template <class Epi, class Sched, bool ALIGN_EPI = false, bool SP2 = false>
; __device__ __forceinline__ void gemm_phase(PG8_LAS unsigned char* lds, const Gemm g, const Sched& S, const Epi& E) {
;     ...
;             PG8_WAIT_V(8); PG8_WAIT_L(0); PG8_BAR; PG8_MMA(1, 0, At, B0); PG8_MMA(1, 1, At, B1); PG8_BAR; PG8_SCHED;
	v_mfma_f32_16x16x32_bf16 v[52:55], v[144:147], v[176:179], v[52:55]
	v_mfma_f32_16x16x32_bf16 v[48:51], v[152:155], v[176:179], v[48:51]
	v_mfma_f32_16x16x32_bf16 v[36:39], v[144:147], v[184:187], v[36:39]
	v_mfma_f32_16x16x32_bf16 v[32:35], v[152:155], v[184:187], v[32:35]
	v_mfma_f32_16x16x32_bf16 v[20:23], v[144:147], v[202:205], v[20:23]
	v_mfma_f32_16x16x32_bf16 v[16:19], v[152:155], v[202:205], v[16:19]
	v_mfma_f32_16x16x32_bf16 v[4:7], v[144:147], v[210:213], v[4:7]
	v_mfma_f32_16x16x32_bf16 v[0:3], v[152:155], v[210:213], v[0:3]
	v_mfma_f32_16x16x32_bf16 v[52:55], v[148:151], v[180:183], v[52:55]
	v_mfma_f32_16x16x32_bf16 v[48:51], v[172:175], v[180:183], v[48:51]
	v_mfma_f32_16x16x32_bf16 v[36:39], v[148:151], v[188:191], v[36:39]
	v_mfma_f32_16x16x32_bf16 v[32:35], v[172:175], v[188:191], v[32:35]
	v_mfma_f32_16x16x32_bf16 v[20:23], v[148:151], v[206:209], v[20:23]
	v_mfma_f32_16x16x32_bf16 v[16:19], v[172:175], v[206:209], v[16:19]
	v_mfma_f32_16x16x32_bf16 v[4:7], v[148:151], v[214:217], v[4:7]
	v_mfma_f32_16x16x32_bf16 v[0:3], v[172:175], v[214:217], v[0:3]

; #define PG8_STAGE(bufoff, gbase, voff) do { _Pragma("unroll") for (int _i = 0; _i < 2; ++_i) \
;         __builtin_amdgcn_global_load_lds((const unsigned*)((const char*)(gbase) + (voff)[_i]), (PG8_LAS unsigned*)(lds + (bufoff) + ldsw + _i * 8192), 16, 0, 0); } while (0)
; #define PG8_LDA(dst, b, h) do { _Pragma("unroll") for (int m = 0; m < 4; ++m) _Pragma("unroll") for (int k = 0; k < 2; ++k) dst[m][k] = *(const PG8_LAS bf16x8*)(lds + PG8_SA(b, h) + aoff + m * 2048 + k * 1024); } while (0)
; #define PG8_LDB(dst, b, h) do { _Pragma("unroll") for (int n = 0; n < 2; ++n) _Pragma("unroll") for (int k = 0; k < 2; ++k) dst[n][k] = *(const PG8_LAS bf16x8*)(lds + PG8_SB(b, h) + boff + n * 2048 + k * 1024); } while (0)
; #define PG8_MMA(ai, bj, At, Bt) do { __builtin_amdgcn_s_setprio(1); _Pragma("unroll") for (int m = 0; m < 4; ++m) _Pragma("unroll") for (int n = 0; n < 2; ++n) _Pragma("unroll") for (int k = 0; k < 2; ++k) \
;         acc[ai][bj][m][n] = __builtin_amdgcn_mfma_f32_16x16x32_bf16(Bt[n][k], At[m][k], acc[ai][bj][m][n], 0, 0, 0); __builtin_amdgcn_s_setprio(0); } while (0)
; #define PG8_WAIT_V(n) asm volatile("s_waitcnt vmcnt(" #n ")" ::: "memory")
; #define PG8_WAIT_L(n) asm volatile("s_waitcnt lgkmcnt(" #n ")" ::: "memory")
; #define PG8_BAR __builtin_amdgcn_s_barrier()
; #define PG8_SCHED __builtin_amdgcn_sched_barrier(0)
; template <class Epi, class Sched, bool ALIGN_EPI = false, bool SP2 = false>
; __device__ __forceinline__ void gemm_phase(PG8_LAS unsigned char* lds, const Gemm g, const Sched& S, const Epi& E) {
;     ...
;             PG8_WAIT_V(8); PG8_WAIT_L(0); PG8_BAR; PG8_MMA(1, 0, At, B0); PG8_MMA(1, 1, At, B1); PG8_BAR; PG8_SCHED;
;             PG8_LDB(B0, 1, 0); PG8_LDB(B1, 1, 1); PG8_SCHED; PG8_LDA(At, 1, 0); PG8_STAGE(PG8_SA(0, 1), a2 + hstep, voffA);
	s_barrier
	s_add_i32 s74, 0, 0x18000
	s_add_i32 s75, 0, 0x1c000


; #define PG8_STAGE(bufoff, gbase, voff) do { _Pragma("unroll") for (int _i = 0; _i < 2; ++_i) \
;         __builtin_amdgcn_global_load_lds((const unsigned*)((const char*)(gbase) + (voff)[_i]), (PG8_LAS unsigned*)(lds + (bufoff) + ldsw + _i * 8192), 16, 0, 0); } while (0)
; #define PG8_LDA(dst, b, h) do { _Pragma("unroll") for (int m = 0; m < 4; ++m) _Pragma("unroll") for (int k = 0; k < 2; ++k) dst[m][k] = *(const PG8_LAS bf16x8*)(lds + PG8_SA(b, h) + aoff + m * 2048 + k * 1024); } while (0)
; #define PG8_LDB(dst, b, h) do { _Pragma("unroll") for (int n = 0; n < 2; ++n) _Pragma("unroll") for (int k = 0; k < 2; ++k) dst[n][k] = *(const PG8_LAS bf16x8*)(lds + PG8_SB(b, h) + boff + n * 2048 + k * 1024); } while (0)
; #define PG8_SCHED __builtin_amdgcn_sched_barrier(0)
; template <class Epi, class Sched, bool ALIGN_EPI = false, bool SP2 = false>
; __device__ __forceinline__ void gemm_phase(PG8_LAS unsigned char* lds, const Gemm g, const Sched& S, const Epi& E) {
;     ...
;             PG8_LDB(B0, 1, 0); PG8_LDB(B1, 1, 1); PG8_SCHED; PG8_LDA(At, 1, 0); PG8_STAGE(PG8_SA(0, 1), a2 + hstep, voffA);
	ds_read_b128 v[96:99], v254
	ds_read_b128 v[100:103], v254 offset:1024
	ds_read_b128 v[104:107], v254 offset:2048
	ds_read_b128 v[112:115], v254 offset:3072
	ds_read_b128 v[144:147], v255
	ds_read_b128 v[148:151], v255 offset:1024
	ds_read_b128 v[152:155], v255 offset:2048
	ds_read_b128 v[172:175], v255 offset:3072
	s_add_u32 s52, s52, 0x200000
	s_addc_u32 s53, s53, 0
	s_mov_b32 m0, s58

; #define PG8_STAGE(bufoff, gbase, voff) do { _Pragma("unroll") for (int _i = 0; _i < 2; ++_i) \
;         __builtin_amdgcn_global_load_lds((const unsigned*)((const char*)(gbase) + (voff)[_i]), (PG8_LAS unsigned*)(lds + (bufoff) + ldsw + _i * 8192), 16, 0, 0); } while (0)
; #define PG8_LDA(dst, b, h) do { _Pragma("unroll") for (int m = 0; m < 4; ++m) _Pragma("unroll") for (int k = 0; k < 2; ++k) dst[m][k] = *(const PG8_LAS bf16x8*)(lds + PG8_SA(b, h) + aoff + m * 2048 + k * 1024); } while (0)
; #define PG8_LDB(dst, b, h) do { _Pragma("unroll") for (int n = 0; n < 2; ++n) _Pragma("unroll") for (int k = 0; k < 2; ++k) dst[n][k] = *(const PG8_LAS bf16x8*)(lds + PG8_SB(b, h) + boff + n * 2048 + k * 1024); } while (0)
; #define PG8_SCHED __builtin_amdgcn_sched_barrier(0)
; template <class Epi, class Sched, bool ALIGN_EPI = false, bool SP2 = false>
; __device__ __forceinline__ void gemm_phase(PG8_LAS unsigned char* lds, const Gemm g, const Sched& S, const Epi& E) {
;     ...
;             PG8_LDB(B0, 1, 0); PG8_LDB(B1, 1, 1); PG8_SCHED; PG8_LDA(At, 1, 0); PG8_STAGE(PG8_SA(0, 1), a2 + hstep, voffA);
	ds_read_b128 v[176:179], v199 offset:32768
	ds_read_b128 v[180:183], v199 offset:33792
	ds_read_b128 v[184:187], v199 offset:34816
	ds_read_b128 v[188:191], v199 offset:35840
	ds_read_b128 v[202:205], v199 offset:36864
	ds_read_b128 v[206:209], v199 offset:37888
	ds_read_b128 v[210:213], v199 offset:38912
	ds_read_b128 v[214:217], v199 offset:39936
	global_load_lds_dwordx4 v156, s[52:53]

; #define PG8_STAGE(bufoff, gbase, voff) do { _Pragma("unroll") for (int _i = 0; _i < 2; ++_i) \
;         __builtin_amdgcn_global_load_lds((const unsigned*)((const char*)(gbase) + (voff)[_i]), (PG8_LAS unsigned*)(lds + (bufoff) + ldsw + _i * 8192), 16, 0, 0); } while (0)
; #define PG8_LDA(dst, b, h) do { _Pragma("unroll") for (int m = 0; m < 4; ++m) _Pragma("unroll") for (int k = 0; k < 2; ++k) dst[m][k] = *(const PG8_LAS bf16x8*)(lds + PG8_SA(b, h) + aoff + m * 2048 + k * 1024); } while (0)
; #define PG8_LDB(dst, b, h) do { _Pragma("unroll") for (int n = 0; n < 2; ++n) _Pragma("unroll") for (int k = 0; k < 2; ++k) dst[n][k] = *(const PG8_LAS bf16x8*)(lds + PG8_SB(b, h) + boff + n * 2048 + k * 1024); } while (0)
; #define PG8_MMA(ai, bj, At, Bt) do { __builtin_amdgcn_s_setprio(1); _Pragma("unroll") for (int m = 0; m < 4; ++m) _Pragma("unroll") for (int n = 0; n < 2; ++n) _Pragma("unroll") for (int k = 0; k < 2; ++k) \
;         acc[ai][bj][m][n] = __builtin_amdgcn_mfma_f32_16x16x32_bf16(Bt[n][k], At[m][k], acc[ai][bj][m][n], 0, 0, 0); __builtin_amdgcn_s_setprio(0); } while (0)
; #define PG8_WAIT_V(n) asm volatile("s_waitcnt vmcnt(" #n ")" ::: "memory")
; #define PG8_WAIT_L(n) asm volatile("s_waitcnt lgkmcnt(" #n ")" ::: "memory")
; #define PG8_BAR __builtin_amdgcn_s_barrier()
; #define PG8_SCHED __builtin_amdgcn_sched_barrier(0)
; template <class Epi, class Sched, bool ALIGN_EPI = false, bool SP2 = false>
; __device__ __forceinline__ void gemm_phase(PG8_LAS unsigned char* lds, const Gemm g, const Sched& S, const Epi& E) {
;     ...
;             PG8_LDB(B0, 1, 0); PG8_LDB(B1, 1, 1); PG8_SCHED; PG8_LDA(At, 1, 0); PG8_STAGE(PG8_SA(0, 1), a2 + hstep, voffA);
;             PG8_WAIT_V(8); PG8_WAIT_L(0); PG8_BAR; PG8_MMA(0, 0, At, B0); PG8_MMA(0, 1, At, B1); PG8_BAR; PG8_SCHED;
	s_mov_b32 m0, s59
	s_nop 0
	global_load_lds_dwordx4 v160, s[52:53]
	s_waitcnt vmcnt(8) lgkmcnt(0)


; #define PG8_MMA(ai, bj, At, Bt) do { __builtin_amdgcn_s_setprio(1); _Pragma("unroll") for (int m = 0; m < 4; ++m) _Pragma("unroll") for (int n = 0; n < 2; ++n) _Pragma("unroll") for (int k = 0; k < 2; ++k) \
;         acc[ai][bj][m][n] = __builtin_amdgcn_mfma_f32_16x16x32_bf16(Bt[n][k], At[m][k], acc[ai][bj][m][n], 0, 0, 0); __builtin_amdgcn_s_setprio(0); } while (0)
; #define PG8_WAIT_V(n) asm volatile("s_waitcnt vmcnt(" #n ")" ::: "memory")
; #define PG8_WAIT_L(n) asm volatile("s_waitcnt lgkmcnt(" #n ")" ::: "memory")
; #define PG8_BAR __builtin_amdgcn_s_barrier()
; #define PG8_SCHED __builtin_amdgcn_sched_barrier(0)
; template <class Epi, class Sched, bool ALIGN_EPI = false, bool SP2 = false>
; __device__ __forceinline__ void gemm_phase(PG8_LAS unsigned char* lds, const Gemm g, const Sched& S, const Epi& E) {
;     ...
;             PG8_WAIT_V(8); PG8_WAIT_L(0); PG8_BAR; PG8_MMA(0, 0, At, B0); PG8_MMA(0, 1, At, B1); PG8_BAR; PG8_SCHED;
	s_barrier

; #define PG8_MMA(ai, bj, At, Bt) do { __builtin_amdgcn_s_setprio(1); _Pragma("unroll") for (int m = 0; m < 4; ++m) _Pragma("unroll") for (int n = 0; n < 2; ++n) _Pragma("unroll") for (int k = 0; k < 2; ++k) \
;         acc[ai][bj][m][n] = __builtin_amdgcn_mfma_f32_16x16x32_bf16(Bt[n][k], At[m][k], acc[ai][bj][m][n], 0, 0, 0); __builtin_amdgcn_s_setprio(0); } while (0)
; #define PG8_WAIT_V(n) asm volatile("s_waitcnt vmcnt(" #n ")" ::: "memory")
; #define PG8_WAIT_L(n) asm volatile("s_waitcnt lgkmcnt(" #n ")" ::: "memory")
; #define PG8_BAR __builtin_amdgcn_s_barrier()
; #define PG8_SCHED __builtin_amdgcn_sched_barrier(0)
; template <class Epi, class Sched, bool ALIGN_EPI = false, bool SP2 = false>
; __device__ __forceinline__ void gemm_phase(PG8_LAS unsigned char* lds, const Gemm g, const Sched& S, const Epi& E) {
;     ...
;             PG8_WAIT_V(8); PG8_WAIT_L(0); PG8_BAR; PG8_MMA(0, 0, At, B0); PG8_MMA(0, 1, At, B1); PG8_BAR; PG8_SCHED;
	v_mfma_f32_16x16x32_bf16 v[140:143], v[96:99], v[176:179], v[140:143]
	v_mfma_f32_16x16x32_bf16 v[136:139], v[104:107], v[176:179], v[136:139]
	v_mfma_f32_16x16x32_bf16 v[124:127], v[96:99], v[184:187], v[124:127]
	v_mfma_f32_16x16x32_bf16 v[120:123], v[104:107], v[184:187], v[120:123]
	v_mfma_f32_16x16x32_bf16 v[92:95], v[96:99], v[202:205], v[92:95]
	v_mfma_f32_16x16x32_bf16 v[88:91], v[104:107], v[202:205], v[88:91]
	v_mfma_f32_16x16x32_bf16 v[76:79], v[96:99], v[210:213], v[76:79]
	v_mfma_f32_16x16x32_bf16 v[72:75], v[104:107], v[210:213], v[72:75]
	v_mfma_f32_16x16x32_bf16 v[140:143], v[100:103], v[180:183], v[140:143]
	v_mfma_f32_16x16x32_bf16 v[136:139], v[112:115], v[180:183], v[136:139]
	v_mfma_f32_16x16x32_bf16 v[124:127], v[100:103], v[188:191], v[124:127]
	v_mfma_f32_16x16x32_bf16 v[120:123], v[112:115], v[188:191], v[120:123]
	v_mfma_f32_16x16x32_bf16 v[92:95], v[100:103], v[206:209], v[92:95]
	v_mfma_f32_16x16x32_bf16 v[88:91], v[112:115], v[206:209], v[88:91]
	v_mfma_f32_16x16x32_bf16 v[76:79], v[100:103], v[214:217], v[76:79]
	v_mfma_f32_16x16x32_bf16 v[72:75], v[112:115], v[214:217], v[72:75]


; #define PG8_MMA(ai, bj, At, Bt) do { __builtin_amdgcn_s_setprio(1); _Pragma("unroll") for (int m = 0; m < 4; ++m) _Pragma("unroll") for (int n = 0; n < 2; ++n) _Pragma("unroll") for (int k = 0; k < 2; ++k) \
;         acc[ai][bj][m][n] = __builtin_amdgcn_mfma_f32_16x16x32_bf16(Bt[n][k], At[m][k], acc[ai][bj][m][n], 0, 0, 0); __builtin_amdgcn_s_setprio(0); } while (0)
; #define PG8_WAIT_V(n) asm volatile("s_waitcnt vmcnt(" #n ")" ::: "memory")
; #define PG8_WAIT_L(n) asm volatile("s_waitcnt lgkmcnt(" #n ")" ::: "memory")
; #define PG8_BAR __builtin_amdgcn_s_barrier()
; #define PG8_SCHED __builtin_amdgcn_sched_barrier(0)
; template <class Epi, class Sched, bool ALIGN_EPI = false, bool SP2 = false>
; __device__ __forceinline__ void gemm_phase(PG8_LAS unsigned char* lds, const Gemm g, const Sched& S, const Epi& E) {
;     ...
;             PG8_WAIT_V(8); PG8_WAIT_L(0); PG8_BAR; PG8_MMA(0, 0, At, B0); PG8_MMA(0, 1, At, B1); PG8_BAR; PG8_SCHED;
	v_mfma_f32_16x16x32_bf16 v[132:135], v[144:147], v[176:179], v[132:135]
	v_mfma_f32_16x16x32_bf16 v[128:131], v[152:155], v[176:179], v[128:131]
	v_mfma_f32_16x16x32_bf16 v[116:119], v[144:147], v[184:187], v[116:119]
	v_mfma_f32_16x16x32_bf16 v[108:111], v[152:155], v[184:187], v[108:111]
	v_mfma_f32_16x16x32_bf16 v[84:87], v[144:147], v[202:205], v[84:87]
	v_mfma_f32_16x16x32_bf16 v[80:83], v[152:155], v[202:205], v[80:83]
	v_mfma_f32_16x16x32_bf16 v[68:71], v[144:147], v[210:213], v[68:71]
	v_mfma_f32_16x16x32_bf16 v[64:67], v[152:155], v[210:213], v[64:67]
	v_mfma_f32_16x16x32_bf16 v[132:135], v[148:151], v[180:183], v[132:135]
	v_mfma_f32_16x16x32_bf16 v[128:131], v[172:175], v[180:183], v[128:131]
	v_mfma_f32_16x16x32_bf16 v[116:119], v[148:151], v[188:191], v[116:119]
	v_mfma_f32_16x16x32_bf16 v[108:111], v[172:175], v[188:191], v[108:111]
	v_mfma_f32_16x16x32_bf16 v[84:87], v[148:151], v[206:209], v[84:87]
	v_mfma_f32_16x16x32_bf16 v[80:83], v[172:175], v[206:209], v[80:83]
	v_mfma_f32_16x16x32_bf16 v[68:71], v[148:151], v[214:217], v[68:71]
	v_mfma_f32_16x16x32_bf16 v[64:67], v[172:175], v[214:217], v[64:67]

; #define PG8_STAGE(bufoff, gbase, voff) do { _Pragma("unroll") for (int _i = 0; _i < 2; ++_i) \
;         __builtin_amdgcn_global_load_lds((const unsigned*)((const char*)(gbase) + (voff)[_i]), (PG8_LAS unsigned*)(lds + (bufoff) + ldsw + _i * 8192), 16, 0, 0); } while (0)
; #define PG8_LDA(dst, b, h) do { _Pragma("unroll") for (int m = 0; m < 4; ++m) _Pragma("unroll") for (int k = 0; k < 2; ++k) dst[m][k] = *(const PG8_LAS bf16x8*)(lds + PG8_SA(b, h) + aoff + m * 2048 + k * 1024); } while (0)
; #define PG8_MMA(ai, bj, At, Bt) do { __builtin_amdgcn_s_setprio(1); _Pragma("unroll") for (int m = 0; m < 4; ++m) _Pragma("unroll") for (int n = 0; n < 2; ++n) _Pragma("unroll") for (int k = 0; k < 2; ++k) \
;         acc[ai][bj][m][n] = __builtin_amdgcn_mfma_f32_16x16x32_bf16(Bt[n][k], At[m][k], acc[ai][bj][m][n], 0, 0, 0); __builtin_amdgcn_s_setprio(0); } while (0)
; #define PG8_WAIT_V(n) asm volatile("s_waitcnt vmcnt(" #n ")" ::: "memory")
; #define PG8_WAIT_L(n) asm volatile("s_waitcnt lgkmcnt(" #n ")" ::: "memory")
; #define PG8_BAR __builtin_amdgcn_s_barrier()
; #define PG8_SCHED __builtin_amdgcn_sched_barrier(0)
; template <class Epi, class Sched, bool ALIGN_EPI = false, bool SP2 = false>
; __device__ __forceinline__ void gemm_phase(PG8_LAS unsigned char* lds, const Gemm g, const Sched& S, const Epi& E) {
;     ...
;             PG8_WAIT_V(8); PG8_WAIT_L(0); PG8_BAR; PG8_MMA(0, 0, At, B0); PG8_MMA(0, 1, At, B1); PG8_BAR; PG8_SCHED;
;             PG8_LDA(At, 1, 1); PG8_STAGE(PG8_SB(1, 0), b3, voffB); PG8_STAGE(PG8_SB(1, 1), b3 + hstep, voffB); PG8_STAGE(PG8_SA(1, 0), a3, voffA);
	s_barrier
	s_add_i32 s52, s74, s55

; #define PG8_STAGE(bufoff, gbase, voff) do { _Pragma("unroll") for (int _i = 0; _i < 2; ++_i) \
;         __builtin_amdgcn_global_load_lds((const unsigned*)((const char*)(gbase) + (voff)[_i]), (PG8_LAS unsigned*)(lds + (bufoff) + ldsw + _i * 8192), 16, 0, 0); } while (0)
; #define PG8_LDA(dst, b, h) do { _Pragma("unroll") for (int m = 0; m < 4; ++m) _Pragma("unroll") for (int k = 0; k < 2; ++k) dst[m][k] = *(const PG8_LAS bf16x8*)(lds + PG8_SA(b, h) + aoff + m * 2048 + k * 1024); } while (0)
; template <class Epi, class Sched, bool ALIGN_EPI = false, bool SP2 = false>
; __device__ __forceinline__ void gemm_phase(PG8_LAS unsigned char* lds, const Gemm g, const Sched& S, const Epi& E) {
;     ...
;             PG8_LDA(At, 1, 1); PG8_STAGE(PG8_SB(1, 0), b3, voffB); PG8_STAGE(PG8_SB(1, 1), b3 + hstep, voffB); PG8_STAGE(PG8_SA(1, 0), a3, voffA);
	s_mov_b32 m0, s52
	ds_read_b128 v[176:179], v199 offset:49152
	ds_read_b128 v[180:183], v199 offset:50176
	ds_read_b128 v[184:187], v199 offset:51200
	ds_read_b128 v[188:191], v199 offset:52224
	ds_read_b128 v[202:205], v199 offset:53248
	ds_read_b128 v[206:209], v199 offset:54272
	ds_read_b128 v[210:213], v199 offset:55296
	ds_read_b128 v[214:217], v199 offset:56320
	global_load_lds_dwordx4 v250, s[96:97]
	s_add_i32 m0, s52, 0x2000
	s_add_u32 s50, s50, 0x200080

; #define PG8_STAGE(bufoff, gbase, voff) do { _Pragma("unroll") for (int _i = 0; _i < 2; ++_i) \
;         __builtin_amdgcn_global_load_lds((const unsigned*)((const char*)(gbase) + (voff)[_i]), (PG8_LAS unsigned*)(lds + (bufoff) + ldsw + _i * 8192), 16, 0, 0); } while (0)
; #define PG8_LDA(dst, b, h) do { _Pragma("unroll") for (int m = 0; m < 4; ++m) _Pragma("unroll") for (int k = 0; k < 2; ++k) dst[m][k] = *(const PG8_LAS bf16x8*)(lds + PG8_SA(b, h) + aoff + m * 2048 + k * 1024); } while (0)
; template <class Epi, class Sched, bool ALIGN_EPI = false, bool SP2 = false>
; __device__ __forceinline__ void gemm_phase(PG8_LAS unsigned char* lds, const Gemm g, const Sched& S, const Epi& E) {
;     ...
;             PG8_LDA(At, 1, 1); PG8_STAGE(PG8_SB(1, 0), b3, voffB); PG8_STAGE(PG8_SB(1, 1), b3 + hstep, voffB); PG8_STAGE(PG8_SA(1, 0), a3, voffA);
	s_addc_u32 s51, s51, 0
	s_add_i32 s52, s75, s55
	global_load_lds_dwordx4 v251, s[96:97]

; #define PG8_STAGE(bufoff, gbase, voff) do { _Pragma("unroll") for (int _i = 0; _i < 2; ++_i) \
;         __builtin_amdgcn_global_load_lds((const unsigned*)((const char*)(gbase) + (voff)[_i]), (PG8_LAS unsigned*)(lds + (bufoff) + ldsw + _i * 8192), 16, 0, 0); } while (0)
; #define PG8_LDA(dst, b, h) do { _Pragma("unroll") for (int m = 0; m < 4; ++m) _Pragma("unroll") for (int k = 0; k < 2; ++k) dst[m][k] = *(const PG8_LAS bf16x8*)(lds + PG8_SA(b, h) + aoff + m * 2048 + k * 1024); } while (0)
; template <class Epi, class Sched, bool ALIGN_EPI = false, bool SP2 = false>
; __device__ __forceinline__ void gemm_phase(PG8_LAS unsigned char* lds, const Gemm g, const Sched& S, const Epi& E) {
;     ...
;             PG8_LDA(At, 1, 1); PG8_STAGE(PG8_SB(1, 0), b3, voffB); PG8_STAGE(PG8_SB(1, 1), b3 + hstep, voffB); PG8_STAGE(PG8_SA(1, 0), a3, voffA);
	s_mov_b32 m0, s52
	s_nop 0
	global_load_lds_dwordx4 v158, s[50:51]

; #define PG8_STAGE(bufoff, gbase, voff) do { _Pragma("unroll") for (int _i = 0; _i < 2; ++_i) \
;         __builtin_amdgcn_global_load_lds((const unsigned*)((const char*)(gbase) + (voff)[_i]), (PG8_LAS unsigned*)(lds + (bufoff) + ldsw + _i * 8192), 16, 0, 0); } while (0)
; #define PG8_LDA(dst, b, h) do { _Pragma("unroll") for (int m = 0; m < 4; ++m) _Pragma("unroll") for (int k = 0; k < 2; ++k) dst[m][k] = *(const PG8_LAS bf16x8*)(lds + PG8_SA(b, h) + aoff + m * 2048 + k * 1024); } while (0)
; template <class Epi, class Sched, bool ALIGN_EPI = false, bool SP2 = false>
; __device__ __forceinline__ void gemm_phase(PG8_LAS unsigned char* lds, const Gemm g, const Sched& S, const Epi& E) {
;     ...
;             PG8_LDA(At, 1, 1); PG8_STAGE(PG8_SB(1, 0), b3, voffB); PG8_STAGE(PG8_SB(1, 1), b3 + hstep, voffB); PG8_STAGE(PG8_SA(1, 0), a3, voffA);
	s_add_i32 m0, s52, 0x2000
	s_nop 0
	global_load_lds_dwordx4 v162, s[50:51]

; #define PG8_STAGE(bufoff, gbase, voff) do { _Pragma("unroll") for (int _i = 0; _i < 2; ++_i) \
;         __builtin_amdgcn_global_load_lds((const unsigned*)((const char*)(gbase) + (voff)[_i]), (PG8_LAS unsigned*)(lds + (bufoff) + ldsw + _i * 8192), 16, 0, 0); } while (0)
; #define PG8_LDA(dst, b, h) do { _Pragma("unroll") for (int m = 0; m < 4; ++m) _Pragma("unroll") for (int k = 0; k < 2; ++k) dst[m][k] = *(const PG8_LAS bf16x8*)(lds + PG8_SA(b, h) + aoff + m * 2048 + k * 1024); } while (0)
; template <class Epi, class Sched, bool ALIGN_EPI = false, bool SP2 = false>
; __device__ __forceinline__ void gemm_phase(PG8_LAS unsigned char* lds, const Gemm g, const Sched& S, const Epi& E) {
;     ...
;             PG8_LDA(At, 1, 1); PG8_STAGE(PG8_SB(1, 0), b3, voffB); PG8_STAGE(PG8_SB(1, 1), b3 + hstep, voffB); PG8_STAGE(PG8_SA(1, 0), a3, voffA);
	s_mov_b32 m0, s61
	s_nop 0
	global_load_lds_dwordx4 v252, s[98:99]

; #define PG8_STAGE(bufoff, gbase, voff) do { _Pragma("unroll") for (int _i = 0; _i < 2; ++_i) \
;         __builtin_amdgcn_global_load_lds((const unsigned*)((const char*)(gbase) + (voff)[_i]), (PG8_LAS unsigned*)(lds + (bufoff) + ldsw + _i * 8192), 16, 0, 0); } while (0)
; #define PG8_LDA(dst, b, h) do { _Pragma("unroll") for (int m = 0; m < 4; ++m) _Pragma("unroll") for (int k = 0; k < 2; ++k) dst[m][k] = *(const PG8_LAS bf16x8*)(lds + PG8_SA(b, h) + aoff + m * 2048 + k * 1024); } while (0)
; #define PG8_MMA(ai, bj, At, Bt) do { __builtin_amdgcn_s_setprio(1); _Pragma("unroll") for (int m = 0; m < 4; ++m) _Pragma("unroll") for (int n = 0; n < 2; ++n) _Pragma("unroll") for (int k = 0; k < 2; ++k) \
;         acc[ai][bj][m][n] = __builtin_amdgcn_mfma_f32_16x16x32_bf16(Bt[n][k], At[m][k], acc[ai][bj][m][n], 0, 0, 0); __builtin_amdgcn_s_setprio(0); } while (0)
; #define PG8_WAIT_V(n) asm volatile("s_waitcnt vmcnt(" #n ")" ::: "memory")
; #define PG8_WAIT_L(n) asm volatile("s_waitcnt lgkmcnt(" #n ")" ::: "memory")
; #define PG8_BAR __builtin_amdgcn_s_barrier()
; #define PG8_SCHED __builtin_amdgcn_sched_barrier(0)
; template <class Epi, class Sched, bool ALIGN_EPI = false, bool SP2 = false>
; __device__ __forceinline__ void gemm_phase(PG8_LAS unsigned char* lds, const Gemm g, const Sched& S, const Epi& E) {
;     ...
;             PG8_LDA(At, 1, 1); PG8_STAGE(PG8_SB(1, 0), b3, voffB); PG8_STAGE(PG8_SB(1, 1), b3 + hstep, voffB); PG8_STAGE(PG8_SA(1, 0), a3, voffA);
;             PG8_WAIT_V(8); PG8_WAIT_L(0); PG8_BAR; PG8_MMA(1, 0, At, B0); PG8_MMA(1, 1, At, B1); PG8_BAR; PG8_SCHED;
	s_mov_b32 m0, s62
	s_nop 0
	global_load_lds_dwordx4 v253, s[98:99]
	s_waitcnt vmcnt(8) lgkmcnt(0)


; #define PG8_MMA(ai, bj, At, Bt) do { __builtin_amdgcn_s_setprio(1); _Pragma("unroll") for (int m = 0; m < 4; ++m) _Pragma("unroll") for (int n = 0; n < 2; ++n) _Pragma("unroll") for (int k = 0; k < 2; ++k) \
;         acc[ai][bj][m][n] = __builtin_amdgcn_mfma_f32_16x16x32_bf16(Bt[n][k], At[m][k], acc[ai][bj][m][n], 0, 0, 0); __builtin_amdgcn_s_setprio(0); } while (0)
; #define PG8_WAIT_V(n) asm volatile("s_waitcnt vmcnt(" #n ")" ::: "memory")
; #define PG8_WAIT_L(n) asm volatile("s_waitcnt lgkmcnt(" #n ")" ::: "memory")
; #define PG8_BAR __builtin_amdgcn_s_barrier()
; #define PG8_SCHED __builtin_amdgcn_sched_barrier(0)
; template <class Epi, class Sched, bool ALIGN_EPI = false, bool SP2 = false>
; __device__ __forceinline__ void gemm_phase(PG8_LAS unsigned char* lds, const Gemm g, const Sched& S, const Epi& E) {
;     ...
;             PG8_WAIT_V(8); PG8_WAIT_L(0); PG8_BAR; PG8_MMA(1, 0, At, B0); PG8_MMA(1, 1, At, B1); PG8_BAR; PG8_SCHED;
	s_barrier

; #define PG8_MMA(ai, bj, At, Bt) do { __builtin_amdgcn_s_setprio(1); _Pragma("unroll") for (int m = 0; m < 4; ++m) _Pragma("unroll") for (int n = 0; n < 2; ++n) _Pragma("unroll") for (int k = 0; k < 2; ++k) \
;         acc[ai][bj][m][n] = __builtin_amdgcn_mfma_f32_16x16x32_bf16(Bt[n][k], At[m][k], acc[ai][bj][m][n], 0, 0, 0); __builtin_amdgcn_s_setprio(0); } while (0)
; #define PG8_WAIT_V(n) asm volatile("s_waitcnt vmcnt(" #n ")" ::: "memory")
; #define PG8_WAIT_L(n) asm volatile("s_waitcnt lgkmcnt(" #n ")" ::: "memory")
; #define PG8_BAR __builtin_amdgcn_s_barrier()
; #define PG8_SCHED __builtin_amdgcn_sched_barrier(0)
; template <class Epi, class Sched, bool ALIGN_EPI = false, bool SP2 = false>
; __device__ __forceinline__ void gemm_phase(PG8_LAS unsigned char* lds, const Gemm g, const Sched& S, const Epi& E) {
;     ...
;             PG8_WAIT_V(8); PG8_WAIT_L(0); PG8_BAR; PG8_MMA(1, 0, At, B0); PG8_MMA(1, 1, At, B1); PG8_BAR; PG8_SCHED;
	v_mfma_f32_16x16x32_bf16 v[60:63], v[96:99], v[176:179], v[60:63]
	v_mfma_f32_16x16x32_bf16 v[56:59], v[104:107], v[176:179], v[56:59]
	v_mfma_f32_16x16x32_bf16 v[44:47], v[96:99], v[184:187], v[44:47]
	v_mfma_f32_16x16x32_bf16 v[40:43], v[104:107], v[184:187], v[40:43]
	v_mfma_f32_16x16x32_bf16 v[28:31], v[96:99], v[202:205], v[28:31]
	v_mfma_f32_16x16x32_bf16 v[24:27], v[104:107], v[202:205], v[24:27]
	v_mfma_f32_16x16x32_bf16 v[12:15], v[96:99], v[210:213], v[12:15]
	v_mfma_f32_16x16x32_bf16 v[8:11], v[104:107], v[210:213], v[8:11]
	v_mfma_f32_16x16x32_bf16 v[60:63], v[100:103], v[180:183], v[60:63]
	v_mfma_f32_16x16x32_bf16 v[56:59], v[112:115], v[180:183], v[56:59]
	v_mfma_f32_16x16x32_bf16 v[44:47], v[100:103], v[188:191], v[44:47]
	v_mfma_f32_16x16x32_bf16 v[40:43], v[112:115], v[188:191], v[40:43]
	v_mfma_f32_16x16x32_bf16 v[28:31], v[100:103], v[206:209], v[28:31]
	v_mfma_f32_16x16x32_bf16 v[24:27], v[112:115], v[206:209], v[24:27]
	v_mfma_f32_16x16x32_bf16 v[12:15], v[100:103], v[214:217], v[12:15]
	v_mfma_f32_16x16x32_bf16 v[8:11], v[112:115], v[214:217], v[8:11]


; #define PG8_MMA(ai, bj, At, Bt) do { __builtin_amdgcn_s_setprio(1); _Pragma("unroll") for (int m = 0; m < 4; ++m) _Pragma("unroll") for (int n = 0; n < 2; ++n) _Pragma("unroll") for (int k = 0; k < 2; ++k) \
;         acc[ai][bj][m][n] = __builtin_amdgcn_mfma_f32_16x16x32_bf16(Bt[n][k], At[m][k], acc[ai][bj][m][n], 0, 0, 0); __builtin_amdgcn_s_setprio(0); } while (0)
; #define PG8_WAIT_V(n) asm volatile("s_waitcnt vmcnt(" #n ")" ::: "memory")
; #define PG8_WAIT_L(n) asm volatile("s_waitcnt lgkmcnt(" #n ")" ::: "memory")
; #define PG8_BAR __builtin_amdgcn_s_barrier()
; #define PG8_SCHED __builtin_amdgcn_sched_barrier(0)
; template <class Epi, class Sched, bool ALIGN_EPI = false, bool SP2 = false>
; __device__ __forceinline__ void gemm_phase(PG8_LAS unsigned char* lds, const Gemm g, const Sched& S, const Epi& E) {
;     ...
;             PG8_WAIT_V(8); PG8_WAIT_L(0); PG8_BAR; PG8_MMA(1, 0, At, B0); PG8_MMA(1, 1, At, B1); PG8_BAR; PG8_SCHED;
	v_mfma_f32_16x16x32_bf16 v[52:55], v[144:147], v[176:179], v[52:55]
	v_mfma_f32_16x16x32_bf16 v[48:51], v[152:155], v[176:179], v[48:51]
	v_mfma_f32_16x16x32_bf16 v[36:39], v[144:147], v[184:187], v[36:39]
	v_mfma_f32_16x16x32_bf16 v[32:35], v[152:155], v[184:187], v[32:35]
	v_mfma_f32_16x16x32_bf16 v[20:23], v[144:147], v[202:205], v[20:23]
	v_mfma_f32_16x16x32_bf16 v[16:19], v[152:155], v[202:205], v[16:19]
	v_mfma_f32_16x16x32_bf16 v[4:7], v[144:147], v[210:213], v[4:7]
	v_mfma_f32_16x16x32_bf16 v[0:3], v[152:155], v[210:213], v[0:3]
	v_mfma_f32_16x16x32_bf16 v[52:55], v[148:151], v[180:183], v[52:55]
	v_mfma_f32_16x16x32_bf16 v[48:51], v[172:175], v[180:183], v[48:51]
	v_mfma_f32_16x16x32_bf16 v[36:39], v[148:151], v[188:191], v[36:39]
	v_mfma_f32_16x16x32_bf16 v[32:35], v[172:175], v[188:191], v[32:35]
	v_mfma_f32_16x16x32_bf16 v[20:23], v[148:151], v[206:209], v[20:23]
	v_mfma_f32_16x16x32_bf16 v[16:19], v[172:175], v[206:209], v[16:19]
	v_mfma_f32_16x16x32_bf16 v[4:7], v[148:151], v[214:217], v[4:7]
	v_mfma_f32_16x16x32_bf16 v[0:3], v[172:175], v[214:217], v[0:3]

; #define PG8_MMA(ai, bj, At, Bt) do { __builtin_amdgcn_s_setprio(1); _Pragma("unroll") for (int m = 0; m < 4; ++m) _Pragma("unroll") for (int n = 0; n < 2; ++n) _Pragma("unroll") for (int k = 0; k < 2; ++k) \
;         acc[ai][bj][m][n] = __builtin_amdgcn_mfma_f32_16x16x32_bf16(Bt[n][k], At[m][k], acc[ai][bj][m][n], 0, 0, 0); __builtin_amdgcn_s_setprio(0); } while (0)
; #define PG8_WAIT_V(n) asm volatile("s_waitcnt vmcnt(" #n ")" ::: "memory")
; #define PG8_WAIT_L(n) asm volatile("s_waitcnt lgkmcnt(" #n ")" ::: "memory")
; #define PG8_BAR __builtin_amdgcn_s_barrier()
; #define PG8_SCHED __builtin_amdgcn_sched_barrier(0)
; template <class Epi, class Sched, bool ALIGN_EPI = false, bool SP2 = false>
; __device__ __forceinline__ void gemm_phase(PG8_LAS unsigned char* lds, const Gemm g, const Sched& S, const Epi& E) {
;     ...
;         for (int t = 0; t < nt; t += 2) {
;     ...
;             PG8_WAIT_V(8); PG8_WAIT_L(0); PG8_BAR; PG8_MMA(1, 0, At, B0); PG8_MMA(1, 1, At, B1); PG8_BAR; PG8_SCHED;
;     ...
;         if constexpr (ALIGN_EPI) { if (wr == 0) PG8_BAR; }
	s_barrier
	s_add_i32 s73, s73, 2
	s_add_u32 s48, s48, 0x100
	s_addc_u32 s49, s49, 0
	s_add_u32 s71, s71, 0x100
	s_addc_u32 s72, s72, 0
	s_cmpk_gt_u32 s73, 0x7d
	s_cbranch_scc0 .LBB0_1114
	s_and_b64 vcc, exec, s[34:35]
	s_cbranch_vccz .LBB0_1117
	s_barrier
